# v28 plus f32->bf16 pack idiom replaced by v_cvt_pk_bf16_f32 at 354 sites (fixpoint matcher, liveness-checked temporaries, hazard-distance repair nops)
# baseline (speedup 1.0000x reference)
.LBB0_378:
	s_or_b64 exec, exec, s[8:9]
	v_readlane_b32 s8, v254, 40
	v_readlane_b32 s9, v254, 41
	s_xor_b64 s[8:9], s[8:9], -1
	s_nop 1
	v_writelane_b32 v254, s8, 49
	v_mov_b32_e32 v1, v0
	s_waitcnt lgkmcnt(0)
	v_mov_b32_e32 v2, v232
	v_writelane_b32 v254, s9, 50
	s_mov_b64 s[8:9], s[44:45]
	s_mov_b64 s[80:81], s[46:47]
	s_mov_b64 s[10:11], s[0:1]
	s_barrier
	v_readlane_b32 s12, v254, 51
	s_lshl_b32 s58, s12, 8
	s_mul_i32 s9, s12, 0x1800000
	s_mul_hi_u32 s8, s12, 0x1800000
	s_add_u32 s61, s9, 0x819100
	s_mov_b32 s59, s71
	s_addc_u32 s74, s8, 0
	v_readlane_b32 s13, v254, 52
	s_branch .LBB0_381

.LBB0_525:
	s_and_b64 vcc, exec, s[8:9]
	s_cbranch_vccz .LBB0_381
	s_cmpk_gt_u32 s86, 0x317
	s_mov_b64 s[8:9], -1
	s_cbranch_scc1 .LBB0_529
	s_add_u32 s62, s80, 0xee19000
	s_addc_u32 s63, s81, 0
	s_sub_i32 s8, s86, 24
	s_lshr_b32 s72, s8, 8
	s_bfe_u32 s60, s8, 0x30005
	s_lshl_b32 s8, s8, 3
	s_lshl_b32 s84, s72, 1
	s_and_b32 s8, s8, 0xf8
	v_readlane_b32 s9, v253, 15
	s_add_i32 s8, s8, s9
	s_sub_i32 s9, 8, s84
	s_lshr_b32 s75, s8, s9
	s_lshl_b32 s9, -1, s9
	s_andn2_b32 s10, s8, s9
	s_lshl_b32 s85, s10, 5
	v_ashrrev_i32_e32 v2, 4, v172
	v_add_u32_e32 v118, s85, v2
	v_lshlrev_b32_e32 v3, 3, v172
	v_lshlrev_b32_e32 v4, s84, v118
	v_and_b32_e32 v3, 0x78, v3
	v_add_u32_e32 v4, s75, v4
	v_mov_b64_e32 v[28:29], s[62:63]
	v_mad_i64_i32 v[4:5], s[8:9], v4, s83, v[28:29]
	s_lshl_b32 s70, s60, 8
	v_lshlrev_b32_e32 v82, 1, v3
	v_add_lshl_u32 v3, v118, 4, s84
	v_lshl_add_u64 v[4:5], v[4:5], 0, s[70:71]
	v_add_u32_e32 v3, s75, v3
	v_lshl_add_u64 v[4:5], v[4:5], 0, v[82:83]
	v_mad_i64_i32 v[6:7], s[8:9], v3, s83, v[28:29]
	v_add_lshl_u32 v3, v118, 8, s84
	v_add_co_u32_e32 v4, vcc, s82, v4
	v_lshl_add_u64 v[6:7], v[6:7], 0, s[70:71]
	v_add_u32_e32 v3, s75, v3
	v_addc_co_u32_e32 v5, vcc, 0, v5, vcc
	v_lshl_add_u64 v[6:7], v[6:7], 0, v[82:83]
	v_mad_i64_i32 v[12:13], s[8:9], v3, s83, v[28:29]
	v_add_lshl_u32 v3, v118, 12, s84
	v_add_co_u32_e32 v8, vcc, s82, v6
	v_lshl_add_u64 v[12:13], v[12:13], 0, s[70:71]
	v_add_u32_e32 v3, s75, v3
	v_addc_co_u32_e32 v9, vcc, 0, v7, vcc
	v_lshl_add_u64 v[12:13], v[12:13], 0, v[82:83]
	v_mad_i64_i32 v[14:15], s[8:9], v3, s83, v[28:29]
	v_add_lshl_u32 v3, v118, 16, s84
	v_add_co_u32_e32 v12, vcc, s82, v12
	v_lshl_add_u64 v[14:15], v[14:15], 0, s[70:71]
	v_add_u32_e32 v3, s75, v3
	v_addc_co_u32_e32 v13, vcc, 0, v13, vcc
	v_lshl_add_u64 v[14:15], v[14:15], 0, v[82:83]
	v_mad_i64_i32 v[20:21], s[8:9], v3, s83, v[28:29]
	v_add_lshl_u32 v3, v118, 20, s84
	v_add_co_u32_e32 v16, vcc, s82, v14
	v_lshl_add_u64 v[20:21], v[20:21], 0, s[70:71]
	v_add_u32_e32 v3, s75, v3
	v_addc_co_u32_e32 v17, vcc, 0, v15, vcc
	v_lshl_add_u64 v[20:21], v[20:21], 0, v[82:83]
	v_mad_i64_i32 v[22:23], s[8:9], v3, s83, v[28:29]
	v_add_lshl_u32 v3, v118, 24, s84
	v_add_co_u32_e32 v20, vcc, s82, v20
	v_lshl_add_u64 v[22:23], v[22:23], 0, s[70:71]
	v_add_u32_e32 v3, s75, v3
	v_addc_co_u32_e32 v21, vcc, 0, v21, vcc
	v_lshl_add_u64 v[22:23], v[22:23], 0, v[82:83]
	v_mad_i64_i32 v[30:31], s[8:9], v3, s83, v[28:29]
	v_add_lshl_u32 v3, v118, 28, s84
	v_add_co_u32_e32 v24, vcc, s82, v22
	v_lshl_add_u64 v[30:31], v[30:31], 0, s[70:71]
	v_add_u32_e32 v3, s75, v3
	v_addc_co_u32_e32 v25, vcc, 0, v23, vcc
	v_lshl_add_u64 v[30:31], v[30:31], 0, v[82:83]
	v_mad_i64_i32 v[28:29], s[8:9], v3, s83, v[28:29]
	v_add_co_u32_e32 v30, vcc, s82, v30
	v_lshl_add_u64 v[28:29], v[28:29], 0, s[70:71]
	s_nop 0
	v_addc_co_u32_e32 v31, vcc, 0, v31, vcc
	v_lshl_add_u64 v[28:29], v[28:29], 0, v[82:83]
	v_add_co_u32_e32 v32, vcc, s82, v28
	global_load_dwordx4 v[4:7], v[4:5], off offset:2048
	s_nop 0
	global_load_dwordx4 v[8:11], v[8:9], off offset:2048
	v_addc_co_u32_e32 v33, vcc, 0, v29, vcc
	global_load_dwordx4 v[12:15], v[12:13], off offset:2048
	s_nop 0
	global_load_dwordx4 v[16:19], v[16:17], off offset:2048
	s_nop 0
	global_load_dwordx4 v[20:23], v[20:21], off offset:2048
	s_nop 0
	global_load_dwordx4 v[24:27], v[24:25], off offset:2048
	s_nop 0
	global_load_dwordx4 v[28:31], v[30:31], off offset:2048
	s_nop 0
	global_load_dwordx4 v[32:35], v[32:33], off offset:2048
	v_lshlrev_b32_e32 v3, 4, v172
	v_and_b32_e32 v3, 0xf0, v3
	v_add_u32_e32 v3, s94, v3
	v_mul_lo_u32 v36, v2, s5
	v_and_b32_e32 v120, 31, v172
	v_add_u32_e32 v121, v3, v36
	v_ashrrev_i32_e32 v119, 5, v172
	v_mov_b32_e32 v3, s94
	s_waitcnt vmcnt(0)
	ds_write_b128 v121, v[4:7]
	ds_write_b128 v121, v[8:11] offset:1088
	ds_write_b128 v121, v[12:15] offset:2176
	ds_write_b128 v121, v[16:19] offset:3264
	ds_write_b128 v121, v[20:23] offset:4352
	ds_write_b128 v121, v[24:27] offset:5440
	ds_write_b128 v121, v[28:31] offset:6528
	ds_write_b128 v121, v[32:35] offset:7616
	v_mad_u32_u24 v3, v120, s5, v3
	v_lshlrev_b32_e32 v4, 4, v119
	s_waitcnt lgkmcnt(0)
	v_add_u32_e32 v122, v3, v4
	ds_read_b128 v[84:87], v122
	ds_read_b128 v[88:91], v122 offset:32
	ds_read_b128 v[92:95], v122 offset:64
	ds_read_b128 v[96:99], v122 offset:96
	ds_read_b128 v[100:103], v122 offset:128
	ds_read_b128 v[104:107], v122 offset:160
	ds_read_b128 v[108:111], v122 offset:192
	ds_read_b128 v[112:115], v122 offset:224
	v_lshlrev_b32_e32 v67, 2, v119
	v_bfe_u32 v3, v172, 2, 2
	v_or_b32_e32 v5, v3, v67
	v_add_u32_e32 v66, 8, v67
	v_and_b32_e32 v4, 16, v172
	v_mul_lo_u32 v70, v5, s5
	v_lshlrev_b32_e32 v5, 2, v172
	s_waitcnt lgkmcnt(0)
	v_and_or_b32 v74, v5, 12, v4
	v_or_b32_e32 v4, v66, v3
	v_add_u32_e32 v69, 16, v67
	v_add_u32_e32 v68, 24, v67
	s_lshl_b32 s87, s60, 7
	v_mul_lo_u32 v71, v4, s5
	v_or_b32_e32 v4, v69, v3
	v_or_b32_e32 v3, v68, v3
	v_mul_lo_u32 v72, v4, s5
	v_mul_lo_u32 v73, v3, s5
	s_cmp_gt_u32 s10, 3
	s_mov_b64 s[8:9], -1
	s_cbranch_scc0 .LBB0_546
	s_add_i32 s8, s85, 0xffffff80
	v_add_u32_e32 v32, s8, v2
	v_lshlrev_b32_e32 v2, s84, v32
	v_add_u32_e32 v2, s75, v2
	v_mov_b64_e32 v[30:31], s[62:63]
	v_mad_i64_i32 v[2:3], s[8:9], v2, s83, v[30:31]
	s_lshl_b32 s70, s87, 1
	v_add_lshl_u32 v6, v32, 4, s84
	v_lshl_add_u64 v[2:3], v[2:3], 0, s[70:71]
	v_add_u32_e32 v6, s75, v6
	v_lshl_add_u64 v[2:3], v[2:3], 0, v[82:83]
	v_mad_i64_i32 v[6:7], s[8:9], v6, s83, v[30:31]
	v_add_lshl_u32 v10, v32, 8, s84
	v_add_co_u32_e32 v34, vcc, 0x2000, v2
	v_lshl_add_u64 v[6:7], v[6:7], 0, s[70:71]
	v_add_u32_e32 v10, s75, v10
	v_addc_co_u32_e32 v35, vcc, 0, v3, vcc
	v_lshl_add_u64 v[6:7], v[6:7], 0, v[82:83]
	v_mad_i64_i32 v[10:11], s[8:9], v10, s83, v[30:31]
	v_add_lshl_u32 v14, v32, 12, s84
	v_add_co_u32_e32 v38, vcc, 0x2000, v6
	v_lshl_add_u64 v[10:11], v[10:11], 0, s[70:71]
	v_add_u32_e32 v14, s75, v14
	v_addc_co_u32_e32 v39, vcc, 0, v7, vcc
	v_lshl_add_u64 v[10:11], v[10:11], 0, v[82:83]
	v_mad_i64_i32 v[14:15], s[8:9], v14, s83, v[30:31]
	v_add_lshl_u32 v18, v32, 16, s84
	v_add_co_u32_e32 v42, vcc, 0x2000, v10
	v_lshl_add_u64 v[14:15], v[14:15], 0, s[70:71]
	v_add_u32_e32 v18, s75, v18
	v_addc_co_u32_e32 v43, vcc, 0, v11, vcc
	v_lshl_add_u64 v[14:15], v[14:15], 0, v[82:83]
	v_mad_i64_i32 v[18:19], s[8:9], v18, s83, v[30:31]
	v_add_lshl_u32 v22, v32, 20, s84
	v_add_co_u32_e32 v46, vcc, 0x2000, v14
	v_lshl_add_u64 v[18:19], v[18:19], 0, s[70:71]
	v_add_u32_e32 v22, s75, v22
	v_addc_co_u32_e32 v47, vcc, 0, v15, vcc
	v_lshl_add_u64 v[18:19], v[18:19], 0, v[82:83]
	v_mad_i64_i32 v[22:23], s[8:9], v22, s83, v[30:31]
	v_add_lshl_u32 v26, v32, 24, s84
	global_load_dwordx4 v[2:5], v[34:35], off
	global_load_dwordx4 v[6:9], v[38:39], off
	v_add_co_u32_e32 v50, vcc, 0x2000, v18
	v_lshl_add_u64 v[22:23], v[22:23], 0, s[70:71]
	v_add_u32_e32 v26, s75, v26
	v_addc_co_u32_e32 v51, vcc, 0, v19, vcc
	v_lshl_add_u64 v[22:23], v[22:23], 0, v[82:83]
	v_mad_i64_i32 v[26:27], s[8:9], v26, s83, v[30:31]
	v_add_lshl_u32 v32, v32, 28, s84
	global_load_dwordx4 v[10:13], v[42:43], off
	global_load_dwordx4 v[14:17], v[46:47], off
	v_add_co_u32_e32 v54, vcc, 0x2000, v22
	v_lshl_add_u64 v[26:27], v[26:27], 0, s[70:71]
	v_add_u32_e32 v32, s75, v32
	v_addc_co_u32_e32 v55, vcc, 0, v23, vcc
	v_lshl_add_u64 v[26:27], v[26:27], 0, v[82:83]
	v_mad_i64_i32 v[30:31], s[8:9], v32, s83, v[30:31]
	global_load_dwordx4 v[18:21], v[50:51], off
	global_load_dwordx4 v[22:25], v[54:55], off
	v_add_co_u32_e32 v58, vcc, 0x2000, v26
	v_lshl_add_u64 v[30:31], v[30:31], 0, s[70:71]
	s_nop 0
	v_addc_co_u32_e32 v59, vcc, 0, v27, vcc
	v_lshl_add_u64 v[30:31], v[30:31], 0, v[82:83]
	global_load_dwordx4 v[26:29], v[58:59], off
	v_add_co_u32_e32 v62, vcc, 0x2000, v30
	v_or_b32_e32 v75, 2, v67
	s_nop 0
	v_addc_co_u32_e32 v63, vcc, 0, v31, vcc
	global_load_dwordx4 v[30:33], v[62:63], off
	s_nop 0
	global_load_dwordx4 v[34:37], v[34:35], off offset:2048
	s_nop 0
	global_load_dwordx4 v[38:41], v[38:39], off offset:2048
	s_nop 0
	global_load_dwordx4 v[42:45], v[42:43], off offset:2048
	s_nop 0
	global_load_dwordx4 v[46:49], v[46:47], off offset:2048
	s_nop 0
	global_load_dwordx4 v[50:53], v[50:51], off offset:2048
	s_nop 0
	global_load_dwordx4 v[54:57], v[54:55], off offset:2048
	s_nop 0
	global_load_dwordx4 v[58:61], v[58:59], off offset:2048
	s_nop 0
	global_load_dwordx4 v[62:65], v[62:63], off offset:2048
	v_cmp_ge_i32_e32 vcc, v67, v120
	v_add_u32_e32 v80, 17, v67
	s_waitcnt vmcnt(15)
	ds_write_b128 v121, v[2:5]
	s_waitcnt vmcnt(14)
	ds_write_b128 v121, v[6:9] offset:1088
	s_waitcnt vmcnt(13)
	ds_write_b128 v121, v[10:13] offset:2176
	s_waitcnt vmcnt(12)
	ds_write_b128 v121, v[14:17] offset:3264
	s_waitcnt vmcnt(11)
	ds_write_b128 v121, v[18:21] offset:4352
	s_waitcnt vmcnt(10)
	ds_write_b128 v121, v[22:25] offset:5440
	s_waitcnt vmcnt(9)
	ds_write_b128 v121, v[26:29] offset:6528
	s_waitcnt vmcnt(8)
	ds_write_b128 v121, v[30:33] offset:7616
	s_waitcnt lgkmcnt(0)
	ds_read_b128 v[2:5], v122
	ds_read_b128 v[18:21], v122 offset:32
	ds_read_b128 v[22:25], v122 offset:64
	ds_read_b128 v[26:29], v122 offset:96
	ds_read_b128 v[30:33], v122 offset:128
	ds_read_b128 v[76:79], v122 offset:160
	ds_read_b128 v[124:127], v122 offset:192
	ds_read_b128 v[128:131], v122 offset:224
	s_waitcnt lgkmcnt(7)
	v_mfma_f32_32x32x16_bf16 v[2:17], v[2:5], v[84:87], 0
	v_add_u32_e32 v81, 18, v67
	s_mov_b32 s8, 0xff800000
	v_add_u32_e32 v139, 19, v67
	v_add_u32_e32 v140, 25, v67
	v_add_u32_e32 v141, 26, v67
	v_add_u32_e32 v142, 27, v67
	s_waitcnt vmcnt(7)
	ds_write_b128 v121, v[34:37]
	s_waitcnt vmcnt(6)
	ds_write_b128 v121, v[38:41] offset:1088
	s_waitcnt vmcnt(5)
	ds_write_b128 v121, v[42:45] offset:2176
	s_waitcnt vmcnt(4)
	ds_write_b128 v121, v[46:49] offset:3264
	s_waitcnt vmcnt(3)
	ds_write_b128 v121, v[50:53] offset:4352
	s_waitcnt vmcnt(2)
	ds_write_b128 v121, v[54:57] offset:5440
	s_waitcnt vmcnt(1)
	ds_write_b128 v121, v[58:61] offset:6528
	s_waitcnt vmcnt(0)
	ds_write_b128 v121, v[62:65] offset:7616
	s_waitcnt lgkmcnt(14)
	v_mfma_f32_32x32x16_bf16 v[2:17], v[18:21], v[88:91], v[2:17]
	s_nop 6
	v_or_b32_e32 v18, 1, v67
	v_and_b32_e32 v20, 64, v249
	v_xor_b32_e32 v19, 32, v249
	v_add_u32_e32 v20, 64, v20
	s_waitcnt lgkmcnt(0)
	v_lshl_add_u32 v138, v74, 1, s93
	v_add_u32_e32 v123, v138, v70
	s_waitcnt lgkmcnt(13)
	v_mfma_f32_32x32x16_bf16 v[2:17], v[22:25], v[92:95], v[2:17]
	v_add_u32_e32 v152, 0x80, v138
	v_add_u32_e32 v132, v152, v71
	v_add_u32_e32 v133, v152, v72
	s_waitcnt lgkmcnt(12)
	v_mfma_f32_32x32x16_bf16 v[2:17], v[26:29], v[96:99], v[2:17]
	s_waitcnt lgkmcnt(11)
	v_mfma_f32_32x32x16_bf16 v[2:17], v[30:33], v[100:103], v[2:17]
	s_waitcnt lgkmcnt(10)
	v_mfma_f32_32x32x16_bf16 v[2:17], v[76:79], v[104:107], v[2:17]
	s_nop 6
	v_or_b32_e32 v76, 3, v67
	v_add_u32_e32 v77, 9, v67
	v_add_u32_e32 v78, 10, v67
	v_add_u32_e32 v79, 11, v67
	s_waitcnt lgkmcnt(9)
	v_mfma_f32_32x32x16_bf16 v[2:17], v[124:127], v[108:111], v[2:17]
	s_nop 6
	v_add_u32_e32 v124, v138, v71
	v_add_u32_e32 v125, v138, v72
	v_add_u32_e32 v126, v138, v73
	s_waitcnt lgkmcnt(8)
	v_mfma_f32_32x32x16_bf16 v[2:17], v[128:131], v[112:115], v[2:17]
	s_nop 6
	v_add_u32_e32 v131, v152, v70
	s_nop 10
	v_cndmask_b32_e32 v2, v228, v2, vcc
	v_cmp_ge_i32_e32 vcc, v18, v120
	s_nop 1
	v_cndmask_b32_e32 v3, v228, v3, vcc
	v_cmp_ge_i32_e32 vcc, v75, v120
	v_max3_f32 v18, v2, s8, v3
	s_mov_b32 s8, 0xf149f2ca
	v_cndmask_b32_e32 v4, v228, v4, vcc
	v_cmp_ge_i32_e32 vcc, v76, v120
	s_nop 1
	v_cndmask_b32_e32 v5, v228, v5, vcc
	v_cmp_ge_i32_e32 vcc, v66, v120
	v_max3_f32 v18, v18, v4, v5
	s_nop 0
	v_cndmask_b32_e32 v6, v228, v6, vcc
	v_cmp_ge_i32_e32 vcc, v77, v120
	s_nop 1
	v_cndmask_b32_e32 v7, v228, v7, vcc
	v_cmp_ge_i32_e32 vcc, v78, v120
	v_max3_f32 v18, v18, v6, v7
	s_nop 0
	v_cndmask_b32_e32 v8, v228, v8, vcc
	v_cmp_ge_i32_e32 vcc, v79, v120
	s_nop 1
	v_cndmask_b32_e32 v9, v228, v9, vcc
	v_cmp_ge_i32_e32 vcc, v69, v120
	v_max3_f32 v18, v18, v8, v9
	s_nop 0
	v_cndmask_b32_e32 v10, v228, v10, vcc
	v_cmp_ge_i32_e32 vcc, v80, v120
	s_nop 1
	v_cndmask_b32_e32 v11, v228, v11, vcc
	v_cmp_ge_i32_e32 vcc, v81, v120
	v_max3_f32 v18, v18, v10, v11
	s_nop 0
	v_cndmask_b32_e32 v12, v228, v12, vcc
	v_cmp_ge_i32_e32 vcc, v139, v120
	s_nop 1
	v_cndmask_b32_e32 v13, v228, v13, vcc
	v_cmp_ge_i32_e32 vcc, v68, v120
	v_max3_f32 v18, v18, v12, v13
	s_nop 0
	v_cndmask_b32_e32 v14, v228, v14, vcc
	v_cmp_ge_i32_e32 vcc, v140, v120
	s_nop 1
	v_cndmask_b32_e32 v15, v228, v15, vcc
	v_cmp_ge_i32_e32 vcc, v141, v120
	v_max3_f32 v18, v18, v14, v15
	s_nop 0
	v_cndmask_b32_e32 v16, v228, v16, vcc
	v_cmp_ge_i32_e32 vcc, v142, v120
	s_nop 1
	v_cndmask_b32_e32 v17, v228, v17, vcc
	v_cmp_lt_i32_e32 vcc, v19, v20
	v_max3_f32 v18, v18, v16, v17
	s_nop 0
	v_cndmask_b32_e32 v19, v249, v19, vcc
	v_lshlrev_b32_e32 v19, 2, v19
	ds_bpermute_b32 v20, v19, v18
	s_waitcnt lgkmcnt(0)
	v_max3_f32 v116, v18, v20, s8
	v_sub_f32_e32 v2, v2, v116
	v_exp_f32_e32 v20, v2
	v_sub_f32_e32 v3, v3, v116
	v_exp_f32_e32 v21, v3
	v_sub_f32_e32 v3, v4, v116
	v_exp_f32_e32 v22, v3
	v_sub_f32_e32 v3, v5, v116
	v_exp_f32_e32 v23, v3
	v_sub_f32_e32 v3, v6, v116
	v_add_f32_e32 v2, 0, v20
	v_exp_f32_e32 v24, v3
	v_sub_f32_e32 v3, v7, v116
	v_add_f32_e32 v2, v21, v2
	v_exp_f32_e32 v25, v3
	v_sub_f32_e32 v3, v8, v116
	v_add_f32_e32 v2, v22, v2
	v_exp_f32_e32 v26, v3
	v_sub_f32_e32 v3, v9, v116
	v_add_f32_e32 v2, v23, v2
	v_exp_f32_e32 v27, v3
	v_sub_f32_e32 v3, v10, v116
	v_add_f32_e32 v2, v24, v2
	v_exp_f32_e32 v28, v3
	v_sub_f32_e32 v3, v11, v116
	v_add_f32_e32 v2, v25, v2
	v_exp_f32_e32 v29, v3
	v_sub_f32_e32 v3, v12, v116
	v_add_f32_e32 v2, v26, v2
	v_exp_f32_e32 v30, v3
	v_sub_f32_e32 v3, v13, v116
	v_add_f32_e32 v2, v27, v2
	v_exp_f32_e32 v31, v3
	v_sub_f32_e32 v3, v14, v116
	v_add_f32_e32 v2, v28, v2
	v_exp_f32_e32 v32, v3
	v_sub_f32_e32 v3, v15, v116
	v_add_f32_e32 v2, v29, v2
	v_exp_f32_e32 v33, v3
	v_sub_f32_e32 v3, v16, v116
	v_add_f32_e32 v2, v30, v2
	v_exp_f32_e32 v34, v3
	v_sub_f32_e32 v3, v17, v116
	v_add_f32_e32 v2, v31, v2
	v_exp_f32_e32 v35, v3
	v_add_f32_e32 v2, v32, v2
	v_add_f32_e32 v2, v33, v2
	v_add_f32_e32 v2, v34, v2
	v_sub_f32_e32 v18, 0xf149f2ca, v116
	v_add_f32_e32 v36, v35, v2
	v_exp_f32_e32 v143, v18
	ds_bpermute_b32 v18, v19, v36
	s_waitcnt lgkmcnt(0)
	v_add_f32_e32 v117, v36, v18
	v_cvt_pk_bf16_f32 v147, v26, v27
	v_cvt_pk_bf16_f32 v146, v24, v25
	v_cvt_pk_bf16_f32 v145, v22, v23
	v_mul_f32_e32 v2, 0, v143
	v_cvt_pk_bf16_f32 v144, v20, v21
	v_mov_b32_e32 v3, v2
	v_mov_b32_e32 v4, v2
	v_mov_b32_e32 v5, v2
	v_mov_b32_e32 v6, v2
	v_mov_b32_e32 v7, v2
	v_mov_b32_e32 v8, v2
	v_mov_b32_e32 v9, v2
	v_mov_b32_e32 v10, v2
	v_mov_b32_e32 v11, v2
	v_mov_b32_e32 v12, v2
	v_mov_b32_e32 v13, v2
	v_mov_b32_e32 v14, v2
	v_mov_b32_e32 v15, v2
	v_mov_b32_e32 v16, v2
	v_mov_b32_e32 v17, v2
	v_cvt_pk_bf16_f32 v151, v34, v35
	v_cvt_pk_bf16_f32 v150, v32, v33
	v_cvt_pk_bf16_f32 v149, v30, v31
	v_cvt_pk_bf16_f32 v148, v28, v29
	ds_read_b64_tr_b16 v[18:19], v123
	ds_read_b64_tr_b16 v[20:21], v124
	s_waitcnt lgkmcnt(0)
	v_add_u32_e32 v22, 64, v138
	v_mfma_f32_32x32x16_bf16 v[50:65], v[18:21], v[144:147], v[2:17]
	ds_read_b64_tr_b16 v[18:19], v125
	ds_read_b64_tr_b16 v[20:21], v126
	s_waitcnt lgkmcnt(0)
	v_add_u32_e32 v127, v22, v70
	v_add_u32_e32 v128, v22, v71
	v_add_u32_e32 v129, v22, v72
	v_add_u32_e32 v130, v22, v73
	v_add_u32_e32 v138, 0xc0, v138
	v_fmac_f32_e32 v117, 0, v143
	v_mfma_f32_32x32x16_bf16 v[50:65], v[18:21], v[148:151], v[50:65]
	ds_read_b64_tr_b16 v[18:19], v127
	ds_read_b64_tr_b16 v[20:21], v128
	s_waitcnt lgkmcnt(0)
	s_nop 0
	v_mfma_f32_32x32x16_bf16 v[34:49], v[18:21], v[144:147], v[2:17]
	ds_read_b64_tr_b16 v[18:19], v129
	ds_read_b64_tr_b16 v[20:21], v130
	s_waitcnt lgkmcnt(0)
	ds_read_b64_tr_b16 v[134:135], v131
	ds_read_b64_tr_b16 v[136:137], v132
	s_waitcnt lgkmcnt(0)
	s_nop 0
	v_mfma_f32_32x32x16_bf16 v[34:49], v[18:21], v[148:151], v[34:49]
	v_mfma_f32_32x32x16_bf16 v[18:33], v[134:137], v[144:147], v[2:17]
	s_nop 6
	v_add_u32_e32 v134, v152, v73
	ds_read_b64_tr_b16 v[152:153], v133
	ds_read_b64_tr_b16 v[154:155], v134
	s_waitcnt lgkmcnt(0)
	v_add_u32_e32 v135, v138, v70
	v_add_u32_e32 v136, v138, v71
	v_add_u32_e32 v137, v138, v72
	v_add_u32_e32 v138, v138, v73
	v_mfma_f32_32x32x16_bf16 v[18:33], v[152:155], v[148:151], v[18:33]
	ds_read_b64_tr_b16 v[152:153], v135
	ds_read_b64_tr_b16 v[154:155], v136
	s_waitcnt lgkmcnt(0)
	s_nop 0
	v_mfma_f32_32x32x16_bf16 v[2:17], v[152:155], v[144:147], v[2:17]
	ds_read_b64_tr_b16 v[144:145], v137
	ds_read_b64_tr_b16 v[146:147], v138
	s_waitcnt lgkmcnt(0)
	s_nop 0
	v_mfma_f32_32x32x16_bf16 v[2:17], v[144:147], v[148:151], v[2:17]
	s_cbranch_execz .LBB0_547
	s_branch .LBB0_548

.LBB0_549:
	v_add_u32_e32 v139, s88, v118
	v_add_u32_e32 v66, 0xffffffa0, v139
	v_lshlrev_b32_e32 v66, s84, v66
	v_add_u32_e32 v66, s75, v66
	v_mov_b64_e32 v[152:153], s[62:63]
	v_add_u32_e32 v70, 0xffffffa4, v139
	v_mad_i64_i32 v[66:67], s[64:65], v66, s83, v[152:153]
	s_lshl_b32 s70, s87, 1
	v_lshlrev_b32_e32 v70, s84, v70
	v_lshl_add_u64 v[66:67], v[66:67], 0, s[70:71]
	v_add_u32_e32 v70, s75, v70
	v_add_u32_e32 v74, 0xffffffa8, v139
	v_lshl_add_u64 v[66:67], v[66:67], 0, v[82:83]
	v_mad_i64_i32 v[70:71], s[64:65], v70, s83, v[152:153]
	v_lshlrev_b32_e32 v74, s84, v74
	v_add_co_u32_e32 v156, vcc, 0x2000, v66
	v_lshl_add_u64 v[70:71], v[70:71], 0, s[70:71]
	v_add_u32_e32 v74, s75, v74
	v_add_u32_e32 v78, 0xffffffac, v139
	v_addc_co_u32_e32 v157, vcc, 0, v67, vcc
	v_lshl_add_u64 v[70:71], v[70:71], 0, v[82:83]
	v_mad_i64_i32 v[74:75], s[64:65], v74, s83, v[152:153]
	v_lshlrev_b32_e32 v78, s84, v78
	v_add_co_u32_e32 v160, vcc, 0x2000, v70
	v_lshl_add_u64 v[74:75], v[74:75], 0, s[70:71]
	v_add_u32_e32 v78, s75, v78
	v_add_u32_e32 v140, 0xffffffb0, v139
	v_addc_co_u32_e32 v161, vcc, 0, v71, vcc
	v_lshl_add_u64 v[74:75], v[74:75], 0, v[82:83]
	v_mad_i64_i32 v[78:79], s[64:65], v78, s83, v[152:153]
	v_lshlrev_b32_e32 v140, s84, v140
	v_add_co_u32_e32 v164, vcc, 0x2000, v74
	v_lshl_add_u64 v[78:79], v[78:79], 0, s[70:71]
	v_add_u32_e32 v140, s75, v140
	v_add_u32_e32 v144, 0xffffffb4, v139
	v_addc_co_u32_e32 v165, vcc, 0, v75, vcc
	v_lshl_add_u64 v[78:79], v[78:79], 0, v[82:83]
	v_mad_i64_i32 v[140:141], s[64:65], v140, s83, v[152:153]
	v_lshlrev_b32_e32 v144, s84, v144
	v_add_co_u32_e32 v168, vcc, 0x2000, v78
	v_lshl_add_u64 v[140:141], v[140:141], 0, s[70:71]
	v_add_u32_e32 v144, s75, v144
	v_add_u32_e32 v148, 0xffffffb8, v139
	v_addc_co_u32_e32 v169, vcc, 0, v79, vcc
	v_lshl_add_u64 v[140:141], v[140:141], 0, v[82:83]
	v_mad_i64_i32 v[144:145], s[64:65], v144, s83, v[152:153]
	v_lshlrev_b32_e32 v148, s84, v148
	global_load_dwordx4 v[66:69], v[156:157], off
	global_load_dwordx4 v[70:73], v[160:161], off
	v_add_co_u32_e32 v174, vcc, 0x2000, v140
	v_lshl_add_u64 v[144:145], v[144:145], 0, s[70:71]
	v_add_u32_e32 v148, s75, v148
	v_add_u32_e32 v139, 0xffffffbc, v139
	v_addc_co_u32_e32 v175, vcc, 0, v141, vcc
	v_lshl_add_u64 v[144:145], v[144:145], 0, v[82:83]
	v_mad_i64_i32 v[148:149], s[64:65], v148, s83, v[152:153]
	v_lshlrev_b32_e32 v139, s84, v139
	global_load_dwordx4 v[74:77], v[164:165], off
	global_load_dwordx4 v[78:81], v[168:169], off
	v_add_co_u32_e32 v178, vcc, 0x2000, v144
	v_lshl_add_u64 v[148:149], v[148:149], 0, s[70:71]
	v_add_u32_e32 v139, s75, v139
	v_addc_co_u32_e32 v179, vcc, 0, v145, vcc
	v_lshl_add_u64 v[148:149], v[148:149], 0, v[82:83]
	v_mad_i64_i32 v[152:153], s[64:65], v139, s83, v[152:153]
	global_load_dwordx4 v[140:143], v[174:175], off
	global_load_dwordx4 v[144:147], v[178:179], off
	v_add_co_u32_e32 v182, vcc, 0x2000, v148
	v_lshl_add_u64 v[152:153], v[152:153], 0, s[70:71]
	s_nop 0
	v_addc_co_u32_e32 v183, vcc, 0, v149, vcc
	v_lshl_add_u64 v[152:153], v[152:153], 0, v[82:83]
	global_load_dwordx4 v[148:151], v[182:183], off
	v_add_co_u32_e32 v186, vcc, 0x2000, v152
	s_cmpk_lg_i32 s88, 0x60
	s_nop 0
	v_addc_co_u32_e32 v187, vcc, 0, v153, vcc
	global_load_dwordx4 v[152:155], v[186:187], off
	s_nop 0
	global_load_dwordx4 v[156:159], v[156:157], off offset:2048
	s_nop 0
	global_load_dwordx4 v[160:163], v[160:161], off offset:2048
	s_nop 0
	global_load_dwordx4 v[164:167], v[164:165], off offset:2048
	s_nop 0
	global_load_dwordx4 v[168:171], v[168:169], off offset:2048
	s_nop 0
	global_load_dwordx4 v[174:177], v[174:175], off offset:2048
	s_nop 0
	global_load_dwordx4 v[178:181], v[178:179], off offset:2048
	s_nop 0
	global_load_dwordx4 v[182:185], v[182:183], off offset:2048
	s_nop 0
	global_load_dwordx4 v[186:189], v[186:187], off offset:2048
	s_waitcnt vmcnt(15)
	ds_write_b128 v121, v[66:69]
	s_waitcnt vmcnt(14)
	ds_write_b128 v121, v[70:73] offset:1088
	s_waitcnt vmcnt(13)
	ds_write_b128 v121, v[74:77] offset:2176
	s_waitcnt vmcnt(12)
	ds_write_b128 v121, v[78:81] offset:3264
	s_waitcnt vmcnt(11)
	ds_write_b128 v121, v[140:143] offset:4352
	s_waitcnt vmcnt(10)
	ds_write_b128 v121, v[144:147] offset:5440
	s_waitcnt vmcnt(9)
	ds_write_b128 v121, v[148:151] offset:6528
	s_waitcnt vmcnt(8)
	ds_write_b128 v121, v[152:155] offset:7616
	s_waitcnt lgkmcnt(0)
	ds_read_b128 v[66:69], v122
	ds_read_b128 v[140:143], v122 offset:32
	s_waitcnt lgkmcnt(1)
	v_mfma_f32_32x32x16_bf16 v[66:81], v[66:69], v[84:87], 0
	s_cselect_b64 s[64:65], -1, 0
	s_or_b64 vcc, s[8:9], s[64:65]
	s_mov_b32 s70, 0xff800000
	s_waitcnt lgkmcnt(0)
	v_mfma_f32_32x32x16_bf16 v[66:81], v[140:143], v[88:91], v[66:81]
	ds_read_b128 v[140:143], v122 offset:64
	ds_read_b128 v[144:147], v122 offset:96
	s_waitcnt lgkmcnt(1)
	v_mfma_f32_32x32x16_bf16 v[66:81], v[140:143], v[92:95], v[66:81]
	s_waitcnt lgkmcnt(0)
	v_mfma_f32_32x32x16_bf16 v[66:81], v[144:147], v[96:99], v[66:81]
	ds_read_b128 v[140:143], v122 offset:128
	ds_read_b128 v[144:147], v122 offset:160
	s_waitcnt lgkmcnt(1)
	v_mfma_f32_32x32x16_bf16 v[66:81], v[140:143], v[100:103], v[66:81]
	s_waitcnt lgkmcnt(0)
	v_mfma_f32_32x32x16_bf16 v[66:81], v[144:147], v[104:107], v[66:81]
	ds_read_b128 v[140:143], v122 offset:192
	ds_read_b128 v[144:147], v122 offset:224
	s_waitcnt vmcnt(7)
	ds_write_b128 v121, v[156:159]
	s_waitcnt vmcnt(6)
	ds_write_b128 v121, v[160:163] offset:1088
	s_waitcnt vmcnt(5)
	ds_write_b128 v121, v[164:167] offset:2176
	s_waitcnt vmcnt(4)
	ds_write_b128 v121, v[168:171] offset:3264
	s_waitcnt vmcnt(3)
	ds_write_b128 v121, v[174:177] offset:4352
	s_waitcnt vmcnt(2)
	ds_write_b128 v121, v[178:181] offset:5440
	s_waitcnt vmcnt(1)
	ds_write_b128 v121, v[182:185] offset:6528
	s_waitcnt vmcnt(0)
	ds_write_b128 v121, v[186:189] offset:7616
	s_waitcnt lgkmcnt(0)
	s_waitcnt lgkmcnt(9)
	v_mfma_f32_32x32x16_bf16 v[66:81], v[140:143], v[108:111], v[66:81]
	s_nop 6
	v_and_b32_e32 v141, 64, v249
	v_xor_b32_e32 v140, 32, v249
	v_add_u32_e32 v141, 64, v141
	s_waitcnt lgkmcnt(8)
	v_mfma_f32_32x32x16_bf16 v[66:81], v[144:147], v[112:115], v[66:81]
	s_nop 11
	v_cndmask_b32_e32 v139, v228, v66, vcc
	s_or_b64 vcc, s[10:11], s[64:65]
	v_cndmask_b32_e32 v67, v228, v67, vcc
	s_or_b64 vcc, s[12:13], s[64:65]
	v_cndmask_b32_e32 v68, v228, v68, vcc
	s_or_b64 vcc, s[14:15], s[64:65]
	v_cndmask_b32_e32 v69, v228, v69, vcc
	s_or_b64 vcc, s[16:17], s[64:65]
	v_cndmask_b32_e32 v70, v228, v70, vcc
	s_or_b64 vcc, s[18:19], s[64:65]
	v_cndmask_b32_e32 v71, v228, v71, vcc
	s_or_b64 vcc, s[20:21], s[64:65]
	v_cndmask_b32_e32 v72, v228, v72, vcc
	s_or_b64 vcc, s[22:23], s[64:65]
	v_cndmask_b32_e32 v73, v228, v73, vcc
	s_or_b64 vcc, s[24:25], s[64:65]
	v_cndmask_b32_e32 v74, v228, v74, vcc
	s_or_b64 vcc, s[26:27], s[64:65]
	v_cndmask_b32_e32 v75, v228, v75, vcc
	s_or_b64 vcc, s[28:29], s[64:65]
	v_cndmask_b32_e32 v76, v228, v76, vcc
	s_or_b64 vcc, s[30:31], s[64:65]
	v_max3_f32 v66, v139, s70, v67
	v_cndmask_b32_e32 v77, v228, v77, vcc
	s_or_b64 vcc, s[34:35], s[64:65]
	v_max3_f32 v66, v66, v68, v69
	v_cndmask_b32_e32 v78, v228, v78, vcc
	s_or_b64 vcc, s[36:37], s[64:65]
	v_max3_f32 v66, v66, v70, v71
	v_cndmask_b32_e32 v79, v228, v79, vcc
	v_max3_f32 v66, v66, v72, v73
	s_or_b64 vcc, s[38:39], s[64:65]
	v_max3_f32 v66, v66, v74, v75
	v_cndmask_b32_e32 v80, v228, v80, vcc
	s_or_b64 vcc, s[40:41], s[64:65]
	v_max3_f32 v66, v66, v76, v77
	v_cndmask_b32_e32 v81, v228, v81, vcc
	v_cmp_lt_i32_e32 vcc, v140, v141
	v_max3_f32 v66, v66, v78, v79
	v_max3_f32 v66, v66, v80, v81
	v_cndmask_b32_e32 v140, v249, v140, vcc
	v_lshlrev_b32_e32 v140, 2, v140
	ds_bpermute_b32 v141, v140, v66
	s_waitcnt lgkmcnt(0)
	v_max3_f32 v66, v116, v66, v141
	v_sub_f32_e32 v139, v139, v66
	v_exp_f32_e32 v139, v139
	v_sub_f32_e32 v67, v67, v66
	v_exp_f32_e32 v67, v67
	v_sub_f32_e32 v68, v68, v66
	v_exp_f32_e32 v142, v68
	v_sub_f32_e32 v68, v69, v66
	v_exp_f32_e32 v69, v68
	v_sub_f32_e32 v68, v70, v66
	v_add_f32_e32 v141, 0, v139
	v_exp_f32_e32 v70, v68
	v_sub_f32_e32 v71, v71, v66
	v_add_f32_e32 v68, v67, v141
	v_exp_f32_e32 v71, v71
	v_sub_f32_e32 v72, v72, v66
	v_add_f32_e32 v68, v142, v68
	v_exp_f32_e32 v72, v72
	v_sub_f32_e32 v73, v73, v66
	v_add_f32_e32 v68, v69, v68
	v_exp_f32_e32 v73, v73
	v_sub_f32_e32 v74, v74, v66
	v_add_f32_e32 v68, v70, v68
	v_exp_f32_e32 v74, v74
	v_sub_f32_e32 v75, v75, v66
	v_add_f32_e32 v68, v71, v68
	v_exp_f32_e32 v75, v75
	v_sub_f32_e32 v76, v76, v66
	v_add_f32_e32 v68, v72, v68
	v_exp_f32_e32 v76, v76
	v_sub_f32_e32 v77, v77, v66
	v_add_f32_e32 v68, v73, v68
	v_exp_f32_e32 v77, v77
	v_sub_f32_e32 v78, v78, v66
	v_add_f32_e32 v68, v74, v68
	v_exp_f32_e32 v78, v78
	v_add_f32_e32 v68, v75, v68
	v_add_f32_e32 v68, v76, v68
	v_add_f32_e32 v68, v77, v68
	v_add_f32_e32 v141, v78, v68
	v_sub_f32_e32 v68, v79, v66
	v_exp_f32_e32 v79, v68
	v_sub_f32_e32 v68, v80, v66
	v_sub_f32_e32 v116, v116, v66
	v_exp_f32_e32 v80, v68
	v_sub_f32_e32 v68, v81, v66
	v_exp_f32_e32 v81, v68
	v_exp_f32_e32 v68, v116
	v_add_f32_e32 v116, v79, v141
	v_pk_mul_f32 v[64:65], v[64:65], v[68:69] op_sel_hi:[1,0]
	v_pk_mul_f32 v[62:63], v[62:63], v[68:69] op_sel_hi:[1,0]
	v_pk_mul_f32 v[60:61], v[60:61], v[68:69] op_sel_hi:[1,0]
	v_pk_mul_f32 v[58:59], v[58:59], v[68:69] op_sel_hi:[1,0]
	v_pk_mul_f32 v[56:57], v[56:57], v[68:69] op_sel_hi:[1,0]
	v_pk_mul_f32 v[54:55], v[54:55], v[68:69] op_sel_hi:[1,0]
	v_pk_mul_f32 v[52:53], v[52:53], v[68:69] op_sel_hi:[1,0]
	v_pk_mul_f32 v[50:51], v[50:51], v[68:69] op_sel_hi:[1,0]
	v_pk_mul_f32 v[48:49], v[48:49], v[68:69] op_sel_hi:[1,0]
	v_pk_mul_f32 v[46:47], v[46:47], v[68:69] op_sel_hi:[1,0]
	v_pk_mul_f32 v[44:45], v[44:45], v[68:69] op_sel_hi:[1,0]
	v_pk_mul_f32 v[42:43], v[42:43], v[68:69] op_sel_hi:[1,0]
	v_pk_mul_f32 v[40:41], v[40:41], v[68:69] op_sel_hi:[1,0]
	v_pk_mul_f32 v[38:39], v[38:39], v[68:69] op_sel_hi:[1,0]
	v_pk_mul_f32 v[36:37], v[36:37], v[68:69] op_sel_hi:[1,0]
	v_pk_mul_f32 v[34:35], v[34:35], v[68:69] op_sel_hi:[1,0]
	v_pk_mul_f32 v[32:33], v[32:33], v[68:69] op_sel_hi:[1,0]
	v_add_f32_e32 v116, v80, v116
	v_cvt_pk_bf16_f32 v73, v72, v73
	v_cvt_pk_bf16_f32 v72, v70, v71
	v_cvt_pk_bf16_f32 v71, v142, v69
	v_cvt_pk_bf16_f32 v70, v139, v67
	v_bfe_u32 v67, v81, 16, 1
	v_bfe_u32 v69, v79, 16, 1
	v_bfe_u32 v139, v77, 16, 1
	v_bfe_u32 v141, v75, 16, 1
	v_add_f32_e32 v116, v81, v116
	v_add3_u32 v141, v75, v141, s73
	v_add3_u32 v75, v77, v139, s73
	v_add3_u32 v69, v79, v69, s73
	v_add3_u32 v67, v81, v67, s73
	v_bfe_u32 v79, v76, 16, 1
	v_bfe_u32 v81, v78, 16, 1
	v_bfe_u32 v139, v80, 16, 1
	v_bfe_u32 v77, v74, 16, 1
	v_add3_u32 v80, v80, v139, s73
	v_add3_u32 v78, v78, v81, s73
	v_add3_u32 v76, v76, v79, s73
	v_add3_u32 v74, v74, v77, s73
	v_lshrrev_b32_e32 v139, 16, v76
	v_lshrrev_b32_e32 v76, 16, v78
	v_lshrrev_b32_e32 v77, 16, v80
	ds_read_b64_tr_b16 v[78:79], v123
	ds_read_b64_tr_b16 v[80:81], v124
	s_waitcnt lgkmcnt(0)
	v_lshrrev_b32_e32 v74, 16, v74
	v_mfma_f32_32x32x16_bf16 v[50:65], v[78:81], v[70:73], v[50:65]
	v_and_or_b32 v77, v67, s33, v77
	v_and_or_b32 v76, v69, s33, v76
	v_and_or_b32 v75, v75, s33, v139
	v_and_or_b32 v74, v141, s33, v74
	ds_read_b64_tr_b16 v[78:79], v125
	ds_read_b64_tr_b16 v[80:81], v126
	s_waitcnt lgkmcnt(0)
	v_mul_f32_e64 v30, v30, v68
	v_mul_f32_e64 v31, v31, v68
	v_pk_mul_f32 v[28:29], v[28:29], v[68:69] op_sel_hi:[1,0]
	v_mfma_f32_32x32x16_bf16 v[50:65], v[78:81], v[74:77], v[50:65]
	ds_read_b64_tr_b16 v[78:79], v127
	ds_read_b64_tr_b16 v[80:81], v128
	s_waitcnt lgkmcnt(0)
	v_mul_f32_e64 v26, v26, v68
	v_mul_f32_e64 v27, v27, v68
	v_mul_f32_e64 v24, v24, v68
	v_mul_f32_e64 v25, v25, v68
	v_mul_f32_e64 v22, v22, v68
	v_mul_f32_e64 v23, v23, v68
	v_pk_mul_f32 v[20:21], v[20:21], v[68:69] op_sel_hi:[1,0]
	v_pk_mul_f32 v[18:19], v[18:19], v[68:69] op_sel_hi:[1,0]
	v_pk_mul_f32 v[16:17], v[16:17], v[68:69] op_sel_hi:[1,0]
	v_mfma_f32_32x32x16_bf16 v[34:49], v[78:81], v[70:73], v[34:49]
	ds_read_b64_tr_b16 v[78:79], v129
	ds_read_b64_tr_b16 v[80:81], v130
	s_waitcnt lgkmcnt(0)
	v_mul_f32_e64 v14, v14, v68
	v_mul_f32_e64 v15, v15, v68
	v_mul_f32_e64 v12, v12, v68
	v_mul_f32_e64 v13, v13, v68
	v_mul_f32_e64 v10, v10, v68
	v_mul_f32_e64 v11, v11, v68
	v_pk_mul_f32 v[8:9], v[8:9], v[68:69] op_sel_hi:[1,0]
	v_pk_mul_f32 v[6:7], v[6:7], v[68:69] op_sel_hi:[1,0]
	v_pk_mul_f32 v[4:5], v[4:5], v[68:69] op_sel_hi:[1,0]
	v_mfma_f32_32x32x16_bf16 v[34:49], v[78:81], v[74:77], v[34:49]
	ds_read_b64_tr_b16 v[78:79], v131
	ds_read_b64_tr_b16 v[80:81], v132
	s_waitcnt lgkmcnt(0)
	v_mul_f32_e64 v2, v2, v68
	v_mul_f32_e64 v3, v3, v68
	ds_bpermute_b32 v67, v140, v116
	s_waitcnt lgkmcnt(0)
	v_add_f32_e32 v67, v116, v67
	v_mfma_f32_32x32x16_bf16 v[18:33], v[78:81], v[70:73], v[18:33]
	ds_read_b64_tr_b16 v[78:79], v133
	ds_read_b64_tr_b16 v[80:81], v134
	s_waitcnt lgkmcnt(0)
	v_fmac_f32_e32 v67, v117, v68
	v_mov_b32_e32 v116, v66
	v_mov_b32_e32 v117, v67
	v_mfma_f32_32x32x16_bf16 v[18:33], v[78:81], v[74:77], v[18:33]
	ds_read_b64_tr_b16 v[78:79], v135
	ds_read_b64_tr_b16 v[80:81], v136
	s_waitcnt lgkmcnt(0)
	s_nop 0
	v_mfma_f32_32x32x16_bf16 v[2:17], v[78:81], v[70:73], v[2:17]
	ds_read_b64_tr_b16 v[70:71], v137
	ds_read_b64_tr_b16 v[72:73], v138
	s_waitcnt lgkmcnt(0)
	s_nop 0
	v_mfma_f32_32x32x16_bf16 v[2:17], v[70:73], v[74:77], v[2:17]
	s_add_i32 s88, s88, 32
	s_cmpk_eq_i32 s88, 0x80
	s_cbranch_scc1 .LBB0_552

.LBB0_552:
	v_or_b32_e32 v68, s85, v120
	v_lshlrev_b32_e32 v69, s84, v68
	v_div_scale_f32 v68, s[8:9], v117, v117, 1.0
	v_rcp_f32_e32 v70, v68
	s_lshl_b32 s8, s72, 13
	s_add_i32 s75, s75, s8
	v_add_u32_e32 v82, s75, v69
	v_fma_f32 v71, -v68, v70, 1.0
	v_fmac_f32_e32 v70, v71, v70
	v_div_scale_f32 v71, vcc, 1.0, v117, 1.0
	v_mul_f32_e32 v72, v71, v70
	v_fma_f32 v73, -v68, v72, v71
	v_fmac_f32_e32 v72, v73, v70
	v_fma_f32 v68, -v68, v72, v71
	v_div_fmas_f32 v68, v68, v70, v72
	v_div_fixup_f32 v68, v68, v117, 1.0
	v_lshlrev_b64 v[70:71], 11, v[82:83]
	v_lshl_add_u64 v[70:71], s[80:81], 0, v[70:71]
	s_lshl_b32 s70, s87, 1
	v_pk_mul_f32 v[50:51], v[50:51], v[68:69] op_sel_hi:[1,0]
	v_lshl_add_u64 v[74:75], v[70:71], 0, s[70:71]
	v_and_b32_sdwa v70, v50, v247 dst_sel:DWORD dst_unused:UNUSED_PAD src0_sel:WORD_1 src1_sel:DWORD
	v_and_b32_sdwa v69, v51, v247 dst_sel:DWORD dst_unused:UNUSED_PAD src0_sel:WORD_1 src1_sel:DWORD
	v_add3_u32 v50, v50, v70, s73
	v_add3_u32 v51, v51, v69, s73
	v_lshrrev_b32_e32 v50, 16, v50
	v_and_or_b32 v70, v51, s33, v50
	v_pk_mul_f32 v[50:51], v[52:53], v[68:69] op_sel_hi:[1,0]
	v_lshlrev_b32_e32 v76, 3, v119
	v_and_b32_sdwa v53, v50, v247 dst_sel:DWORD dst_unused:UNUSED_PAD src0_sel:WORD_1 src1_sel:DWORD
	v_and_b32_sdwa v52, v51, v247 dst_sel:DWORD dst_unused:UNUSED_PAD src0_sel:WORD_1 src1_sel:DWORD
	v_add3_u32 v50, v50, v53, s73
	v_add3_u32 v51, v51, v52, s73
	v_lshrrev_b32_e32 v50, 16, v50
	v_and_or_b32 v71, v51, s33, v50
	v_pk_mul_f32 v[50:51], v[54:55], v[68:69] op_sel_hi:[1,0]
	v_ashrrev_i32_e32 v77, 31, v76
	v_and_b32_sdwa v53, v50, v247 dst_sel:DWORD dst_unused:UNUSED_PAD src0_sel:WORD_1 src1_sel:DWORD
	v_and_b32_sdwa v52, v51, v247 dst_sel:DWORD dst_unused:UNUSED_PAD src0_sel:WORD_1 src1_sel:DWORD
	v_add3_u32 v50, v50, v53, s73
	v_add3_u32 v51, v51, v52, s73
	v_lshrrev_b32_e32 v50, 16, v50
	v_and_or_b32 v72, v51, s33, v50
	v_pk_mul_f32 v[50:51], v[56:57], v[68:69] op_sel_hi:[1,0]
	s_mov_b64 s[8:9], 0x1869e000
	v_and_b32_sdwa v53, v50, v247 dst_sel:DWORD dst_unused:UNUSED_PAD src0_sel:WORD_1 src1_sel:DWORD
	v_and_b32_sdwa v52, v51, v247 dst_sel:DWORD dst_unused:UNUSED_PAD src0_sel:WORD_1 src1_sel:DWORD
	v_add3_u32 v50, v50, v53, s73
	v_add3_u32 v51, v51, v52, s73
	v_lshrrev_b32_e32 v50, 16, v50
	v_lshl_add_u64 v[52:53], v[76:77], 1, v[74:75]
	v_and_or_b32 v73, v51, s33, v50
	v_lshl_add_u64 v[50:51], v[52:53], 0, s[8:9]
	s_mov_b32 s8, 0x1869e000
	v_add_co_u32_e32 v52, vcc, s8, v52
	v_permlane32_swap_b32_e32 v70, v72
	v_permlane32_swap_b32_e32 v71, v73
	v_addc_co_u32_e32 v53, vcc, 0, v53, vcc
	global_store_dwordx4 v[52:53], v[70:73], off
	s_nop 1
	v_pk_mul_f32 v[52:53], v[58:59], v[68:69] op_sel_hi:[1,0]
	v_pk_mul_f32 v[34:35], v[34:35], v[68:69] op_sel_hi:[1,0]
	v_and_b32_sdwa v54, v53, v247 dst_sel:DWORD dst_unused:UNUSED_PAD src0_sel:WORD_1 src1_sel:DWORD
	v_and_b32_sdwa v55, v52, v247 dst_sel:DWORD dst_unused:UNUSED_PAD src0_sel:WORD_1 src1_sel:DWORD
	v_add3_u32 v53, v53, v54, s73
	v_add3_u32 v52, v52, v55, s73
	v_pk_mul_f32 v[54:55], v[60:61], v[68:69] op_sel_hi:[1,0]
	v_lshrrev_b32_e32 v52, 16, v52
	v_and_b32_sdwa v56, v54, v247 dst_sel:DWORD dst_unused:UNUSED_PAD src0_sel:WORD_1 src1_sel:DWORD
	v_and_or_b32 v52, v53, s33, v52
	v_and_b32_sdwa v53, v55, v247 dst_sel:DWORD dst_unused:UNUSED_PAD src0_sel:WORD_1 src1_sel:DWORD
	v_add3_u32 v54, v54, v56, s73
	v_add3_u32 v53, v55, v53, s73
	v_lshrrev_b32_e32 v54, 16, v54
	v_and_or_b32 v53, v53, s33, v54
	v_pk_mul_f32 v[54:55], v[62:63], v[68:69] op_sel_hi:[1,0]
	v_pk_mul_f32 v[36:37], v[36:37], v[68:69] op_sel_hi:[1,0]
	v_and_b32_sdwa v56, v55, v247 dst_sel:DWORD dst_unused:UNUSED_PAD src0_sel:WORD_1 src1_sel:DWORD
	v_and_b32_sdwa v57, v54, v247 dst_sel:DWORD dst_unused:UNUSED_PAD src0_sel:WORD_1 src1_sel:DWORD
	v_add3_u32 v55, v55, v56, s73
	v_add3_u32 v54, v54, v57, s73
	v_pk_mul_f32 v[56:57], v[64:65], v[68:69] op_sel_hi:[1,0]
	v_lshrrev_b32_e32 v54, 16, v54
	v_and_b32_sdwa v58, v56, v247 dst_sel:DWORD dst_unused:UNUSED_PAD src0_sel:WORD_1 src1_sel:DWORD
	v_and_or_b32 v54, v55, s33, v54
	v_and_b32_sdwa v55, v57, v247 dst_sel:DWORD dst_unused:UNUSED_PAD src0_sel:WORD_1 src1_sel:DWORD
	v_add3_u32 v56, v56, v58, s73
	v_add3_u32 v55, v57, v55, s73
	v_lshrrev_b32_e32 v56, 16, v56
	v_and_or_b32 v55, v55, s33, v56
	v_permlane32_swap_b32_e32 v52, v54
	s_nop 0
	v_permlane32_swap_b32_e32 v53, v55
	global_store_dwordx4 v[50:51], v[52:55], off offset:32
	v_pk_mul_f32 v[18:19], v[18:19], v[68:69] op_sel_hi:[1,0]
	v_pk_mul_f32 v[20:21], v[20:21], v[68:69] op_sel_hi:[1,0]
	v_and_b32_sdwa v53, v34, v247 dst_sel:DWORD dst_unused:UNUSED_PAD src0_sel:WORD_1 src1_sel:DWORD
	v_and_b32_sdwa v52, v35, v247 dst_sel:DWORD dst_unused:UNUSED_PAD src0_sel:WORD_1 src1_sel:DWORD
	v_add3_u32 v34, v34, v53, s73
	v_add3_u32 v35, v35, v52, s73
	v_lshrrev_b32_e32 v34, 16, v34
	v_and_b32_sdwa v52, v36, v247 dst_sel:DWORD dst_unused:UNUSED_PAD src0_sel:WORD_1 src1_sel:DWORD
	v_and_or_b32 v34, v35, s33, v34
	v_and_b32_sdwa v35, v37, v247 dst_sel:DWORD dst_unused:UNUSED_PAD src0_sel:WORD_1 src1_sel:DWORD
	v_add3_u32 v36, v36, v52, s73
	v_add3_u32 v35, v37, v35, s73
	v_lshrrev_b32_e32 v36, 16, v36
	v_and_or_b32 v35, v35, s33, v36
	v_pk_mul_f32 v[36:37], v[38:39], v[68:69] op_sel_hi:[1,0]
	v_pk_mul_f32 v[2:3], v[2:3], v[68:69] op_sel_hi:[1,0]
	v_and_b32_sdwa v38, v37, v247 dst_sel:DWORD dst_unused:UNUSED_PAD src0_sel:WORD_1 src1_sel:DWORD
	v_and_b32_sdwa v39, v36, v247 dst_sel:DWORD dst_unused:UNUSED_PAD src0_sel:WORD_1 src1_sel:DWORD
	v_add3_u32 v37, v37, v38, s73
	v_add3_u32 v36, v36, v39, s73
	v_pk_mul_f32 v[38:39], v[40:41], v[68:69] op_sel_hi:[1,0]
	v_lshrrev_b32_e32 v36, 16, v36
	v_and_b32_sdwa v40, v38, v247 dst_sel:DWORD dst_unused:UNUSED_PAD src0_sel:WORD_1 src1_sel:DWORD
	v_and_or_b32 v36, v37, s33, v36
	v_and_b32_sdwa v37, v39, v247 dst_sel:DWORD dst_unused:UNUSED_PAD src0_sel:WORD_1 src1_sel:DWORD
	v_add3_u32 v38, v38, v40, s73
	v_add3_u32 v37, v39, v37, s73
	v_lshrrev_b32_e32 v38, 16, v38
	v_and_or_b32 v37, v37, s33, v38
	v_permlane32_swap_b32_e32 v34, v36
	s_nop 0
	v_permlane32_swap_b32_e32 v35, v37
	global_store_dwordx4 v[50:51], v[34:37], off offset:64
	v_pk_mul_f32 v[4:5], v[4:5], v[68:69] op_sel_hi:[1,0]
	v_cmp_gt_u32_e32 vcc, 32, v172
	v_pk_mul_f32 v[34:35], v[42:43], v[68:69] op_sel_hi:[1,0]
	s_nop 0
	v_and_b32_sdwa v36, v35, v247 dst_sel:DWORD dst_unused:UNUSED_PAD src0_sel:WORD_1 src1_sel:DWORD
	v_and_b32_sdwa v37, v34, v247 dst_sel:DWORD dst_unused:UNUSED_PAD src0_sel:WORD_1 src1_sel:DWORD
	v_add3_u32 v35, v35, v36, s73
	v_add3_u32 v34, v34, v37, s73
	v_pk_mul_f32 v[36:37], v[44:45], v[68:69] op_sel_hi:[1,0]
	v_lshrrev_b32_e32 v34, 16, v34
	v_and_b32_sdwa v38, v36, v247 dst_sel:DWORD dst_unused:UNUSED_PAD src0_sel:WORD_1 src1_sel:DWORD
	v_and_or_b32 v34, v35, s33, v34
	v_and_b32_sdwa v35, v37, v247 dst_sel:DWORD dst_unused:UNUSED_PAD src0_sel:WORD_1 src1_sel:DWORD
	v_add3_u32 v36, v36, v38, s73
	v_add3_u32 v35, v37, v35, s73
	v_lshrrev_b32_e32 v36, 16, v36
	v_and_or_b32 v35, v35, s33, v36
	v_pk_mul_f32 v[36:37], v[46:47], v[68:69] op_sel_hi:[1,0]
	s_nop 0
	v_and_b32_sdwa v38, v37, v247 dst_sel:DWORD dst_unused:UNUSED_PAD src0_sel:WORD_1 src1_sel:DWORD
	v_and_b32_sdwa v39, v36, v247 dst_sel:DWORD dst_unused:UNUSED_PAD src0_sel:WORD_1 src1_sel:DWORD
	v_add3_u32 v37, v37, v38, s73
	v_add3_u32 v36, v36, v39, s73
	v_pk_mul_f32 v[38:39], v[48:49], v[68:69] op_sel_hi:[1,0]
	v_lshrrev_b32_e32 v36, 16, v36
	v_and_b32_sdwa v40, v38, v247 dst_sel:DWORD dst_unused:UNUSED_PAD src0_sel:WORD_1 src1_sel:DWORD
	v_and_or_b32 v36, v37, s33, v36
	v_and_b32_sdwa v37, v39, v247 dst_sel:DWORD dst_unused:UNUSED_PAD src0_sel:WORD_1 src1_sel:DWORD
	v_add3_u32 v38, v38, v40, s73
	v_add3_u32 v37, v39, v37, s73
	v_lshrrev_b32_e32 v38, 16, v38
	v_and_or_b32 v37, v37, s33, v38
	v_permlane32_swap_b32_e32 v34, v36
	s_nop 0
	v_permlane32_swap_b32_e32 v35, v37
	global_store_dwordx4 v[50:51], v[34:37], off offset:96
	s_nop 1
	v_and_b32_sdwa v35, v18, v247 dst_sel:DWORD dst_unused:UNUSED_PAD src0_sel:WORD_1 src1_sel:DWORD
	v_and_b32_sdwa v34, v19, v247 dst_sel:DWORD dst_unused:UNUSED_PAD src0_sel:WORD_1 src1_sel:DWORD
	v_add3_u32 v18, v18, v35, s73
	v_add3_u32 v19, v19, v34, s73
	v_lshrrev_b32_e32 v18, 16, v18
	v_and_b32_sdwa v34, v20, v247 dst_sel:DWORD dst_unused:UNUSED_PAD src0_sel:WORD_1 src1_sel:DWORD
	v_and_or_b32 v18, v19, s33, v18
	v_and_b32_sdwa v19, v21, v247 dst_sel:DWORD dst_unused:UNUSED_PAD src0_sel:WORD_1 src1_sel:DWORD
	v_add3_u32 v20, v20, v34, s73
	v_add3_u32 v19, v21, v19, s73
	v_lshrrev_b32_e32 v20, 16, v20
	v_and_or_b32 v19, v19, s33, v20
	v_pk_mul_f32 v[20:21], v[22:23], v[68:69] op_sel_hi:[1,0]
	s_nop 0
	v_and_b32_sdwa v22, v21, v247 dst_sel:DWORD dst_unused:UNUSED_PAD src0_sel:WORD_1 src1_sel:DWORD
	v_and_b32_sdwa v23, v20, v247 dst_sel:DWORD dst_unused:UNUSED_PAD src0_sel:WORD_1 src1_sel:DWORD
	v_add3_u32 v21, v21, v22, s73
	v_add3_u32 v20, v20, v23, s73
	v_pk_mul_f32 v[22:23], v[24:25], v[68:69] op_sel_hi:[1,0]
	v_lshrrev_b32_e32 v20, 16, v20
	v_and_b32_sdwa v24, v22, v247 dst_sel:DWORD dst_unused:UNUSED_PAD src0_sel:WORD_1 src1_sel:DWORD
	v_and_or_b32 v20, v21, s33, v20
	v_and_b32_sdwa v21, v23, v247 dst_sel:DWORD dst_unused:UNUSED_PAD src0_sel:WORD_1 src1_sel:DWORD
	v_add3_u32 v22, v22, v24, s73
	v_add3_u32 v21, v23, v21, s73
	v_lshrrev_b32_e32 v22, 16, v22
	v_and_or_b32 v21, v21, s33, v22
	v_permlane32_swap_b32_e32 v18, v20
	s_nop 0
	v_permlane32_swap_b32_e32 v19, v21
	global_store_dwordx4 v[50:51], v[18:21], off offset:128
	s_nop 1
	v_pk_mul_f32 v[18:19], v[26:27], v[68:69] op_sel_hi:[1,0]
	s_nop 0
	v_and_b32_sdwa v20, v19, v247 dst_sel:DWORD dst_unused:UNUSED_PAD src0_sel:WORD_1 src1_sel:DWORD
	v_and_b32_sdwa v21, v18, v247 dst_sel:DWORD dst_unused:UNUSED_PAD src0_sel:WORD_1 src1_sel:DWORD
	v_add3_u32 v19, v19, v20, s73
	v_add3_u32 v18, v18, v21, s73
	v_pk_mul_f32 v[20:21], v[28:29], v[68:69] op_sel_hi:[1,0]
	v_lshrrev_b32_e32 v18, 16, v18
	v_and_b32_sdwa v22, v20, v247 dst_sel:DWORD dst_unused:UNUSED_PAD src0_sel:WORD_1 src1_sel:DWORD
	v_and_or_b32 v18, v19, s33, v18
	v_and_b32_sdwa v19, v21, v247 dst_sel:DWORD dst_unused:UNUSED_PAD src0_sel:WORD_1 src1_sel:DWORD
	v_add3_u32 v20, v20, v22, s73
	v_add3_u32 v19, v21, v19, s73
	v_lshrrev_b32_e32 v20, 16, v20
	v_and_or_b32 v19, v19, s33, v20
	v_pk_mul_f32 v[20:21], v[30:31], v[68:69] op_sel_hi:[1,0]
	s_nop 0
	v_and_b32_sdwa v22, v21, v247 dst_sel:DWORD dst_unused:UNUSED_PAD src0_sel:WORD_1 src1_sel:DWORD
	v_and_b32_sdwa v23, v20, v247 dst_sel:DWORD dst_unused:UNUSED_PAD src0_sel:WORD_1 src1_sel:DWORD
	v_add3_u32 v21, v21, v22, s73
	v_add3_u32 v20, v20, v23, s73
	v_pk_mul_f32 v[22:23], v[32:33], v[68:69] op_sel_hi:[1,0]
	v_lshrrev_b32_e32 v20, 16, v20
	v_and_b32_sdwa v24, v22, v247 dst_sel:DWORD dst_unused:UNUSED_PAD src0_sel:WORD_1 src1_sel:DWORD
	v_and_or_b32 v20, v21, s33, v20
	v_and_b32_sdwa v21, v23, v247 dst_sel:DWORD dst_unused:UNUSED_PAD src0_sel:WORD_1 src1_sel:DWORD
	v_add3_u32 v22, v22, v24, s73
	v_add3_u32 v21, v23, v21, s73
	v_lshrrev_b32_e32 v22, 16, v22
	v_and_or_b32 v21, v21, s33, v22
	v_permlane32_swap_b32_e32 v18, v20
	s_nop 0
	v_permlane32_swap_b32_e32 v19, v21
	global_store_dwordx4 v[50:51], v[18:21], off offset:160
	s_nop 1
	v_and_b32_sdwa v19, v2, v247 dst_sel:DWORD dst_unused:UNUSED_PAD src0_sel:WORD_1 src1_sel:DWORD
	v_and_b32_sdwa v18, v3, v247 dst_sel:DWORD dst_unused:UNUSED_PAD src0_sel:WORD_1 src1_sel:DWORD
	v_add3_u32 v2, v2, v19, s73
	v_add3_u32 v3, v3, v18, s73
	v_lshrrev_b32_e32 v2, 16, v2
	v_and_b32_sdwa v18, v4, v247 dst_sel:DWORD dst_unused:UNUSED_PAD src0_sel:WORD_1 src1_sel:DWORD
	v_and_or_b32 v2, v3, s33, v2
	v_and_b32_sdwa v3, v5, v247 dst_sel:DWORD dst_unused:UNUSED_PAD src0_sel:WORD_1 src1_sel:DWORD
	v_add3_u32 v4, v4, v18, s73
	v_add3_u32 v3, v5, v3, s73
	v_lshrrev_b32_e32 v4, 16, v4
	v_and_or_b32 v3, v3, s33, v4
	v_pk_mul_f32 v[4:5], v[6:7], v[68:69] op_sel_hi:[1,0]
	s_nop 0
	v_and_b32_sdwa v6, v5, v247 dst_sel:DWORD dst_unused:UNUSED_PAD src0_sel:WORD_1 src1_sel:DWORD
	v_and_b32_sdwa v7, v4, v247 dst_sel:DWORD dst_unused:UNUSED_PAD src0_sel:WORD_1 src1_sel:DWORD
	v_add3_u32 v5, v5, v6, s73
	v_add3_u32 v4, v4, v7, s73
	v_pk_mul_f32 v[6:7], v[8:9], v[68:69] op_sel_hi:[1,0]
	v_lshrrev_b32_e32 v4, 16, v4
	v_and_b32_sdwa v8, v6, v247 dst_sel:DWORD dst_unused:UNUSED_PAD src0_sel:WORD_1 src1_sel:DWORD
	v_and_or_b32 v4, v5, s33, v4
	v_and_b32_sdwa v5, v7, v247 dst_sel:DWORD dst_unused:UNUSED_PAD src0_sel:WORD_1 src1_sel:DWORD
	v_add3_u32 v6, v6, v8, s73
	v_add3_u32 v5, v7, v5, s73
	v_lshrrev_b32_e32 v6, 16, v6
	v_and_or_b32 v5, v5, s33, v6
	v_permlane32_swap_b32_e32 v2, v4
	s_nop 0
	v_permlane32_swap_b32_e32 v3, v5
	global_store_dwordx4 v[50:51], v[2:5], off offset:192
	s_nop 1
	v_pk_mul_f32 v[2:3], v[10:11], v[68:69] op_sel_hi:[1,0]
	s_nop 0
	v_and_b32_sdwa v4, v3, v247 dst_sel:DWORD dst_unused:UNUSED_PAD src0_sel:WORD_1 src1_sel:DWORD
	v_and_b32_sdwa v5, v2, v247 dst_sel:DWORD dst_unused:UNUSED_PAD src0_sel:WORD_1 src1_sel:DWORD
	v_add3_u32 v3, v3, v4, s73
	v_add3_u32 v2, v2, v5, s73
	v_pk_mul_f32 v[4:5], v[12:13], v[68:69] op_sel_hi:[1,0]
	v_lshrrev_b32_e32 v2, 16, v2
	v_and_b32_sdwa v6, v4, v247 dst_sel:DWORD dst_unused:UNUSED_PAD src0_sel:WORD_1 src1_sel:DWORD
	v_and_or_b32 v2, v3, s33, v2
	v_and_b32_sdwa v3, v5, v247 dst_sel:DWORD dst_unused:UNUSED_PAD src0_sel:WORD_1 src1_sel:DWORD
	v_add3_u32 v4, v4, v6, s73
	v_add3_u32 v3, v5, v3, s73
	v_lshrrev_b32_e32 v4, 16, v4
	v_and_or_b32 v3, v3, s33, v4
	v_pk_mul_f32 v[4:5], v[14:15], v[68:69] op_sel_hi:[1,0]
	s_nop 0
	v_and_b32_sdwa v6, v5, v247 dst_sel:DWORD dst_unused:UNUSED_PAD src0_sel:WORD_1 src1_sel:DWORD
	v_and_b32_sdwa v7, v4, v247 dst_sel:DWORD dst_unused:UNUSED_PAD src0_sel:WORD_1 src1_sel:DWORD
	v_add3_u32 v5, v5, v6, s73
	v_add3_u32 v4, v4, v7, s73
	v_pk_mul_f32 v[6:7], v[16:17], v[68:69] op_sel_hi:[1,0]
	v_lshrrev_b32_e32 v4, 16, v4
	v_and_b32_sdwa v8, v6, v247 dst_sel:DWORD dst_unused:UNUSED_PAD src0_sel:WORD_1 src1_sel:DWORD
	v_and_or_b32 v4, v5, s33, v4
	v_and_b32_sdwa v5, v7, v247 dst_sel:DWORD dst_unused:UNUSED_PAD src0_sel:WORD_1 src1_sel:DWORD
	v_add3_u32 v6, v6, v8, s73
	v_add3_u32 v5, v7, v5, s73
	v_lshrrev_b32_e32 v6, 16, v6
	v_and_or_b32 v5, v5, s33, v6
	v_permlane32_swap_b32_e32 v2, v4
	s_nop 0
	v_permlane32_swap_b32_e32 v3, v5
	global_store_dwordx4 v[50:51], v[2:5], off offset:224
	s_and_saveexec_b64 s[8:9], vcc
	s_xor_b64 s[8:9], exec, s[8:9]
	s_cbranch_execz .LBB0_554
	v_lshlrev_b64 v[2:3], 6, v[82:83]
	v_lshl_add_u64 v[2:3], s[80:81], 0, v[2:3]
	s_lshl_b32 s70, s60, 3
	v_lshl_add_u64 v[2:3], v[2:3], 0, s[70:71]
	v_add_co_u32_e32 v2, vcc, 0x1b69e000, v2
	s_nop 1
	v_addc_co_u32_e32 v3, vcc, 0, v3, vcc
	global_store_dwordx2 v[2:3], v[66:67], off

.LBB0_561:
	v_readlane_b32 s10, v253, 5
	s_add_u32 s8, s80, 0xee19000
	s_addc_u32 s9, s81, 0
	v_add_u32_e32 v2, s10, v172
	v_ashrrev_i32_e32 v22, 4, v2
	v_add_u32_e32 v33, 0x100, v2
	v_add_u32_e32 v12, 0x200, v2
	v_add_u32_e32 v14, 0x300, v2
	v_add_u32_e32 v4, s19, v22
	v_mov_b64_e32 v[20:21], s[8:9]
	v_ashrrev_i32_e32 v24, 4, v33
	v_ashrrev_i32_e32 v26, 4, v12
	v_ashrrev_i32_e32 v28, 4, v14
	v_mad_i64_i32 v[4:5], s[8:9], v4, s83, v[20:21]
	v_add_u32_e32 v6, s19, v24
	v_add_u32_e32 v12, s19, v26
	v_add_u32_e32 v14, s19, v28
	v_lshlrev_b32_e32 v32, 4, v172
	s_lshl_b32 s8, s20, 8
	s_mov_b32 s9, s71
	v_mad_i64_i32 v[6:7], s[10:11], v6, s83, v[20:21]
	v_mad_i64_i32 v[12:13], s[10:11], v12, s83, v[20:21]
	v_mad_i64_i32 v[14:15], s[10:11], v14, s83, v[20:21]
	v_and_b32_e32 v82, 0xf0, v32
	v_lshl_add_u64 v[4:5], v[4:5], 0, s[8:9]
	v_lshl_add_u64 v[6:7], v[6:7], 0, s[8:9]
	v_lshl_add_u64 v[12:13], v[12:13], 0, s[8:9]
	v_lshl_add_u64 v[14:15], v[14:15], 0, s[8:9]
	v_lshl_add_u64 v[4:5], v[4:5], 0, v[82:83]
	v_lshl_add_u64 v[8:9], v[6:7], 0, v[82:83]
	v_lshl_add_u64 v[12:13], v[12:13], 0, v[82:83]
	v_lshl_add_u64 v[16:17], v[14:15], 0, v[82:83]
	global_load_dwordx4 v[4:7], v[4:5], off offset:2048
	s_nop 0
	global_load_dwordx4 v[8:11], v[8:9], off offset:2048
	s_nop 0
	global_load_dwordx4 v[12:15], v[12:13], off offset:2048
	s_nop 0
	global_load_dwordx4 v[16:19], v[16:17], off offset:2048
	v_ashrrev_i32_e32 v34, 3, v2
	v_add_u32_e32 v30, s19, v34
	s_lshl_b32 s70, s20, 7
	v_readlane_b32 s10, v254, 2
	v_mad_i64_i32 v[30:31], s[8:9], v30, s83, v[20:21]
	s_nop 0
	v_add_u32_e32 v2, s10, v82
	v_lshl_add_u64 v[30:31], v[30:31], 0, s[70:71]
	v_and_b32_e32 v82, 0x70, v32
	v_mad_u64_u32 v[22:23], s[8:9], v22, s5, v[2:3]
	v_lshl_add_u64 v[30:31], v[30:31], 0, v[82:83]
	v_mad_u64_u32 v[24:25], s[8:9], v24, s5, v[2:3]
	v_mad_u64_u32 v[26:27], s[8:9], v26, s5, v[2:3]
	v_mad_u64_u32 v[28:29], s[8:9], v28, s5, v[2:3]
	v_and_b32_e32 v3, 12, v3
	v_ashrrev_i32_e32 v43, 5, v172
	v_bfe_u32 v44, v172, 2, 2
	v_lshlrev_b32_e32 v45, 3, v43
	v_or_b32_e32 v46, 4, v44
	s_movk_i32 s11, 0x90
	s_waitcnt vmcnt(0)
	ds_write_b128 v22, v[4:7]
	ds_write_b128 v24, v[8:11]
	ds_write_b128 v26, v[12:15]
	ds_write_b128 v28, v[16:19]
	s_waitcnt lgkmcnt(0)
	s_barrier
	global_load_dwordx4 v[4:7], v[30:31], off offset:1024
	v_ashrrev_i32_e32 v18, 3, v33
	v_add_u32_e32 v2, s19, v18
	v_mad_i64_i32 v[8:9], s[8:9], v2, s83, v[20:21]
	v_lshl_add_u64 v[8:9], v[8:9], 0, s[70:71]
	v_lshl_add_u64 v[8:9], v[8:9], 0, v[82:83]
	global_load_dwordx4 v[8:11], v[8:9], off offset:1024
	v_and_b32_e32 v2, 16, v172
	v_readlane_b32 s8, v253, 9
	v_or_b32_e32 v16, v45, v44
	v_or_b32_e32 v17, v46, v45
	v_or3_b32 v12, v2, s8, v3
	v_or_b32_e32 v2, v3, v2
	v_readlane_b32 s8, v253, 10
	v_lshlrev_b32_e32 v2, 1, v2
	v_lshl_add_u32 v3, v34, 2, s10
	v_lshl_add_u32 v42, v12, 1, s8
	v_readlane_b32 s8, v253, 8
	v_add_u32_e32 v19, 16, v45
	v_lshl_add_u32 v26, v18, 2, s10
	v_add_u32_e32 v47, s8, v2
	v_readlane_b32 s8, v253, 11
	v_or_b32_e32 v49, v19, v44
	v_or_b32_e32 v50, v19, v46
	v_add_u32_e32 v48, s8, v2
	v_mad_u64_u32 v[14:15], s[8:9], v17, s5, v[42:43]
	v_mul_lo_u32 v2, v16, s11
	v_mad_u64_u32 v[12:13], s[8:9], v16, s5, v[42:43]
	v_add_u32_e32 v15, v47, v2
	v_add_u32_e32 v35, v48, v2
	v_add_u32_e32 v2, s10, v82
	v_mul_lo_u32 v13, v17, s11
	v_mad_u64_u32 v[16:17], s[8:9], v34, s11, v[2:3]
	v_mad_u64_u32 v[18:19], s[8:9], v18, s11, v[2:3]
	ds_read_b32 v2, v3 offset:26624
	v_add_u32_e32 v27, v13, v47
	v_mad_u64_u32 v[38:39], s[8:9], v49, s5, v[42:43]
	v_mad_u64_u32 v[40:41], s[8:9], v50, s5, v[42:43]
	v_mul_lo_u32 v49, v49, s11
	v_mul_lo_u32 v50, v50, s11
	v_add_u32_e32 v51, v49, v47
	v_add_u32_e32 v52, v50, v47
	v_add_u32_e32 v49, v49, v48
	v_add_u32_e32 v50, v50, v48
	s_waitcnt vmcnt(1)
	v_lshlrev_b32_e32 v21, 16, v5
	v_lshlrev_b32_e32 v20, 16, v4
	v_and_b32_e32 v5, 0xffff0000, v5
	v_and_b32_e32 v4, 0xffff0000, v4
	v_lshlrev_b32_e32 v23, 16, v7
	v_lshlrev_b32_e32 v22, 16, v6
	v_and_b32_e32 v7, 0xffff0000, v7
	v_and_b32_e32 v6, 0xffff0000, v6
	s_waitcnt lgkmcnt(0)
	v_pk_mul_f32 v[20:21], v[2:3], v[20:21] op_sel_hi:[0,1]
	v_pk_mul_f32 v[4:5], v[2:3], v[4:5] op_sel_hi:[0,1]
	v_pk_mul_f32 v[22:23], v[2:3], v[22:23] op_sel_hi:[0,1]
	v_pk_mul_f32 v[2:3], v[2:3], v[6:7] op_sel_hi:[0,1]
	v_bfe_u32 v17, v5, 16, 1
	v_bfe_u32 v19, v4, 16, 1
	v_bfe_u32 v28, v20, 16, 1
	v_bfe_u32 v29, v21, 16, 1
	v_add3_u32 v19, v4, v19, s73
	v_add3_u32 v17, v5, v17, s73
	v_add3_u32 v6, v21, v29, s73
	v_add3_u32 v7, v20, v28, s73
	v_lshrrev_b32_e32 v7, 16, v7
	v_lshrrev_b32_e32 v6, 16, v6
	v_cvt_pk_bf16_f32 v5, v23, v3
	v_cvt_pk_bf16_f32 v4, v22, v2
	v_and_or_b32 v3, v17, s33, v6
	v_and_or_b32 v2, v19, s33, v7
	ds_write_b128 v16, v[2:5] offset:17408
	ds_read_b32 v2, v26 offset:26624
	s_waitcnt vmcnt(0)
	v_lshlrev_b32_e32 v25, 16, v9
	v_lshlrev_b32_e32 v24, 16, v8
	v_and_b32_e32 v9, 0xffff0000, v9
	v_and_b32_e32 v8, 0xffff0000, v8
	v_lshlrev_b32_e32 v5, 16, v11
	v_lshlrev_b32_e32 v4, 16, v10
	v_and_b32_e32 v7, 0xffff0000, v11
	v_and_b32_e32 v6, 0xffff0000, v10
	s_waitcnt lgkmcnt(0)
	v_pk_mul_f32 v[10:11], v[2:3], v[24:25] op_sel_hi:[0,1]
	v_pk_mul_f32 v[8:9], v[2:3], v[8:9] op_sel_hi:[0,1]
	v_pk_mul_f32 v[4:5], v[2:3], v[4:5] op_sel_hi:[0,1]
	v_pk_mul_f32 v[2:3], v[2:3], v[6:7] op_sel_hi:[0,1]
	s_nop 0
	v_cvt_pk_bf16_f32 v5, v5, v3
	v_cvt_pk_bf16_f32 v4, v4, v2
	v_cvt_pk_bf16_f32 v3, v11, v9
	v_cvt_pk_bf16_f32 v2, v10, v8
	ds_write_b128 v18, v[2:5] offset:17408
	s_waitcnt lgkmcnt(0)
	s_barrier
	ds_read_b64_tr_b16 v[2:3], v12
	ds_read_b64_tr_b16 v[4:5], v14
	s_waitcnt lgkmcnt(0)
	ds_read_b64_tr_b16 v[6:7], v15
	ds_read_b64_tr_b16 v[8:9], v27
	s_waitcnt lgkmcnt(0)
	v_add_u32_e32 v10, v13, v48
	v_mfma_f32_32x32x16_bf16 v[18:33], v[2:5], v[6:9], 0
	ds_read_b64_tr_b16 v[6:7], v35
	ds_read_b64_tr_b16 v[8:9], v10
	s_waitcnt lgkmcnt(0)
	ds_read_b64_tr_b16 v[34:35], v38
	ds_read_b64_tr_b16 v[36:37], v40
	s_waitcnt lgkmcnt(0)
	ds_read_b64_tr_b16 v[38:39], v51
	ds_read_b64_tr_b16 v[40:41], v52
	s_waitcnt lgkmcnt(0)
	s_nop 0
	v_mfma_f32_32x32x16_bf16 v[2:17], v[2:5], v[6:9], 0
	v_mfma_f32_32x32x16_bf16 v[18:33], v[34:37], v[38:41], v[18:33]
	ds_read_b64_tr_b16 v[38:39], v49
	ds_read_b64_tr_b16 v[40:41], v50
	s_waitcnt lgkmcnt(0)
	s_nop 0
	v_mfma_f32_32x32x16_bf16 v[2:17], v[34:37], v[38:41], v[2:17]
	s_nop 6
	v_add_u32_e32 v34, 32, v45
	v_or_b32_e32 v49, v34, v44
	v_mad_u64_u32 v[38:39], s[8:9], v49, s5, v[42:43]
	v_or_b32_e32 v39, v34, v46
	v_mad_u64_u32 v[40:41], s[8:9], v39, s5, v[42:43]
	ds_read_b64_tr_b16 v[34:35], v38
	ds_read_b64_tr_b16 v[36:37], v40
	s_waitcnt lgkmcnt(0)
	v_mul_lo_u32 v49, v49, s11
	v_mul_lo_u32 v51, v39, s11
	v_add_u32_e32 v50, v49, v47
	v_add_u32_e32 v52, v51, v47
	ds_read_b64_tr_b16 v[38:39], v50
	ds_read_b64_tr_b16 v[40:41], v52
	s_waitcnt lgkmcnt(0)
	v_add_u32_e32 v49, v49, v48
	v_mfma_f32_32x32x16_bf16 v[18:33], v[34:37], v[38:41], v[18:33]
	v_add_u32_e32 v50, v51, v48
	ds_read_b64_tr_b16 v[38:39], v49
	ds_read_b64_tr_b16 v[40:41], v50
	s_waitcnt lgkmcnt(0)
	s_nop 0
	v_mfma_f32_32x32x16_bf16 v[2:17], v[34:37], v[38:41], v[2:17]
	s_nop 6
	v_add_u32_e32 v34, 48, v45
	v_or_b32_e32 v44, v34, v44
	v_mad_u64_u32 v[38:39], s[8:9], v44, s5, v[42:43]
	v_or_b32_e32 v39, v34, v46
	v_mad_u64_u32 v[40:41], s[8:9], v39, s5, v[42:43]
	ds_read_b64_tr_b16 v[34:35], v38
	ds_read_b64_tr_b16 v[36:37], v40
	s_waitcnt lgkmcnt(0)
	v_mul_lo_u32 v42, v44, s11
	v_mul_lo_u32 v45, v39, s11
	s_mul_i32 s9, s18, 0x8100
	v_add_u32_e32 v44, v42, v47
	v_add_u32_e32 v46, v45, v47
	ds_read_b64_tr_b16 v[38:39], v44
	ds_read_b64_tr_b16 v[40:41], v46
	s_waitcnt lgkmcnt(0)
	s_mul_hi_u32 s8, s18, 0x8100
	v_mfma_f32_32x32x16_bf16 v[18:33], v[34:37], v[38:41], v[18:33]
	s_add_u32 s9, s80, s9
	v_add_u32_e32 v42, v42, v48
	v_add_u32_e32 v45, v45, v48
	ds_read_b64_tr_b16 v[38:39], v42
	ds_read_b64_tr_b16 v[40:41], v45
	s_waitcnt lgkmcnt(0)
	s_addc_u32 s10, s81, s8
	s_add_u32 s8, s9, 0x1525d000
	s_addc_u32 s9, s10, 0
	v_mfma_f32_32x32x16_bf16 v[2:17], v[34:37], v[38:41], v[2:17]
	v_readlane_b32 s10, v253, 12
	v_and_b32_e32 v44, 31, v172
	v_lshlrev_b32_e32 v82, 2, v44
	s_nop 3
	v_lshl_add_u32 v34, v43, 8, s10
	v_ashrrev_i32_e32 v35, 31, v34
	v_lshl_add_u64 v[36:37], v[34:35], 2, s[8:9]
	v_lshl_add_u64 v[36:37], v[36:37], 0, v[82:83]
	global_store_dword v[36:37], v18, off
	s_nop 3
	global_store_dword v[36:37], v2, off offset:128
	global_store_dword v[36:37], v19, off offset:256
	global_store_dword v[36:37], v3, off offset:384
	global_store_dword v[36:37], v20, off offset:512
	global_store_dword v[36:37], v4, off offset:640
	global_store_dword v[36:37], v21, off offset:768
	global_store_dword v[36:37], v5, off offset:896
	global_store_dword v[36:37], v22, off offset:2048
	global_store_dword v[36:37], v6, off offset:2176
	global_store_dword v[36:37], v23, off offset:2304
	global_store_dword v[36:37], v7, off offset:2432
	global_store_dword v[36:37], v24, off offset:2560
	global_store_dword v[36:37], v8, off offset:2688
	global_store_dword v[36:37], v25, off offset:2816
	global_store_dword v[36:37], v9, off offset:2944
	v_add_u32_e32 v2, 0x400, v34
	v_ashrrev_i32_e32 v3, 31, v2
	v_lshl_add_u64 v[2:3], v[2:3], 2, s[8:9]
	v_lshl_add_u64 v[2:3], v[2:3], 0, v[82:83]
	global_store_dword v[2:3], v26, off
	global_store_dword v[2:3], v10, off offset:128
	v_add_u32_e32 v2, 0x440, v34
	v_ashrrev_i32_e32 v3, 31, v2
	v_lshl_add_u64 v[2:3], v[2:3], 2, s[8:9]
	v_lshl_add_u64 v[2:3], v[2:3], 0, v[82:83]
	global_store_dword v[2:3], v27, off
	global_store_dword v[2:3], v11, off offset:128
	v_add_u32_e32 v2, 0x480, v34
	v_ashrrev_i32_e32 v3, 31, v2
	v_lshl_add_u64 v[2:3], v[2:3], 2, s[8:9]
	v_lshl_add_u64 v[2:3], v[2:3], 0, v[82:83]
	global_store_dword v[2:3], v28, off
	global_store_dword v[2:3], v12, off offset:128
	v_add_u32_e32 v2, 0x4c0, v34
	v_ashrrev_i32_e32 v3, 31, v2
	v_lshl_add_u64 v[2:3], v[2:3], 2, s[8:9]
	v_lshl_add_u64 v[2:3], v[2:3], 0, v[82:83]
	global_store_dword v[2:3], v29, off
	global_store_dword v[2:3], v13, off offset:128
	v_add_u32_e32 v2, 0x600, v34
	v_ashrrev_i32_e32 v3, 31, v2
	v_lshl_add_u64 v[2:3], v[2:3], 2, s[8:9]
	v_lshl_add_u64 v[2:3], v[2:3], 0, v[82:83]
	global_store_dword v[2:3], v30, off
	global_store_dword v[2:3], v14, off offset:128
	v_add_u32_e32 v2, 0x640, v34
	v_ashrrev_i32_e32 v3, 31, v2
	v_lshl_add_u64 v[2:3], v[2:3], 2, s[8:9]
	v_lshl_add_u64 v[2:3], v[2:3], 0, v[82:83]
	global_store_dword v[2:3], v31, off
	global_store_dword v[2:3], v15, off offset:128
	v_add_u32_e32 v2, 0x680, v34
	v_ashrrev_i32_e32 v3, 31, v2
	v_lshl_add_u64 v[2:3], v[2:3], 2, s[8:9]
	v_lshl_add_u64 v[2:3], v[2:3], 0, v[82:83]
	global_store_dword v[2:3], v32, off
	global_store_dword v[2:3], v16, off offset:128
	v_add_u32_e32 v2, 0x6c0, v34
	v_ashrrev_i32_e32 v3, 31, v2
	v_readlane_b32 s10, v253, 13
	v_lshl_add_u64 v[2:3], v[2:3], 2, s[8:9]
	v_readlane_b32 s11, v253, 14
	v_lshl_add_u64 v[2:3], v[2:3], 0, v[82:83]
	s_andn2_b64 vcc, exec, s[10:11]
	global_store_dword v[2:3], v33, off
	global_store_dword v[2:3], v17, off offset:128
	s_cbranch_vccnz .LBB0_379
	v_readlane_b32 s10, v254, 3
	v_mov_b32_e32 v3, 0
	s_nop 0
	v_lshl_add_u32 v2, v172, 1, s10
	s_mov_b32 s10, 0

.LBB0_810:
	s_and_b64 vcc, exec, s[10:11]
	s_mov_b32 s18, s54
	s_cbranch_vccz .LBB0_812
	s_nop 8
	v_lshl_add_u64 v[66:67], v[238:239], 0, s[70:71]
	v_lshl_add_u64 v[66:67], v[236:237], 1, v[66:67]
	v_lshl_add_u64 v[74:75], v[66:67], 0, s[6:7]
	v_add_co_u32_e32 v66, vcc, 0x2000, v66
	global_load_dwordx4 v[70:73], v[74:75], off offset:32
	s_nop 0
	v_addc_co_u32_e32 v67, vcc, 0, v67, vcc
	global_load_dwordx4 v[66:69], v[66:67], off
	s_movk_i32 s18, 0xa00
	v_mov_b32_e32 v180, 0x800
	s_waitcnt vmcnt(1)
	v_cndmask_b32_e64 v115, v73, 0, s[8:9]
	v_cndmask_b32_e64 v114, v72, 0, s[8:9]
	v_cndmask_b32_e64 v113, v71, 0, s[8:9]
	v_cndmask_b32_e64 v112, v70, 0, s[8:9]
	global_load_dwordx4 v[70:73], v[74:75], off offset:64
	s_waitcnt vmcnt(1)
	v_cndmask_b32_e64 v69, v69, 0, s[8:9]
	v_cndmask_b32_e64 v68, v68, 0, s[8:9]
	v_cndmask_b32_e64 v67, v67, 0, s[8:9]
	v_cndmask_b32_e64 v66, v66, 0, s[8:9]
	s_waitcnt vmcnt(0)
	v_cndmask_b32_e64 v107, v73, 0, s[8:9]
	v_cndmask_b32_e64 v106, v72, 0, s[8:9]
	v_cndmask_b32_e64 v105, v71, 0, s[8:9]
	v_cndmask_b32_e64 v104, v70, 0, s[8:9]
	global_load_dwordx4 v[70:73], v[74:75], off offset:96
	s_waitcnt vmcnt(0)
	v_cndmask_b32_e64 v99, v73, 0, s[8:9]
	v_cndmask_b32_e64 v98, v72, 0, s[8:9]
	v_cndmask_b32_e64 v97, v71, 0, s[8:9]
	v_cndmask_b32_e64 v96, v70, 0, s[8:9]
	global_load_dwordx4 v[70:73], v[74:75], off offset:128
	s_waitcnt vmcnt(0)
	v_cndmask_b32_e64 v103, v73, 0, s[8:9]
	v_cndmask_b32_e64 v102, v72, 0, s[8:9]
	v_cndmask_b32_e64 v101, v71, 0, s[8:9]
	v_cndmask_b32_e64 v100, v70, 0, s[8:9]
	global_load_dwordx4 v[70:73], v[74:75], off offset:160
	s_waitcnt vmcnt(0)
	v_cndmask_b32_e64 v95, v73, 0, s[8:9]
	v_cndmask_b32_e64 v94, v72, 0, s[8:9]
	v_cndmask_b32_e64 v93, v71, 0, s[8:9]
	v_cndmask_b32_e64 v92, v70, 0, s[8:9]
	global_load_dwordx4 v[70:73], v[74:75], off offset:192
	s_waitcnt vmcnt(0)
	v_cndmask_b32_e64 v91, v73, 0, s[8:9]
	v_cndmask_b32_e64 v90, v72, 0, s[8:9]
	v_cndmask_b32_e64 v89, v71, 0, s[8:9]
	v_cndmask_b32_e64 v88, v70, 0, s[8:9]
	global_load_dwordx4 v[70:73], v[74:75], off offset:224
	s_waitcnt vmcnt(0)
	v_cndmask_b32_e64 v85, v71, 0, s[8:9]
	v_ashrrev_i32_e32 v71, 4, v235
	v_cndmask_b32_e64 v87, v73, 0, s[8:9]
	v_and_or_b32 v73, v71, 7, s97
	v_mul_lo_u32 v82, v73, s48
	v_cndmask_b32_e64 v84, v70, 0, s[8:9]
	v_lshlrev_b32_e32 v70, 4, v235
	v_lshl_add_u64 v[74:75], v[82:83], 1, s[84:85]
	v_cndmask_b32_e64 v86, v72, 0, s[8:9]
	v_and_b32_e32 v72, 0xf0, v70
	v_lshl_add_u64 v[74:75], v[74:75], 0, s[70:71]
	v_mov_b32_e32 v73, v83
	v_lshl_add_u64 v[74:75], v[74:75], 0, v[72:73]
	v_add_co_u32_e32 v74, vcc, s67, v74
	v_add_u32_e32 v70, s94, v72
	s_nop 0
	v_addc_co_u32_e32 v75, vcc, 0, v75, vcc
	global_load_dwordx4 v[74:77], v[74:75], off offset:2048
	v_cmp_gt_i32_e32 vcc, 8, v71
	v_mad_u64_u32 v[78:79], s[8:9], v71, s5, v[70:71]
	v_add_u32_e32 v71, 64, v235
	v_ashrrev_i32_e32 v71, 4, v71
	s_waitcnt vmcnt(0)
	v_cndmask_b32_e32 v77, 0, v77, vcc
	v_cndmask_b32_e32 v76, 0, v76, vcc
	v_cndmask_b32_e32 v75, 0, v75, vcc
	v_cndmask_b32_e32 v74, 0, v74, vcc
	ds_write_b128 v78, v[74:77]
	v_and_or_b32 v74, v71, 7, s97
	v_mul_lo_u32 v82, v74, s48
	v_lshl_add_u64 v[74:75], v[82:83], 1, s[84:85]
	v_lshl_add_u64 v[74:75], v[74:75], 0, s[70:71]
	v_lshl_add_u64 v[74:75], v[74:75], 0, v[72:73]
	v_add_co_u32_e32 v74, vcc, s67, v74
	v_mad_u64_u32 v[78:79], s[8:9], v71, s5, v[70:71]
	s_nop 0
	v_addc_co_u32_e32 v75, vcc, 0, v75, vcc
	global_load_dwordx4 v[74:77], v[74:75], off offset:2048
	v_cmp_gt_i32_e32 vcc, 8, v71
	v_add_u32_e32 v71, 0x80, v235
	v_ashrrev_i32_e32 v71, 4, v71
	s_waitcnt vmcnt(0)
	v_cndmask_b32_e32 v77, 0, v77, vcc
	v_cndmask_b32_e32 v76, 0, v76, vcc
	v_cndmask_b32_e32 v75, 0, v75, vcc
	v_cndmask_b32_e32 v74, 0, v74, vcc
	ds_write_b128 v78, v[74:77]
	v_and_or_b32 v74, v71, 7, s97
	v_mul_lo_u32 v82, v74, s48
	v_lshl_add_u64 v[74:75], v[82:83], 1, s[84:85]
	v_lshl_add_u64 v[74:75], v[74:75], 0, s[70:71]
	v_lshl_add_u64 v[74:75], v[74:75], 0, v[72:73]
	v_add_co_u32_e32 v74, vcc, s67, v74
	v_mad_u64_u32 v[78:79], s[8:9], v71, s5, v[70:71]
	s_nop 0
	v_addc_co_u32_e32 v75, vcc, 0, v75, vcc
	global_load_dwordx4 v[74:77], v[74:75], off offset:2048
	v_cmp_gt_i32_e32 vcc, 8, v71
	v_add_u32_e32 v71, 0xc0, v235
	v_ashrrev_i32_e32 v71, 4, v71
	s_waitcnt vmcnt(0)
	v_cndmask_b32_e32 v77, 0, v77, vcc
	v_cndmask_b32_e32 v76, 0, v76, vcc
	v_cndmask_b32_e32 v75, 0, v75, vcc
	v_cndmask_b32_e32 v74, 0, v74, vcc
	ds_write_b128 v78, v[74:77]
	v_and_or_b32 v74, v71, 7, s97
	v_mul_lo_u32 v82, v74, s48
	v_lshl_add_u64 v[74:75], v[82:83], 1, s[84:85]
	v_lshl_add_u64 v[74:75], v[74:75], 0, s[70:71]
	v_lshl_add_u64 v[74:75], v[74:75], 0, v[72:73]
	v_add_co_u32_e32 v74, vcc, s67, v74
	v_mad_u64_u32 v[78:79], s[8:9], v71, s5, v[70:71]
	s_nop 0
	v_addc_co_u32_e32 v75, vcc, 0, v75, vcc
	global_load_dwordx4 v[74:77], v[74:75], off offset:2048
	v_cmp_gt_i32_e32 vcc, 8, v71
	v_add_u32_e32 v71, 0x100, v235
	v_ashrrev_i32_e32 v71, 4, v71
	s_waitcnt vmcnt(0)
	v_cndmask_b32_e32 v77, 0, v77, vcc
	v_cndmask_b32_e32 v76, 0, v76, vcc
	v_cndmask_b32_e32 v75, 0, v75, vcc
	v_cndmask_b32_e32 v74, 0, v74, vcc
	ds_write_b128 v78, v[74:77]
	v_and_or_b32 v74, v71, 7, s97
	v_mul_lo_u32 v82, v74, s48
	v_lshl_add_u64 v[74:75], v[82:83], 1, s[84:85]
	v_lshl_add_u64 v[74:75], v[74:75], 0, s[70:71]
	v_lshl_add_u64 v[74:75], v[74:75], 0, v[72:73]
	v_add_co_u32_e32 v74, vcc, s67, v74
	v_mad_u64_u32 v[78:79], s[8:9], v71, s5, v[70:71]
	s_nop 0
	v_addc_co_u32_e32 v75, vcc, 0, v75, vcc
	global_load_dwordx4 v[74:77], v[74:75], off offset:2048
	v_cmp_gt_i32_e32 vcc, 8, v71
	v_add_u32_e32 v71, 0x140, v235
	v_ashrrev_i32_e32 v71, 4, v71
	s_waitcnt vmcnt(0)
	v_cndmask_b32_e32 v77, 0, v77, vcc
	v_cndmask_b32_e32 v76, 0, v76, vcc
	v_cndmask_b32_e32 v75, 0, v75, vcc
	v_cndmask_b32_e32 v74, 0, v74, vcc
	ds_write_b128 v78, v[74:77]
	v_and_or_b32 v74, v71, 7, s97
	v_mul_lo_u32 v82, v74, s48
	v_lshl_add_u64 v[74:75], v[82:83], 1, s[84:85]
	v_lshl_add_u64 v[74:75], v[74:75], 0, s[70:71]
	v_lshl_add_u64 v[74:75], v[74:75], 0, v[72:73]
	v_add_co_u32_e32 v74, vcc, s67, v74
	v_mad_u64_u32 v[78:79], s[8:9], v71, s5, v[70:71]
	s_nop 0
	v_addc_co_u32_e32 v75, vcc, 0, v75, vcc
	global_load_dwordx4 v[74:77], v[74:75], off offset:2048
	v_cmp_gt_i32_e32 vcc, 8, v71
	v_add_u32_e32 v71, 0x180, v235
	v_ashrrev_i32_e32 v71, 4, v71
	s_waitcnt vmcnt(0)
	v_cndmask_b32_e32 v77, 0, v77, vcc
	v_cndmask_b32_e32 v76, 0, v76, vcc
	v_cndmask_b32_e32 v75, 0, v75, vcc
	v_cndmask_b32_e32 v74, 0, v74, vcc
	ds_write_b128 v78, v[74:77]
	v_and_or_b32 v74, v71, 7, s97
	v_mul_lo_u32 v82, v74, s48
	v_lshl_add_u64 v[74:75], v[82:83], 1, s[84:85]
	v_lshl_add_u64 v[74:75], v[74:75], 0, s[70:71]
	v_lshl_add_u64 v[74:75], v[74:75], 0, v[72:73]
	v_add_co_u32_e32 v74, vcc, s67, v74
	v_mad_u64_u32 v[78:79], s[8:9], v71, s5, v[70:71]
	s_nop 0
	v_addc_co_u32_e32 v75, vcc, 0, v75, vcc
	global_load_dwordx4 v[74:77], v[74:75], off offset:2048
	v_cmp_gt_i32_e32 vcc, 8, v71
	v_add_u32_e32 v71, 0x1c0, v235
	v_ashrrev_i32_e32 v71, 4, v71
	s_waitcnt vmcnt(0)
	v_cndmask_b32_e32 v77, 0, v77, vcc
	v_cndmask_b32_e32 v76, 0, v76, vcc
	v_cndmask_b32_e32 v75, 0, v75, vcc
	v_cndmask_b32_e32 v74, 0, v74, vcc
	ds_write_b128 v78, v[74:77]
	v_and_or_b32 v74, v71, 7, s97
	v_mul_lo_u32 v82, v74, s48
	v_lshl_add_u64 v[74:75], v[82:83], 1, s[84:85]
	v_lshl_add_u64 v[74:75], v[74:75], 0, s[70:71]
	v_lshl_add_u64 v[72:73], v[74:75], 0, v[72:73]
	v_add_co_u32_e32 v72, vcc, s67, v72
	s_nop 1
	v_addc_co_u32_e32 v73, vcc, 0, v73, vcc
	global_load_dwordx4 v[72:75], v[72:73], off offset:2048
	v_cmp_gt_i32_e32 vcc, 8, v71
	v_mad_u64_u32 v[70:71], s[8:9], v71, s5, v[70:71]
	s_waitcnt vmcnt(0)
	v_cndmask_b32_e32 v75, 0, v75, vcc
	v_cndmask_b32_e32 v74, 0, v74, vcc
	v_cndmask_b32_e32 v73, 0, v73, vcc
	v_cndmask_b32_e32 v72, 0, v72, vcc
	ds_write_b128 v70, v[72:75]
	v_mfma_f32_32x32x16_bf16 v[66:81], v[66:69], v[152:155], 0
	v_mfma_f32_32x32x16_bf16 v[66:81], v[112:115], v[144:147], v[66:81]
	v_mfma_f32_32x32x16_bf16 v[66:81], v[104:107], v[140:143], v[66:81]
	v_mfma_f32_32x32x16_bf16 v[66:81], v[96:99], v[132:135], v[66:81]
	v_mfma_f32_32x32x16_bf16 v[66:81], v[100:103], v[128:131], v[66:81]
	v_mfma_f32_32x32x16_bf16 v[66:81], v[92:95], v[120:123], v[66:81]
	v_mfma_f32_32x32x16_bf16 v[66:81], v[88:91], v[116:119], v[66:81]
	v_mfma_f32_32x32x16_bf16 v[66:81], v[84:87], v[108:111], v[66:81]
	s_nop 6
	v_mov_b32_e32 v84, 0
	v_mov_b32_e32 v85, v84
	v_mov_b32_e32 v86, v84
	v_mov_b32_e32 v87, v84
	v_mov_b32_e32 v88, v84
	v_mov_b32_e32 v89, v84
	v_mov_b32_e32 v90, v84
	v_mov_b32_e32 v91, v84
	v_mov_b32_e32 v92, v84
	v_mov_b32_e32 v93, v84
	v_mov_b32_e32 v94, v84
	v_mov_b32_e32 v95, v84
	v_mov_b32_e32 v96, v84
	v_mov_b32_e32 v97, v84
	v_mov_b32_e32 v98, v84
	v_mov_b32_e32 v99, v84
	v_mov_b32_e32 v100, v84
	v_mov_b32_e32 v101, v84
	v_mov_b32_e32 v102, v84
	v_mov_b32_e32 v103, v84
	v_mov_b32_e32 v104, v84
	v_mov_b32_e32 v105, v84
	v_mov_b32_e32 v106, v84
	v_mov_b32_e32 v107, v84
	v_mov_b32_e32 v112, v84
	v_mov_b32_e32 v113, v84
	v_mov_b32_e32 v114, v84
	v_mov_b32_e32 v115, v84
	v_mov_b32_e32 v124, v84
	v_mov_b32_e32 v125, v84
	v_mov_b32_e32 v126, v84
	v_mov_b32_e32 v127, v84
	v_mov_b32_e32 v136, v84
	v_mov_b32_e32 v137, v84
	v_mov_b32_e32 v138, v84
	v_mov_b32_e32 v139, v84
	v_mov_b32_e32 v148, v84
	v_mov_b32_e32 v149, v84
	v_mov_b32_e32 v150, v84
	v_mov_b32_e32 v151, v84
	v_mov_b32_e32 v156, v84
	v_mov_b32_e32 v157, v84
	v_mov_b32_e32 v158, v84
	v_mov_b32_e32 v159, v84
	v_mov_b32_e32 v160, v84
	v_mov_b32_e32 v161, v84
	v_mov_b32_e32 v162, v84
	v_mov_b32_e32 v163, v84
	v_mov_b32_e32 v164, v84
	v_mov_b32_e32 v165, v84
	v_mov_b32_e32 v166, v84
	v_mov_b32_e32 v167, v84
	v_mov_b32_e32 v168, v84
	v_mov_b32_e32 v169, v84
	v_mov_b32_e32 v170, v84
	v_mov_b32_e32 v171, v84
	v_mov_b32_e32 v172, v84
	v_mov_b32_e32 v173, v84
	v_mov_b32_e32 v174, v84
	v_mov_b32_e32 v175, v84
	v_mov_b32_e32 v176, v84
	v_mov_b32_e32 v177, v84
	v_mov_b32_e32 v178, v84
	v_mov_b32_e32 v179, v84

.LBB0_972:
	s_or_b64 exec, exec, s[10:11]
	v_max_f32_e32 v135, v66, v66
	v_max_f32_e32 v135, 0xff800000, v135
	v_cmp_eq_u32_e32 vcc, 0, v109
	v_max_f32_e32 v140, v67, v67
	v_cmp_eq_u32_e64 s[8:9], 0, v111
	v_cndmask_b32_e32 v135, v135, v228, vcc
	v_max_f32_e32 v140, v135, v140
	v_cndmask_b32_e64 v135, v140, v135, s[8:9]
	v_max_f32_e32 v140, v68, v68
	v_max_f32_e32 v140, v135, v140
	v_cmp_eq_u32_e64 s[10:11], 0, v117
	v_cmp_eq_u32_e64 s[12:13], 0, v118
	v_cmp_eq_u32_e64 s[14:15], 0, v120
	v_cndmask_b32_e64 v135, v140, v135, s[10:11]
	v_max_f32_e32 v140, v69, v69
	v_max_f32_e32 v140, v135, v140
	v_cndmask_b32_e64 v135, v140, v135, s[12:13]
	v_max_f32_e32 v140, v70, v70
	v_max_f32_e32 v140, v135, v140
	v_cndmask_b32_e64 v135, v140, v135, s[14:15]
	v_max_f32_e32 v140, v135, v135
	v_max_f32_e32 v141, v71, v71
	v_max_f32_e32 v140, v140, v141
	v_cmp_eq_u32_e64 s[16:17], 0, v121
	v_max_f32_e32 v141, v72, v72
	v_cmp_eq_u32_e64 s[18:19], 0, v122
	v_cndmask_b32_e64 v135, v140, v135, s[16:17]
	v_max_f32_e32 v140, v135, v135
	v_max_f32_e32 v140, v140, v141
	v_cndmask_b32_e64 v135, v140, v135, s[18:19]
	v_max_f32_e32 v140, v135, v135
	v_max_f32_e32 v141, v73, v73
	v_max_f32_e32 v140, v140, v141
	v_cmp_eq_u32_e64 s[20:21], 0, v123
	v_max_f32_e32 v141, v74, v74
	v_cmp_eq_u32_e64 s[22:23], 0, v128
	v_cndmask_b32_e64 v135, v140, v135, s[20:21]
	v_max_f32_e32 v140, v135, v135
	v_max_f32_e32 v140, v140, v141
	v_cndmask_b32_e64 v135, v140, v135, s[22:23]
	v_max_f32_e32 v140, v135, v135
	v_max_f32_e32 v141, v75, v75
	v_max_f32_e32 v140, v140, v141
	v_cmp_eq_u32_e64 s[24:25], 0, v129
	v_max_f32_e32 v141, v76, v76
	v_cmp_eq_u32_e64 s[26:27], 0, v130
	v_cndmask_b32_e64 v135, v140, v135, s[24:25]
	v_max_f32_e32 v140, v135, v135
	v_max_f32_e32 v140, v140, v141
	v_cndmask_b32_e64 v135, v140, v135, s[26:27]
	v_max_f32_e32 v140, v135, v135
	v_max_f32_e32 v141, v77, v77
	v_max_f32_e32 v140, v140, v141
	v_cmp_eq_u32_e64 s[28:29], 0, v131
	v_max_f32_e32 v141, v78, v78
	v_cmp_eq_u32_e64 s[30:31], 0, v132
	v_cndmask_b32_e64 v135, v140, v135, s[28:29]
	v_max_f32_e32 v140, v135, v135
	v_max_f32_e32 v140, v140, v141
	v_cndmask_b32_e64 v135, v140, v135, s[30:31]
	v_max_f32_e32 v140, v135, v135
	v_max_f32_e32 v141, v79, v79
	v_max_f32_e32 v140, v140, v141
	v_cmp_eq_u32_e64 s[34:35], 0, v133
	v_max_f32_e32 v141, v80, v80
	v_cmp_eq_u32_e64 s[36:37], 0, v134
	v_cndmask_b32_e64 v135, v140, v135, s[34:35]
	v_max_f32_e32 v140, v135, v135
	v_max_f32_e32 v140, v140, v141
	v_cmp_eq_u32_e64 s[38:39], 2, v134
	v_cndmask_b32_e64 v135, v140, v135, s[36:37]
	s_nop 0
	v_cndmask_b32_e64 v140, 0, 1.0, s[38:39]
	v_cmp_ne_u32_e64 s[38:39], 3, v134
	s_nop 1
	v_cndmask_b32_e64 v134, v229, v140, s[38:39]
	v_add_f32_e32 v80, v80, v134
	v_cndmask_b32_e64 v134, v80, v228, s[36:37]
	v_cmp_eq_u32_e64 s[36:37], 2, v133
	s_nop 1
	v_cndmask_b32_e64 v80, 0, 1.0, s[36:37]
	v_cmp_ne_u32_e64 s[36:37], 3, v133
	s_nop 1
	v_cndmask_b32_e64 v80, v229, v80, s[36:37]
	v_add_f32_e32 v79, v79, v80
	v_cndmask_b32_e64 v79, v79, v228, s[34:35]
	v_cmp_eq_u32_e64 s[34:35], 2, v132
	s_nop 1
	v_cndmask_b32_e64 v80, 0, 1.0, s[34:35]
	v_cmp_ne_u32_e64 s[34:35], 3, v132
	s_nop 1
	v_cndmask_b32_e64 v80, v229, v80, s[34:35]
	v_add_f32_e32 v78, v78, v80
	v_cndmask_b32_e64 v132, v78, v228, s[30:31]
	v_cmp_eq_u32_e64 s[30:31], 2, v131
	v_and_b32_e32 v80, 64, v249
	v_add_u32_e32 v80, 64, v80
	v_cndmask_b32_e64 v78, 0, 1.0, s[30:31]
	v_cmp_ne_u32_e64 s[30:31], 3, v131
	s_nop 1
	v_cndmask_b32_e64 v78, v229, v78, s[30:31]
	v_add_f32_e32 v77, v77, v78
	v_cndmask_b32_e64 v77, v77, v228, s[28:29]
	v_cmp_eq_u32_e64 s[28:29], 2, v130
	s_nop 1
	v_cndmask_b32_e64 v78, 0, 1.0, s[28:29]
	v_cmp_ne_u32_e64 s[28:29], 3, v130
	s_nop 1
	v_cndmask_b32_e64 v78, v229, v78, s[28:29]
	v_add_f32_e32 v76, v76, v78
	v_cndmask_b32_e64 v76, v76, v228, s[26:27]
	v_cmp_eq_u32_e64 s[26:27], 2, v129
	s_nop 1
	v_cndmask_b32_e64 v78, 0, 1.0, s[26:27]
	v_cmp_ne_u32_e64 s[26:27], 3, v129
	s_nop 1
	v_cndmask_b32_e64 v78, v229, v78, s[26:27]
	v_add_f32_e32 v75, v75, v78
	v_cndmask_b32_e64 v129, v75, v228, s[24:25]
	v_cmp_eq_u32_e64 s[24:25], 2, v128
	s_nop 1
	v_cndmask_b32_e64 v75, 0, 1.0, s[24:25]
	v_cmp_ne_u32_e64 s[24:25], 3, v128
	s_nop 1
	v_cndmask_b32_e64 v75, v229, v75, s[24:25]
	v_add_f32_e32 v74, v74, v75
	v_cndmask_b32_e64 v128, v74, v228, s[22:23]
	v_cmp_eq_u32_e64 s[22:23], 2, v123
	v_xor_b32_e32 v75, 32, v249
	s_nop 0
	v_cndmask_b32_e64 v74, 0, 1.0, s[22:23]
	v_cmp_ne_u32_e64 s[22:23], 3, v123
	s_nop 1
	v_cndmask_b32_e64 v74, v229, v74, s[22:23]
	v_add_f32_e32 v73, v73, v74
	v_cndmask_b32_e64 v73, v73, v228, s[20:21]
	v_cmp_eq_u32_e64 s[20:21], 2, v122
	s_nop 1
	v_cndmask_b32_e64 v74, 0, 1.0, s[20:21]
	v_cmp_ne_u32_e64 s[20:21], 3, v122
	s_nop 1
	v_cndmask_b32_e64 v74, v229, v74, s[20:21]
	v_add_f32_e32 v72, v72, v74
	v_cndmask_b32_e64 v78, v72, v228, s[18:19]
	v_cmp_eq_u32_e64 s[18:19], 2, v121
	s_nop 1
	v_cndmask_b32_e64 v72, 0, 1.0, s[18:19]
	v_cmp_ne_u32_e64 s[18:19], 3, v121
	s_nop 1
	v_cndmask_b32_e64 v72, v229, v72, s[18:19]
	v_add_f32_e32 v71, v71, v72
	v_cndmask_b32_e64 v71, v71, v228, s[16:17]
	v_cmp_eq_u32_e64 s[16:17], 2, v120
	s_nop 1
	v_cndmask_b32_e64 v72, 0, 1.0, s[16:17]
	v_cmp_ne_u32_e64 s[16:17], 3, v120
	s_nop 1
	v_cndmask_b32_e64 v72, v229, v72, s[16:17]
	v_add_f32_e32 v70, v70, v72
	v_cndmask_b32_e64 v74, v70, v228, s[14:15]
	v_cmp_eq_u32_e64 s[14:15], 2, v118
	s_nop 1
	v_cndmask_b32_e64 v70, 0, 1.0, s[14:15]
	v_cmp_ne_u32_e64 s[14:15], 3, v118
	s_nop 1
	v_cndmask_b32_e64 v70, v229, v70, s[14:15]
	v_add_f32_e32 v69, v69, v70
	v_cndmask_b32_e64 v69, v69, v228, s[12:13]
	v_cmp_eq_u32_e64 s[12:13], 2, v117
	s_nop 1
	v_cndmask_b32_e64 v70, 0, 1.0, s[12:13]
	v_cmp_ne_u32_e64 s[12:13], 3, v117
	s_nop 1
	v_cndmask_b32_e64 v70, v229, v70, s[12:13]
	v_add_f32_e32 v68, v68, v70
	v_cndmask_b32_e64 v70, v68, v228, s[10:11]
	v_cmp_eq_u32_e64 s[10:11], 2, v111
	s_nop 1
	v_cndmask_b32_e64 v68, 0, 1.0, s[10:11]
	v_cmp_ne_u32_e64 s[10:11], 3, v111
	s_nop 1
	v_cndmask_b32_e64 v68, v229, v68, s[10:11]
	v_add_f32_e32 v67, v67, v68
	v_cndmask_b32_e64 v72, v67, v228, s[8:9]
	v_cmp_eq_u32_e64 s[8:9], 2, v109
	v_max_f32_e32 v68, v81, v81
	s_nop 0
	v_cndmask_b32_e64 v67, 0, 1.0, s[8:9]
	v_cmp_ne_u32_e64 s[8:9], 3, v109
	s_nop 1
	v_cndmask_b32_e64 v67, v229, v67, s[8:9]
	v_add_f32_e32 v66, v66, v67
	v_max_f32_e32 v67, v135, v135
	v_cmp_eq_u32_e64 s[8:9], 2, v116
	v_max_f32_e32 v67, v67, v68
	v_cndmask_b32_e32 v66, v66, v228, vcc
	v_cndmask_b32_e64 v68, 0, 1.0, s[8:9]
	v_cmp_lt_i32_e64 s[8:9], v75, v80
	v_cmp_eq_u32_e32 vcc, 0, v116
	s_nop 0
	v_cndmask_b32_e64 v75, v249, v75, s[8:9]
	v_cndmask_b32_e32 v67, v67, v135, vcc
	v_lshlrev_b32_e32 v117, 2, v75
	ds_bpermute_b32 v75, v117, v67
	v_cmp_ne_u32_e64 s[8:9], 3, v116
	s_waitcnt lgkmcnt(0)
	v_max3_f32 v67, v246, v67, v75
	v_cndmask_b32_e64 v68, v229, v68, s[8:9]
	v_add_f32_e32 v68, v81, v68
	v_sub_f32_e32 v66, v66, v67
	v_cndmask_b32_e32 v111, v68, v228, vcc
	v_exp_f32_e32 v68, v66
	v_sub_f32_e32 v66, v72, v67
	v_exp_f32_e32 v72, v66
	v_sub_f32_e32 v66, v70, v67
	v_exp_f32_e32 v70, v66
	v_sub_f32_e32 v66, v69, v67
	v_exp_f32_e32 v75, v66
	v_sub_f32_e32 v69, v74, v67
	v_add_f32_e32 v66, 0, v68
	v_exp_f32_e32 v74, v69
	v_sub_f32_e32 v69, v71, v67
	v_add_f32_e32 v66, v72, v66
	v_exp_f32_e32 v80, v69
	v_sub_f32_e32 v69, v78, v67
	v_add_f32_e32 v66, v70, v66
	v_exp_f32_e32 v78, v69
	v_sub_f32_e32 v69, v73, v67
	v_add_f32_e32 v66, v75, v66
	v_exp_f32_e32 v109, v69
	v_sub_f32_e32 v69, v128, v67
	v_add_f32_e32 v66, v74, v66
	v_exp_f32_e32 v69, v69
	v_sub_f32_e32 v71, v129, v67
	v_add_f32_e32 v66, v80, v66
	v_exp_f32_e32 v73, v71
	v_sub_f32_e32 v71, v76, v67
	v_add_f32_e32 v66, v78, v66
	v_exp_f32_e32 v71, v71
	v_sub_f32_e32 v76, v77, v67
	v_add_f32_e32 v66, v109, v66
	v_exp_f32_e32 v77, v76
	v_sub_f32_e32 v76, v132, v67
	v_add_f32_e32 v66, v69, v66
	v_exp_f32_e32 v76, v76
	v_sub_f32_e32 v79, v79, v67
	v_add_f32_e32 v66, v73, v66
	v_exp_f32_e32 v81, v79
	v_sub_f32_e32 v79, v134, v67
	v_add_f32_e32 v66, v71, v66
	v_exp_f32_e32 v79, v79
	v_sub_f32_e32 v111, v111, v67
	v_add_f32_e32 v66, v77, v66
	v_exp_f32_e32 v111, v111
	v_add_f32_e32 v66, v76, v66
	v_add_f32_e32 v66, v81, v66
	v_add_f32_e32 v66, v79, v66
	v_add_f32_e32 v116, v111, v66
	ds_bpermute_b32 v117, v117, v116
	s_andn2_b64 vcc, exec, s[62:63]
	s_cbranch_vccnz .LBB0_974
	s_waitcnt vmcnt(15)
	v_lshlrev_b32_e32 v66, 3, v235
	v_cvt_pk_bf16_f32 v84, v84, v85
	v_and_b32_e32 v66, 0xf8, v66
	v_add_u32_e32 v66, s94, v66
	v_cvt_pk_bf16_f32 v85, v86, v87
	v_mad_u64_u32 v[86:87], s[8:9], v224, s5, v[66:67]
	ds_write_b64 v86, v[84:85]
	v_add_u32_e32 v84, 64, v235
	v_ashrrev_i32_e32 v86, 5, v84
	s_waitcnt vmcnt(14)
	v_cvt_pk_bf16_f32 v84, v88, v89
	v_cvt_pk_bf16_f32 v85, v90, v91
	v_mad_u64_u32 v[86:87], s[8:9], v86, s5, v[66:67]
	ds_write_b64 v86, v[84:85]
	v_add_u32_e32 v84, 0x80, v235
	v_ashrrev_i32_e32 v86, 5, v84
	s_waitcnt vmcnt(13)
	v_cvt_pk_bf16_f32 v84, v92, v93
	v_cvt_pk_bf16_f32 v85, v94, v95
	v_mad_u64_u32 v[86:87], s[8:9], v86, s5, v[66:67]
	ds_write_b64 v86, v[84:85]
	v_add_u32_e32 v84, 0xc0, v235
	v_ashrrev_i32_e32 v86, 5, v84
	s_waitcnt vmcnt(12)
	v_cvt_pk_bf16_f32 v84, v96, v97
	v_cvt_pk_bf16_f32 v85, v98, v99
	v_mad_u64_u32 v[86:87], s[8:9], v86, s5, v[66:67]
	ds_write_b64 v86, v[84:85]
	v_add_u32_e32 v84, 0x100, v235
	v_ashrrev_i32_e32 v86, 5, v84
	s_waitcnt vmcnt(11)
	v_cvt_pk_bf16_f32 v84, v100, v101
	v_cvt_pk_bf16_f32 v85, v102, v103
	v_mad_u64_u32 v[86:87], s[8:9], v86, s5, v[66:67]
	ds_write_b64 v86, v[84:85]
	v_add_u32_e32 v84, 0x140, v235
	v_ashrrev_i32_e32 v86, 5, v84
	s_waitcnt vmcnt(10)
	v_cvt_pk_bf16_f32 v84, v104, v105
	v_cvt_pk_bf16_f32 v85, v106, v107
	v_mad_u64_u32 v[86:87], s[8:9], v86, s5, v[66:67]
	ds_write_b64 v86, v[84:85]
	v_add_u32_e32 v84, 0x180, v235
	v_ashrrev_i32_e32 v86, 5, v84
	s_waitcnt vmcnt(9)
	v_cvt_pk_bf16_f32 v84, v112, v113
	v_cvt_pk_bf16_f32 v85, v114, v115
	v_mad_u64_u32 v[86:87], s[8:9], v86, s5, v[66:67]
	ds_write_b64 v86, v[84:85]
	v_add_u32_e32 v84, 0x1c0, v235
	v_ashrrev_i32_e32 v86, 5, v84
	s_waitcnt vmcnt(8)
	v_cvt_pk_bf16_f32 v84, v124, v125
	v_cvt_pk_bf16_f32 v85, v126, v127
	v_mad_u64_u32 v[86:87], s[8:9], v86, s5, v[66:67]
	ds_write_b64 v86, v[84:85]
	v_add_u32_e32 v84, 0x200, v235
	v_ashrrev_i32_e32 v86, 5, v84
	s_waitcnt vmcnt(7)
	v_cvt_pk_bf16_f32 v84, v136, v137
	v_cvt_pk_bf16_f32 v85, v138, v139
	v_mad_u64_u32 v[86:87], s[8:9], v86, s5, v[66:67]
	ds_write_b64 v86, v[84:85]
	v_add_u32_e32 v84, 0x240, v235
	v_ashrrev_i32_e32 v86, 5, v84
	s_waitcnt vmcnt(6)
	v_cvt_pk_bf16_f32 v84, v148, v149
	v_cvt_pk_bf16_f32 v85, v150, v151
	v_mad_u64_u32 v[86:87], s[8:9], v86, s5, v[66:67]
	ds_write_b64 v86, v[84:85]
	v_add_u32_e32 v84, 0x280, v235
	v_ashrrev_i32_e32 v86, 5, v84
	s_waitcnt vmcnt(5)
	v_cvt_pk_bf16_f32 v84, v156, v157
	v_cvt_pk_bf16_f32 v85, v158, v159
	v_mad_u64_u32 v[86:87], s[8:9], v86, s5, v[66:67]
	ds_write_b64 v86, v[84:85]
	v_add_u32_e32 v84, 0x2c0, v235
	v_ashrrev_i32_e32 v86, 5, v84
	s_waitcnt vmcnt(4)
	v_cvt_pk_bf16_f32 v84, v160, v161
	v_cvt_pk_bf16_f32 v85, v162, v163
	v_mad_u64_u32 v[86:87], s[8:9], v86, s5, v[66:67]
	ds_write_b64 v86, v[84:85]
	v_add_u32_e32 v84, 0x300, v235
	v_ashrrev_i32_e32 v86, 5, v84
	s_waitcnt vmcnt(3)
	v_cvt_pk_bf16_f32 v84, v164, v165
	v_cvt_pk_bf16_f32 v85, v166, v167
	v_mad_u64_u32 v[86:87], s[8:9], v86, s5, v[66:67]
	ds_write_b64 v86, v[84:85]
	v_add_u32_e32 v84, 0x340, v235
	v_ashrrev_i32_e32 v86, 5, v84
	s_waitcnt vmcnt(2)
	v_cvt_pk_bf16_f32 v84, v168, v169
	v_cvt_pk_bf16_f32 v85, v170, v171
	v_mad_u64_u32 v[86:87], s[8:9], v86, s5, v[66:67]
	ds_write_b64 v86, v[84:85]
	v_add_u32_e32 v84, 0x380, v235
	v_ashrrev_i32_e32 v86, 5, v84
	s_waitcnt vmcnt(1)
	v_cvt_pk_bf16_f32 v84, v172, v173
	v_cvt_pk_bf16_f32 v85, v174, v175
	v_mad_u64_u32 v[86:87], s[8:9], v86, s5, v[66:67]
	ds_write_b64 v86, v[84:85]
	v_add_u32_e32 v84, 0x3c0, v235
	v_ashrrev_i32_e32 v86, 5, v84
	s_waitcnt vmcnt(0)
	v_cvt_pk_bf16_f32 v84, v176, v177
	v_cvt_pk_bf16_f32 v85, v178, v179
	v_mad_u64_u32 v[86:87], s[8:9], v86, s5, v[66:67]
	ds_write_b64 v86, v[84:85]

.LBB0_977:
	s_nop 4
	v_mov_b32_e32 v17, 0
	v_mov_b32_e32 v67, 0xf149f2ca
	v_mov_b32_e32 v16, v17
	v_mov_b32_e32 v15, v17
	v_mov_b32_e32 v14, v17
	v_mov_b32_e32 v13, v17
	v_mov_b32_e32 v12, v17
	v_mov_b32_e32 v11, v17
	v_mov_b32_e32 v10, v17
	v_mov_b32_e32 v9, v17
	v_mov_b32_e32 v8, v17
	v_mov_b32_e32 v7, v17
	v_mov_b32_e32 v6, v17
	v_mov_b32_e32 v5, v17
	v_mov_b32_e32 v4, v17
	v_mov_b32_e32 v3, v17
	v_mov_b32_e32 v2, v17
	v_mov_b32_e32 v33, v17
	v_mov_b32_e32 v32, v17
	v_mov_b32_e32 v31, v17
	v_mov_b32_e32 v30, v17
	v_mov_b32_e32 v29, v17
	v_mov_b32_e32 v28, v17
	v_mov_b32_e32 v27, v17
	v_mov_b32_e32 v26, v17
	v_mov_b32_e32 v25, v17
	v_mov_b32_e32 v24, v17
	v_mov_b32_e32 v23, v17
	v_mov_b32_e32 v22, v17
	v_mov_b32_e32 v21, v17
	v_mov_b32_e32 v20, v17
	v_mov_b32_e32 v19, v17
	v_mov_b32_e32 v18, v17
	v_mov_b32_e32 v49, v17
	v_mov_b32_e32 v48, v17
	v_mov_b32_e32 v47, v17
	v_mov_b32_e32 v46, v17
	v_mov_b32_e32 v45, v17
	v_mov_b32_e32 v44, v17
	v_mov_b32_e32 v43, v17
	v_mov_b32_e32 v42, v17
	v_mov_b32_e32 v41, v17
	v_mov_b32_e32 v40, v17
	v_mov_b32_e32 v39, v17
	v_mov_b32_e32 v38, v17
	v_mov_b32_e32 v37, v17
	v_mov_b32_e32 v36, v17
	v_mov_b32_e32 v35, v17
	v_mov_b32_e32 v34, v17
	v_mov_b32_e32 v65, v17
	v_mov_b32_e32 v64, v17
	v_mov_b32_e32 v63, v17
	v_mov_b32_e32 v62, v17
	v_mov_b32_e32 v61, v17
	v_mov_b32_e32 v60, v17
	v_mov_b32_e32 v59, v17
	v_mov_b32_e32 v58, v17
	v_mov_b32_e32 v57, v17
	v_mov_b32_e32 v56, v17
	v_mov_b32_e32 v55, v17
	v_mov_b32_e32 v54, v17
	v_mov_b32_e32 v53, v17
	v_mov_b32_e32 v52, v17
	v_mov_b32_e32 v51, v17
	v_mov_b32_e32 v50, v17
	v_mov_b32_e32 v66, v17
	v_and_b32_e32 v68, 31, v1
	v_cmp_gt_u32_e32 vcc, 8, v68
	s_and_saveexec_b64 s[8:9], vcc
	s_cbranch_execnz .LBB0_979
	s_branch .LBB0_981

.LBB0_1001:
	v_lshl_add_u64 v[10:11], v[6:7], 0, s[10:11]
	global_load_dword v32, v[10:11], off
	ds_read_b128 v[20:23], v18
	ds_read_b128 v[24:27], v18 offset:16
	ds_read_b128 v[28:31], v18 offset:32
	ds_read_b128 v[2:5], v18 offset:48
	ds_read_b128 v[40:43], v18 offset:1024
	s_waitcnt lgkmcnt(4)
	v_mov_b32_e32 v44, v20
	global_load_dword v20, v[10:11], off offset:512
	s_add_u32 s10, s10, 0x4000
	s_addc_u32 s11, s11, 0
	s_waitcnt lgkmcnt(0)
	v_mov_b32_e32 v45, v40
	v_mov_b32_e32 v40, v21
	s_cmpk_eq_u32 s10, 0x8000
	s_waitcnt vmcnt(1)
	v_pk_fma_f32 v[8:9], v[32:33], v[44:45], v[8:9] op_sel_hi:[0,1,1]
	v_mov_b32_e32 v32, v22
	v_mov_b32_e32 v33, v42
	s_waitcnt vmcnt(0)
	v_pk_fma_f32 v[8:9], v[20:21], v[40:41], v[8:9] op_sel_hi:[0,1,1]
	global_load_dword v20, v[10:11], off offset:1024
	v_mov_b32_e32 v40, v24
	global_load_dword v24, v[10:11], off offset:2560
	v_mov_b32_e32 v42, v23
	s_waitcnt vmcnt(1)
	v_pk_fma_f32 v[8:9], v[20:21], v[32:33], v[8:9] op_sel_hi:[0,1,1]
	global_load_dword v20, v[10:11], off offset:1536
	global_load_dword v32, v[10:11], off offset:2048
	s_waitcnt vmcnt(1)
	v_pk_fma_f32 v[8:9], v[20:21], v[42:43], v[8:9] op_sel_hi:[0,1,1]
	ds_read_b128 v[20:23], v18 offset:1040
	s_waitcnt lgkmcnt(0)
	v_mov_b32_e32 v41, v20
	s_waitcnt vmcnt(0)
	v_pk_fma_f32 v[8:9], v[32:33], v[40:41], v[8:9] op_sel_hi:[0,1,1]
	v_mov_b32_e32 v20, v25
	v_pk_fma_f32 v[8:9], v[24:25], v[20:21], v[8:9] op_sel_hi:[0,1,1]
	global_load_dword v20, v[10:11], off offset:3072
	v_mov_b32_e32 v24, v26
	v_mov_b32_e32 v25, v22
	v_add_co_u32_e32 v26, vcc, s82, v10
	v_mov_b32_e32 v22, v27
	s_nop 0
	v_addc_co_u32_e32 v27, vcc, 0, v11, vcc
	v_mov_b32_e32 v40, v28
	global_load_dword v28, v[26:27], off offset:512
	s_waitcnt vmcnt(1)
	v_pk_fma_f32 v[8:9], v[20:21], v[24:25], v[8:9] op_sel_hi:[0,1,1]
	global_load_dword v20, v[10:11], off offset:3584
	s_waitcnt vmcnt(0)
	v_pk_fma_f32 v[24:25], v[20:21], v[22:23], v[8:9] op_sel_hi:[0,1,1]
	v_add_co_u32_e32 v8, vcc, s67, v10
	ds_read_b128 v[20:23], v18 offset:1056
	s_nop 0
	v_addc_co_u32_e32 v9, vcc, 0, v11, vcc
	global_load_dword v32, v[8:9], off offset:-4096
	s_waitcnt lgkmcnt(0)
	v_mov_b32_e32 v41, v20
	v_mov_b32_e32 v20, v29
	s_waitcnt vmcnt(0)
	v_pk_fma_f32 v[24:25], v[32:33], v[40:41], v[24:25] op_sel_hi:[0,1,1]
	s_nop 0
	v_pk_fma_f32 v[20:21], v[28:29], v[20:21], v[24:25] op_sel_hi:[0,1,1]
	global_load_dword v24, v[26:27], off offset:1024
	v_mov_b32_e32 v28, v30
	v_mov_b32_e32 v29, v22
	v_mov_b32_e32 v30, v2
	global_load_dword v2, v[26:27], off offset:2560
	v_mov_b32_e32 v22, v31
	s_waitcnt vmcnt(1)
	v_pk_fma_f32 v[20:21], v[24:25], v[28:29], v[20:21] op_sel_hi:[0,1,1]
	global_load_dword v24, v[26:27], off offset:1536
	global_load_dword v28, v[26:27], off offset:2048
	s_waitcnt vmcnt(1)
	v_pk_fma_f32 v[24:25], v[24:25], v[22:23], v[20:21] op_sel_hi:[0,1,1]
	ds_read_b128 v[20:23], v18 offset:1072
	s_waitcnt lgkmcnt(0)
	v_mov_b32_e32 v31, v20
	s_waitcnt vmcnt(0)
	v_pk_fma_f32 v[24:25], v[28:29], v[30:31], v[24:25] op_sel_hi:[0,1,1]
	v_mov_b32_e32 v20, v3
	v_pk_fma_f32 v[2:3], v[2:3], v[20:21], v[24:25] op_sel_hi:[0,1,1]
	global_load_dword v20, v[26:27], off offset:3072
	v_mov_b32_e32 v24, v4
	global_load_dword v4, v[26:27], off offset:3584
	v_mov_b32_e32 v25, v22
	v_mov_b32_e32 v22, v5
	global_load_dword v26, v[8:9], off
	s_waitcnt vmcnt(2)
	v_pk_fma_f32 v[2:3], v[20:21], v[24:25], v[2:3] op_sel_hi:[0,1,1]
	s_waitcnt vmcnt(1)
	v_pk_fma_f32 v[24:25], v[4:5], v[22:23], v[2:3] op_sel_hi:[0,1,1]
	ds_read_b128 v[2:5], v18 offset:64
	ds_read_b128 v[20:23], v18 offset:1088
	s_waitcnt lgkmcnt(1)
	v_mov_b32_e32 v28, v2
	global_load_dword v2, v[8:9], off offset:512
	s_waitcnt lgkmcnt(0)
	v_mov_b32_e32 v29, v20
	s_waitcnt vmcnt(1)
	v_pk_fma_f32 v[24:25], v[26:27], v[28:29], v[24:25] op_sel_hi:[0,1,1]
	v_mov_b32_e32 v20, v3
	global_load_dword v26, v[8:9], off offset:2048
	s_waitcnt vmcnt(1)
	v_pk_fma_f32 v[2:3], v[2:3], v[20:21], v[24:25] op_sel_hi:[0,1,1]
	global_load_dword v20, v[8:9], off offset:1024
	v_mov_b32_e32 v24, v4
	global_load_dword v4, v[8:9], off offset:1536
	v_mov_b32_e32 v25, v22
	v_mov_b32_e32 v22, v5
	s_waitcnt vmcnt(1)
	v_pk_fma_f32 v[2:3], v[20:21], v[24:25], v[2:3] op_sel_hi:[0,1,1]
	s_waitcnt vmcnt(0)
	v_pk_fma_f32 v[24:25], v[4:5], v[22:23], v[2:3] op_sel_hi:[0,1,1]
	ds_read_b128 v[2:5], v18 offset:80
	ds_read_b128 v[20:23], v18 offset:1104
	s_waitcnt lgkmcnt(1)
	v_mov_b32_e32 v28, v2
	global_load_dword v2, v[8:9], off offset:2560
	s_waitcnt lgkmcnt(0)
	v_mov_b32_e32 v29, v20
	v_pk_fma_f32 v[24:25], v[26:27], v[28:29], v[24:25] op_sel_hi:[0,1,1]
	v_mov_b32_e32 v20, v3
	s_waitcnt vmcnt(0)
	v_pk_fma_f32 v[2:3], v[2:3], v[20:21], v[24:25] op_sel_hi:[0,1,1]
	global_load_dword v20, v[8:9], off offset:3072
	v_mov_b32_e32 v24, v4
	global_load_dword v4, v[8:9], off offset:3584
	v_mov_b32_e32 v25, v22
	v_mov_b32_e32 v22, v5
	s_waitcnt vmcnt(1)
	v_pk_fma_f32 v[2:3], v[20:21], v[24:25], v[2:3] op_sel_hi:[0,1,1]
	s_waitcnt vmcnt(0)
	v_pk_fma_f32 v[20:21], v[4:5], v[22:23], v[2:3] op_sel_hi:[0,1,1]
	v_add_co_u32_e32 v22, vcc, s83, v10
	s_nop 1
	v_addc_co_u32_e32 v23, vcc, 0, v11, vcc
	global_load_dword v24, v[22:23], off
	ds_read_b128 v[2:5], v18 offset:96
	ds_read_b128 v[8:11], v18 offset:1120
	s_waitcnt lgkmcnt(1)
	v_mov_b32_e32 v26, v2
	global_load_dword v2, v[22:23], off offset:512
	s_waitcnt lgkmcnt(0)
	v_mov_b32_e32 v27, v8
	v_mov_b32_e32 v8, v3
	s_waitcnt vmcnt(1)
	v_pk_fma_f32 v[20:21], v[24:25], v[26:27], v[20:21] op_sel_hi:[0,1,1]
	global_load_dword v24, v[22:23], off offset:2048
	s_waitcnt vmcnt(1)
	v_pk_fma_f32 v[2:3], v[2:3], v[8:9], v[20:21] op_sel_hi:[0,1,1]
	global_load_dword v8, v[22:23], off offset:1024
	v_mov_b32_e32 v20, v4
	global_load_dword v4, v[22:23], off offset:1536
	v_mov_b32_e32 v21, v10
	v_mov_b32_e32 v10, v5
	s_waitcnt vmcnt(1)
	v_pk_fma_f32 v[2:3], v[8:9], v[20:21], v[2:3] op_sel_hi:[0,1,1]
	s_waitcnt vmcnt(0)
	v_pk_fma_f32 v[20:21], v[4:5], v[10:11], v[2:3] op_sel_hi:[0,1,1]
	ds_read_b128 v[2:5], v18 offset:112
	ds_read_b128 v[8:11], v18 offset:1136
	v_add_u32_e32 v18, 0x80, v18
	s_waitcnt lgkmcnt(1)
	v_mov_b32_e32 v26, v2
	global_load_dword v2, v[22:23], off offset:2560
	s_waitcnt lgkmcnt(0)
	v_mov_b32_e32 v27, v8
	v_pk_fma_f32 v[20:21], v[24:25], v[26:27], v[20:21] op_sel_hi:[0,1,1]
	v_mov_b32_e32 v8, v3
	s_waitcnt vmcnt(0)
	v_pk_fma_f32 v[2:3], v[2:3], v[8:9], v[20:21] op_sel_hi:[0,1,1]
	global_load_dword v8, v[22:23], off offset:3072
	v_mov_b32_e32 v20, v4
	global_load_dword v4, v[22:23], off offset:3584
	v_mov_b32_e32 v21, v10
	v_mov_b32_e32 v10, v5
	s_waitcnt vmcnt(1)
	v_pk_fma_f32 v[2:3], v[8:9], v[20:21], v[2:3] op_sel_hi:[0,1,1]
	s_waitcnt vmcnt(0)
	v_pk_fma_f32 v[8:9], v[4:5], v[10:11], v[2:3] op_sel_hi:[0,1,1]
	s_cbranch_scc0 .LBB0_1001
	v_lshl_add_u32 v5, v13, 2, 0
	v_lshl_add_u32 v4, v12, 2, 0
	v_mad_u64_u32 v[10:11], s[10:11], v12, 28, v[4:5]
	s_movk_i32 s10, 0xffe4
	v_add_u32_e32 v13, 4, v12
	v_mad_u64_u32 v[2:3], s[10:11], v12, s10, v[10:11]
	v_add_u32_e32 v11, 0x2000, v4
	ds_read2st64_b32 v[46:47], v5 offset0:16 offset1:18
	ds_read2st64_b32 v[44:45], v5 offset0:20 offset1:22
	ds_read2st64_b32 v[42:43], v5 offset0:24 offset1:26
	ds_read2st64_b32 v[40:41], v5 offset0:28 offset1:30
	ds_read_b128 v[4:7], v10 offset:8192
	ds_read2_b32 v[30:31], v11 offset0:88 offset1:92
	v_lshl_add_u32 v11, v13, 5, 0
	ds_read_b128 v[18:21], v11 offset:8192
	ds_read_b128 v[22:25], v10 offset:8208
	ds_read_b128 v[26:29], v11 offset:8208
	s_waitcnt lgkmcnt(4)
	v_mul_f32_e32 v10, v46, v4
	s_waitcnt lgkmcnt(3)
	v_fmac_f32_e32 v10, v8, v30
	s_waitcnt lgkmcnt(2)
	v_mul_f32_e32 v8, v46, v18
	v_fmac_f32_e32 v8, v9, v31
	v_fmac_f32_e32 v10, v47, v5
	v_fmac_f32_e32 v8, v47, v19
	v_fmac_f32_e32 v10, v44, v6
	v_fmac_f32_e32 v8, v44, v20
	v_add_u32_e32 v4, 0x2000, v2
	v_fmac_f32_e32 v10, v45, v7
	v_fmac_f32_e32 v8, v45, v21
	ds_read2_b32 v[4:5], v4 offset0:104 offset1:108
	s_waitcnt lgkmcnt(2)
	v_fmac_f32_e32 v10, v42, v22
	s_waitcnt lgkmcnt(1)
	v_fmac_f32_e32 v8, v42, v26
	v_fmac_f32_e32 v10, v43, v23
	v_fmac_f32_e32 v8, v43, v27
	v_fmac_f32_e32 v10, v40, v24
	v_fmac_f32_e32 v8, v40, v28
	v_fmac_f32_e32 v10, v41, v25
	v_fmac_f32_e32 v8, v41, v29
	s_waitcnt lgkmcnt(0)
	v_mul_f32_e32 v58, v10, v4
	v_mul_f32_e32 v57, v8, v5
	v_mul_f32_e32 v4, v58, v58
	v_mul_f32_e32 v5, v57, v57
	ds_bpermute_b32 v4, v17, v4
	ds_bpermute_b32 v5, v17, v5
	v_xor_b32_e32 v3, 8, v249
	v_cmp_lt_i32_e32 vcc, v3, v14
	v_xor_b32_e32 v8, 16, v249
	s_waitcnt lgkmcnt(1)
	v_fmac_f32_e32 v4, v58, v58
	s_waitcnt lgkmcnt(0)
	v_fmac_f32_e32 v5, v57, v57
	ds_bpermute_b32 v6, v16, v4
	ds_bpermute_b32 v7, v16, v5
	v_cndmask_b32_e32 v3, v249, v3, vcc
	v_lshlrev_b32_e32 v3, 2, v3
	v_cmp_lt_i32_e32 vcc, v8, v14
	s_waitcnt lgkmcnt(1)
	v_add_f32_e32 v4, v4, v6
	s_waitcnt lgkmcnt(0)
	v_add_f32_e32 v5, v5, v7
	ds_bpermute_b32 v6, v15, v4
	ds_bpermute_b32 v7, v15, v5
	v_cndmask_b32_e32 v8, v249, v8, vcc
	v_lshlrev_b32_e32 v60, 3, v12
	v_lshlrev_b32_e32 v59, 3, v13
	s_waitcnt lgkmcnt(1)
	v_add_f32_e32 v4, v4, v6
	s_waitcnt lgkmcnt(0)
	v_add_f32_e32 v5, v5, v7
	ds_bpermute_b32 v6, v3, v4
	ds_bpermute_b32 v3, v3, v5
	v_lshlrev_b32_e32 v7, 2, v8
	v_xor_b32_e32 v8, 32, v249
	v_cmp_lt_i32_e32 vcc, v8, v14
	s_waitcnt lgkmcnt(1)
	v_add_f32_e32 v4, v4, v6
	s_waitcnt lgkmcnt(0)
	v_add_f32_e32 v5, v5, v3
	ds_bpermute_b32 v6, v7, v4
	ds_bpermute_b32 v7, v7, v5
	v_cndmask_b32_e32 v3, v249, v8, vcc
	v_lshlrev_b32_e32 v8, 2, v3
	v_cmp_eq_u32_e32 vcc, 0, v1
	s_waitcnt lgkmcnt(1)
	v_add_f32_e32 v3, v4, v6
	s_waitcnt lgkmcnt(0)
	v_add_f32_e32 v5, v5, v7
	ds_bpermute_b32 v4, v8, v3
	ds_bpermute_b32 v6, v8, v5
	s_and_saveexec_b64 s[10:11], vcc
	s_cbranch_execz .LBB0_1004
	v_readlane_b32 s21, v253, 23
	s_waitcnt lgkmcnt(1)
	v_add_f32_e32 v3, v3, v4
	s_waitcnt lgkmcnt(0)
	v_add_f32_e32 v5, v5, v6
	v_add_u32_e32 v4, s21, v60
	ds_write_b32 v4, v3 offset:8640
	v_add_u32_e32 v3, s21, v59
	ds_write_b32 v3, v5 offset:8640

.LBB0_1014:
	v_ashrrev_i32_e32 v2, 7, v6
	v_ashrrev_i32_e32 v3, 31, v2
	v_lshlrev_b64 v[8:9], 6, v[2:3]
	v_lshrrev_b32_e32 v10, 1, v6
	v_and_b32_e32 v82, 56, v10
	v_lshl_add_u64 v[10:11], s[12:13], 0, v[8:9]
	v_lshl_add_u64 v[12:13], s[14:15], 0, v[8:9]
	v_lshl_add_u64 v[8:9], s[16:17], 0, v[8:9]
	v_lshl_add_u64 v[10:11], v[10:11], 0, v[82:83]
	v_lshl_add_u64 v[12:13], v[12:13], 0, v[82:83]
	v_lshl_add_u64 v[8:9], v[8:9], 0, v[82:83]
	global_load_dwordx2 v[10:11], v[10:11], off
	v_add_u32_e32 v6, 0x200, v6
	global_load_dwordx2 v[12:13], v[12:13], off
	s_nop 0
	global_load_dwordx2 v[8:9], v[8:9], off
	s_waitcnt vmcnt(0)
	v_max3_f32 v14, v10, v12, v8
	v_sub_f32_e32 v10, v10, v14
	v_sub_f32_e32 v12, v12, v14
	v_sub_f32_e32 v8, v8, v14
	v_exp_f32_e32 v10, v10
	v_exp_f32_e32 v15, v12
	v_exp_f32_e32 v14, v8
	v_mov_b32_e32 v12, v9
	v_fma_f32 v8, v11, v10, 0
	v_mul_f32_e32 v18, v11, v10
	v_pk_mul_f32 v[20:21], v[12:13], v[14:15]
	s_nop 0
	v_add_f32_e32 v8, v21, v8
	v_add_f32_e32 v8, v20, v8
	v_div_scale_f32 v9, s[24:25], v8, v8, 1.0
	v_rcp_f32_e32 v10, v9
	s_nop 0
	v_fma_f32 v11, -v9, v10, 1.0
	v_fmac_f32_e32 v10, v11, v10
	v_div_scale_f32 v11, vcc, 1.0, v8, 1.0
	v_mul_f32_e32 v12, v11, v10
	v_fma_f32 v13, -v9, v12, v11
	v_fmac_f32_e32 v12, v13, v10
	v_fma_f32 v9, -v9, v12, v11
	v_div_fmas_f32 v9, v9, v10, v12
	v_div_fixup_f32 v23, v9, v8, 1.0
	v_lshlrev_b64 v[8:9], 11, v[2:3]
	v_and_b32_e32 v10, 0x3f8, v5
	v_lshl_add_u64 v[8:9], s[10:11], 0, v[8:9]
	v_lshlrev_b32_e32 v82, 1, v10
	v_lshl_add_u64 v[16:17], v[8:9], 0, v[82:83]
	v_add_co_u32_e32 v12, vcc, s56, v16
	global_load_dwordx4 v[8:11], v[16:17], off
	s_nop 0
	v_addc_co_u32_e32 v13, vcc, 0, v17, vcc
	global_load_dwordx4 v[12:15], v[12:13], off
	v_add_co_u32_e32 v16, vcc, s57, v16
	v_mul_f32_e32 v22, v18, v23
	s_nop 0
	v_addc_co_u32_e32 v17, vcc, 0, v17, vcc
	global_load_dwordx4 v[16:19], v[16:17], off
	v_mul_f32_e32 v24, v21, v23
	v_mul_f32_e32 v20, v20, v23
	v_lshlrev_b64 v[2:3], 12, v[2:3]
	v_lshl_add_u64 v[2:3], s[88:89], 0, v[2:3]
	v_lshl_add_u64 v[2:3], v[2:3], 0, v[82:83]
	v_add_co_u32_e32 v2, vcc, 0x1b81e000, v2
	v_add_u32_e32 v5, 0x1000, v5
	s_nop 0
	v_addc_co_u32_e32 v3, vcc, 0, v3, vcc
	v_add_co_u32_e32 v7, vcc, 1, v7
	s_or_b64 s[20:21], vcc, s[20:21]
	s_waitcnt vmcnt(2)
	v_lshlrev_b32_e32 v27, 16, v9
	v_lshlrev_b32_e32 v26, 16, v8
	v_and_b32_e32 v9, 0xffff0000, v9
	v_and_b32_e32 v8, 0xffff0000, v8
	v_pk_fma_f32 v[8:9], v[22:23], v[8:9], 0 op_sel_hi:[0,1,0]
	s_waitcnt vmcnt(1)
	v_lshlrev_b32_e32 v29, 16, v13
	v_lshlrev_b32_e32 v28, 16, v12
	v_and_b32_e32 v13, 0xffff0000, v13
	v_and_b32_e32 v12, 0xffff0000, v12
	v_pk_fma_f32 v[8:9], v[24:25], v[12:13], v[8:9] op_sel_hi:[0,1,1]
	s_waitcnt vmcnt(0)
	v_lshlrev_b32_e32 v13, 16, v17
	v_lshlrev_b32_e32 v12, 16, v16
	v_and_b32_e32 v17, 0xffff0000, v17
	v_and_b32_e32 v16, 0xffff0000, v16
	v_pk_fma_f32 v[8:9], v[20:21], v[16:17], v[8:9] op_sel_hi:[0,1,1]
	v_lshlrev_b32_e32 v17, 16, v11
	v_lshlrev_b32_e32 v16, 16, v10
	v_and_b32_e32 v11, 0xffff0000, v11
	v_and_b32_e32 v10, 0xffff0000, v10
	v_pk_fma_f32 v[26:27], v[22:23], v[26:27], 0 op_sel_hi:[0,1,0]
	v_pk_fma_f32 v[16:17], v[22:23], v[16:17], 0 op_sel_hi:[0,1,0]
	v_pk_fma_f32 v[10:11], v[22:23], v[10:11], 0 op_sel_hi:[0,1,0]
	v_lshlrev_b32_e32 v23, 16, v15
	v_lshlrev_b32_e32 v22, 16, v14
	v_and_b32_e32 v15, 0xffff0000, v15
	v_and_b32_e32 v14, 0xffff0000, v14
	v_pk_fma_f32 v[16:17], v[24:25], v[22:23], v[16:17] op_sel_hi:[0,1,1]
	v_pk_fma_f32 v[10:11], v[24:25], v[14:15], v[10:11] op_sel_hi:[0,1,1]
	v_lshlrev_b32_e32 v15, 16, v19
	v_lshlrev_b32_e32 v14, 16, v18
	v_pk_fma_f32 v[14:15], v[20:21], v[14:15], v[16:17] op_sel_hi:[0,1,1]
	v_and_b32_e32 v17, 0xffff0000, v19
	v_and_b32_e32 v16, 0xffff0000, v18
	v_pk_fma_f32 v[26:27], v[24:25], v[28:29], v[26:27] op_sel_hi:[0,1,1]
	v_pk_fma_f32 v[10:11], v[20:21], v[16:17], v[10:11] op_sel_hi:[0,1,1]
	v_pk_fma_f32 v[12:13], v[20:21], v[12:13], v[26:27] op_sel_hi:[0,1,1]
	s_nop 0
	s_nop 0
	v_cvt_pk_bf16_f32 v11, v15, v11
	v_cvt_pk_bf16_f32 v10, v14, v10
	v_cvt_pk_bf16_f32 v9, v13, v9
	v_cvt_pk_bf16_f32 v8, v12, v8
	global_store_dwordx4 v[2:3], v[8:11], off offset:2048
	s_andn2_b64 exec, exec, s[20:21]
	s_cbranch_execnz .LBB0_1014
	s_or_b64 exec, exec, s[20:21]

.LBB0_1018:
	v_ashrrev_i32_e32 v4, 7, v6
	v_ashrrev_i32_e32 v5, 31, v4
	v_lshlrev_b64 v[2:3], 6, v[4:5]
	v_lshrrev_b32_e32 v8, 1, v6
	v_and_b32_e32 v82, 56, v8
	v_lshl_add_u64 v[8:9], s[12:13], 0, v[2:3]
	v_lshl_add_u64 v[10:11], s[14:15], 0, v[2:3]
	v_lshl_add_u64 v[2:3], s[16:17], 0, v[2:3]
	v_lshl_add_u64 v[8:9], v[8:9], 0, v[82:83]
	v_lshl_add_u64 v[10:11], v[10:11], 0, v[82:83]
	v_lshl_add_u64 v[2:3], v[2:3], 0, v[82:83]
	global_load_dwordx2 v[8:9], v[8:9], off
	s_nop 0
	global_load_dwordx2 v[10:11], v[10:11], off
	s_nop 0
	global_load_dwordx2 v[2:3], v[2:3], off
	s_waitcnt vmcnt(0)
	v_max3_f32 v12, v8, v10, v2
	v_sub_f32_e32 v8, v8, v12
	v_sub_f32_e32 v10, v10, v12
	v_sub_f32_e32 v2, v2, v12
	v_exp_f32_e32 v8, v8
	v_exp_f32_e32 v13, v10
	v_exp_f32_e32 v12, v2
	v_mov_b32_e32 v10, v3
	v_fma_f32 v2, v9, v8, 0
	v_mul_f32_e32 v14, v9, v8
	v_pk_mul_f32 v[20:21], v[10:11], v[12:13]
	s_nop 0
	v_add_f32_e32 v2, v21, v2
	v_add_f32_e32 v2, v20, v2
	v_div_scale_f32 v3, s[20:21], v2, v2, 1.0
	v_rcp_f32_e32 v8, v3
	s_nop 0
	v_fma_f32 v9, -v3, v8, 1.0
	v_fmac_f32_e32 v8, v9, v8
	v_div_scale_f32 v9, vcc, 1.0, v2, 1.0
	v_mul_f32_e32 v10, v9, v8
	v_fma_f32 v11, -v3, v10, v9
	v_fmac_f32_e32 v10, v11, v8
	v_fma_f32 v3, -v3, v10, v9
	v_div_fmas_f32 v3, v3, v8, v10
	v_div_fixup_f32 v23, v3, v2, 1.0
	v_lshlrev_b64 v[2:3], 11, v[4:5]
	v_lshl_add_u64 v[8:9], s[10:11], 0, v[2:3]
	v_and_b32_e32 v2, 0x3f8, v7
	v_lshlrev_b32_e32 v2, 1, v2
	v_mov_b32_e32 v3, v83
	v_lshl_add_u64 v[16:17], v[8:9], 0, v[2:3]
	v_add_co_u32_e32 v12, vcc, s56, v16
	global_load_dwordx4 v[8:11], v[16:17], off
	s_nop 0
	v_addc_co_u32_e32 v13, vcc, 0, v17, vcc
	v_mul_f32_e32 v22, v14, v23
	global_load_dwordx4 v[12:15], v[12:13], off
	v_add_co_u32_e32 v16, vcc, s57, v16
	v_mul_f32_e32 v24, v21, v23
	s_nop 0
	v_addc_co_u32_e32 v17, vcc, 0, v17, vcc
	global_load_dwordx4 v[16:19], v[16:17], off
	v_mul_f32_e32 v20, v20, v23
	v_lshlrev_b64 v[4:5], 12, v[4:5]
	v_lshl_add_u64 v[4:5], s[88:89], 0, v[4:5]
	v_lshl_add_u64 v[4:5], v[4:5], 0, v[2:3]
	v_add_co_u32_e32 v4, vcc, s62, v4
	v_add_u32_e32 v7, 0x4000, v7
	s_nop 0
	v_addc_co_u32_e32 v5, vcc, 0, v5, vcc
	s_waitcnt vmcnt(2)
	v_lshlrev_b32_e32 v27, 16, v9
	v_lshlrev_b32_e32 v26, 16, v8
	v_and_b32_e32 v9, 0xffff0000, v9
	v_and_b32_e32 v8, 0xffff0000, v8
	v_pk_fma_f32 v[8:9], v[22:23], v[8:9], 0 op_sel_hi:[0,1,0]
	s_waitcnt vmcnt(1)
	v_lshlrev_b32_e32 v29, 16, v13
	v_lshlrev_b32_e32 v28, 16, v12
	v_and_b32_e32 v13, 0xffff0000, v13
	v_and_b32_e32 v12, 0xffff0000, v12
	v_pk_fma_f32 v[8:9], v[24:25], v[12:13], v[8:9] op_sel_hi:[0,1,1]
	s_waitcnt vmcnt(0)
	v_lshlrev_b32_e32 v13, 16, v17
	v_lshlrev_b32_e32 v12, 16, v16
	v_and_b32_e32 v17, 0xffff0000, v17
	v_and_b32_e32 v16, 0xffff0000, v16
	v_pk_fma_f32 v[8:9], v[20:21], v[16:17], v[8:9] op_sel_hi:[0,1,1]
	v_lshlrev_b32_e32 v17, 16, v11
	v_lshlrev_b32_e32 v16, 16, v10
	v_and_b32_e32 v11, 0xffff0000, v11
	v_and_b32_e32 v10, 0xffff0000, v10
	v_pk_fma_f32 v[26:27], v[22:23], v[26:27], 0 op_sel_hi:[0,1,0]
	v_pk_fma_f32 v[16:17], v[22:23], v[16:17], 0 op_sel_hi:[0,1,0]
	v_pk_fma_f32 v[10:11], v[22:23], v[10:11], 0 op_sel_hi:[0,1,0]
	v_lshlrev_b32_e32 v23, 16, v15
	v_lshlrev_b32_e32 v22, 16, v14
	v_and_b32_e32 v15, 0xffff0000, v15
	v_and_b32_e32 v14, 0xffff0000, v14
	v_pk_fma_f32 v[16:17], v[24:25], v[22:23], v[16:17] op_sel_hi:[0,1,1]
	v_pk_fma_f32 v[10:11], v[24:25], v[14:15], v[10:11] op_sel_hi:[0,1,1]
	v_lshlrev_b32_e32 v15, 16, v19
	v_lshlrev_b32_e32 v14, 16, v18
	v_pk_fma_f32 v[14:15], v[20:21], v[14:15], v[16:17] op_sel_hi:[0,1,1]
	v_and_b32_e32 v17, 0xffff0000, v19
	v_and_b32_e32 v16, 0xffff0000, v18
	v_pk_fma_f32 v[26:27], v[24:25], v[28:29], v[26:27] op_sel_hi:[0,1,1]
	v_pk_fma_f32 v[10:11], v[20:21], v[16:17], v[10:11] op_sel_hi:[0,1,1]
	v_pk_fma_f32 v[12:13], v[20:21], v[12:13], v[26:27] op_sel_hi:[0,1,1]
	v_cvt_pk_bf16_f32 v11, v15, v11
	v_cvt_pk_bf16_f32 v10, v14, v10
	v_cvt_pk_bf16_f32 v9, v13, v9
	v_cvt_pk_bf16_f32 v8, v12, v8
	global_store_dwordx4 v[4:5], v[8:11], off offset:2048
	s_nop 1
	v_add_u32_e32 v4, 0x200, v6
	v_ashrrev_i32_e32 v4, 7, v4
	v_ashrrev_i32_e32 v5, 31, v4
	v_lshlrev_b64 v[8:9], 6, v[4:5]
	v_lshl_add_u64 v[10:11], s[12:13], 0, v[8:9]
	v_lshl_add_u64 v[12:13], s[14:15], 0, v[8:9]
	v_lshl_add_u64 v[8:9], s[16:17], 0, v[8:9]
	v_lshl_add_u64 v[10:11], v[10:11], 0, v[82:83]
	v_lshl_add_u64 v[12:13], v[12:13], 0, v[82:83]
	v_lshl_add_u64 v[8:9], v[8:9], 0, v[82:83]
	global_load_dwordx2 v[10:11], v[10:11], off
	s_nop 0
	global_load_dwordx2 v[12:13], v[12:13], off
	s_nop 0
	global_load_dwordx2 v[8:9], v[8:9], off
	s_waitcnt vmcnt(0)
	v_max3_f32 v14, v10, v12, v8
	v_sub_f32_e32 v10, v10, v14
	v_sub_f32_e32 v12, v12, v14
	v_sub_f32_e32 v8, v8, v14
	v_exp_f32_e32 v10, v10
	v_exp_f32_e32 v15, v12
	v_exp_f32_e32 v14, v8
	v_mov_b32_e32 v12, v9
	v_fma_f32 v8, v11, v10, 0
	v_mul_f32_e32 v18, v11, v10
	v_pk_mul_f32 v[20:21], v[12:13], v[14:15]
	s_nop 0
	v_add_f32_e32 v8, v21, v8
	v_add_f32_e32 v8, v20, v8
	v_div_scale_f32 v9, s[20:21], v8, v8, 1.0
	v_rcp_f32_e32 v10, v9
	s_nop 0
	v_fma_f32 v11, -v9, v10, 1.0
	v_fmac_f32_e32 v10, v11, v10
	v_div_scale_f32 v11, vcc, 1.0, v8, 1.0
	v_mul_f32_e32 v12, v11, v10
	v_fma_f32 v13, -v9, v12, v11
	v_fmac_f32_e32 v12, v13, v10
	v_fma_f32 v9, -v9, v12, v11
	v_div_fmas_f32 v9, v9, v10, v12
	v_div_fixup_f32 v23, v9, v8, 1.0
	v_lshlrev_b64 v[8:9], 11, v[4:5]
	v_lshl_add_u64 v[8:9], s[10:11], 0, v[8:9]
	v_lshl_add_u64 v[16:17], v[8:9], 0, v[2:3]
	v_add_co_u32_e32 v12, vcc, s56, v16
	global_load_dwordx4 v[8:11], v[16:17], off
	s_nop 0
	v_addc_co_u32_e32 v13, vcc, 0, v17, vcc
	global_load_dwordx4 v[12:15], v[12:13], off
	v_add_co_u32_e32 v16, vcc, s57, v16
	v_mul_f32_e32 v22, v18, v23
	s_nop 0
	v_addc_co_u32_e32 v17, vcc, 0, v17, vcc
	global_load_dwordx4 v[16:19], v[16:17], off
	v_mul_f32_e32 v24, v21, v23
	v_mul_f32_e32 v20, v20, v23
	v_lshlrev_b64 v[4:5], 12, v[4:5]
	v_lshl_add_u64 v[4:5], s[88:89], 0, v[4:5]
	v_lshl_add_u64 v[4:5], v[4:5], 0, v[2:3]
	v_add_co_u32_e32 v4, vcc, s62, v4
	s_waitcnt vmcnt(2)
	v_lshlrev_b32_e32 v27, 16, v9
	v_lshlrev_b32_e32 v26, 16, v8
	v_and_b32_e32 v9, 0xffff0000, v9
	v_and_b32_e32 v8, 0xffff0000, v8
	v_pk_fma_f32 v[8:9], v[22:23], v[8:9], 0 op_sel_hi:[0,1,0]
	s_waitcnt vmcnt(1)
	v_lshlrev_b32_e32 v29, 16, v13
	v_lshlrev_b32_e32 v28, 16, v12
	v_and_b32_e32 v13, 0xffff0000, v13
	v_and_b32_e32 v12, 0xffff0000, v12
	v_pk_fma_f32 v[8:9], v[24:25], v[12:13], v[8:9] op_sel_hi:[0,1,1]
	s_waitcnt vmcnt(0)
	v_lshlrev_b32_e32 v13, 16, v17
	v_lshlrev_b32_e32 v12, 16, v16
	v_and_b32_e32 v17, 0xffff0000, v17
	v_and_b32_e32 v16, 0xffff0000, v16
	v_pk_fma_f32 v[8:9], v[20:21], v[16:17], v[8:9] op_sel_hi:[0,1,1]
	v_lshlrev_b32_e32 v17, 16, v11
	v_lshlrev_b32_e32 v16, 16, v10
	v_and_b32_e32 v11, 0xffff0000, v11
	v_and_b32_e32 v10, 0xffff0000, v10
	v_pk_fma_f32 v[26:27], v[22:23], v[26:27], 0 op_sel_hi:[0,1,0]
	v_pk_fma_f32 v[16:17], v[22:23], v[16:17], 0 op_sel_hi:[0,1,0]
	v_pk_fma_f32 v[10:11], v[22:23], v[10:11], 0 op_sel_hi:[0,1,0]
	v_lshlrev_b32_e32 v23, 16, v15
	v_lshlrev_b32_e32 v22, 16, v14
	v_and_b32_e32 v15, 0xffff0000, v15
	v_and_b32_e32 v14, 0xffff0000, v14
	v_pk_fma_f32 v[16:17], v[24:25], v[22:23], v[16:17] op_sel_hi:[0,1,1]
	v_pk_fma_f32 v[10:11], v[24:25], v[14:15], v[10:11] op_sel_hi:[0,1,1]
	v_lshlrev_b32_e32 v15, 16, v19
	v_lshlrev_b32_e32 v14, 16, v18
	v_pk_fma_f32 v[14:15], v[20:21], v[14:15], v[16:17] op_sel_hi:[0,1,1]
	v_and_b32_e32 v17, 0xffff0000, v19
	v_and_b32_e32 v16, 0xffff0000, v18
	v_pk_fma_f32 v[26:27], v[24:25], v[28:29], v[26:27] op_sel_hi:[0,1,1]
	v_pk_fma_f32 v[10:11], v[20:21], v[16:17], v[10:11] op_sel_hi:[0,1,1]
	v_pk_fma_f32 v[12:13], v[20:21], v[12:13], v[26:27] op_sel_hi:[0,1,1]
	v_cvt_pk_bf16_f32 v11, v15, v11
	v_cvt_pk_bf16_f32 v10, v14, v10
	v_cvt_pk_bf16_f32 v9, v13, v9
	v_cvt_pk_bf16_f32 v8, v12, v8
	v_addc_co_u32_e32 v5, vcc, 0, v5, vcc
	global_store_dwordx4 v[4:5], v[8:11], off offset:2048
	s_nop 1
	v_add_u32_e32 v4, 0x400, v6
	v_ashrrev_i32_e32 v4, 7, v4
	v_ashrrev_i32_e32 v5, 31, v4
	v_lshlrev_b64 v[8:9], 6, v[4:5]
	v_lshl_add_u64 v[10:11], s[12:13], 0, v[8:9]
	v_lshl_add_u64 v[12:13], s[14:15], 0, v[8:9]
	v_lshl_add_u64 v[8:9], s[16:17], 0, v[8:9]
	v_lshl_add_u64 v[10:11], v[10:11], 0, v[82:83]
	v_lshl_add_u64 v[12:13], v[12:13], 0, v[82:83]
	v_lshl_add_u64 v[8:9], v[8:9], 0, v[82:83]
	global_load_dwordx2 v[10:11], v[10:11], off
	s_nop 0
	global_load_dwordx2 v[12:13], v[12:13], off
	s_nop 0
	global_load_dwordx2 v[8:9], v[8:9], off
	s_waitcnt vmcnt(0)
	v_max3_f32 v14, v10, v12, v8
	v_sub_f32_e32 v10, v10, v14
	v_sub_f32_e32 v12, v12, v14
	v_sub_f32_e32 v8, v8, v14
	v_exp_f32_e32 v10, v10
	v_exp_f32_e32 v15, v12
	v_exp_f32_e32 v14, v8
	v_mov_b32_e32 v12, v9
	v_fma_f32 v8, v11, v10, 0
	v_mul_f32_e32 v18, v11, v10
	v_pk_mul_f32 v[20:21], v[12:13], v[14:15]
	s_nop 0
	v_add_f32_e32 v8, v21, v8
	v_add_f32_e32 v8, v20, v8
	v_div_scale_f32 v9, s[20:21], v8, v8, 1.0
	v_rcp_f32_e32 v10, v9
	s_nop 0
	v_fma_f32 v11, -v9, v10, 1.0
	v_fmac_f32_e32 v10, v11, v10
	v_div_scale_f32 v11, vcc, 1.0, v8, 1.0
	v_mul_f32_e32 v12, v11, v10
	v_fma_f32 v13, -v9, v12, v11
	v_fmac_f32_e32 v12, v13, v10
	v_fma_f32 v9, -v9, v12, v11
	v_div_fmas_f32 v9, v9, v10, v12
	v_div_fixup_f32 v23, v9, v8, 1.0
	v_lshlrev_b64 v[8:9], 11, v[4:5]
	v_lshl_add_u64 v[8:9], s[10:11], 0, v[8:9]
	v_lshl_add_u64 v[16:17], v[8:9], 0, v[2:3]
	v_add_co_u32_e32 v12, vcc, s56, v16
	global_load_dwordx4 v[8:11], v[16:17], off
	s_nop 0
	v_addc_co_u32_e32 v13, vcc, 0, v17, vcc
	global_load_dwordx4 v[12:15], v[12:13], off
	v_add_co_u32_e32 v16, vcc, s57, v16
	v_mul_f32_e32 v22, v18, v23
	s_nop 0
	v_addc_co_u32_e32 v17, vcc, 0, v17, vcc
	global_load_dwordx4 v[16:19], v[16:17], off
	v_mul_f32_e32 v24, v21, v23
	v_mul_f32_e32 v20, v20, v23
	v_lshlrev_b64 v[4:5], 12, v[4:5]
	v_lshl_add_u64 v[4:5], s[88:89], 0, v[4:5]
	v_lshl_add_u64 v[4:5], v[4:5], 0, v[2:3]
	v_add_co_u32_e32 v4, vcc, s62, v4
	s_waitcnt vmcnt(2)
	v_lshlrev_b32_e32 v27, 16, v9
	v_lshlrev_b32_e32 v26, 16, v8
	v_and_b32_e32 v9, 0xffff0000, v9
	v_and_b32_e32 v8, 0xffff0000, v8
	v_pk_fma_f32 v[8:9], v[22:23], v[8:9], 0 op_sel_hi:[0,1,0]
	s_waitcnt vmcnt(1)
	v_lshlrev_b32_e32 v29, 16, v13
	v_lshlrev_b32_e32 v28, 16, v12
	v_and_b32_e32 v13, 0xffff0000, v13
	v_and_b32_e32 v12, 0xffff0000, v12
	v_pk_fma_f32 v[8:9], v[24:25], v[12:13], v[8:9] op_sel_hi:[0,1,1]
	s_waitcnt vmcnt(0)
	v_lshlrev_b32_e32 v13, 16, v17
	v_lshlrev_b32_e32 v12, 16, v16
	v_and_b32_e32 v17, 0xffff0000, v17
	v_and_b32_e32 v16, 0xffff0000, v16
	v_pk_fma_f32 v[8:9], v[20:21], v[16:17], v[8:9] op_sel_hi:[0,1,1]
	v_lshlrev_b32_e32 v17, 16, v11
	v_lshlrev_b32_e32 v16, 16, v10
	v_and_b32_e32 v11, 0xffff0000, v11
	v_and_b32_e32 v10, 0xffff0000, v10
	v_pk_fma_f32 v[26:27], v[22:23], v[26:27], 0 op_sel_hi:[0,1,0]
	v_pk_fma_f32 v[16:17], v[22:23], v[16:17], 0 op_sel_hi:[0,1,0]
	v_pk_fma_f32 v[10:11], v[22:23], v[10:11], 0 op_sel_hi:[0,1,0]
	v_lshlrev_b32_e32 v23, 16, v15
	v_lshlrev_b32_e32 v22, 16, v14
	v_and_b32_e32 v15, 0xffff0000, v15
	v_and_b32_e32 v14, 0xffff0000, v14
	v_pk_fma_f32 v[16:17], v[24:25], v[22:23], v[16:17] op_sel_hi:[0,1,1]
	v_pk_fma_f32 v[10:11], v[24:25], v[14:15], v[10:11] op_sel_hi:[0,1,1]
	v_lshlrev_b32_e32 v15, 16, v19
	v_lshlrev_b32_e32 v14, 16, v18
	v_pk_fma_f32 v[14:15], v[20:21], v[14:15], v[16:17] op_sel_hi:[0,1,1]
	v_and_b32_e32 v17, 0xffff0000, v19
	v_and_b32_e32 v16, 0xffff0000, v18
	v_pk_fma_f32 v[26:27], v[24:25], v[28:29], v[26:27] op_sel_hi:[0,1,1]
	v_pk_fma_f32 v[10:11], v[20:21], v[16:17], v[10:11] op_sel_hi:[0,1,1]
	v_pk_fma_f32 v[12:13], v[20:21], v[12:13], v[26:27] op_sel_hi:[0,1,1]
	v_cvt_pk_bf16_f32 v11, v15, v11
	v_cvt_pk_bf16_f32 v10, v14, v10
	v_cvt_pk_bf16_f32 v9, v13, v9
	v_cvt_pk_bf16_f32 v8, v12, v8
	v_addc_co_u32_e32 v5, vcc, 0, v5, vcc
	global_store_dwordx4 v[4:5], v[8:11], off offset:2048
	s_nop 1
	v_add_u32_e32 v4, 0x600, v6
	v_ashrrev_i32_e32 v4, 7, v4
	v_ashrrev_i32_e32 v5, 31, v4
	v_lshlrev_b64 v[8:9], 6, v[4:5]
	v_lshl_add_u64 v[10:11], s[12:13], 0, v[8:9]
	v_lshl_add_u64 v[12:13], s[14:15], 0, v[8:9]
	v_lshl_add_u64 v[8:9], s[16:17], 0, v[8:9]
	v_lshl_add_u64 v[10:11], v[10:11], 0, v[82:83]
	v_lshl_add_u64 v[12:13], v[12:13], 0, v[82:83]
	v_lshl_add_u64 v[8:9], v[8:9], 0, v[82:83]
	global_load_dwordx2 v[10:11], v[10:11], off
	v_add_u32_e32 v6, 0x800, v6
	global_load_dwordx2 v[12:13], v[12:13], off
	s_nop 0
	global_load_dwordx2 v[8:9], v[8:9], off
	s_waitcnt vmcnt(0)
	v_max3_f32 v14, v10, v12, v8
	v_sub_f32_e32 v10, v10, v14
	v_sub_f32_e32 v12, v12, v14
	v_sub_f32_e32 v8, v8, v14
	v_exp_f32_e32 v10, v10
	v_exp_f32_e32 v15, v12
	v_exp_f32_e32 v14, v8
	v_mov_b32_e32 v12, v9
	v_fma_f32 v8, v11, v10, 0
	v_mul_f32_e32 v18, v11, v10
	v_pk_mul_f32 v[20:21], v[12:13], v[14:15]
	s_nop 0
	v_add_f32_e32 v8, v21, v8
	v_add_f32_e32 v8, v20, v8
	v_div_scale_f32 v9, s[20:21], v8, v8, 1.0
	v_rcp_f32_e32 v10, v9
	s_nop 0
	v_fma_f32 v11, -v9, v10, 1.0
	v_fmac_f32_e32 v10, v11, v10
	v_div_scale_f32 v11, vcc, 1.0, v8, 1.0
	v_mul_f32_e32 v12, v11, v10
	v_fma_f32 v13, -v9, v12, v11
	v_fmac_f32_e32 v12, v13, v10
	v_fma_f32 v9, -v9, v12, v11
	v_div_fmas_f32 v9, v9, v10, v12
	v_div_fixup_f32 v23, v9, v8, 1.0
	v_lshlrev_b64 v[8:9], 11, v[4:5]
	v_lshl_add_u64 v[8:9], s[10:11], 0, v[8:9]
	v_lshl_add_u64 v[16:17], v[8:9], 0, v[2:3]
	v_add_co_u32_e32 v12, vcc, s56, v16
	global_load_dwordx4 v[8:11], v[16:17], off
	s_nop 0
	v_addc_co_u32_e32 v13, vcc, 0, v17, vcc
	global_load_dwordx4 v[12:15], v[12:13], off
	v_add_co_u32_e32 v16, vcc, s57, v16
	v_mul_f32_e32 v22, v18, v23
	s_nop 0
	v_addc_co_u32_e32 v17, vcc, 0, v17, vcc
	global_load_dwordx4 v[16:19], v[16:17], off
	v_mul_f32_e32 v24, v21, v23
	v_mul_f32_e32 v20, v20, v23
	v_lshlrev_b64 v[4:5], 12, v[4:5]
	v_lshl_add_u64 v[4:5], s[88:89], 0, v[4:5]
	v_lshl_add_u64 v[2:3], v[4:5], 0, v[2:3]
	v_add_co_u32_e32 v2, vcc, 0x1b81e000, v2
	s_waitcnt vmcnt(2)
	v_lshlrev_b32_e32 v27, 16, v9
	v_lshlrev_b32_e32 v26, 16, v8
	v_and_b32_e32 v9, 0xffff0000, v9
	v_and_b32_e32 v8, 0xffff0000, v8
	v_pk_fma_f32 v[8:9], v[22:23], v[8:9], 0 op_sel_hi:[0,1,0]
	s_waitcnt vmcnt(1)
	v_lshlrev_b32_e32 v29, 16, v13
	v_lshlrev_b32_e32 v28, 16, v12
	v_and_b32_e32 v13, 0xffff0000, v13
	v_and_b32_e32 v12, 0xffff0000, v12
	v_pk_fma_f32 v[8:9], v[24:25], v[12:13], v[8:9] op_sel_hi:[0,1,1]
	s_waitcnt vmcnt(0)
	v_lshlrev_b32_e32 v13, 16, v17
	v_lshlrev_b32_e32 v12, 16, v16
	v_and_b32_e32 v17, 0xffff0000, v17
	v_and_b32_e32 v16, 0xffff0000, v16
	v_pk_fma_f32 v[8:9], v[20:21], v[16:17], v[8:9] op_sel_hi:[0,1,1]
	v_lshlrev_b32_e32 v17, 16, v11
	v_lshlrev_b32_e32 v16, 16, v10
	v_and_b32_e32 v11, 0xffff0000, v11
	v_and_b32_e32 v10, 0xffff0000, v10
	v_pk_fma_f32 v[26:27], v[22:23], v[26:27], 0 op_sel_hi:[0,1,0]
	v_pk_fma_f32 v[16:17], v[22:23], v[16:17], 0 op_sel_hi:[0,1,0]
	v_pk_fma_f32 v[10:11], v[22:23], v[10:11], 0 op_sel_hi:[0,1,0]
	v_lshlrev_b32_e32 v23, 16, v15
	v_lshlrev_b32_e32 v22, 16, v14
	v_and_b32_e32 v15, 0xffff0000, v15
	v_and_b32_e32 v14, 0xffff0000, v14
	v_pk_fma_f32 v[16:17], v[24:25], v[22:23], v[16:17] op_sel_hi:[0,1,1]
	v_pk_fma_f32 v[10:11], v[24:25], v[14:15], v[10:11] op_sel_hi:[0,1,1]
	v_lshlrev_b32_e32 v15, 16, v19
	v_lshlrev_b32_e32 v14, 16, v18
	v_pk_fma_f32 v[14:15], v[20:21], v[14:15], v[16:17] op_sel_hi:[0,1,1]
	v_and_b32_e32 v17, 0xffff0000, v19
	v_and_b32_e32 v16, 0xffff0000, v18
	v_pk_fma_f32 v[26:27], v[24:25], v[28:29], v[26:27] op_sel_hi:[0,1,1]
	v_pk_fma_f32 v[10:11], v[20:21], v[16:17], v[10:11] op_sel_hi:[0,1,1]
	v_pk_fma_f32 v[12:13], v[20:21], v[12:13], v[26:27] op_sel_hi:[0,1,1]
	v_addc_co_u32_e32 v3, vcc, 0, v3, vcc
	v_cmp_le_i32_e32 vcc, s22, v6
	v_cvt_pk_bf16_f32 v11, v15, v11
	v_cvt_pk_bf16_f32 v10, v14, v10
	v_cvt_pk_bf16_f32 v9, v13, v9
	v_cvt_pk_bf16_f32 v8, v12, v8
	s_or_b64 s[18:19], vcc, s[18:19]
	global_store_dwordx4 v[2:3], v[8:11], off offset:2048
	s_andn2_b64 exec, exec, s[18:19]
	s_cbranch_execnz .LBB0_1018

.LBB0_1034:
	s_or_b64 exec, exec, s[8:9]
	s_add_u32 s62, s88, 0xee19000
	s_addc_u32 s63, s89, 0
	s_lshl_b32 s8, s96, 2
	v_readlane_b32 s9, v253, 16
	s_add_i32 s8, s9, s8
	s_lshl_b32 s10, s8, 3
	s_and_b32 s55, s10, 0x7fffffc0
	v_readlane_b32 s10, v253, 19
	v_lshlrev_b32_e32 v12, 4, v1
	s_and_b32 s9, s8, 7
	v_add_u32_e32 v7, s10, v1
	v_ashrrev_i32_e32 v10, 4, v7
	v_and_b32_e32 v82, 0xf0, v12
	v_readlane_b32 s10, v253, 18
	v_add_u32_e32 v2, s55, v10
	v_mov_b64_e32 v[8:9], s[62:63]
	v_add_u32_e32 v6, s10, v82
	v_mad_i64_i32 v[2:3], s[10:11], v2, s83, v[8:9]
	s_lshl_b32 s70, s9, 8
	v_lshl_add_u64 v[2:3], v[2:3], 0, s[70:71]
	v_lshl_add_u64 v[2:3], v[2:3], 0, v[82:83]
	s_barrier
	global_load_dwordx4 v[2:5], v[2:3], off offset:2048
	v_mad_u64_u32 v[10:11], s[10:11], v10, s5, v[6:7]
	s_lshl_b32 s54, s9, 7
	s_mov_b32 s9, s71
	s_waitcnt vmcnt(10)
	v_and_b32_e32 v138, 31, v1
	v_readlane_b32 s14, v253, 17
	s_mul_i32 s13, s8, 0x300
	s_load_dwordx2 s[64:65], s[40:41], 0x70
	v_or_b32_e32 v141, s14, v138
	s_mul_hi_u32 s12, s8, 0x300
	v_ashrrev_i32_e32 v143, 5, v1
	v_lshlrev_b32_e32 v134, 2, v143
	s_movk_i32 s61, 0x440
	v_ashrrev_i32_e32 v135, 31, v134
	s_mov_b32 s60, 0
	v_mov_b32_e32 v146, 0
	s_waitcnt vmcnt(0)
	ds_write_b128 v10, v[2:5]
	v_add_u32_e32 v2, 0x80, v7
	v_ashrrev_i32_e32 v10, 4, v2
	v_add_u32_e32 v2, s55, v10
	v_mad_i64_i32 v[2:3], s[10:11], v2, s83, v[8:9]
	v_lshl_add_u64 v[2:3], v[2:3], 0, s[70:71]
	v_lshl_add_u64 v[2:3], v[2:3], 0, v[82:83]
	global_load_dwordx4 v[2:5], v[2:3], off offset:2048
	v_mad_u64_u32 v[10:11], s[10:11], v10, s5, v[6:7]
	s_waitcnt vmcnt(0)
	ds_write_b128 v10, v[2:5]
	v_add_u32_e32 v2, 0x100, v7
	v_ashrrev_i32_e32 v10, 4, v2
	v_add_u32_e32 v2, s55, v10
	v_mad_i64_i32 v[2:3], s[10:11], v2, s83, v[8:9]
	v_lshl_add_u64 v[2:3], v[2:3], 0, s[70:71]
	v_lshl_add_u64 v[2:3], v[2:3], 0, v[82:83]
	global_load_dwordx4 v[2:5], v[2:3], off offset:2048
	v_mad_u64_u32 v[10:11], s[10:11], v10, s5, v[6:7]
	s_waitcnt vmcnt(0)
	ds_write_b128 v10, v[2:5]
	v_add_u32_e32 v2, 0x180, v7
	v_ashrrev_i32_e32 v10, 4, v2
	v_add_u32_e32 v2, s55, v10
	v_mad_i64_i32 v[2:3], s[10:11], v2, s83, v[8:9]
	v_lshl_add_u64 v[2:3], v[2:3], 0, s[70:71]
	v_lshl_add_u64 v[2:3], v[2:3], 0, v[82:83]
	global_load_dwordx4 v[2:5], v[2:3], off offset:2048
	v_mad_u64_u32 v[10:11], s[10:11], v10, s5, v[6:7]
	s_waitcnt vmcnt(0)
	ds_write_b128 v10, v[2:5]
	v_add_u32_e32 v2, 0x200, v7
	v_ashrrev_i32_e32 v10, 4, v2
	v_add_u32_e32 v2, s55, v10
	v_mad_i64_i32 v[2:3], s[10:11], v2, s83, v[8:9]
	v_lshl_add_u64 v[2:3], v[2:3], 0, s[70:71]
	v_lshl_add_u64 v[2:3], v[2:3], 0, v[82:83]
	global_load_dwordx4 v[2:5], v[2:3], off offset:2048
	v_mad_u64_u32 v[10:11], s[10:11], v10, s5, v[6:7]
	s_waitcnt vmcnt(0)
	ds_write_b128 v10, v[2:5]
	v_add_u32_e32 v2, 0x280, v7
	v_ashrrev_i32_e32 v10, 4, v2
	v_add_u32_e32 v2, s55, v10
	v_mad_i64_i32 v[2:3], s[10:11], v2, s83, v[8:9]
	v_lshl_add_u64 v[2:3], v[2:3], 0, s[70:71]
	v_lshl_add_u64 v[2:3], v[2:3], 0, v[82:83]
	global_load_dwordx4 v[2:5], v[2:3], off offset:2048
	v_mad_u64_u32 v[10:11], s[10:11], v10, s5, v[6:7]
	s_waitcnt vmcnt(0)
	ds_write_b128 v10, v[2:5]
	v_add_u32_e32 v2, 0x300, v7
	v_ashrrev_i32_e32 v10, 4, v2
	v_add_u32_e32 v2, s55, v10
	v_mad_i64_i32 v[2:3], s[10:11], v2, s83, v[8:9]
	v_lshl_add_u64 v[2:3], v[2:3], 0, s[70:71]
	v_lshl_add_u64 v[2:3], v[2:3], 0, v[82:83]
	global_load_dwordx4 v[2:5], v[2:3], off offset:2048
	v_mad_u64_u32 v[10:11], s[10:11], v10, s5, v[6:7]
	s_waitcnt vmcnt(0)
	ds_write_b128 v10, v[2:5]
	v_add_u32_e32 v2, 0x380, v7
	v_ashrrev_i32_e32 v7, 4, v2
	v_add_u32_e32 v2, s55, v7
	v_mad_i64_i32 v[2:3], s[10:11], v2, s83, v[8:9]
	v_lshl_add_u64 v[2:3], v[2:3], 0, s[70:71]
	v_lshl_add_u64 v[2:3], v[2:3], 0, v[82:83]
	global_load_dwordx4 v[2:5], v[2:3], off offset:2048
	v_mad_u64_u32 v[6:7], s[10:11], v7, s5, v[6:7]
	s_lshl_b64 s[10:11], s[8:9], 2
	s_add_u32 s10, s88, s10
	s_addc_u32 s11, s89, s11
	s_add_u32 s40, s88, s13
	v_lshlrev_b32_e32 v82, 2, v141
	s_addc_u32 s41, s89, s12
	s_mov_b32 s9, 0x1519d000
	s_waitcnt vmcnt(0)
	ds_write_b128 v6, v[2:5]
	v_mov_b32_e32 v2, 0x1869d000
	global_load_dword v6, v2, s[10:11]
	v_lshl_add_u64 v[2:3], s[40:41], 0, v[82:83]
	s_mov_b64 s[10:11], 0x1519d000
	v_lshl_add_u64 v[4:5], v[2:3], 0, s[10:11]
	v_add_co_u32_e32 v2, vcc, s9, v2
	s_add_u32 s10, s62, s54
	s_nop 0
	v_addc_co_u32_e32 v3, vcc, 0, v3, vcc
	global_load_dword v139, v[2:3], off
	s_nop 0
	global_load_dword v2, v[4:5], off offset:512
	s_addc_u32 s11, s63, 0
	v_and_b32_e32 v82, 0x70, v12
	v_lshl_add_u64 v[132:133], s[10:11], 0, v[82:83]
	v_readlane_b32 s9, v253, 20
	s_waitcnt vmcnt(2)
	v_max_f32_e32 v3, v6, v6
	v_add_u32_e32 v20, s9, v82
	s_waitcnt vmcnt(0)
	v_max_f32_e32 v2, v2, v2
	v_max_f32_e32 v140, v3, v2
	v_sub_f32_e32 v2, v6, v140
	v_mul_f32_e32 v3, 0x3fb8aa3b, v2
	v_ashrrev_i32_e32 v2, 3, v1
	v_add_u32_e32 v142, s55, v2
	v_add_u32_e32 v16, s14, v142
	v_mad_i64_i32 v[4:5], s[10:11], v16, s83, v[132:133]
	v_add_u32_e32 v8, 8, v16
	global_load_dwordx4 v[4:7], v[4:5], off
	v_mad_i64_i32 v[8:9], s[10:11], v8, s83, v[132:133]
	v_add_u32_e32 v12, 16, v16
	global_load_dwordx4 v[8:11], v[8:9], off
	v_mad_i64_i32 v[12:13], s[10:11], v12, s83, v[132:133]
	v_add_u32_e32 v16, 24, v16
	global_load_dwordx4 v[12:15], v[12:13], off
	v_mad_i64_i32 v[16:17], s[10:11], v16, s83, v[132:133]
	global_load_dwordx4 v[16:19], v[16:17], off
	s_movk_i32 s10, 0x90
	v_mul_lo_u32 v21, v2, s10
	v_add_u32_e32 v144, v20, v21
	s_waitcnt vmcnt(3)
	ds_write_b128 v144, v[4:7]
	s_waitcnt vmcnt(2)
	ds_write_b128 v144, v[8:11] offset:1152
	s_waitcnt vmcnt(1)
	ds_write_b128 v144, v[12:15] offset:2304
	s_waitcnt vmcnt(0)
	ds_write_b128 v144, v[16:19] offset:3456
	v_exp_f32_e32 v4, v3
	v_mov_b32_e32 v3, s9
	v_mad_u32_u24 v3, v138, s10, v3
	v_lshlrev_b32_e32 v5, 4, v143
	s_waitcnt lgkmcnt(0)
	v_add_u32_e32 v145, v3, v5
	ds_read_b128 v[96:99], v145
	ds_read_b128 v[104:107], v145 offset:32
	ds_read_b128 v[108:111], v145 offset:64
	ds_read_b128 v[112:115], v145 offset:96
	s_mul_hi_u32 s9, s8, 0x5000
	s_waitcnt lgkmcnt(0)
	v_and_b32_e32 v9, 0xffff0000, v97
	v_and_b32_e32 v8, 0xffff0000, v96
	v_and_b32_e32 v13, 0xffff0000, v99
	v_and_b32_e32 v12, 0xffff0000, v98
	v_lshlrev_b32_e32 v7, 16, v97
	v_lshlrev_b32_e32 v6, 16, v96
	v_pk_mul_f32 v[8:9], v[4:5], v[8:9] op_sel_hi:[0,1]
	v_lshlrev_b32_e32 v11, 16, v99
	v_lshlrev_b32_e32 v10, 16, v98
	v_pk_mul_f32 v[12:13], v[4:5], v[12:13] op_sel_hi:[0,1]
	v_pk_mul_f32 v[6:7], v[4:5], v[6:7] op_sel_hi:[0,1]
	v_pk_mul_f32 v[10:11], v[4:5], v[10:11] op_sel_hi:[0,1]
	v_bfe_u32 v3, v13, 16, 1
	v_bfe_u32 v5, v12, 16, 1
	v_add3_u32 v5, v12, v5, s73
	v_add3_u32 v3, v13, v3, s73
	v_bfe_u32 v14, v10, 16, 1
	v_bfe_u32 v15, v11, 16, 1
	v_add3_u32 v11, v11, v15, s73
	v_add3_u32 v10, v10, v14, s73
	v_lshrrev_b32_e32 v10, 16, v10
	v_lshrrev_b32_e32 v11, 16, v11
	v_and_b32_e32 v13, 0xffff0000, v107
	v_and_b32_e32 v12, 0xffff0000, v106
	v_and_or_b32 v91, v3, s33, v11
	v_and_or_b32 v90, v5, s33, v10
	v_cvt_pk_bf16_f32 v89, v7, v9
	v_cvt_pk_bf16_f32 v88, v6, v8
	v_lshlrev_b32_e32 v7, 16, v105
	v_lshlrev_b32_e32 v6, 16, v104
	v_and_b32_e32 v9, 0xffff0000, v105
	v_and_b32_e32 v8, 0xffff0000, v104
	v_lshlrev_b32_e32 v11, 16, v107
	v_lshlrev_b32_e32 v10, 16, v106
	v_pk_mul_f32 v[12:13], v[4:5], v[12:13] op_sel_hi:[0,1]
	v_pk_mul_f32 v[6:7], v[4:5], v[6:7] op_sel_hi:[0,1]
	v_pk_mul_f32 v[8:9], v[4:5], v[8:9] op_sel_hi:[0,1]
	v_pk_mul_f32 v[10:11], v[4:5], v[10:11] op_sel_hi:[0,1]
	v_bfe_u32 v3, v13, 16, 1
	v_bfe_u32 v5, v12, 16, 1
	v_add3_u32 v5, v12, v5, s73
	v_add3_u32 v3, v13, v3, s73
	v_bfe_u32 v14, v10, 16, 1
	v_bfe_u32 v15, v11, 16, 1
	v_add3_u32 v11, v11, v15, s73
	v_add3_u32 v10, v10, v14, s73
	v_lshrrev_b32_e32 v10, 16, v10
	v_lshrrev_b32_e32 v11, 16, v11
	v_cvt_pk_bf16_f32 v85, v7, v9
	v_cvt_pk_bf16_f32 v84, v6, v8
	v_and_b32_e32 v9, 0xffff0000, v109
	v_and_b32_e32 v8, 0xffff0000, v108
	v_and_b32_e32 v13, 0xffff0000, v111
	v_and_b32_e32 v12, 0xffff0000, v110
	v_and_or_b32 v87, v3, s33, v11
	v_and_or_b32 v86, v5, s33, v10
	v_lshlrev_b32_e32 v7, 16, v109
	v_lshlrev_b32_e32 v6, 16, v108
	v_pk_mul_f32 v[8:9], v[4:5], v[8:9] op_sel_hi:[0,1]
	v_lshlrev_b32_e32 v11, 16, v111
	v_lshlrev_b32_e32 v10, 16, v110
	v_pk_mul_f32 v[12:13], v[4:5], v[12:13] op_sel_hi:[0,1]
	v_pk_mul_f32 v[6:7], v[4:5], v[6:7] op_sel_hi:[0,1]
	v_pk_mul_f32 v[10:11], v[4:5], v[10:11] op_sel_hi:[0,1]
	v_bfe_u32 v5, v12, 16, 1
	v_add3_u32 v5, v12, v5, s73
	v_bfe_u32 v14, v10, 16, 1
	v_add3_u32 v10, v10, v14, s73
	v_lshrrev_b32_e32 v10, 16, v10
	v_cvt_pk_bf16_f32 v95, v11, v13
	v_and_or_b32 v94, v5, s33, v10
	v_cvt_pk_bf16_f32 v93, v7, v9
	v_cvt_pk_bf16_f32 v92, v6, v8
	v_lshlrev_b32_e32 v7, 16, v113
	v_lshlrev_b32_e32 v6, 16, v112
	v_and_b32_e32 v9, 0xffff0000, v113
	v_and_b32_e32 v8, 0xffff0000, v112
	v_lshlrev_b32_e32 v11, 16, v115
	v_lshlrev_b32_e32 v10, 16, v114
	v_and_b32_e32 v13, 0xffff0000, v115
	v_and_b32_e32 v12, 0xffff0000, v114
	v_pk_mul_f32 v[6:7], v[4:5], v[6:7] op_sel_hi:[0,1]
	v_pk_mul_f32 v[8:9], v[4:5], v[8:9] op_sel_hi:[0,1]
	v_pk_mul_f32 v[10:11], v[4:5], v[10:11] op_sel_hi:[0,1]
	v_pk_mul_f32 v[4:5], v[4:5], v[12:13] op_sel_hi:[0,1]
	s_nop 0
	v_bfe_u32 v12, v4, 16, 1
	v_bfe_u32 v13, v9, 16, 1
	v_bfe_u32 v14, v8, 16, 1
	v_bfe_u32 v3, v5, 16, 1
	v_add3_u32 v8, v8, v14, s73
	v_add3_u32 v9, v9, v13, s73
	v_add3_u32 v4, v4, v12, s73
	v_bfe_u32 v12, v7, 16, 1
	v_bfe_u32 v13, v10, 16, 1
	v_bfe_u32 v14, v11, 16, 1
	v_add3_u32 v3, v5, v3, s73
	v_bfe_u32 v5, v6, 16, 1
	v_add3_u32 v11, v11, v14, s73
	v_add3_u32 v10, v10, v13, s73
	v_add3_u32 v7, v7, v12, s73
	s_mulk_i32 s8, 0x5000
	v_add3_u32 v5, v6, v5, s73
	v_lshrrev_b32_e32 v6, 16, v7
	v_lshrrev_b32_e32 v7, 16, v10
	v_lshrrev_b32_e32 v10, 16, v11
	s_add_u32 s8, s88, s8
	v_lshrrev_b32_e32 v5, 16, v5
	v_and_or_b32 v103, v3, s33, v10
	s_addc_u32 s9, s89, s9
	v_ashrrev_i32_e32 v3, 31, v2
	v_and_or_b32 v102, v4, s33, v7
	v_and_or_b32 v100, v8, s33, v5
	v_lshl_add_u64 v[4:5], s[8:9], 0, v[82:83]
	v_lshlrev_b64 v[2:3], 7, v[2:3]
	v_lshl_add_u64 v[66:67], v[4:5], 0, v[2:3]
	s_mov_b64 s[8:9], 0x1729d000
	v_lshl_add_u64 v[14:15], v[66:67], 0, s[8:9]
	s_mov_b32 s8, 0x1729e000
	v_add_co_u32_e32 v30, vcc, s8, v66
	v_and_or_b32 v101, v9, s33, v6
	s_nop 0
	v_addc_co_u32_e32 v31, vcc, 0, v67, vcc
	global_load_dwordx4 v[2:5], v[30:31], off offset:-4096
	global_load_dwordx4 v[6:9], v[14:15], off offset:1024
	global_load_dwordx4 v[10:13], v[14:15], off offset:2048
	s_nop 0
	global_load_dwordx4 v[14:17], v[14:15], off offset:3072
	s_waitcnt vmcnt(3)
	ds_write_b128 v144, v[2:5]
	s_waitcnt vmcnt(2)
	ds_write_b128 v144, v[6:9] offset:1152
	s_waitcnt vmcnt(1)
	ds_write_b128 v144, v[10:13] offset:2304
	s_waitcnt vmcnt(0)
	ds_write_b128 v144, v[14:17] offset:3456
	s_waitcnt lgkmcnt(0)
	ds_read_b128 v[2:5], v145
	ds_read_b128 v[18:21], v145 offset:32
	s_waitcnt lgkmcnt(1)
	v_mfma_f32_32x32x16_bf16 v[2:17], v[2:5], v[88:91], 0
	s_mov_b32 s8, 0x1729f000
	v_add_co_u32_e32 v46, vcc, s8, v66
	s_mov_b32 s8, 0x172a0000
	s_nop 0
	v_addc_co_u32_e32 v47, vcc, 0, v67, vcc
	v_add_co_u32_e32 v62, vcc, s8, v66
	s_waitcnt lgkmcnt(0)
	v_mfma_f32_32x32x16_bf16 v[2:17], v[18:21], v[84:87], v[2:17]
	ds_read_b128 v[18:21], v145 offset:64
	v_addc_co_u32_e32 v63, vcc, 0, v67, vcc
	s_mov_b32 s8, 0x172a1000
	v_add_co_u32_e32 v78, vcc, s8, v66
	v_cmp_lt_i32_e64 s[8:9], v134, v138
	s_waitcnt lgkmcnt(0)
	v_mfma_f32_32x32x16_bf16 v[2:17], v[18:21], v[92:95], v[2:17]
	ds_read_b128 v[18:21], v145 offset:96
	v_addc_co_u32_e32 v79, vcc, 0, v67, vcc
	v_cmp_le_i32_e32 vcc, v134, v138
	s_waitcnt lgkmcnt(0)
	v_mfma_f32_32x32x16_bf16 v[2:17], v[18:21], v[100:103], v[2:17]
	global_load_dwordx4 v[18:21], v[30:31], off
	global_load_dwordx4 v[22:25], v[30:31], off offset:1024
	global_load_dwordx4 v[26:29], v[30:31], off offset:2048
	s_nop 0
	global_load_dwordx4 v[30:33], v[30:31], off offset:3072
	s_waitcnt vmcnt(3)
	ds_write_b128 v144, v[18:21]
	s_waitcnt vmcnt(2)
	ds_write_b128 v144, v[22:25] offset:1152
	s_waitcnt vmcnt(1)
	ds_write_b128 v144, v[26:29] offset:2304
	s_waitcnt vmcnt(0)
	ds_write_b128 v144, v[30:33] offset:3456
	s_waitcnt lgkmcnt(0)
	ds_read_b128 v[18:21], v145
	ds_read_b128 v[34:37], v145 offset:32
	s_waitcnt lgkmcnt(1)
	v_mfma_f32_32x32x16_bf16 v[18:33], v[18:21], v[88:91], 0
	s_waitcnt lgkmcnt(0)
	v_mfma_f32_32x32x16_bf16 v[18:33], v[34:37], v[84:87], v[18:33]
	ds_read_b128 v[34:37], v145 offset:64
	s_waitcnt lgkmcnt(0)
	v_mfma_f32_32x32x16_bf16 v[18:33], v[34:37], v[92:95], v[18:33]
	ds_read_b128 v[34:37], v145 offset:96
	s_waitcnt lgkmcnt(0)
	v_mfma_f32_32x32x16_bf16 v[18:33], v[34:37], v[100:103], v[18:33]
	global_load_dwordx4 v[34:37], v[62:63], off offset:-4096
	global_load_dwordx4 v[38:41], v[46:47], off offset:1024
	global_load_dwordx4 v[42:45], v[46:47], off offset:2048
	s_nop 0
	global_load_dwordx4 v[46:49], v[46:47], off offset:3072
	s_waitcnt vmcnt(3)
	ds_write_b128 v144, v[34:37]
	s_waitcnt vmcnt(2)
	ds_write_b128 v144, v[38:41] offset:1152
	s_waitcnt vmcnt(1)
	ds_write_b128 v144, v[42:45] offset:2304
	s_waitcnt vmcnt(0)
	ds_write_b128 v144, v[46:49] offset:3456
	s_waitcnt lgkmcnt(0)
	ds_read_b128 v[34:37], v145
	ds_read_b128 v[50:53], v145 offset:32
	s_waitcnt lgkmcnt(1)
	v_mfma_f32_32x32x16_bf16 v[34:49], v[34:37], v[88:91], 0
	s_waitcnt lgkmcnt(0)
	v_mfma_f32_32x32x16_bf16 v[34:49], v[50:53], v[84:87], v[34:49]
	ds_read_b128 v[50:53], v145 offset:64
	s_waitcnt lgkmcnt(0)
	v_mfma_f32_32x32x16_bf16 v[34:49], v[50:53], v[92:95], v[34:49]
	ds_read_b128 v[50:53], v145 offset:96
	s_waitcnt lgkmcnt(0)
	v_mfma_f32_32x32x16_bf16 v[34:49], v[50:53], v[100:103], v[34:49]
	global_load_dwordx4 v[50:53], v[62:63], off
	global_load_dwordx4 v[54:57], v[62:63], off offset:1024
	global_load_dwordx4 v[58:61], v[62:63], off offset:2048
	s_nop 0
	global_load_dwordx4 v[62:65], v[62:63], off offset:3072
	s_waitcnt vmcnt(3)
	ds_write_b128 v144, v[50:53]
	s_waitcnt vmcnt(2)
	ds_write_b128 v144, v[54:57] offset:1152
	s_waitcnt vmcnt(1)
	ds_write_b128 v144, v[58:61] offset:2304
	s_waitcnt vmcnt(0)
	ds_write_b128 v144, v[62:65] offset:3456
	s_waitcnt lgkmcnt(0)
	ds_read_b128 v[50:53], v145
	ds_read_b128 v[68:71], v145 offset:32
	s_waitcnt lgkmcnt(1)
	v_mfma_f32_32x32x16_bf16 v[50:65], v[50:53], v[88:91], 0
	s_waitcnt lgkmcnt(0)
	v_mfma_f32_32x32x16_bf16 v[50:65], v[68:71], v[84:87], v[50:65]
	ds_read_b128 v[68:71], v145 offset:64
	s_waitcnt lgkmcnt(0)
	v_mfma_f32_32x32x16_bf16 v[50:65], v[68:71], v[92:95], v[50:65]
	ds_read_b128 v[68:71], v145 offset:96
	s_waitcnt lgkmcnt(0)
	v_mfma_f32_32x32x16_bf16 v[50:65], v[68:71], v[100:103], v[50:65]
	global_load_dwordx4 v[66:69], v[78:79], off
	global_load_dwordx4 v[70:73], v[78:79], off offset:1024
	global_load_dwordx4 v[74:77], v[78:79], off offset:2048
	s_nop 0
	global_load_dwordx4 v[78:81], v[78:79], off offset:3072
	s_waitcnt vmcnt(3)
	ds_write_b128 v144, v[66:69]
	s_waitcnt vmcnt(2)
	ds_write_b128 v144, v[70:73] offset:1152
	s_waitcnt vmcnt(1)
	ds_write_b128 v144, v[74:77] offset:2304
	s_waitcnt vmcnt(0)
	ds_write_b128 v144, v[78:81] offset:3456
	v_add_u32_e32 v66, 8, v134
	v_cmp_le_i32_e64 s[14:15], v66, v138
	v_add_u32_e32 v66, 9, v134
	v_cmp_le_i32_e64 s[16:17], v66, v138
	v_add_u32_e32 v66, 10, v134
	v_cmp_le_i32_e64 s[18:19], v66, v138
	v_add_u32_e32 v66, 11, v134
	v_cmp_le_i32_e64 s[20:21], v66, v138
	v_add_u32_e32 v66, 17, v134
	v_cmp_le_i32_e64 s[24:25], v66, v138
	v_add_u32_e32 v66, 18, v134
	v_cmp_le_i32_e64 s[26:27], v66, v138
	v_add_u32_e32 v66, 19, v134
	s_waitcnt lgkmcnt(0)
	v_cmp_le_i32_e64 s[28:29], v66, v138
	v_add_u32_e32 v66, 25, v134
	ds_read_b128 v[128:131], v145
	ds_read_b128 v[124:127], v145 offset:32
	ds_read_b128 v[120:123], v145 offset:64
	ds_read_b128 v[116:119], v145 offset:96
	v_cmp_le_i32_e64 s[34:35], v66, v138
	v_add_u32_e32 v66, 26, v134
	v_bfe_u32 v67, v1, 2, 2
	v_cmp_le_i32_e64 s[36:37], v66, v138
	v_add_u32_e32 v66, 27, v134
	v_cmp_le_i32_e64 s[38:39], v66, v138
	v_mul_lo_u32 v66, v143, s61
	v_mul_u32_u24_e32 v67, 0x110, v67
	v_readlane_b32 s61, v253, 60
	v_or_b32_e32 v70, 2, v134
	v_add_u32_e32 v68, 16, v134
	v_add3_u32 v66, s61, v66, v67
	v_lshlrev_b32_e32 v67, 1, v1
	v_and_b32_e32 v1, 3, v1
	v_and_b32_e32 v67, 32, v67
	v_lshlrev_b32_e32 v1, 3, v1
	v_add_u32_e32 v69, 24, v134
	v_cmp_le_i32_e64 s[10:11], v70, v138
	v_or_b32_e32 v70, 3, v134
	v_add3_u32 v1, v66, v67, v1
	v_lshl_add_u64 v[66:67], v[134:135], 2, s[40:41]
	s_mov_b64 s[40:41], 0x1519d160
	v_cmp_le_i32_e64 s[12:13], v70, v138
	v_cmp_le_i32_e64 s[22:23], v68, v138
	v_cmp_le_i32_e64 s[30:31], v69, v138
	v_lshl_add_u64 v[136:137], v[66:67], 0, s[40:41]
	s_mov_b32 s61, 0
	s_waitcnt lgkmcnt(0)
	s_barrier
.LBB0_1035:
	v_mad_i64_i32 v[66:67], s[40:41], v142, s83, v[132:133]
	v_add_u32_e32 v70, 8, v142
	global_load_dwordx4 v[66:69], v[66:67], off offset:1024
	v_mad_i64_i32 v[70:71], s[40:41], v70, s83, v[132:133]
	v_add_u32_e32 v74, 16, v142
	global_load_dwordx4 v[70:73], v[70:71], off offset:1024
	v_mad_i64_i32 v[74:75], s[40:41], v74, s83, v[132:133]
	v_add_u32_e32 v78, 24, v142
	global_load_dwordx4 v[74:77], v[74:75], off offset:1024
	v_mad_i64_i32 v[78:79], s[40:41], v78, s83, v[132:133]
	global_load_dwordx4 v[78:81], v[78:79], off offset:1024
	s_cmp_lt_u32 s61, s95
	s_cselect_b64 s[74:75], -1, 0
	s_or_b64 s[40:41], s[74:75], vcc
	s_add_i32 s61, s61, 1
	v_add_u32_e32 v142, 32, v142
	s_waitcnt vmcnt(3)
	ds_write_b128 v144, v[66:69]
	s_waitcnt vmcnt(2)
	ds_write_b128 v144, v[70:73] offset:1152
	s_waitcnt vmcnt(1)
	ds_write_b128 v144, v[74:77] offset:2304
	s_waitcnt vmcnt(0)
	ds_write_b128 v144, v[78:81] offset:3456
	s_waitcnt lgkmcnt(0)
	ds_read_b128 v[66:69], v145
	ds_read_b128 v[148:151], v145 offset:32
	s_waitcnt lgkmcnt(1)
	v_mfma_f32_32x32x16_bf16 v[66:81], v[66:69], v[96:99], 0
	s_waitcnt lgkmcnt(0)
	v_mfma_f32_32x32x16_bf16 v[66:81], v[148:151], v[104:107], v[66:81]
	ds_read_b128 v[148:151], v145 offset:64
	s_waitcnt lgkmcnt(0)
	v_mfma_f32_32x32x16_bf16 v[66:81], v[148:151], v[108:111], v[66:81]
	ds_read_b128 v[148:151], v145 offset:96
	s_waitcnt lgkmcnt(0)
	v_mfma_f32_32x32x16_bf16 v[66:81], v[148:151], v[112:115], v[66:81]
	global_load_dwordx4 v[148:151], v[136:137], off offset:-96
	s_waitcnt vmcnt(0)
	v_sub_f32_e32 v82, v148, v140
	v_mul_f32_e32 v82, 0x3fb8aa3b, v82
	v_exp_f32_e32 v82, v82
	s_nop 6
	v_mul_f32_e32 v66, v66, v82
	v_cndmask_b32_e64 v82, 0, v66, s[40:41]
	v_add_f32_e32 v66, v146, v82
	v_sub_f32_e32 v146, v149, v140
	v_mul_f32_e32 v146, 0x3fb8aa3b, v146
	v_exp_f32_e32 v146, v146
	s_or_b64 s[40:41], s[74:75], s[8:9]
	v_mul_f32_e32 v67, v67, v146
	v_cndmask_b32_e64 v146, 0, v67, s[40:41]
	v_sub_f32_e32 v67, v150, v140
	v_mul_f32_e32 v67, 0x3fb8aa3b, v67
	v_exp_f32_e32 v67, v67
	s_or_b64 s[40:41], s[74:75], s[10:11]
	v_add_f32_e32 v66, v146, v66
	v_mul_f32_e32 v67, v68, v67
	v_cndmask_b32_e64 v147, 0, v67, s[40:41]
	v_sub_f32_e32 v67, v151, v140
	v_mul_f32_e32 v67, 0x3fb8aa3b, v67
	v_exp_f32_e32 v67, v67
	s_or_b64 s[40:41], s[74:75], s[12:13]
	v_add_f32_e32 v66, v147, v66
	v_mul_f32_e32 v67, v69, v67
	v_cndmask_b32_e64 v148, 0, v67, s[40:41]
	v_add_f32_e32 v149, v148, v66
	global_load_dwordx4 v[66:69], v[136:137], off offset:-64
	s_or_b64 s[40:41], s[74:75], s[14:15]
	s_waitcnt vmcnt(0)
	v_sub_f32_e32 v66, v66, v140
	v_mul_f32_e32 v66, 0x3fb8aa3b, v66
	v_sub_f32_e32 v67, v67, v140
	v_exp_f32_e32 v66, v66
	v_mul_f32_e32 v67, 0x3fb8aa3b, v67
	v_exp_f32_e32 v67, v67
	v_mul_f32_e32 v66, v70, v66
	v_cndmask_b32_e64 v70, 0, v66, s[40:41]
	s_or_b64 s[40:41], s[74:75], s[16:17]
	v_mul_f32_e32 v67, v71, v67
	v_cndmask_b32_e64 v71, 0, v67, s[40:41]
	v_sub_f32_e32 v67, v68, v140
	v_mul_f32_e32 v67, 0x3fb8aa3b, v67
	v_exp_f32_e32 v67, v67
	s_or_b64 s[40:41], s[74:75], s[18:19]
	v_add_f32_e32 v66, v70, v149
	v_add_f32_e32 v66, v71, v66
	v_mul_f32_e32 v67, v72, v67
	v_cndmask_b32_e64 v72, 0, v67, s[40:41]
	v_sub_f32_e32 v67, v69, v140
	v_mul_f32_e32 v67, 0x3fb8aa3b, v67
	v_exp_f32_e32 v67, v67
	s_or_b64 s[40:41], s[74:75], s[20:21]
	v_add_f32_e32 v66, v72, v66
	v_mul_f32_e32 v67, v73, v67
	v_cndmask_b32_e64 v73, 0, v67, s[40:41]
	v_add_f32_e32 v149, v73, v66
	global_load_dwordx4 v[66:69], v[136:137], off offset:-32
	s_or_b64 s[40:41], s[74:75], s[22:23]
	s_waitcnt vmcnt(0)
	v_sub_f32_e32 v66, v66, v140
	v_mul_f32_e32 v66, 0x3fb8aa3b, v66
	v_sub_f32_e32 v67, v67, v140
	v_exp_f32_e32 v66, v66
	v_mul_f32_e32 v67, 0x3fb8aa3b, v67
	v_exp_f32_e32 v67, v67
	v_mul_f32_e32 v66, v74, v66
	v_cndmask_b32_e64 v74, 0, v66, s[40:41]
	s_or_b64 s[40:41], s[74:75], s[24:25]
	v_mul_f32_e32 v67, v75, v67
	v_cndmask_b32_e64 v75, 0, v67, s[40:41]
	v_sub_f32_e32 v67, v68, v140
	v_mul_f32_e32 v67, 0x3fb8aa3b, v67
	v_exp_f32_e32 v67, v67
	s_or_b64 s[40:41], s[74:75], s[26:27]
	v_add_f32_e32 v66, v74, v149
	v_add_f32_e32 v66, v75, v66
	v_mul_f32_e32 v67, v76, v67
	v_cndmask_b32_e64 v76, 0, v67, s[40:41]
	v_sub_f32_e32 v67, v69, v140
	v_mul_f32_e32 v67, 0x3fb8aa3b, v67
	v_exp_f32_e32 v67, v67
	s_or_b64 s[40:41], s[74:75], s[28:29]
	v_add_f32_e32 v66, v76, v66
	v_mul_f32_e32 v67, v77, v67
	v_cndmask_b32_e64 v77, 0, v67, s[40:41]
	v_add_f32_e32 v149, v77, v66
	global_load_dwordx4 v[66:69], v[136:137], off
	s_or_b64 s[40:41], s[74:75], s[30:31]
	v_lshl_add_u64 v[136:137], v[136:137], 0, s[68:69]
	s_waitcnt vmcnt(0)
	v_sub_f32_e32 v66, v66, v140
	v_mul_f32_e32 v66, 0x3fb8aa3b, v66
	v_sub_f32_e32 v67, v67, v140
	v_exp_f32_e32 v66, v66
	v_mul_f32_e32 v67, 0x3fb8aa3b, v67
	v_exp_f32_e32 v67, v67
	v_mul_f32_e32 v66, v78, v66
	v_cndmask_b32_e64 v150, 0, v66, s[40:41]
	s_or_b64 s[40:41], s[74:75], s[34:35]
	v_mul_f32_e32 v67, v79, v67
	v_add_f32_e32 v66, v150, v149
	v_cndmask_b32_e64 v149, 0, v67, s[40:41]
	v_sub_f32_e32 v67, v68, v140
	v_mul_f32_e32 v67, 0x3fb8aa3b, v67
	v_exp_f32_e32 v67, v67
	s_or_b64 s[40:41], s[74:75], s[36:37]
	v_add_f32_e32 v66, v149, v66
	v_mul_f32_e32 v67, v80, v67
	v_cndmask_b32_e64 v80, 0, v67, s[40:41]
	v_add_f32_e32 v78, v80, v66
	v_sub_f32_e32 v66, v69, v140
	v_mul_f32_e32 v66, 0x3fb8aa3b, v66
	v_exp_f32_e32 v66, v66
	s_or_b64 s[40:41], s[74:75], s[38:39]
	v_mul_f32_e32 v66, v81, v66
	v_cndmask_b32_e64 v79, 0, v66, s[40:41]
	v_cvt_pk_bf16_f32 v66, v82, v146
	v_cvt_pk_bf16_f32 v67, v147, v148
	v_cvt_pk_bf16_f32 v68, v70, v71
	v_cvt_pk_bf16_f32 v69, v72, v73
	v_cvt_pk_bf16_f32 v70, v74, v75
	v_cvt_pk_bf16_f32 v71, v76, v77
	v_cvt_pk_bf16_f32 v72, v150, v149
	v_bfe_u32 v73, v80, 16, 1
	v_add3_u32 v73, v80, v73, s73
	v_bfe_u32 v74, v79, 16, 1
	v_lshrrev_b32_e32 v73, 16, v73
	v_add3_u32 v74, v79, v74, s73
	v_add_u32_e32 v80, s60, v1
	v_and_or_b32 v73, v74, s33, v73
	v_add_u32_e32 v81, 0x880, v80
	ds_read_b64_tr_b16 v[74:75], v80
	ds_read_b64_tr_b16 v[76:77], v81
	s_waitcnt lgkmcnt(0)
	v_add_u32_e32 v81, 0x1100, v80
	v_mfma_f32_32x32x16_bf16 v[2:17], v[74:77], v[66:69], v[2:17]
	v_add_u32_e32 v82, 0x1980, v80
	ds_read_b64_tr_b16 v[74:75], v81
	ds_read_b64_tr_b16 v[76:77], v82
	s_waitcnt lgkmcnt(0)
	v_add_u32_e32 v81, 64, v80
	v_add_u32_e32 v82, 0x8c0, v80
	s_addk_i32 s60, 0x2200
	v_add_f32_e32 v146, v79, v78
	s_cmp_lg_u32 s66, s60
	v_mfma_f32_32x32x16_bf16 v[2:17], v[74:77], v[70:73], v[2:17]
	ds_read_b64_tr_b16 v[74:75], v81
	ds_read_b64_tr_b16 v[76:77], v82
	s_waitcnt lgkmcnt(0)
	v_add_u32_e32 v81, 0x1140, v80
	v_add_u32_e32 v82, 0x19c0, v80
	v_mfma_f32_32x32x16_bf16 v[18:33], v[74:77], v[66:69], v[18:33]
	ds_read_b64_tr_b16 v[74:75], v81
	ds_read_b64_tr_b16 v[76:77], v82
	s_waitcnt lgkmcnt(0)
	v_add_u32_e32 v81, 0x80, v80
	v_add_u32_e32 v82, 0x900, v80
	v_mfma_f32_32x32x16_bf16 v[18:33], v[74:77], v[70:73], v[18:33]
	ds_read_b64_tr_b16 v[74:75], v81
	ds_read_b64_tr_b16 v[76:77], v82
	s_waitcnt lgkmcnt(0)
	v_add_u32_e32 v81, 0x1180, v80
	v_add_u32_e32 v82, 0x1a00, v80
	v_mfma_f32_32x32x16_bf16 v[34:49], v[74:77], v[66:69], v[34:49]
	ds_read_b64_tr_b16 v[74:75], v81
	ds_read_b64_tr_b16 v[76:77], v82
	s_waitcnt lgkmcnt(0)
	v_add_u32_e32 v81, 0xc0, v80
	v_add_u32_e32 v82, 0x940, v80
	v_mfma_f32_32x32x16_bf16 v[34:49], v[74:77], v[70:73], v[34:49]
	ds_read_b64_tr_b16 v[74:75], v81
	ds_read_b64_tr_b16 v[76:77], v82
	s_waitcnt lgkmcnt(0)
	s_nop 0
	v_mfma_f32_32x32x16_bf16 v[50:65], v[74:77], v[66:69], v[50:65]
	s_nop 6
	v_add_u32_e32 v74, 0x11c0, v80
	v_add_u32_e32 v75, 0x1a40, v80
	ds_read_b64_tr_b16 v[66:67], v74
	ds_read_b64_tr_b16 v[68:69], v75
	s_waitcnt lgkmcnt(0)
	s_nop 0
	v_mfma_f32_32x32x16_bf16 v[50:65], v[66:69], v[70:73], v[50:65]
	s_cbranch_scc1 .LBB0_1035
	v_readlane_b32 s8, v254, 53
	v_readlane_b32 s9, v254, 54
	s_lshl_b64 s[8:9], s[8:9], 2
	s_add_u32 s10, s64, s8
	v_or_b32_e32 v82, s55, v141
	s_nop 0
	v_mov_b64_e32 v[66:67], s[62:63]
	s_addc_u32 s11, s65, s9
	v_mad_u64_u32 v[66:67], s[8:9], v82, s83, v[66:67]
	s_lshl_b32 s70, s54, 1
	v_lshl_add_u64 v[66:67], v[66:67], 0, s[70:71]
	v_lshl_add_u64 v[96:97], v[134:135], 1, v[66:67]
	v_add_co_u32_e32 v66, vcc, s82, v96
	s_mov_b64 s[8:9], 0x1000
	s_nop 0
	v_addc_co_u32_e32 v67, vcc, 0, v97, vcc
	global_load_dwordx2 v[104:105], v[66:67], off
	v_mfma_f32_32x32x16_bf16 v[66:81], v[128:131], v[88:91], 0
	s_nop 6
	v_lshl_add_u64 v[88:89], v[96:97], 0, s[8:9]
	global_load_dwordx2 v[98:99], v[88:89], off offset:16
	v_xor_b32_e32 v1, 32, v249
	s_lshl_b32 s8, s54, 2
	s_add_u32 s8, s10, s8
	s_addc_u32 s9, s11, 0
	v_lshlrev_b32_e32 v96, 3, v143
	v_mfma_f32_32x32x16_bf16 v[66:81], v[124:127], v[84:87], v[66:81]
	s_nop 6
	v_and_b32_e32 v84, 64, v249
	v_add_u32_e32 v86, 64, v84
	v_cmp_lt_i32_e32 vcc, v1, v86
	v_add_f32_e32 v85, v139, v140
	v_or_b32_e32 v87, v84, v138
	v_cndmask_b32_e32 v1, v249, v1, vcc
	v_lshlrev_b32_e32 v1, 2, v1
	v_mfma_f32_32x32x16_bf16 v[66:81], v[120:123], v[92:95], v[66:81]
	v_mul_f32_e32 v90, 0xbfb8aa3b, v85
	v_lshlrev_b64 v[84:85], 12, v[82:83]
	v_lshlrev_b32_e32 v82, 2, v87
	ds_bpermute_b32 v87, v1, v146
	v_exp_f32_e32 v86, v90
	v_lshl_add_u64 v[84:85], s[88:89], 0, v[84:85]
	s_nop 0
	v_lshl_add_u64 v[94:95], v[84:85], 0, s[70:71]
	v_mfma_f32_32x32x16_bf16 v[66:81], v[116:119], v[100:103], v[66:81]
	s_mov_b32 s62, 0x1b81e000
	s_nop 10
	ds_bpermute_b32 v66, v82, v66
	s_waitcnt lgkmcnt(1)
	v_add_f32_e32 v67, v146, v87
	v_lshl_add_u64 v[74:75], v[134:135], 2, s[8:9]
	s_mov_b32 s8, 0xf800000
	s_waitcnt lgkmcnt(0)
	v_add_f32_e32 v66, v67, v66
	v_max_f32_e64 v66, |v66|, v86
	v_div_scale_f32 v67, s[10:11], v66, v66, 1.0
	v_rcp_f32_e32 v68, v67
	v_div_scale_f32 v69, vcc, 1.0, v66, 1.0
	v_fma_f32 v70, -v67, v68, 1.0
	v_fmac_f32_e32 v68, v70, v68
	v_mul_f32_e32 v70, v69, v68
	v_fma_f32 v71, -v67, v70, v69
	v_fmac_f32_e32 v70, v71, v68
	v_fma_f32 v67, -v67, v70, v69
	v_div_fmas_f32 v67, v67, v68, v70
	v_div_fixup_f32 v82, v67, v66, 1.0
	v_pk_mul_f32 v[68:69], v[64:65], v[82:83] op_sel_hi:[1,0]
	v_pk_mul_f32 v[126:127], v[2:3], v[82:83] op_sel_hi:[1,0]
	v_pk_mul_f32 v[102:103], v[4:5], v[82:83] op_sel_hi:[1,0]
	v_pk_mul_f32 v[128:129], v[126:127], v[126:127]
	v_pk_mul_f32 v[72:73], v[60:61], v[82:83] op_sel_hi:[1,0]
	v_pk_mul_f32 v[70:71], v[62:63], v[82:83] op_sel_hi:[1,0]
	v_pk_mul_f32 v[118:119], v[102:103], v[102:103]
	v_pk_mul_f32 v[122:123], v[8:9], v[82:83] op_sel_hi:[1,0]
	v_pk_mul_f32 v[130:131], v[6:7], v[82:83] op_sel_hi:[1,0]
	v_pk_mul_f32 v[110:111], v[12:13], v[82:83] op_sel_hi:[1,0]
	v_pk_mul_f32 v[100:101], v[16:17], v[82:83] op_sel_hi:[1,0]
	v_pk_mul_f32 v[116:117], v[10:11], v[82:83] op_sel_hi:[1,0]
	v_pk_mul_f32 v[108:109], v[14:15], v[82:83] op_sel_hi:[1,0]
	v_pk_mul_f32 v[90:91], v[20:21], v[82:83] op_sel_hi:[1,0]
	v_pk_mul_f32 v[84:85], v[24:25], v[82:83] op_sel_hi:[1,0]
	v_pk_mul_f32 v[92:93], v[18:19], v[82:83] op_sel_hi:[1,0]
	v_pk_mul_f32 v[86:87], v[22:23], v[82:83] op_sel_hi:[1,0]
	v_pk_mul_f32 v[78:79], v[28:29], v[82:83] op_sel_hi:[1,0]
	v_pk_mul_f32 v[32:33], v[32:33], v[82:83] op_sel_hi:[1,0]
	v_pk_mul_f32 v[80:81], v[26:27], v[82:83] op_sel_hi:[1,0]
	v_pk_mul_f32 v[28:29], v[36:37], v[82:83] op_sel_hi:[1,0]
	v_pk_mul_f32 v[24:25], v[40:41], v[82:83] op_sel_hi:[1,0]
	v_pk_mul_f32 v[26:27], v[38:39], v[82:83] op_sel_hi:[1,0]
	v_pk_mul_f32 v[20:21], v[44:45], v[82:83] op_sel_hi:[1,0]
	s_waitcnt vmcnt(0)
	v_lshlrev_b32_e32 v64, 16, v98
	v_and_b32_e32 v65, 0xffff0000, v98
	v_mul_f32_e32 v64, 0xbfb8aa3b, v64
	v_mul_f32_e32 v65, 0xbfb8aa3b, v65
	v_exp_f32_e32 v76, v64
	v_exp_f32_e32 v77, v65
	v_pk_mul_f32 v[16:17], v[48:49], v[82:83] op_sel_hi:[1,0]
	v_pk_mul_f32 v[22:23], v[42:43], v[82:83] op_sel_hi:[1,0]
	v_add_f32_e32 v76, 1.0, v76
	v_rcp_f32_e32 v120, v76
	v_add_f32_e32 v76, 1.0, v77
	v_rcp_f32_e32 v121, v76
	v_lshlrev_b32_e32 v76, 16, v99
	v_mul_f32_e32 v97, 0xbfb8aa3b, v76
	v_pk_mul_f32 v[76:77], v[30:31], v[82:83] op_sel_hi:[1,0]
	v_pk_mul_f32 v[30:31], v[34:35], v[82:83] op_sel_hi:[1,0]
	v_pk_mul_f32 v[18:19], v[46:47], v[82:83] op_sel_hi:[1,0]
	v_pk_mul_f32 v[12:13], v[52:53], v[82:83] op_sel_hi:[1,0]
	v_pk_mul_f32 v[6:7], v[56:57], v[82:83] op_sel_hi:[1,0]
	v_pk_mul_f32 v[14:15], v[50:51], v[82:83] op_sel_hi:[1,0]
	v_pk_mul_f32 v[8:9], v[54:55], v[82:83] op_sel_hi:[1,0]
	v_pk_mul_f32 v[2:3], v[58:59], v[82:83] op_sel_hi:[1,0]
	v_add_f32_e32 v82, v128, v129
	v_add_f32_e32 v82, v118, v82
	v_pk_mul_f32 v[132:133], v[130:131], v[130:131]
	v_add_f32_e32 v82, v119, v82
	v_add_f32_e32 v82, v132, v82
	v_pk_mul_f32 v[124:125], v[122:123], v[122:123]
	v_add_f32_e32 v82, v133, v82
	v_add_f32_e32 v82, v124, v82
	v_pk_mul_f32 v[10:11], v[116:117], v[116:117]
	v_add_f32_e32 v82, v125, v82
	v_add_f32_e32 v10, v10, v82
	v_pk_mul_f32 v[134:135], v[110:111], v[110:111]
	v_add_f32_e32 v10, v11, v10
	v_add_f32_e32 v10, v134, v10
	v_pk_mul_f32 v[138:139], v[108:109], v[108:109]
	v_add_f32_e32 v10, v135, v10
	v_add_f32_e32 v10, v138, v10
	v_pk_mul_f32 v[136:137], v[100:101], v[100:101]
	v_add_f32_e32 v10, v139, v10
	v_lshlrev_b32_e32 v60, 16, v104
	v_and_b32_e32 v61, 0xffff0000, v104
	v_lshlrev_b32_e32 v62, 16, v105
	v_and_b32_e32 v63, 0xffff0000, v105
	v_add_f32_e32 v10, v136, v10
	v_mul_f32_e32 v60, 0xbfb8aa3b, v60
	v_mul_f32_e32 v61, 0xbfb8aa3b, v61
	v_mul_f32_e32 v62, 0xbfb8aa3b, v62
	v_mul_f32_e32 v63, 0xbfb8aa3b, v63
	v_pk_mul_f32 v[144:145], v[92:93], v[92:93]
	v_add_f32_e32 v10, v137, v10
	v_exp_f32_e32 v60, v60
	v_exp_f32_e32 v61, v61
	v_exp_f32_e32 v62, v62
	v_exp_f32_e32 v63, v63
	v_add_f32_e32 v10, v144, v10
	v_pk_mul_f32 v[140:141], v[90:91], v[90:91]
	v_add_f32_e32 v10, v145, v10
	v_add_f32_e32 v10, v140, v10
	v_pk_mul_f32 v[146:147], v[86:87], v[86:87]
	v_add_f32_e32 v10, v141, v10
	v_add_f32_e32 v60, 1.0, v60
	v_add_f32_e32 v61, 1.0, v61
	v_add_f32_e32 v62, 1.0, v62
	v_add_f32_e32 v63, 1.0, v63
	v_add_f32_e32 v10, v146, v10
	v_rcp_f32_e32 v106, v60
	v_rcp_f32_e32 v107, v61
	v_rcp_f32_e32 v104, v62
	v_rcp_f32_e32 v105, v63
	global_load_dwordx4 v[64:67], v[74:75], off
	global_load_dwordx4 v[60:63], v[74:75], off offset:32
	v_pk_mul_f32 v[142:143], v[84:85], v[84:85]
	v_add_f32_e32 v10, v147, v10
	v_add_f32_e32 v10, v142, v10
	v_pk_mul_f32 v[152:153], v[80:81], v[80:81]
	v_add_f32_e32 v10, v143, v10
	v_add_f32_e32 v10, v152, v10
	v_pk_mul_f32 v[148:149], v[78:79], v[78:79]
	v_add_f32_e32 v10, v153, v10
	v_add_f32_e32 v10, v148, v10
	v_pk_mul_f32 v[154:155], v[76:77], v[76:77]
	v_add_f32_e32 v10, v149, v10
	v_add_f32_e32 v10, v154, v10
	v_pk_mul_f32 v[150:151], v[32:33], v[32:33]
	v_add_f32_e32 v10, v155, v10
	v_add_f32_e32 v10, v150, v10
	v_pk_mul_f32 v[34:35], v[30:31], v[30:31]
	v_add_f32_e32 v10, v151, v10
	v_add_f32_e32 v10, v34, v10
	v_pk_mul_f32 v[36:37], v[28:29], v[28:29]
	v_add_f32_e32 v10, v35, v10
	v_add_f32_e32 v10, v36, v10
	v_pk_mul_f32 v[38:39], v[26:27], v[26:27]
	v_add_f32_e32 v10, v37, v10
	v_add_f32_e32 v10, v38, v10
	v_pk_mul_f32 v[40:41], v[24:25], v[24:25]
	v_add_f32_e32 v10, v39, v10
	v_add_f32_e32 v10, v40, v10
	v_pk_mul_f32 v[42:43], v[22:23], v[22:23]
	v_add_f32_e32 v10, v41, v10
	v_add_f32_e32 v10, v42, v10
	v_pk_mul_f32 v[44:45], v[20:21], v[20:21]
	v_add_f32_e32 v10, v43, v10
	v_add_f32_e32 v10, v44, v10
	v_pk_mul_f32 v[46:47], v[18:19], v[18:19]
	v_add_f32_e32 v10, v45, v10
	v_add_f32_e32 v10, v46, v10
	v_pk_mul_f32 v[48:49], v[16:17], v[16:17]
	v_add_f32_e32 v10, v47, v10
	v_add_f32_e32 v10, v48, v10
	v_pk_mul_f32 v[50:51], v[14:15], v[14:15]
	v_add_f32_e32 v10, v49, v10
	v_add_f32_e32 v10, v50, v10
	v_pk_mul_f32 v[52:53], v[12:13], v[12:13]
	v_add_f32_e32 v10, v51, v10
	v_add_f32_e32 v10, v52, v10
	v_pk_mul_f32 v[54:55], v[8:9], v[8:9]
	v_add_f32_e32 v10, v53, v10
	v_add_f32_e32 v10, v54, v10
	v_pk_mul_f32 v[56:57], v[6:7], v[6:7]
	v_add_f32_e32 v10, v55, v10
	v_add_f32_e32 v10, v56, v10
	v_pk_mul_f32 v[58:59], v[2:3], v[2:3]
	v_add_f32_e32 v10, v57, v10
	v_add_f32_e32 v10, v58, v10
	v_pk_mul_f32 v[114:115], v[72:73], v[72:73]
	v_add_f32_e32 v10, v59, v10
	v_add_f32_e32 v10, v114, v10
	v_pk_mul_f32 v[112:113], v[70:71], v[70:71]
	v_add_f32_e32 v10, v115, v10
	v_add_f32_e32 v10, v112, v10
	v_pk_mul_f32 v[4:5], v[68:69], v[68:69]
	v_add_f32_e32 v10, v113, v10
	v_add_f32_e32 v4, v4, v10
	v_add_f32_e32 v4, v5, v4
	ds_bpermute_b32 v1, v1, v4
	v_and_b32_e32 v10, 0xffff0000, v99
	v_exp_f32_e32 v5, v97
	v_mul_f32_e32 v10, 0xbfb8aa3b, v10
	v_exp_f32_e32 v11, v10
	s_waitcnt lgkmcnt(0)
	v_add_f32_e32 v1, v4, v1
	v_fmamk_f32 v1, v1, 0x3c000000, v245
	v_mul_f32_e32 v4, 0x4f800000, v1
	v_cmp_gt_f32_e32 vcc, s8, v1
	v_add_f32_e32 v5, 1.0, v5
	v_rcp_f32_e32 v10, v5
	v_cndmask_b32_e32 v1, v1, v4, vcc
	v_sqrt_f32_e32 v4, v1
	v_add_f32_e32 v5, 1.0, v11
	v_ashrrev_i32_e32 v97, 31, v96
	v_lshl_add_u64 v[42:43], v[96:97], 1, v[94:95]
	v_add_u32_e32 v11, -1, v4
	v_fma_f32 v34, -v11, v4, v1
	v_cmp_ge_f32_e64 s[8:9], 0, v34
	v_add_u32_e32 v34, 1, v4
	s_nop 0
	v_cndmask_b32_e64 v11, v4, v11, s[8:9]
	v_fma_f32 v4, -v34, v4, v1
	v_cmp_lt_f32_e64 s[8:9], 0, v4
	s_nop 1
	v_cndmask_b32_e64 v4, v11, v34, s[8:9]
	v_mul_f32_e32 v11, 0x37800000, v4
	v_cndmask_b32_e32 v4, v4, v11, vcc
	v_cmp_class_f32_e32 vcc, v1, v251
	v_rcp_f32_e32 v11, v5
	s_nop 0
	v_cndmask_b32_e32 v1, v4, v1, vcc
	v_div_scale_f32 v4, s[8:9], v1, v1, 1.0
	v_rcp_f32_e32 v34, v4
	s_mov_b64 s[8:9], 0x1b81e000
	v_fma_f32 v5, -v4, v34, 1.0
	v_fmac_f32_e32 v34, v5, v34
	v_div_scale_f32 v5, vcc, 1.0, v1, 1.0
	v_mul_f32_e32 v35, v5, v34
	v_fma_f32 v36, -v4, v35, v5
	v_fmac_f32_e32 v35, v36, v34
	v_fma_f32 v4, -v4, v35, v5
	v_div_fmas_f32 v4, v4, v34, v35
	v_div_fixup_f32 v4, v4, v1, 1.0
	v_pk_mul_f32 v[34:35], v[126:127], v[4:5] op_sel_hi:[1,0]
	v_pk_mul_f32 v[36:37], v[102:103], v[4:5] op_sel_hi:[1,0]
	s_waitcnt vmcnt(1)
	v_pk_mul_f32 v[34:35], v[64:65], v[34:35]
	v_pk_mul_f32 v[36:37], v[66:67], v[36:37]
	v_pk_mul_f32 v[34:35], v[106:107], v[34:35]
	v_pk_mul_f32 v[36:37], v[104:105], v[36:37]
	v_and_b32_sdwa v5, v34, v247 dst_sel:DWORD dst_unused:UNUSED_PAD src0_sel:WORD_1 src1_sel:DWORD
	v_and_b32_sdwa v1, v35, v247 dst_sel:DWORD dst_unused:UNUSED_PAD src0_sel:WORD_1 src1_sel:DWORD
	v_add3_u32 v5, v34, v5, s73
	v_add3_u32 v1, v35, v1, s73
	v_lshrrev_b32_e32 v5, 16, v5
	v_and_or_b32 v34, v1, s33, v5
	v_and_b32_sdwa v5, v36, v247 dst_sel:DWORD dst_unused:UNUSED_PAD src0_sel:WORD_1 src1_sel:DWORD
	s_nop 0
	v_add3_u32 v5, v36, v5, s73
	v_and_b32_sdwa v1, v37, v247 dst_sel:DWORD dst_unused:UNUSED_PAD src0_sel:WORD_1 src1_sel:DWORD
	v_lshrrev_b32_e32 v5, 16, v5
	v_add3_u32 v1, v37, v1, s73
	v_pk_mul_f32 v[36:37], v[130:131], v[4:5] op_sel_hi:[1,0]
	v_and_or_b32 v35, v1, s33, v5
	s_waitcnt vmcnt(0)
	v_pk_mul_f32 v[36:37], v[60:61], v[36:37]
	v_pk_mul_f32 v[38:39], v[122:123], v[4:5] op_sel_hi:[1,0]
	v_pk_mul_f32 v[36:37], v[120:121], v[36:37]
	v_pk_mul_f32 v[38:39], v[62:63], v[38:39]
	v_and_b32_sdwa v5, v36, v247 dst_sel:DWORD dst_unused:UNUSED_PAD src0_sel:WORD_1 src1_sel:DWORD
	v_and_b32_sdwa v1, v37, v247 dst_sel:DWORD dst_unused:UNUSED_PAD src0_sel:WORD_1 src1_sel:DWORD
	v_add3_u32 v5, v36, v5, s73
	v_pk_mul_f32 v[10:11], v[10:11], v[38:39]
	v_add3_u32 v1, v37, v1, s73
	v_lshrrev_b32_e32 v5, 16, v5
	v_and_or_b32 v36, v1, s33, v5
	v_and_b32_sdwa v5, v10, v247 dst_sel:DWORD dst_unused:UNUSED_PAD src0_sel:WORD_1 src1_sel:DWORD
	v_and_b32_sdwa v1, v11, v247 dst_sel:DWORD dst_unused:UNUSED_PAD src0_sel:WORD_1 src1_sel:DWORD
	v_add3_u32 v5, v10, v5, s73
	v_add3_u32 v1, v11, v1, s73
	v_lshrrev_b32_e32 v5, 16, v5
	v_and_or_b32 v37, v1, s33, v5
	v_add_co_u32_e32 v10, vcc, s62, v42
	v_permlane32_swap_b32_e32 v34, v36
	v_permlane32_swap_b32_e32 v35, v37
	v_addc_co_u32_e32 v11, vcc, 0, v43, vcc
	global_store_dwordx4 v[10:11], v[34:37], off
	global_load_dwordx2 v[44:45], v[88:89], off offset:32
	s_nop 0
	global_load_dwordx4 v[34:37], v[74:75], off offset:64
	global_load_dwordx2 v[46:47], v[88:89], off offset:48
	global_load_dwordx4 v[38:41], v[74:75], off offset:96
	v_lshl_add_u64 v[10:11], v[42:43], 0, s[8:9]
	s_mov_b64 s[8:9], 0
	s_waitcnt vmcnt(3)
	v_lshlrev_b32_e32 v1, 16, v44
	v_mul_f32_e32 v1, 0xbfb8aa3b, v1
	v_and_b32_e32 v5, 0xffff0000, v44
	v_exp_f32_e32 v1, v1
	v_mul_f32_e32 v5, 0xbfb8aa3b, v5
	v_exp_f32_e32 v5, v5
	v_and_b32_e32 v43, 0xffff0000, v45
	v_add_f32_e32 v1, 1.0, v1
	v_rcp_f32_e32 v42, v1
	v_pk_mul_f32 v[48:49], v[116:117], v[4:5] op_sel_hi:[1,0]
	v_add_f32_e32 v1, 1.0, v5
	v_lshlrev_b32_e32 v5, 16, v45
	v_mul_f32_e32 v5, 0xbfb8aa3b, v5
	v_exp_f32_e32 v5, v5
	v_mul_f32_e32 v43, 0xbfb8aa3b, v43
	v_exp_f32_e32 v45, v43
	v_rcp_f32_e32 v43, v1
	v_add_f32_e32 v1, 1.0, v5
	v_rcp_f32_e32 v44, v1
	v_add_f32_e32 v1, 1.0, v45
	s_waitcnt vmcnt(2)
	v_pk_mul_f32 v[34:35], v[34:35], v[48:49]
	v_rcp_f32_e32 v45, v1
	v_pk_mul_f32 v[34:35], v[42:43], v[34:35]
	v_pk_mul_f32 v[42:43], v[110:111], v[4:5] op_sel_hi:[1,0]
	v_and_b32_sdwa v5, v34, v247 dst_sel:DWORD dst_unused:UNUSED_PAD src0_sel:WORD_1 src1_sel:DWORD
	v_pk_mul_f32 v[36:37], v[36:37], v[42:43]
	v_and_b32_sdwa v1, v35, v247 dst_sel:DWORD dst_unused:UNUSED_PAD src0_sel:WORD_1 src1_sel:DWORD
	v_add3_u32 v5, v34, v5, s73
	v_pk_mul_f32 v[36:37], v[44:45], v[36:37]
	v_add3_u32 v1, v35, v1, s73
	v_lshrrev_b32_e32 v5, 16, v5
	v_and_or_b32 v34, v1, s33, v5
	v_and_b32_sdwa v5, v36, v247 dst_sel:DWORD dst_unused:UNUSED_PAD src0_sel:WORD_1 src1_sel:DWORD
	v_and_b32_sdwa v1, v37, v247 dst_sel:DWORD dst_unused:UNUSED_PAD src0_sel:WORD_1 src1_sel:DWORD
	s_waitcnt vmcnt(1)
	v_lshlrev_b32_e32 v35, 16, v46
	v_add3_u32 v5, v36, v5, s73
	v_add3_u32 v1, v37, v1, s73
	v_mul_f32_e32 v35, 0xbfb8aa3b, v35
	v_lshrrev_b32_e32 v5, 16, v5
	v_exp_f32_e32 v37, v35
	v_and_or_b32 v35, v1, s33, v5
	v_and_b32_e32 v5, 0xffff0000, v46
	v_mul_f32_e32 v5, 0xbfb8aa3b, v5
	v_exp_f32_e32 v5, v5
	v_add_f32_e32 v1, 1.0, v37
	v_rcp_f32_e32 v36, v1
	v_and_b32_e32 v37, 0xffff0000, v47
	v_pk_mul_f32 v[42:43], v[108:109], v[4:5] op_sel_hi:[1,0]
	v_add_f32_e32 v1, 1.0, v5
	v_lshlrev_b32_e32 v5, 16, v47
	v_mul_f32_e32 v5, 0xbfb8aa3b, v5
	v_exp_f32_e32 v5, v5
	v_mul_f32_e32 v37, 0xbfb8aa3b, v37
	s_waitcnt vmcnt(0)
	v_pk_mul_f32 v[38:39], v[38:39], v[42:43]
	v_exp_f32_e32 v43, v37
	v_rcp_f32_e32 v37, v1
	v_add_f32_e32 v1, 1.0, v5
	v_rcp_f32_e32 v42, v1
	v_add_f32_e32 v1, 1.0, v43
	v_rcp_f32_e32 v43, v1
	v_pk_mul_f32 v[36:37], v[36:37], v[38:39]
	v_pk_mul_f32 v[38:39], v[100:101], v[4:5] op_sel_hi:[1,0]
	v_and_b32_sdwa v5, v36, v247 dst_sel:DWORD dst_unused:UNUSED_PAD src0_sel:WORD_1 src1_sel:DWORD
	v_pk_mul_f32 v[38:39], v[40:41], v[38:39]
	v_and_b32_sdwa v1, v37, v247 dst_sel:DWORD dst_unused:UNUSED_PAD src0_sel:WORD_1 src1_sel:DWORD
	v_add3_u32 v5, v36, v5, s73
	v_pk_mul_f32 v[38:39], v[42:43], v[38:39]
	v_add3_u32 v1, v37, v1, s73
	v_lshrrev_b32_e32 v5, 16, v5
	v_and_or_b32 v36, v1, s33, v5
	v_and_b32_sdwa v5, v38, v247 dst_sel:DWORD dst_unused:UNUSED_PAD src0_sel:WORD_1 src1_sel:DWORD
	v_and_b32_sdwa v1, v39, v247 dst_sel:DWORD dst_unused:UNUSED_PAD src0_sel:WORD_1 src1_sel:DWORD
	v_add3_u32 v5, v38, v5, s73
	v_add3_u32 v1, v39, v1, s73
	v_lshrrev_b32_e32 v5, 16, v5
	v_and_or_b32 v37, v1, s33, v5
	v_permlane32_swap_b32_e32 v34, v36
	s_nop 0
	v_permlane32_swap_b32_e32 v35, v37
	global_store_dwordx4 v[10:11], v[34:37], off offset:32
	global_load_dwordx2 v[42:43], v[88:89], off offset:64
	s_nop 0
	global_load_dwordx4 v[34:37], v[74:75], off offset:128
	global_load_dwordx2 v[44:45], v[88:89], off offset:80
	global_load_dwordx4 v[38:41], v[74:75], off offset:160
	s_waitcnt vmcnt(3)
	v_lshlrev_b32_e32 v1, 16, v42
	v_mul_f32_e32 v1, 0xbfb8aa3b, v1
	v_and_b32_e32 v5, 0xffff0000, v42
	v_exp_f32_e32 v1, v1
	v_mul_f32_e32 v5, 0xbfb8aa3b, v5
	v_exp_f32_e32 v5, v5
	v_add_f32_e32 v1, 1.0, v1
	v_rcp_f32_e32 v42, v1
	v_pk_mul_f32 v[46:47], v[92:93], v[4:5] op_sel_hi:[1,0]
	v_add_f32_e32 v1, 1.0, v5
	v_lshlrev_b32_e32 v5, 16, v43
	v_mul_f32_e32 v5, 0xbfb8aa3b, v5
	v_and_b32_e32 v43, 0xffff0000, v43
	v_exp_f32_e32 v5, v5
	v_mul_f32_e32 v43, 0xbfb8aa3b, v43
	s_waitcnt vmcnt(2)
	v_pk_mul_f32 v[34:35], v[34:35], v[46:47]
	v_exp_f32_e32 v47, v43
	v_rcp_f32_e32 v43, v1
	v_add_f32_e32 v1, 1.0, v5
	v_rcp_f32_e32 v46, v1
	v_add_f32_e32 v1, 1.0, v47
	v_rcp_f32_e32 v47, v1
	v_pk_mul_f32 v[34:35], v[42:43], v[34:35]
	v_pk_mul_f32 v[42:43], v[90:91], v[4:5] op_sel_hi:[1,0]
	v_and_b32_sdwa v5, v34, v247 dst_sel:DWORD dst_unused:UNUSED_PAD src0_sel:WORD_1 src1_sel:DWORD
	v_pk_mul_f32 v[36:37], v[36:37], v[42:43]
	v_and_b32_sdwa v1, v35, v247 dst_sel:DWORD dst_unused:UNUSED_PAD src0_sel:WORD_1 src1_sel:DWORD
	v_add3_u32 v5, v34, v5, s73
	v_pk_mul_f32 v[36:37], v[46:47], v[36:37]
	v_add3_u32 v1, v35, v1, s73
	v_lshrrev_b32_e32 v5, 16, v5
	v_and_or_b32 v34, v1, s33, v5
	v_and_b32_sdwa v5, v36, v247 dst_sel:DWORD dst_unused:UNUSED_PAD src0_sel:WORD_1 src1_sel:DWORD
	v_and_b32_sdwa v1, v37, v247 dst_sel:DWORD dst_unused:UNUSED_PAD src0_sel:WORD_1 src1_sel:DWORD
	s_waitcnt vmcnt(1)
	v_lshlrev_b32_e32 v35, 16, v44
	v_add3_u32 v5, v36, v5, s73
	v_add3_u32 v1, v37, v1, s73
	v_mul_f32_e32 v35, 0xbfb8aa3b, v35
	v_lshrrev_b32_e32 v5, 16, v5
	v_exp_f32_e32 v37, v35
	v_and_or_b32 v35, v1, s33, v5
	v_and_b32_e32 v5, 0xffff0000, v44
	v_mul_f32_e32 v5, 0xbfb8aa3b, v5
	v_exp_f32_e32 v5, v5
	v_add_f32_e32 v1, 1.0, v37
	v_rcp_f32_e32 v36, v1
	v_and_b32_e32 v37, 0xffff0000, v45
	v_pk_mul_f32 v[42:43], v[86:87], v[4:5] op_sel_hi:[1,0]
	v_add_f32_e32 v1, 1.0, v5
	v_lshlrev_b32_e32 v5, 16, v45
	v_mul_f32_e32 v5, 0xbfb8aa3b, v5
	v_exp_f32_e32 v5, v5
	v_mul_f32_e32 v37, 0xbfb8aa3b, v37
	s_waitcnt vmcnt(0)
	v_pk_mul_f32 v[38:39], v[38:39], v[42:43]
	v_exp_f32_e32 v43, v37
	v_rcp_f32_e32 v37, v1
	v_add_f32_e32 v1, 1.0, v5
	v_rcp_f32_e32 v42, v1
	v_add_f32_e32 v1, 1.0, v43
	v_rcp_f32_e32 v43, v1
	v_pk_mul_f32 v[36:37], v[36:37], v[38:39]
	v_pk_mul_f32 v[38:39], v[84:85], v[4:5] op_sel_hi:[1,0]
	v_and_b32_sdwa v5, v36, v247 dst_sel:DWORD dst_unused:UNUSED_PAD src0_sel:WORD_1 src1_sel:DWORD
	v_pk_mul_f32 v[38:39], v[40:41], v[38:39]
	v_and_b32_sdwa v1, v37, v247 dst_sel:DWORD dst_unused:UNUSED_PAD src0_sel:WORD_1 src1_sel:DWORD
	v_add3_u32 v5, v36, v5, s73
	v_pk_mul_f32 v[38:39], v[42:43], v[38:39]
	v_add3_u32 v1, v37, v1, s73
	v_lshrrev_b32_e32 v5, 16, v5
	v_and_or_b32 v36, v1, s33, v5
	v_and_b32_sdwa v5, v38, v247 dst_sel:DWORD dst_unused:UNUSED_PAD src0_sel:WORD_1 src1_sel:DWORD
	v_and_b32_sdwa v1, v39, v247 dst_sel:DWORD dst_unused:UNUSED_PAD src0_sel:WORD_1 src1_sel:DWORD
	v_add3_u32 v5, v38, v5, s73
	v_add3_u32 v1, v39, v1, s73
	v_lshrrev_b32_e32 v5, 16, v5
	v_and_or_b32 v37, v1, s33, v5
	v_permlane32_swap_b32_e32 v34, v36
	s_nop 0
	v_permlane32_swap_b32_e32 v35, v37
	global_store_dwordx4 v[10:11], v[34:37], off offset:64
	global_load_dwordx2 v[42:43], v[88:89], off offset:96
	s_nop 0
	global_load_dwordx4 v[34:37], v[74:75], off offset:192
	global_load_dwordx2 v[44:45], v[88:89], off offset:112
	global_load_dwordx4 v[38:41], v[74:75], off offset:224
	s_waitcnt vmcnt(3)
	v_lshlrev_b32_e32 v1, 16, v42
	v_mul_f32_e32 v1, 0xbfb8aa3b, v1
	v_and_b32_e32 v5, 0xffff0000, v42
	v_exp_f32_e32 v1, v1
	v_mul_f32_e32 v5, 0xbfb8aa3b, v5
	v_exp_f32_e32 v5, v5
	v_add_f32_e32 v1, 1.0, v1
	v_rcp_f32_e32 v42, v1
	v_pk_mul_f32 v[46:47], v[80:81], v[4:5] op_sel_hi:[1,0]
	v_add_f32_e32 v1, 1.0, v5
	v_lshlrev_b32_e32 v5, 16, v43
	v_mul_f32_e32 v5, 0xbfb8aa3b, v5
	v_and_b32_e32 v43, 0xffff0000, v43
	v_exp_f32_e32 v5, v5
	v_mul_f32_e32 v43, 0xbfb8aa3b, v43
	s_waitcnt vmcnt(2)
	v_pk_mul_f32 v[34:35], v[34:35], v[46:47]
	v_exp_f32_e32 v47, v43
	v_rcp_f32_e32 v43, v1
	v_add_f32_e32 v1, 1.0, v5
	v_rcp_f32_e32 v46, v1
	v_add_f32_e32 v1, 1.0, v47
	v_rcp_f32_e32 v47, v1
	v_pk_mul_f32 v[34:35], v[42:43], v[34:35]
	v_pk_mul_f32 v[42:43], v[78:79], v[4:5] op_sel_hi:[1,0]
	v_and_b32_sdwa v5, v34, v247 dst_sel:DWORD dst_unused:UNUSED_PAD src0_sel:WORD_1 src1_sel:DWORD
	v_pk_mul_f32 v[36:37], v[36:37], v[42:43]
	v_and_b32_sdwa v1, v35, v247 dst_sel:DWORD dst_unused:UNUSED_PAD src0_sel:WORD_1 src1_sel:DWORD
	v_add3_u32 v5, v34, v5, s73
	v_pk_mul_f32 v[36:37], v[46:47], v[36:37]
	v_add3_u32 v1, v35, v1, s73
	v_lshrrev_b32_e32 v5, 16, v5
	v_and_or_b32 v34, v1, s33, v5
	v_and_b32_sdwa v5, v36, v247 dst_sel:DWORD dst_unused:UNUSED_PAD src0_sel:WORD_1 src1_sel:DWORD
	v_and_b32_sdwa v1, v37, v247 dst_sel:DWORD dst_unused:UNUSED_PAD src0_sel:WORD_1 src1_sel:DWORD
	s_waitcnt vmcnt(1)
	v_lshlrev_b32_e32 v35, 16, v44
	v_add3_u32 v5, v36, v5, s73
	v_add3_u32 v1, v37, v1, s73
	v_mul_f32_e32 v35, 0xbfb8aa3b, v35
	v_lshrrev_b32_e32 v5, 16, v5
	v_exp_f32_e32 v37, v35
	v_and_or_b32 v35, v1, s33, v5
	v_and_b32_e32 v5, 0xffff0000, v44
	v_mul_f32_e32 v5, 0xbfb8aa3b, v5
	v_exp_f32_e32 v5, v5
	v_add_f32_e32 v1, 1.0, v37
	v_rcp_f32_e32 v36, v1
	v_and_b32_e32 v37, 0xffff0000, v45
	v_pk_mul_f32 v[42:43], v[76:77], v[4:5] op_sel_hi:[1,0]
	v_add_f32_e32 v1, 1.0, v5
	v_lshlrev_b32_e32 v5, 16, v45
	v_mul_f32_e32 v5, 0xbfb8aa3b, v5
	v_exp_f32_e32 v5, v5
	v_mul_f32_e32 v37, 0xbfb8aa3b, v37
	s_waitcnt vmcnt(0)
	v_pk_mul_f32 v[38:39], v[38:39], v[42:43]
	v_exp_f32_e32 v43, v37
	v_rcp_f32_e32 v37, v1
	v_add_f32_e32 v1, 1.0, v5
	v_rcp_f32_e32 v42, v1
	v_add_f32_e32 v1, 1.0, v43
	v_rcp_f32_e32 v43, v1
	v_pk_mul_f32 v[36:37], v[36:37], v[38:39]
	v_pk_mul_f32 v[32:33], v[32:33], v[4:5] op_sel_hi:[1,0]
	v_and_b32_sdwa v5, v36, v247 dst_sel:DWORD dst_unused:UNUSED_PAD src0_sel:WORD_1 src1_sel:DWORD
	v_pk_mul_f32 v[32:33], v[40:41], v[32:33]
	v_and_b32_sdwa v1, v37, v247 dst_sel:DWORD dst_unused:UNUSED_PAD src0_sel:WORD_1 src1_sel:DWORD
	v_add3_u32 v5, v36, v5, s73
	v_pk_mul_f32 v[32:33], v[42:43], v[32:33]
	v_add3_u32 v1, v37, v1, s73
	v_lshrrev_b32_e32 v5, 16, v5
	v_and_or_b32 v36, v1, s33, v5
	v_and_b32_sdwa v5, v32, v247 dst_sel:DWORD dst_unused:UNUSED_PAD src0_sel:WORD_1 src1_sel:DWORD
	v_and_b32_sdwa v1, v33, v247 dst_sel:DWORD dst_unused:UNUSED_PAD src0_sel:WORD_1 src1_sel:DWORD
	v_add3_u32 v5, v32, v5, s73
	v_add3_u32 v1, v33, v1, s73
	v_lshrrev_b32_e32 v5, 16, v5
	v_and_or_b32 v37, v1, s33, v5
	v_permlane32_swap_b32_e32 v34, v36
	s_nop 0
	v_permlane32_swap_b32_e32 v35, v37
	global_store_dwordx4 v[10:11], v[34:37], off offset:96
	global_load_dwordx2 v[40:41], v[88:89], off offset:128
	s_nop 0
	global_load_dwordx4 v[32:35], v[74:75], off offset:256
	global_load_dwordx2 v[42:43], v[88:89], off offset:144
	global_load_dwordx4 v[36:39], v[74:75], off offset:288
	s_waitcnt vmcnt(3)
	v_lshlrev_b32_e32 v1, 16, v40
	v_mul_f32_e32 v1, 0xbfb8aa3b, v1
	v_and_b32_e32 v5, 0xffff0000, v40
	v_exp_f32_e32 v1, v1
	v_mul_f32_e32 v5, 0xbfb8aa3b, v5
	v_exp_f32_e32 v5, v5
	v_add_f32_e32 v1, 1.0, v1
	v_rcp_f32_e32 v40, v1
	v_pk_mul_f32 v[30:31], v[30:31], v[4:5] op_sel_hi:[1,0]
	v_add_f32_e32 v1, 1.0, v5
	v_lshlrev_b32_e32 v5, 16, v41
	s_waitcnt vmcnt(2)
	v_pk_mul_f32 v[30:31], v[32:33], v[30:31]
	v_mul_f32_e32 v5, 0xbfb8aa3b, v5
	v_and_b32_e32 v32, 0xffff0000, v41
	v_exp_f32_e32 v5, v5
	v_mul_f32_e32 v32, 0xbfb8aa3b, v32
	v_exp_f32_e32 v33, v32
	v_rcp_f32_e32 v41, v1
	v_add_f32_e32 v1, 1.0, v5
	v_rcp_f32_e32 v32, v1
	v_add_f32_e32 v1, 1.0, v33
	v_rcp_f32_e32 v33, v1
	v_pk_mul_f32 v[30:31], v[40:41], v[30:31]
	v_pk_mul_f32 v[28:29], v[28:29], v[4:5] op_sel_hi:[1,0]
	v_and_b32_sdwa v5, v30, v247 dst_sel:DWORD dst_unused:UNUSED_PAD src0_sel:WORD_1 src1_sel:DWORD
	v_pk_mul_f32 v[28:29], v[34:35], v[28:29]
	v_and_b32_sdwa v1, v31, v247 dst_sel:DWORD dst_unused:UNUSED_PAD src0_sel:WORD_1 src1_sel:DWORD
	v_add3_u32 v5, v30, v5, s73
	v_pk_mul_f32 v[32:33], v[32:33], v[28:29]
	v_add3_u32 v1, v31, v1, s73
	v_lshrrev_b32_e32 v5, 16, v5
	v_and_or_b32 v28, v1, s33, v5
	v_and_b32_sdwa v5, v32, v247 dst_sel:DWORD dst_unused:UNUSED_PAD src0_sel:WORD_1 src1_sel:DWORD
	v_and_b32_sdwa v1, v33, v247 dst_sel:DWORD dst_unused:UNUSED_PAD src0_sel:WORD_1 src1_sel:DWORD
	s_waitcnt vmcnt(1)
	v_lshlrev_b32_e32 v29, 16, v42
	v_add3_u32 v5, v32, v5, s73
	v_add3_u32 v1, v33, v1, s73
	v_mul_f32_e32 v29, 0xbfb8aa3b, v29
	v_lshrrev_b32_e32 v5, 16, v5
	v_exp_f32_e32 v30, v29
	v_and_or_b32 v29, v1, s33, v5
	v_and_b32_e32 v5, 0xffff0000, v42
	v_mul_f32_e32 v5, 0xbfb8aa3b, v5
	v_exp_f32_e32 v5, v5
	v_add_f32_e32 v1, 1.0, v30
	v_rcp_f32_e32 v30, v1
	v_and_b32_e32 v31, 0xffff0000, v43
	v_pk_mul_f32 v[26:27], v[26:27], v[4:5] op_sel_hi:[1,0]
	v_add_f32_e32 v1, 1.0, v5
	v_lshlrev_b32_e32 v5, 16, v43
	v_mul_f32_e32 v5, 0xbfb8aa3b, v5
	v_exp_f32_e32 v5, v5
	v_mul_f32_e32 v31, 0xbfb8aa3b, v31
	v_exp_f32_e32 v33, v31
	v_rcp_f32_e32 v31, v1
	v_add_f32_e32 v1, 1.0, v5
	v_rcp_f32_e32 v32, v1
	v_add_f32_e32 v1, 1.0, v33
	s_waitcnt vmcnt(0)
	v_pk_mul_f32 v[26:27], v[36:37], v[26:27]
	v_rcp_f32_e32 v33, v1
	v_pk_mul_f32 v[26:27], v[30:31], v[26:27]
	v_pk_mul_f32 v[24:25], v[24:25], v[4:5] op_sel_hi:[1,0]
	v_and_b32_sdwa v5, v26, v247 dst_sel:DWORD dst_unused:UNUSED_PAD src0_sel:WORD_1 src1_sel:DWORD
	v_pk_mul_f32 v[24:25], v[38:39], v[24:25]
	v_and_b32_sdwa v1, v27, v247 dst_sel:DWORD dst_unused:UNUSED_PAD src0_sel:WORD_1 src1_sel:DWORD
	v_add3_u32 v5, v26, v5, s73
	v_pk_mul_f32 v[24:25], v[32:33], v[24:25]
	v_add3_u32 v1, v27, v1, s73
	v_lshrrev_b32_e32 v5, 16, v5
	v_and_or_b32 v30, v1, s33, v5
	v_and_b32_sdwa v5, v24, v247 dst_sel:DWORD dst_unused:UNUSED_PAD src0_sel:WORD_1 src1_sel:DWORD
	v_and_b32_sdwa v1, v25, v247 dst_sel:DWORD dst_unused:UNUSED_PAD src0_sel:WORD_1 src1_sel:DWORD
	v_add3_u32 v5, v24, v5, s73
	v_add3_u32 v1, v25, v1, s73
	v_lshrrev_b32_e32 v5, 16, v5
	v_and_or_b32 v31, v1, s33, v5
	v_permlane32_swap_b32_e32 v28, v30
	s_nop 0
	v_permlane32_swap_b32_e32 v29, v31
	global_store_dwordx4 v[10:11], v[28:31], off offset:128
	global_load_dwordx2 v[32:33], v[88:89], off offset:160
	global_load_dwordx4 v[24:27], v[74:75], off offset:320
	global_load_dwordx2 v[34:35], v[88:89], off offset:176
	s_nop 0
	global_load_dwordx4 v[28:31], v[74:75], off offset:352
	s_waitcnt vmcnt(3)
	v_lshlrev_b32_e32 v1, 16, v32
	v_mul_f32_e32 v1, 0xbfb8aa3b, v1
	v_and_b32_e32 v5, 0xffff0000, v32
	v_exp_f32_e32 v1, v1
	v_mul_f32_e32 v5, 0xbfb8aa3b, v5
	v_exp_f32_e32 v5, v5
	v_add_f32_e32 v1, 1.0, v1
	v_rcp_f32_e32 v32, v1
	v_pk_mul_f32 v[22:23], v[22:23], v[4:5] op_sel_hi:[1,0]
	v_add_f32_e32 v1, 1.0, v5
	v_lshlrev_b32_e32 v5, 16, v33
	s_waitcnt vmcnt(2)
	v_pk_mul_f32 v[22:23], v[24:25], v[22:23]
	v_mul_f32_e32 v5, 0xbfb8aa3b, v5
	v_and_b32_e32 v24, 0xffff0000, v33
	v_exp_f32_e32 v5, v5
	v_mul_f32_e32 v24, 0xbfb8aa3b, v24
	v_exp_f32_e32 v25, v24
	v_rcp_f32_e32 v33, v1
	v_add_f32_e32 v1, 1.0, v5
	v_rcp_f32_e32 v24, v1
	v_add_f32_e32 v1, 1.0, v25
	v_rcp_f32_e32 v25, v1
	v_pk_mul_f32 v[22:23], v[32:33], v[22:23]
	v_pk_mul_f32 v[20:21], v[20:21], v[4:5] op_sel_hi:[1,0]
	v_and_b32_sdwa v5, v22, v247 dst_sel:DWORD dst_unused:UNUSED_PAD src0_sel:WORD_1 src1_sel:DWORD
	v_pk_mul_f32 v[20:21], v[26:27], v[20:21]
	v_and_b32_sdwa v1, v23, v247 dst_sel:DWORD dst_unused:UNUSED_PAD src0_sel:WORD_1 src1_sel:DWORD
	v_add3_u32 v5, v22, v5, s73
	v_pk_mul_f32 v[24:25], v[24:25], v[20:21]
	v_add3_u32 v1, v23, v1, s73
	v_lshrrev_b32_e32 v5, 16, v5
	v_and_or_b32 v20, v1, s33, v5
	v_and_b32_sdwa v5, v24, v247 dst_sel:DWORD dst_unused:UNUSED_PAD src0_sel:WORD_1 src1_sel:DWORD
	v_and_b32_sdwa v1, v25, v247 dst_sel:DWORD dst_unused:UNUSED_PAD src0_sel:WORD_1 src1_sel:DWORD
	s_waitcnt vmcnt(1)
	v_lshlrev_b32_e32 v21, 16, v34
	v_add3_u32 v5, v24, v5, s73
	v_add3_u32 v1, v25, v1, s73
	v_mul_f32_e32 v21, 0xbfb8aa3b, v21
	v_lshrrev_b32_e32 v5, 16, v5
	v_exp_f32_e32 v22, v21
	v_and_or_b32 v21, v1, s33, v5
	v_and_b32_e32 v5, 0xffff0000, v34
	v_mul_f32_e32 v5, 0xbfb8aa3b, v5
	v_exp_f32_e32 v5, v5
	v_add_f32_e32 v1, 1.0, v22
	v_rcp_f32_e32 v22, v1
	v_and_b32_e32 v23, 0xffff0000, v35
	v_pk_mul_f32 v[18:19], v[18:19], v[4:5] op_sel_hi:[1,0]
	v_add_f32_e32 v1, 1.0, v5
	v_lshlrev_b32_e32 v5, 16, v35
	v_mul_f32_e32 v5, 0xbfb8aa3b, v5
	v_exp_f32_e32 v5, v5
	v_mul_f32_e32 v23, 0xbfb8aa3b, v23
	v_exp_f32_e32 v25, v23
	v_rcp_f32_e32 v23, v1
	v_add_f32_e32 v1, 1.0, v5
	v_rcp_f32_e32 v24, v1
	v_add_f32_e32 v1, 1.0, v25
	s_waitcnt vmcnt(0)
	v_pk_mul_f32 v[18:19], v[28:29], v[18:19]
	v_rcp_f32_e32 v25, v1
	v_pk_mul_f32 v[18:19], v[22:23], v[18:19]
	v_pk_mul_f32 v[16:17], v[16:17], v[4:5] op_sel_hi:[1,0]
	v_and_b32_sdwa v5, v18, v247 dst_sel:DWORD dst_unused:UNUSED_PAD src0_sel:WORD_1 src1_sel:DWORD
	v_pk_mul_f32 v[16:17], v[30:31], v[16:17]
	v_and_b32_sdwa v1, v19, v247 dst_sel:DWORD dst_unused:UNUSED_PAD src0_sel:WORD_1 src1_sel:DWORD
	v_add3_u32 v5, v18, v5, s73
	v_pk_mul_f32 v[16:17], v[24:25], v[16:17]
	v_add3_u32 v1, v19, v1, s73
	v_lshrrev_b32_e32 v5, 16, v5
	v_and_or_b32 v22, v1, s33, v5
	v_and_b32_sdwa v5, v16, v247 dst_sel:DWORD dst_unused:UNUSED_PAD src0_sel:WORD_1 src1_sel:DWORD
	v_and_b32_sdwa v1, v17, v247 dst_sel:DWORD dst_unused:UNUSED_PAD src0_sel:WORD_1 src1_sel:DWORD
	v_add3_u32 v5, v16, v5, s73
	v_add3_u32 v1, v17, v1, s73
	v_lshrrev_b32_e32 v5, 16, v5
	v_and_or_b32 v23, v1, s33, v5
	v_permlane32_swap_b32_e32 v20, v22
	s_nop 0
	v_permlane32_swap_b32_e32 v21, v23
	global_store_dwordx4 v[10:11], v[20:23], off offset:160
	global_load_dwordx2 v[24:25], v[88:89], off offset:192
	global_load_dwordx4 v[16:19], v[74:75], off offset:384
	global_load_dwordx2 v[26:27], v[88:89], off offset:208
	s_nop 0
	global_load_dwordx4 v[20:23], v[74:75], off offset:416
	s_waitcnt vmcnt(3)
	v_lshlrev_b32_e32 v1, 16, v24
	v_mul_f32_e32 v1, 0xbfb8aa3b, v1
	v_and_b32_e32 v5, 0xffff0000, v24
	v_exp_f32_e32 v1, v1
	v_mul_f32_e32 v5, 0xbfb8aa3b, v5
	v_exp_f32_e32 v5, v5
	v_add_f32_e32 v1, 1.0, v1
	v_rcp_f32_e32 v24, v1
	v_pk_mul_f32 v[14:15], v[14:15], v[4:5] op_sel_hi:[1,0]
	v_add_f32_e32 v1, 1.0, v5
	v_lshlrev_b32_e32 v5, 16, v25
	s_waitcnt vmcnt(2)
	v_pk_mul_f32 v[14:15], v[16:17], v[14:15]
	v_mul_f32_e32 v5, 0xbfb8aa3b, v5
	v_and_b32_e32 v16, 0xffff0000, v25
	v_exp_f32_e32 v5, v5
	v_mul_f32_e32 v16, 0xbfb8aa3b, v16
	v_exp_f32_e32 v17, v16
	v_rcp_f32_e32 v25, v1
	v_add_f32_e32 v1, 1.0, v5
	v_rcp_f32_e32 v16, v1
	v_add_f32_e32 v1, 1.0, v17
	v_rcp_f32_e32 v17, v1
	v_pk_mul_f32 v[14:15], v[24:25], v[14:15]
	v_pk_mul_f32 v[12:13], v[12:13], v[4:5] op_sel_hi:[1,0]
	v_and_b32_sdwa v5, v14, v247 dst_sel:DWORD dst_unused:UNUSED_PAD src0_sel:WORD_1 src1_sel:DWORD
	v_pk_mul_f32 v[12:13], v[18:19], v[12:13]
	v_and_b32_sdwa v1, v15, v247 dst_sel:DWORD dst_unused:UNUSED_PAD src0_sel:WORD_1 src1_sel:DWORD
	v_add3_u32 v5, v14, v5, s73
	v_pk_mul_f32 v[16:17], v[16:17], v[12:13]
	v_add3_u32 v1, v15, v1, s73
	v_lshrrev_b32_e32 v5, 16, v5
	v_and_or_b32 v12, v1, s33, v5
	v_and_b32_sdwa v5, v16, v247 dst_sel:DWORD dst_unused:UNUSED_PAD src0_sel:WORD_1 src1_sel:DWORD
	v_and_b32_sdwa v1, v17, v247 dst_sel:DWORD dst_unused:UNUSED_PAD src0_sel:WORD_1 src1_sel:DWORD
	s_waitcnt vmcnt(1)
	v_lshlrev_b32_e32 v13, 16, v26
	v_add3_u32 v5, v16, v5, s73
	v_add3_u32 v1, v17, v1, s73
	v_mul_f32_e32 v13, 0xbfb8aa3b, v13
	v_lshrrev_b32_e32 v5, 16, v5
	v_exp_f32_e32 v14, v13
	v_and_or_b32 v13, v1, s33, v5
	v_and_b32_e32 v5, 0xffff0000, v26
	v_mul_f32_e32 v5, 0xbfb8aa3b, v5
	v_exp_f32_e32 v5, v5
	v_add_f32_e32 v1, 1.0, v14
	v_rcp_f32_e32 v14, v1
	v_and_b32_e32 v15, 0xffff0000, v27
	v_pk_mul_f32 v[8:9], v[8:9], v[4:5] op_sel_hi:[1,0]
	v_add_f32_e32 v1, 1.0, v5
	v_lshlrev_b32_e32 v5, 16, v27
	v_mul_f32_e32 v5, 0xbfb8aa3b, v5
	v_exp_f32_e32 v5, v5
	v_mul_f32_e32 v15, 0xbfb8aa3b, v15
	v_exp_f32_e32 v17, v15
	v_rcp_f32_e32 v15, v1
	v_add_f32_e32 v1, 1.0, v5
	v_rcp_f32_e32 v16, v1
	v_add_f32_e32 v1, 1.0, v17
	s_waitcnt vmcnt(0)
	v_pk_mul_f32 v[8:9], v[20:21], v[8:9]
	v_rcp_f32_e32 v17, v1
	v_pk_mul_f32 v[8:9], v[14:15], v[8:9]
	v_pk_mul_f32 v[6:7], v[6:7], v[4:5] op_sel_hi:[1,0]
	v_and_b32_sdwa v5, v8, v247 dst_sel:DWORD dst_unused:UNUSED_PAD src0_sel:WORD_1 src1_sel:DWORD
	v_pk_mul_f32 v[6:7], v[22:23], v[6:7]
	v_and_b32_sdwa v1, v9, v247 dst_sel:DWORD dst_unused:UNUSED_PAD src0_sel:WORD_1 src1_sel:DWORD
	v_add3_u32 v5, v8, v5, s73
	v_pk_mul_f32 v[6:7], v[16:17], v[6:7]
	v_add3_u32 v1, v9, v1, s73
	v_lshrrev_b32_e32 v5, 16, v5
	v_and_or_b32 v14, v1, s33, v5
	v_and_b32_sdwa v5, v6, v247 dst_sel:DWORD dst_unused:UNUSED_PAD src0_sel:WORD_1 src1_sel:DWORD
	v_and_b32_sdwa v1, v7, v247 dst_sel:DWORD dst_unused:UNUSED_PAD src0_sel:WORD_1 src1_sel:DWORD
	v_add3_u32 v5, v6, v5, s73
	v_add3_u32 v1, v7, v1, s73
	v_lshrrev_b32_e32 v5, 16, v5
	v_and_or_b32 v15, v1, s33, v5
	v_permlane32_swap_b32_e32 v12, v14
	s_nop 0
	v_permlane32_swap_b32_e32 v13, v15
	global_store_dwordx4 v[10:11], v[12:15], off offset:192
	global_load_dwordx2 v[16:17], v[88:89], off offset:224
	global_load_dwordx4 v[6:9], v[74:75], off offset:448
	global_load_dwordx2 v[18:19], v[88:89], off offset:240
	s_nop 0
	global_load_dwordx4 v[12:15], v[74:75], off offset:480
	s_waitcnt vmcnt(3)
	v_lshlrev_b32_e32 v1, 16, v16
	v_and_b32_e32 v5, 0xffff0000, v16
	v_mul_f32_e32 v1, 0xbfb8aa3b, v1
	v_mul_f32_e32 v5, 0xbfb8aa3b, v5
	v_exp_f32_e32 v1, v1
	v_exp_f32_e32 v5, v5
	v_add_f32_e32 v1, 1.0, v1
	v_pk_mul_f32 v[2:3], v[2:3], v[4:5] op_sel_hi:[1,0]
	v_add_f32_e32 v5, 1.0, v5
	s_waitcnt vmcnt(2)
	v_pk_mul_f32 v[2:3], v[6:7], v[2:3]
	v_rcp_f32_e32 v6, v1
	v_lshlrev_b32_e32 v1, 16, v17
	v_rcp_f32_e32 v7, v5
	v_mul_f32_e32 v1, 0xbfb8aa3b, v1
	v_and_b32_e32 v5, 0xffff0000, v17
	v_exp_f32_e32 v1, v1
	v_mul_f32_e32 v5, 0xbfb8aa3b, v5
	v_exp_f32_e32 v5, v5
	v_pk_mul_f32 v[2:3], v[6:7], v[2:3]
	v_add_f32_e32 v1, 1.0, v1
	v_rcp_f32_e32 v16, v1
	v_add_f32_e32 v1, 1.0, v5
	v_and_b32_sdwa v5, v2, v247 dst_sel:DWORD dst_unused:UNUSED_PAD src0_sel:WORD_1 src1_sel:DWORD
	v_rcp_f32_e32 v17, v1
	v_and_b32_sdwa v1, v3, v247 dst_sel:DWORD dst_unused:UNUSED_PAD src0_sel:WORD_1 src1_sel:DWORD
	v_add3_u32 v2, v2, v5, s73
	v_add3_u32 v1, v3, v1, s73
	v_lshrrev_b32_e32 v2, 16, v2
	v_and_or_b32 v6, v1, s33, v2
	v_pk_mul_f32 v[2:3], v[72:73], v[4:5] op_sel_hi:[1,0]
	s_nop 0
	v_pk_mul_f32 v[2:3], v[8:9], v[2:3]
	s_nop 0
	v_pk_mul_f32 v[2:3], v[16:17], v[2:3]
	s_nop 0
	v_and_b32_sdwa v1, v3, v247 dst_sel:DWORD dst_unused:UNUSED_PAD src0_sel:WORD_1 src1_sel:DWORD
	s_nop 0
	v_add3_u32 v1, v3, v1, s73
	s_waitcnt vmcnt(1)
	v_lshlrev_b32_e32 v3, 16, v18
	v_and_b32_sdwa v5, v2, v247 dst_sel:DWORD dst_unused:UNUSED_PAD src0_sel:WORD_1 src1_sel:DWORD
	v_mul_f32_e32 v3, 0xbfb8aa3b, v3
	v_add3_u32 v2, v2, v5, s73
	v_exp_f32_e32 v3, v3
	v_and_b32_e32 v5, 0xffff0000, v18
	v_mul_f32_e32 v5, 0xbfb8aa3b, v5
	v_exp_f32_e32 v5, v5
	v_lshrrev_b32_e32 v2, 16, v2
	v_and_or_b32 v7, v1, s33, v2
	v_add_f32_e32 v1, 1.0, v3
	v_lshlrev_b32_e32 v3, 16, v19
	v_mul_f32_e32 v3, 0xbfb8aa3b, v3
	v_rcp_f32_e32 v2, v1
	v_add_f32_e32 v1, 1.0, v5
	v_exp_f32_e32 v5, v3
	v_and_b32_e32 v3, 0xffff0000, v19
	v_mul_f32_e32 v3, 0xbfb8aa3b, v3
	v_exp_f32_e32 v8, v3
	v_rcp_f32_e32 v3, v1
	v_add_f32_e32 v1, 1.0, v5
	v_rcp_f32_e32 v16, v1
	v_add_f32_e32 v1, 1.0, v8
	v_pk_mul_f32 v[8:9], v[70:71], v[4:5] op_sel_hi:[1,0]
	v_rcp_f32_e32 v17, v1
	s_waitcnt vmcnt(0)
	v_pk_mul_f32 v[8:9], v[12:13], v[8:9]
	s_nop 0
	v_pk_mul_f32 v[2:3], v[2:3], v[8:9]
	s_nop 0
	v_and_b32_sdwa v5, v2, v247 dst_sel:DWORD dst_unused:UNUSED_PAD src0_sel:WORD_1 src1_sel:DWORD
	v_and_b32_sdwa v1, v3, v247 dst_sel:DWORD dst_unused:UNUSED_PAD src0_sel:WORD_1 src1_sel:DWORD
	v_add3_u32 v2, v2, v5, s73
	v_add3_u32 v1, v3, v1, s73
	v_lshrrev_b32_e32 v2, 16, v2
	v_and_or_b32 v8, v1, s33, v2
	v_pk_mul_f32 v[2:3], v[68:69], v[4:5] op_sel_hi:[1,0]
	s_nop 0
	v_permlane32_swap_b32_e32 v6, v8
	v_pk_mul_f32 v[2:3], v[14:15], v[2:3]
	s_nop 0
	v_pk_mul_f32 v[2:3], v[16:17], v[2:3]
	s_nop 0
	v_and_b32_sdwa v4, v2, v247 dst_sel:DWORD dst_unused:UNUSED_PAD src0_sel:WORD_1 src1_sel:DWORD
	v_and_b32_sdwa v1, v3, v247 dst_sel:DWORD dst_unused:UNUSED_PAD src0_sel:WORD_1 src1_sel:DWORD
	v_add3_u32 v2, v2, v4, s73
	v_add3_u32 v1, v3, v1, s73
	v_lshrrev_b32_e32 v2, 16, v2
	v_and_or_b32 v9, v1, s33, v2
	s_nop 1
	v_permlane32_swap_b32_e32 v7, v9
	global_store_dwordx4 v[10:11], v[6:9], off offset:224
	s_barrier
	s_branch .LBB0_619

.LBB0_1130:
	s_lshl_b32 s19, s38, 8
	v_mov_b32_e32 v132, v200
	v_mov_b32_e32 v133, v1
	s_or_b32 s19, s19, s80
	s_mov_b64 s[38:39], -1
	v_lshl_add_u32 v176, v133, 3, s19
	v_add_u32_e32 v174, s79, v132
	s_cmp_lt_i32 s36, 32
	v_ashrrev_i32_e32 v177, 31, v176
	s_mov_b64 s[58:59], 0x80000
	s_cbranch_scc0 .LBB0_1133
	v_lshlrev_b32_e32 v178, 2, v176
	v_lshl_add_u32 v179, s36, 8, v174
	v_lshl_add_u32 v179, v179, 13, v178
	global_load_dwordx4 v[132:135], v178, s[14:15]
	global_load_dwordx4 v[136:139], v178, s[14:15] offset:16
	global_load_dwordx4 v[140:143], v178, s[14:15] offset:512
	global_load_dwordx4 v[144:147], v178, s[14:15] offset:528
	global_load_dwordx4 v[148:151], v179, s[10:11]
	global_load_dwordx4 v[152:155], v179, s[10:11] offset:16
	global_load_dwordx4 v[156:159], v179, s[10:11] offset:512
	global_load_dwordx4 v[160:163], v179, s[10:11] offset:528
	v_add_u32_e32 v178, 0x20000, v179
	global_load_dwordx4 v[180:183], v178, s[10:11]
	global_load_dwordx4 v[184:187], v178, s[10:11] offset:16
	global_load_dwordx4 v[188:191], v178, s[10:11] offset:512
	global_load_dwordx4 v[192:195], v178, s[10:11] offset:528
	v_add_u32_e32 v178, 0x40000, v179
	global_load_dwordx4 v[196:199], v178, s[10:11]
	global_load_dwordx4 v[204:207], v178, s[10:11] offset:16
	global_load_dwordx4 v[208:211], v178, s[10:11] offset:512
	global_load_dwordx4 v[212:215], v178, s[10:11] offset:528
	s_waitcnt vmcnt(12)
	v_pk_add_f32 v[132:133], v[132:133], 1.0 op_sel_hi:[1,0]
	v_pk_add_f32 v[134:135], v[134:135], 1.0 op_sel_hi:[1,0]
	v_pk_add_f32 v[136:137], v[136:137], 1.0 op_sel_hi:[1,0]
	v_pk_add_f32 v[138:139], v[138:139], 1.0 op_sel_hi:[1,0]
	v_pk_add_f32 v[140:141], v[140:141], 1.0 op_sel_hi:[1,0]
	v_pk_add_f32 v[142:143], v[142:143], 1.0 op_sel_hi:[1,0]
	v_pk_add_f32 v[144:145], v[144:145], 1.0 op_sel_hi:[1,0]
	v_pk_add_f32 v[146:147], v[146:147], 1.0 op_sel_hi:[1,0]
	s_waitcnt vmcnt(8)
	v_pk_mul_f32 v[148:149], v[148:149], s[92:93] op_sel_hi:[1,0]
	v_pk_mul_f32 v[150:151], v[150:151], s[92:93] op_sel_hi:[1,0]
	v_pk_fma_f32 v[148:149], v[128:129], v[132:133], v[148:149]
	v_pk_fma_f32 v[150:151], v[130:131], v[134:135], v[150:151]
	v_pk_mul_f32 v[152:153], v[152:153], s[92:93] op_sel_hi:[1,0]
	v_pk_mul_f32 v[154:155], v[154:155], s[92:93] op_sel_hi:[1,0]
	v_pk_fma_f32 v[152:153], v[124:125], v[136:137], v[152:153]
	v_pk_fma_f32 v[154:155], v[126:127], v[138:139], v[154:155]
	v_pk_mul_f32 v[156:157], v[156:157], s[92:93] op_sel_hi:[1,0]
	v_pk_mul_f32 v[158:159], v[158:159], s[92:93] op_sel_hi:[1,0]
	v_pk_fma_f32 v[156:157], v[112:113], v[140:141], v[156:157]
	v_pk_fma_f32 v[158:159], v[114:115], v[142:143], v[158:159]
	v_pk_mul_f32 v[160:161], v[160:161], s[92:93] op_sel_hi:[1,0]
	v_pk_mul_f32 v[162:163], v[162:163], s[92:93] op_sel_hi:[1,0]
	v_pk_fma_f32 v[160:161], v[104:105], v[144:145], v[160:161]
	v_pk_fma_f32 v[162:163], v[106:107], v[146:147], v[162:163]
	v_cvt_pk_bf16_f32 v128, v148, v149
	v_cvt_pk_bf16_f32 v129, v150, v151
	v_cvt_pk_bf16_f32 v130, v152, v153
	v_cvt_pk_bf16_f32 v131, v154, v155
	v_cvt_pk_bf16_f32 v112, v156, v157
	v_cvt_pk_bf16_f32 v113, v158, v159
	v_cvt_pk_bf16_f32 v114, v160, v161
	v_cvt_pk_bf16_f32 v115, v162, v163
	v_add_u32_e32 v178, 0x60000, v179
	global_load_dwordx4 v[148:151], v178, s[10:11]
	global_load_dwordx4 v[152:155], v178, s[10:11] offset:16
	global_load_dwordx4 v[156:159], v178, s[10:11] offset:512
	global_load_dwordx4 v[160:163], v178, s[10:11] offset:528
	s_waitcnt vmcnt(8)
	v_pk_mul_f32 v[180:181], v[180:181], s[92:93] op_sel_hi:[1,0]
	v_pk_mul_f32 v[182:183], v[182:183], s[92:93] op_sel_hi:[1,0]
	v_pk_fma_f32 v[180:181], v[120:121], v[132:133], v[180:181]
	v_pk_fma_f32 v[182:183], v[122:123], v[134:135], v[182:183]
	v_pk_mul_f32 v[184:185], v[184:185], s[92:93] op_sel_hi:[1,0]
	v_pk_mul_f32 v[186:187], v[186:187], s[92:93] op_sel_hi:[1,0]
	v_pk_fma_f32 v[184:185], v[116:117], v[136:137], v[184:185]
	v_pk_fma_f32 v[186:187], v[118:119], v[138:139], v[186:187]
	v_pk_mul_f32 v[188:189], v[188:189], s[92:93] op_sel_hi:[1,0]
	v_pk_mul_f32 v[190:191], v[190:191], s[92:93] op_sel_hi:[1,0]
	v_pk_fma_f32 v[188:189], v[96:97], v[140:141], v[188:189]
	v_pk_fma_f32 v[190:191], v[98:99], v[142:143], v[190:191]
	v_pk_mul_f32 v[192:193], v[192:193], s[92:93] op_sel_hi:[1,0]
	v_pk_mul_f32 v[194:195], v[194:195], s[92:93] op_sel_hi:[1,0]
	v_pk_fma_f32 v[192:193], v[88:89], v[144:145], v[192:193]
	v_pk_fma_f32 v[194:195], v[90:91], v[146:147], v[194:195]
	v_cvt_pk_bf16_f32 v120, v180, v181
	v_cvt_pk_bf16_f32 v121, v182, v183
	v_cvt_pk_bf16_f32 v122, v184, v185
	v_cvt_pk_bf16_f32 v123, v186, v187
	v_cvt_pk_bf16_f32 v96, v188, v189
	v_cvt_pk_bf16_f32 v97, v190, v191
	v_cvt_pk_bf16_f32 v98, v192, v193
	v_cvt_pk_bf16_f32 v99, v194, v195
	v_add_u32_e32 v178, 0x100000, v179
	global_load_dwordx4 v[180:183], v178, s[10:11]
	global_load_dwordx4 v[184:187], v178, s[10:11] offset:16
	global_load_dwordx4 v[188:191], v178, s[10:11] offset:512
	global_load_dwordx4 v[192:195], v178, s[10:11] offset:528
	s_waitcnt vmcnt(8)
	v_pk_mul_f32 v[196:197], v[196:197], s[92:93] op_sel_hi:[1,0]
	v_pk_mul_f32 v[198:199], v[198:199], s[92:93] op_sel_hi:[1,0]
	v_pk_fma_f32 v[196:197], v[108:109], v[132:133], v[196:197]
	v_pk_fma_f32 v[198:199], v[110:111], v[134:135], v[198:199]
	v_pk_mul_f32 v[204:205], v[204:205], s[92:93] op_sel_hi:[1,0]
	v_pk_mul_f32 v[206:207], v[206:207], s[92:93] op_sel_hi:[1,0]
	v_pk_fma_f32 v[204:205], v[100:101], v[136:137], v[204:205]
	v_pk_fma_f32 v[206:207], v[102:103], v[138:139], v[206:207]
	v_pk_mul_f32 v[208:209], v[208:209], s[92:93] op_sel_hi:[1,0]
	v_pk_mul_f32 v[210:211], v[210:211], s[92:93] op_sel_hi:[1,0]
	v_pk_fma_f32 v[208:209], v[78:79], v[140:141], v[208:209]
	v_pk_fma_f32 v[210:211], v[80:81], v[142:143], v[210:211]
	v_pk_mul_f32 v[212:213], v[212:213], s[92:93] op_sel_hi:[1,0]
	v_pk_mul_f32 v[214:215], v[214:215], s[92:93] op_sel_hi:[1,0]
	v_pk_fma_f32 v[212:213], v[74:75], v[144:145], v[212:213]
	v_pk_fma_f32 v[214:215], v[76:77], v[146:147], v[214:215]
	v_cvt_pk_bf16_f32 v108, v196, v197
	v_cvt_pk_bf16_f32 v109, v198, v199
	v_cvt_pk_bf16_f32 v110, v204, v205
	v_cvt_pk_bf16_f32 v111, v206, v207
	v_cvt_pk_bf16_f32 v78, v208, v209
	v_cvt_pk_bf16_f32 v79, v210, v211
	v_cvt_pk_bf16_f32 v80, v212, v213
	v_cvt_pk_bf16_f32 v81, v214, v215
	v_add_u32_e32 v178, 0x120000, v179
	global_load_dwordx4 v[196:199], v178, s[10:11]
	global_load_dwordx4 v[204:207], v178, s[10:11] offset:16
	global_load_dwordx4 v[208:211], v178, s[10:11] offset:512
	global_load_dwordx4 v[212:215], v178, s[10:11] offset:528
	s_waitcnt vmcnt(8)
	v_pk_mul_f32 v[148:149], v[148:149], s[92:93] op_sel_hi:[1,0]
	v_pk_mul_f32 v[150:151], v[150:151], s[92:93] op_sel_hi:[1,0]
	v_pk_fma_f32 v[148:149], v[92:93], v[132:133], v[148:149]
	v_pk_fma_f32 v[150:151], v[94:95], v[134:135], v[150:151]
	v_pk_mul_f32 v[152:153], v[152:153], s[92:93] op_sel_hi:[1,0]
	v_pk_mul_f32 v[154:155], v[154:155], s[92:93] op_sel_hi:[1,0]
	v_pk_fma_f32 v[152:153], v[84:85], v[136:137], v[152:153]
	v_pk_fma_f32 v[154:155], v[86:87], v[138:139], v[154:155]
	v_pk_mul_f32 v[156:157], v[156:157], s[92:93] op_sel_hi:[1,0]
	v_pk_mul_f32 v[158:159], v[158:159], s[92:93] op_sel_hi:[1,0]
	v_pk_fma_f32 v[156:157], v[70:71], v[140:141], v[156:157]
	v_pk_fma_f32 v[158:159], v[72:73], v[142:143], v[158:159]
	v_pk_mul_f32 v[160:161], v[160:161], s[92:93] op_sel_hi:[1,0]
	v_pk_mul_f32 v[162:163], v[162:163], s[92:93] op_sel_hi:[1,0]
	v_pk_fma_f32 v[160:161], v[66:67], v[144:145], v[160:161]
	v_pk_fma_f32 v[162:163], v[68:69], v[146:147], v[162:163]
	v_cvt_pk_bf16_f32 v92, v148, v149
	v_cvt_pk_bf16_f32 v93, v150, v151
	v_cvt_pk_bf16_f32 v94, v152, v153
	v_cvt_pk_bf16_f32 v95, v154, v155
	v_cvt_pk_bf16_f32 v70, v156, v157
	v_cvt_pk_bf16_f32 v71, v158, v159
	v_cvt_pk_bf16_f32 v72, v160, v161
	v_cvt_pk_bf16_f32 v73, v162, v163
	v_add_u32_e32 v178, 0x140000, v179
	global_load_dwordx4 v[148:151], v178, s[10:11]
	global_load_dwordx4 v[152:155], v178, s[10:11] offset:16
	global_load_dwordx4 v[156:159], v178, s[10:11] offset:512
	global_load_dwordx4 v[160:163], v178, s[10:11] offset:528
	s_waitcnt vmcnt(8)
	v_pk_mul_f32 v[180:181], v[180:181], s[92:93] op_sel_hi:[1,0]
	v_pk_mul_f32 v[182:183], v[182:183], s[92:93] op_sel_hi:[1,0]
	v_pk_fma_f32 v[180:181], v[62:63], v[132:133], v[180:181]
	v_pk_fma_f32 v[182:183], v[64:65], v[134:135], v[182:183]
	v_pk_mul_f32 v[184:185], v[184:185], s[92:93] op_sel_hi:[1,0]
	v_pk_mul_f32 v[186:187], v[186:187], s[92:93] op_sel_hi:[1,0]
	v_pk_fma_f32 v[184:185], v[58:59], v[136:137], v[184:185]
	v_pk_fma_f32 v[186:187], v[60:61], v[138:139], v[186:187]
	v_pk_mul_f32 v[188:189], v[188:189], s[92:93] op_sel_hi:[1,0]
	v_pk_mul_f32 v[190:191], v[190:191], s[92:93] op_sel_hi:[1,0]
	v_pk_fma_f32 v[188:189], v[46:47], v[140:141], v[188:189]
	v_pk_fma_f32 v[190:191], v[48:49], v[142:143], v[190:191]
	v_pk_mul_f32 v[192:193], v[192:193], s[92:93] op_sel_hi:[1,0]
	v_pk_mul_f32 v[194:195], v[194:195], s[92:93] op_sel_hi:[1,0]
	v_pk_fma_f32 v[192:193], v[42:43], v[144:145], v[192:193]
	v_pk_fma_f32 v[194:195], v[44:45], v[146:147], v[194:195]
	v_cvt_pk_bf16_f32 v62, v180, v181
	v_cvt_pk_bf16_f32 v63, v182, v183
	v_cvt_pk_bf16_f32 v64, v184, v185
	v_cvt_pk_bf16_f32 v65, v186, v187
	v_cvt_pk_bf16_f32 v46, v188, v189
	v_cvt_pk_bf16_f32 v47, v190, v191
	v_cvt_pk_bf16_f32 v48, v192, v193
	v_cvt_pk_bf16_f32 v49, v194, v195
	v_add_u32_e32 v178, 0x160000, v179
	global_load_dwordx4 v[180:183], v178, s[10:11]
	global_load_dwordx4 v[184:187], v178, s[10:11] offset:16
	global_load_dwordx4 v[188:191], v178, s[10:11] offset:512
	global_load_dwordx4 v[192:195], v178, s[10:11] offset:528
	s_waitcnt vmcnt(8)
	v_pk_mul_f32 v[196:197], v[196:197], s[92:93] op_sel_hi:[1,0]
	v_pk_mul_f32 v[198:199], v[198:199], s[92:93] op_sel_hi:[1,0]
	v_pk_fma_f32 v[196:197], v[54:55], v[132:133], v[196:197]
	v_pk_fma_f32 v[198:199], v[56:57], v[134:135], v[198:199]
	v_pk_mul_f32 v[204:205], v[204:205], s[92:93] op_sel_hi:[1,0]
	v_pk_mul_f32 v[206:207], v[206:207], s[92:93] op_sel_hi:[1,0]
	v_pk_fma_f32 v[204:205], v[50:51], v[136:137], v[204:205]
	v_pk_fma_f32 v[206:207], v[52:53], v[138:139], v[206:207]
	v_pk_mul_f32 v[208:209], v[208:209], s[92:93] op_sel_hi:[1,0]
	v_pk_mul_f32 v[210:211], v[210:211], s[92:93] op_sel_hi:[1,0]
	v_pk_fma_f32 v[208:209], v[30:31], v[140:141], v[208:209]
	v_pk_fma_f32 v[210:211], v[32:33], v[142:143], v[210:211]
	v_pk_mul_f32 v[212:213], v[212:213], s[92:93] op_sel_hi:[1,0]
	v_pk_mul_f32 v[214:215], v[214:215], s[92:93] op_sel_hi:[1,0]
	v_pk_fma_f32 v[212:213], v[26:27], v[144:145], v[212:213]
	v_pk_fma_f32 v[214:215], v[28:29], v[146:147], v[214:215]
	v_cvt_pk_bf16_f32 v54, v196, v197
	v_cvt_pk_bf16_f32 v55, v198, v199
	v_cvt_pk_bf16_f32 v56, v204, v205
	v_cvt_pk_bf16_f32 v57, v206, v207
	v_cvt_pk_bf16_f32 v30, v208, v209
	v_cvt_pk_bf16_f32 v31, v210, v211
	v_cvt_pk_bf16_f32 v32, v212, v213
	v_cvt_pk_bf16_f32 v33, v214, v215
	s_waitcnt vmcnt(4)
	v_pk_mul_f32 v[148:149], v[148:149], s[92:93] op_sel_hi:[1,0]
	v_pk_mul_f32 v[150:151], v[150:151], s[92:93] op_sel_hi:[1,0]
	v_pk_fma_f32 v[148:149], v[38:39], v[132:133], v[148:149]
	v_pk_fma_f32 v[150:151], v[40:41], v[134:135], v[150:151]
	v_pk_mul_f32 v[152:153], v[152:153], s[92:93] op_sel_hi:[1,0]
	v_pk_mul_f32 v[154:155], v[154:155], s[92:93] op_sel_hi:[1,0]
	v_pk_fma_f32 v[152:153], v[34:35], v[136:137], v[152:153]
	v_pk_fma_f32 v[154:155], v[36:37], v[138:139], v[154:155]
	v_pk_mul_f32 v[156:157], v[156:157], s[92:93] op_sel_hi:[1,0]
	v_pk_mul_f32 v[158:159], v[158:159], s[92:93] op_sel_hi:[1,0]
	v_pk_fma_f32 v[156:157], v[14:15], v[140:141], v[156:157]
	v_pk_fma_f32 v[158:159], v[16:17], v[142:143], v[158:159]
	v_pk_mul_f32 v[160:161], v[160:161], s[92:93] op_sel_hi:[1,0]
	v_pk_mul_f32 v[162:163], v[162:163], s[92:93] op_sel_hi:[1,0]
	v_pk_fma_f32 v[160:161], v[10:11], v[144:145], v[160:161]
	v_pk_fma_f32 v[162:163], v[12:13], v[146:147], v[162:163]
	v_cvt_pk_bf16_f32 v38, v148, v149
	v_cvt_pk_bf16_f32 v39, v150, v151
	v_cvt_pk_bf16_f32 v40, v152, v153
	v_cvt_pk_bf16_f32 v41, v154, v155
	v_cvt_pk_bf16_f32 v14, v156, v157
	v_cvt_pk_bf16_f32 v15, v158, v159
	v_cvt_pk_bf16_f32 v16, v160, v161
	v_cvt_pk_bf16_f32 v17, v162, v163
	s_waitcnt vmcnt(0)
	v_pk_mul_f32 v[180:181], v[180:181], s[92:93] op_sel_hi:[1,0]
	v_pk_mul_f32 v[182:183], v[182:183], s[92:93] op_sel_hi:[1,0]
	v_pk_fma_f32 v[180:181], v[22:23], v[132:133], v[180:181]
	v_pk_fma_f32 v[182:183], v[24:25], v[134:135], v[182:183]
	v_pk_mul_f32 v[184:185], v[184:185], s[92:93] op_sel_hi:[1,0]
	v_pk_mul_f32 v[186:187], v[186:187], s[92:93] op_sel_hi:[1,0]
	v_pk_fma_f32 v[184:185], v[18:19], v[136:137], v[184:185]
	v_pk_fma_f32 v[186:187], v[20:21], v[138:139], v[186:187]
	v_pk_mul_f32 v[188:189], v[188:189], s[92:93] op_sel_hi:[1,0]
	v_pk_mul_f32 v[190:191], v[190:191], s[92:93] op_sel_hi:[1,0]
	v_pk_fma_f32 v[188:189], v[6:7], v[140:141], v[188:189]
	v_pk_fma_f32 v[190:191], v[8:9], v[142:143], v[190:191]
	v_pk_mul_f32 v[192:193], v[192:193], s[92:93] op_sel_hi:[1,0]
	v_pk_mul_f32 v[194:195], v[194:195], s[92:93] op_sel_hi:[1,0]
	v_pk_fma_f32 v[192:193], v[2:3], v[144:145], v[192:193]
	v_pk_fma_f32 v[194:195], v[4:5], v[146:147], v[194:195]
	v_cvt_pk_bf16_f32 v22, v180, v181
	v_cvt_pk_bf16_f32 v23, v182, v183
	v_cvt_pk_bf16_f32 v24, v184, v185
	v_cvt_pk_bf16_f32 v25, v186, v187
	v_cvt_pk_bf16_f32 v6, v188, v189
	v_cvt_pk_bf16_f32 v7, v190, v191
	v_cvt_pk_bf16_f32 v8, v192, v193
	v_cvt_pk_bf16_f32 v9, v194, v195
	v_lshrrev_b32_e32 v179, 1, v179
	global_store_dwordx4 v179, v[128:131], s[12:13]
	global_store_dwordx4 v179, v[112:115], s[12:13] offset:256
	v_add_u32_e32 v178, 0x10000, v179
	global_store_dwordx4 v178, v[120:123], s[12:13]
	global_store_dwordx4 v178, v[96:99], s[12:13] offset:256
	s_nop 1
	v_add_u32_e32 v178, 0x20000, v179
	global_store_dwordx4 v178, v[108:111], s[12:13]
	global_store_dwordx4 v178, v[78:81], s[12:13] offset:256
	s_nop 1
	v_add_u32_e32 v178, 0x30000, v179
	global_store_dwordx4 v178, v[92:95], s[12:13]
	global_store_dwordx4 v178, v[70:73], s[12:13] offset:256
	s_nop 1
	v_add_u32_e32 v178, 0x80000, v179
	global_store_dwordx4 v178, v[62:65], s[12:13]
	global_store_dwordx4 v178, v[46:49], s[12:13] offset:256
	s_nop 1
	v_add_u32_e32 v178, 0x90000, v179
	global_store_dwordx4 v178, v[54:57], s[12:13]
	global_store_dwordx4 v178, v[30:33], s[12:13] offset:256
	s_nop 1
	v_add_u32_e32 v178, 0xa0000, v179
	global_store_dwordx4 v178, v[38:41], s[12:13]
	global_store_dwordx4 v178, v[14:17], s[12:13] offset:256
	s_nop 1
	v_add_u32_e32 v178, 0xb0000, v179
	global_store_dwordx4 v178, v[22:25], s[12:13]
	global_store_dwordx4 v178, v[6:9], s[12:13] offset:256
	s_nop 1
	s_cbranch_execz .LBB0_1134

.LBB0_1140:
	s_mul_i32 s20, s16, 0x3020000
	s_sext_i32_i16 s19, s17
	s_mul_hi_i32 s17, s16, 0x3020000
	s_waitcnt lgkmcnt(0)
	s_add_u32 s20, s8, s20
	s_addc_u32 s21, s9, s17
	s_mul_hi_i32 s17, s16, 0x1800000
	s_mul_i32 s16, s16, 0x1800000
	v_lshl_add_u64 v[14:15], v[12:13], 0, s[16:17]
	s_lshl_b32 s16, s19, 6
	s_ashr_i32 s19, s18, 31
	s_lshl_b64 s[18:19], s[18:19], 2
	s_add_u32 s18, s20, s18
	s_addc_u32 s19, s21, s19
	v_lshlrev_b32_e32 v82, 2, v4
	v_add_u32_e32 v50, s16, v1
	v_lshl_add_u64 v[48:49], s[18:19], 0, v[82:83]
	v_mad_i64_i32 v[20:21], s[18:19], v50, s40, v[48:49]
	v_add_u32_e32 v24, 8, v50
	global_load_dwordx4 v[20:23], v[20:21], off
	v_mad_i64_i32 v[24:25], s[18:19], v24, s40, v[48:49]
	global_load_dwordx4 v[24:27], v[24:25], off
	v_add_u32_e32 v28, 16, v50
	v_mad_i64_i32 v[28:29], s[18:19], v28, s40, v[48:49]
	global_load_dwordx4 v[28:31], v[28:29], off
	v_add_u32_e32 v32, 24, v50
	v_mad_i64_i32 v[32:33], s[18:19], v32, s40, v[48:49]
	global_load_dwordx4 v[32:35], v[32:33], off
	v_add_u32_e32 v36, 32, v50
	v_mad_i64_i32 v[36:37], s[18:19], v36, s40, v[48:49]
	global_load_dwordx4 v[36:39], v[36:37], off
	v_add_u32_e32 v40, 40, v50
	v_mad_i64_i32 v[40:41], s[18:19], v40, s40, v[48:49]
	global_load_dwordx4 v[40:43], v[40:41], off
	v_add_u32_e32 v44, 48, v50
	v_mad_i64_i32 v[44:45], s[18:19], v44, s40, v[48:49]
	global_load_dwordx4 v[44:47], v[44:45], off
	v_add_u32_e32 v50, 56, v50
	v_mad_i64_i32 v[48:49], s[18:19], v50, s40, v[48:49]
	global_load_dwordx4 v[48:51], v[48:49], off
	v_add_u32_e32 v52, v5, v7
	s_ashr_i32 s17, s16, 31
	s_lshl_b64 s[16:17], s[16:17], 1
	v_lshl_add_u64 v[14:15], v[14:15], 0, s[16:17]
	v_lshlrev_b32_e32 v82, 1, v6
	v_lshl_add_u64 v[14:15], v[14:15], 0, v[82:83]
	s_waitcnt vmcnt(7)
	ds_write2_b32 v52, v20, v21 offset1:1
	ds_write2_b32 v52, v22, v23 offset0:2 offset1:3
	v_add_u32_e32 v20, 0x420, v52
	s_waitcnt vmcnt(6)
	ds_write2_b32 v20, v24, v25 offset1:1
	v_add_u32_e32 v20, 0x428, v52
	ds_write2_b32 v20, v26, v27 offset1:1
	v_add_u32_e32 v20, 0x840, v52
	s_waitcnt vmcnt(5)
	ds_write2_b32 v20, v28, v29 offset1:1
	v_add_u32_e32 v20, 0x848, v52
	ds_write2_b32 v20, v30, v31 offset1:1
	v_add_u32_e32 v20, 0xc60, v52
	s_waitcnt vmcnt(4)
	ds_write2_b32 v20, v32, v33 offset1:1
	v_add_u32_e32 v20, 0xc68, v52
	ds_write2_b32 v20, v34, v35 offset1:1
	v_add_u32_e32 v20, 0x1080, v52
	s_waitcnt vmcnt(3)
	ds_write2_b32 v20, v36, v37 offset1:1
	v_add_u32_e32 v20, 0x1088, v52
	ds_write2_b32 v20, v38, v39 offset1:1
	v_add_u32_e32 v20, 0x14a0, v52
	s_waitcnt vmcnt(2)
	ds_write2_b32 v20, v40, v41 offset1:1
	v_add_u32_e32 v20, 0x14a8, v52
	ds_write2_b32 v20, v42, v43 offset1:1
	v_add_u32_e32 v20, 0x18c0, v52
	s_waitcnt vmcnt(1)
	ds_write2_b32 v20, v44, v45 offset1:1
	v_add_u32_e32 v20, 0x18c8, v52
	ds_write2_b32 v20, v46, v47 offset1:1
	v_add_u32_e32 v20, 0x1ce0, v52
	s_waitcnt vmcnt(0)
	ds_write2_b32 v20, v48, v49 offset1:1
	v_add_u32_e32 v20, 0x1ce8, v52
	ds_write2_b32 v20, v50, v51 offset1:1
	s_waitcnt lgkmcnt(0)
	ds_read2_b32 v[24:25], v19 offset0:33 offset1:41
	ds_read2_b32 v[26:27], v19 offset1:8
	ds_read2_b32 v[28:29], v19 offset0:66 offset1:74
	ds_read2_b32 v[30:31], v19 offset0:99 offset1:107
	ds_read2_b32 v[32:33], v19 offset0:132 offset1:140
	ds_read2_b32 v[34:35], v19 offset0:165 offset1:173
	ds_read2_b32 v[36:37], v19 offset0:198 offset1:206
	ds_read2_b32 v[38:39], v19 offset0:231 offset1:239
	s_waitcnt lgkmcnt(7)
	s_waitcnt lgkmcnt(6)
	v_cvt_pk_bf16_f32 v20, v26, v24
	s_waitcnt lgkmcnt(5)
	s_waitcnt lgkmcnt(4)
	v_cvt_pk_bf16_f32 v21, v28, v30
	s_waitcnt lgkmcnt(3)
	s_waitcnt lgkmcnt(2)
	v_cvt_pk_bf16_f32 v22, v32, v34
	s_waitcnt lgkmcnt(1)
	v_add_u32_e32 v40, s25, v1
	s_waitcnt lgkmcnt(0)
	v_ashrrev_i32_e32 v41, 31, v40
	v_lshlrev_b64 v[40:41], 12, v[40:41]
	v_cvt_pk_bf16_f32 v23, v36, v38
	v_lshl_add_u64 v[40:41], v[14:15], 0, v[40:41]
	global_store_dwordx4 v[40:41], v[20:23], off
	s_nop 1
	v_cvt_pk_bf16_f32 v20, v27, v25
	v_cvt_pk_bf16_f32 v21, v29, v31
	v_cvt_pk_bf16_f32 v22, v33, v35
	v_cvt_pk_bf16_f32 v23, v37, v39
	v_add_u32_e32 v24, s25, v16
	v_ashrrev_i32_e32 v25, 31, v24
	v_lshlrev_b64 v[24:25], 12, v[24:25]
	v_lshl_add_u64 v[24:25], v[14:15], 0, v[24:25]
	global_store_dwordx4 v[24:25], v[20:23], off
	s_nop 1
	ds_read2_b32 v[24:25], v19 offset0:49 offset1:57
	ds_read2_b32 v[26:27], v19 offset0:16 offset1:24
	ds_read2_b32 v[28:29], v19 offset0:82 offset1:90
	ds_read2_b32 v[30:31], v19 offset0:115 offset1:123
	ds_read2_b32 v[32:33], v19 offset0:148 offset1:156
	ds_read2_b32 v[34:35], v19 offset0:181 offset1:189
	ds_read2_b32 v[36:37], v19 offset0:214 offset1:222
	ds_read2_b32 v[38:39], v19 offset0:247 offset1:255
	s_waitcnt lgkmcnt(7)
	s_waitcnt lgkmcnt(6)
	v_cvt_pk_bf16_f32 v20, v26, v24
	s_waitcnt lgkmcnt(5)
	s_waitcnt lgkmcnt(4)
	v_cvt_pk_bf16_f32 v21, v28, v30
	s_waitcnt lgkmcnt(3)
	s_waitcnt lgkmcnt(2)
	v_cvt_pk_bf16_f32 v22, v32, v34
	s_waitcnt lgkmcnt(1)
	v_add_u32_e32 v40, s25, v17
	s_waitcnt lgkmcnt(0)
	v_ashrrev_i32_e32 v41, 31, v40
	v_lshlrev_b64 v[40:41], 12, v[40:41]
	v_cvt_pk_bf16_f32 v23, v36, v38
	v_lshl_add_u64 v[40:41], v[14:15], 0, v[40:41]
	global_store_dwordx4 v[40:41], v[20:23], off
	s_nop 1
	v_cvt_pk_bf16_f32 v20, v27, v25
	v_cvt_pk_bf16_f32 v21, v29, v31
	v_cvt_pk_bf16_f32 v22, v33, v35
	v_cvt_pk_bf16_f32 v23, v37, v39
	v_add_u32_e32 v24, s25, v18
	v_ashrrev_i32_e32 v25, 31, v24
	v_lshlrev_b64 v[24:25], 12, v[24:25]
	v_lshl_add_u64 v[14:15], v[14:15], 0, v[24:25]
	global_store_dwordx4 v[14:15], v[20:23], off
	s_waitcnt lgkmcnt(0)

.LBB0_1142:
	s_mul_hi_i32 s16, s22, 0x5397829d
	s_lshr_b32 s17, s16, 31
	s_ashr_i32 s16, s16, 13
	s_add_i32 s16, s16, s17
	s_mul_i32 s17, s16, 0xffff9e00
	s_add_i32 s25, s22, s17
	s_cmpk_gt_i32 s25, 0x17ff
	s_mov_b64 s[18:19], -1
	s_cbranch_scc0 .LBB0_1152
	s_cmpk_gt_u32 s25, 0x1fff
	s_cbranch_scc0 .LBB0_1149
	s_mov_b64 s[20:21], -1
	s_cmpk_gt_u32 s25, 0x4bff
	s_mul_hi_i32 s19, s16, 0x2c00000
	s_mul_i32 s18, s16, 0x2c00000
	s_cbranch_scc0 .LBB0_1146
	s_and_b32 s17, s25, 0x7fffffc0
	s_add_i32 s70, s17, 0xffffb400
	s_waitcnt lgkmcnt(0)
	s_add_u32 s26, s14, s18
	s_addc_u32 s27, s15, s19
	s_mul_hi_i32 s21, s16, 0x1600000
	s_mul_i32 s20, s16, 0x1600000
	s_and_b32 s17, s23, 0x7e0
	v_lshl_add_u64 v[14:15], v[2:3], 0, s[20:21]
	s_lshl_b32 s20, s17, 2
	v_add_u32_e32 v20, s70, v1
	s_add_u32 s20, s26, s20
	s_addc_u32 s21, s27, 0
	v_lshlrev_b32_e32 v82, 2, v4
	v_ashrrev_i32_e32 v21, 31, v20
	v_lshl_add_u64 v[22:23], s[20:21], 0, v[82:83]
	v_lshlrev_b64 v[20:21], 13, v[20:21]
	v_lshl_add_u64 v[48:49], v[22:23], 0, v[20:21]
	s_mov_b32 s20, 0x10000
	v_add_co_u32_e32 v24, vcc, s20, v48
	global_load_dwordx4 v[20:23], v[48:49], off
	s_nop 0
	v_addc_co_u32_e32 v25, vcc, 0, v49, vcc
	s_mov_b32 s20, 0x20000
	global_load_dwordx4 v[24:27], v[24:25], off
	v_add_co_u32_e32 v28, vcc, s20, v48
	s_mov_b32 s20, 0x30000
	s_nop 0
	v_addc_co_u32_e32 v29, vcc, 0, v49, vcc
	global_load_dwordx4 v[28:31], v[28:29], off
	v_add_co_u32_e32 v32, vcc, s20, v48
	s_mov_b32 s20, 0x40000
	s_nop 0
	v_addc_co_u32_e32 v33, vcc, 0, v49, vcc
	global_load_dwordx4 v[32:35], v[32:33], off
	v_add_co_u32_e32 v36, vcc, s20, v48
	s_mov_b32 s20, 0x50000
	s_nop 0
	v_addc_co_u32_e32 v37, vcc, 0, v49, vcc
	global_load_dwordx4 v[36:39], v[36:37], off
	v_add_co_u32_e32 v40, vcc, s20, v48
	s_mov_b32 s20, 0x60000
	s_nop 0
	v_addc_co_u32_e32 v41, vcc, 0, v49, vcc
	global_load_dwordx4 v[40:43], v[40:41], off
	v_add_co_u32_e32 v44, vcc, s20, v48
	s_mov_b32 s20, 0x70000
	s_nop 0
	v_addc_co_u32_e32 v45, vcc, 0, v49, vcc
	global_load_dwordx4 v[44:47], v[44:45], off
	v_add_co_u32_e32 v48, vcc, s20, v48
	v_add_u32_e32 v52, v5, v7
	s_nop 0
	v_addc_co_u32_e32 v49, vcc, 0, v49, vcc
	global_load_dwordx4 v[48:51], v[48:49], off
	s_lshl_b64 s[20:21], s[70:71], 1
	v_lshl_add_u64 v[14:15], v[14:15], 0, s[20:21]
	v_lshlrev_b32_e32 v82, 1, v6
	v_lshl_add_u64 v[14:15], v[14:15], 0, v[82:83]
	s_movk_i32 s26, 0x2c00
	s_waitcnt vmcnt(7)
	ds_write2_b32 v52, v20, v21 offset1:1
	ds_write2_b32 v52, v22, v23 offset0:2 offset1:3
	v_add_u32_e32 v20, 0x420, v52
	s_waitcnt vmcnt(6)
	ds_write2_b32 v20, v24, v25 offset1:1
	v_add_u32_e32 v20, 0x428, v52
	ds_write2_b32 v20, v26, v27 offset1:1
	v_add_u32_e32 v20, 0x840, v52
	s_waitcnt vmcnt(5)
	ds_write2_b32 v20, v28, v29 offset1:1
	v_add_u32_e32 v20, 0x848, v52
	ds_write2_b32 v20, v30, v31 offset1:1
	v_add_u32_e32 v20, 0xc60, v52
	s_waitcnt vmcnt(4)
	ds_write2_b32 v20, v32, v33 offset1:1
	v_add_u32_e32 v20, 0xc68, v52
	ds_write2_b32 v20, v34, v35 offset1:1
	v_add_u32_e32 v20, 0x1080, v52
	s_waitcnt vmcnt(3)
	ds_write2_b32 v20, v36, v37 offset1:1
	v_add_u32_e32 v20, 0x1088, v52
	ds_write2_b32 v20, v38, v39 offset1:1
	v_add_u32_e32 v20, 0x14a0, v52
	s_waitcnt vmcnt(2)
	ds_write2_b32 v20, v40, v41 offset1:1
	v_add_u32_e32 v20, 0x14a8, v52
	ds_write2_b32 v20, v42, v43 offset1:1
	v_add_u32_e32 v20, 0x18c0, v52
	s_waitcnt vmcnt(1)
	ds_write2_b32 v20, v44, v45 offset1:1
	v_add_u32_e32 v20, 0x18c8, v52
	ds_write2_b32 v20, v46, v47 offset1:1
	v_add_u32_e32 v20, 0x1ce0, v52
	s_waitcnt vmcnt(0)
	ds_write2_b32 v20, v48, v49 offset1:1
	v_add_u32_e32 v20, 0x1ce8, v52
	ds_write2_b32 v20, v50, v51 offset1:1
	s_waitcnt lgkmcnt(0)
	ds_read2_b32 v[24:25], v19 offset0:33 offset1:41
	ds_read2_b32 v[26:27], v19 offset1:8
	ds_read2_b32 v[28:29], v19 offset0:66 offset1:74
	ds_read2_b32 v[30:31], v19 offset0:99 offset1:107
	ds_read2_b32 v[32:33], v19 offset0:132 offset1:140
	ds_read2_b32 v[34:35], v19 offset0:165 offset1:173
	ds_read2_b32 v[36:37], v19 offset0:198 offset1:206
	ds_read2_b32 v[38:39], v19 offset0:231 offset1:239
	s_waitcnt lgkmcnt(7)
	s_waitcnt lgkmcnt(6)
	v_cvt_pk_bf16_f32 v20, v26, v24
	s_waitcnt lgkmcnt(5)
	s_waitcnt lgkmcnt(4)
	v_cvt_pk_bf16_f32 v21, v28, v30
	s_waitcnt lgkmcnt(3)
	s_waitcnt lgkmcnt(2)
	v_cvt_pk_bf16_f32 v22, v32, v34
	s_waitcnt lgkmcnt(1)
	s_waitcnt lgkmcnt(0)
	v_cvt_pk_bf16_f32 v23, v36, v38
	v_add_u32_e32 v24, s17, v1
	v_mad_i64_i32 v[40:41], s[20:21], v24, s26, v[14:15]
	global_store_dwordx4 v[40:41], v[20:23], off
	s_nop 1
	v_cvt_pk_bf16_f32 v20, v27, v25
	v_cvt_pk_bf16_f32 v21, v29, v31
	v_cvt_pk_bf16_f32 v22, v33, v35
	v_cvt_pk_bf16_f32 v23, v37, v39
	v_add_u32_e32 v24, s17, v16
	v_mad_i64_i32 v[24:25], s[20:21], v24, s26, v[14:15]
	global_store_dwordx4 v[24:25], v[20:23], off
	s_nop 1
	ds_read2_b32 v[24:25], v19 offset0:49 offset1:57
	ds_read2_b32 v[26:27], v19 offset0:16 offset1:24
	ds_read2_b32 v[28:29], v19 offset0:82 offset1:90
	ds_read2_b32 v[30:31], v19 offset0:115 offset1:123
	ds_read2_b32 v[32:33], v19 offset0:148 offset1:156
	ds_read2_b32 v[34:35], v19 offset0:181 offset1:189
	ds_read2_b32 v[36:37], v19 offset0:214 offset1:222
	ds_read2_b32 v[38:39], v19 offset0:247 offset1:255
	s_waitcnt lgkmcnt(7)
	s_waitcnt lgkmcnt(6)
	v_cvt_pk_bf16_f32 v20, v26, v24
	s_waitcnt lgkmcnt(5)
	s_waitcnt lgkmcnt(4)
	v_cvt_pk_bf16_f32 v21, v28, v30
	s_waitcnt lgkmcnt(3)
	s_waitcnt lgkmcnt(2)
	v_cvt_pk_bf16_f32 v22, v32, v34
	s_waitcnt lgkmcnt(1)
	s_waitcnt lgkmcnt(0)
	v_cvt_pk_bf16_f32 v23, v36, v38
	v_add_u32_e32 v24, s17, v17
	v_mad_i64_i32 v[40:41], s[20:21], v24, s26, v[14:15]
	global_store_dwordx4 v[40:41], v[20:23], off
	s_nop 1
	v_cvt_pk_bf16_f32 v20, v27, v25
	v_cvt_pk_bf16_f32 v21, v29, v31
	v_cvt_pk_bf16_f32 v22, v33, v35
	s_nop 0
	v_cvt_pk_bf16_f32 v23, v37, v39
	v_add_u32_e32 v24, s17, v18
	v_mad_i64_i32 v[14:15], s[20:21], v24, s26, v[14:15]
	global_store_dwordx4 v[14:15], v[20:23], off
	s_waitcnt lgkmcnt(0)
	s_mov_b64 s[20:21], 0
.LBB0_1146:
	s_andn2_b64 vcc, exec, s[20:21]
	s_cbranch_vccnz .LBB0_1148
	s_add_i32 s17, s25, 0xe000
	s_and_b32 s20, s17, 0xffff
	s_mul_i32 s20, s20, 0xba2f
	s_lshr_b32 s20, s20, 24
	s_mul_i32 s21, s20, 0x160
	s_sub_i32 s21, s17, s21
	s_and_b32 s26, s21, 0xffff
	s_lshl_b32 s17, s26, 5
	s_mul_i32 s28, s16, 0x5800000
	s_mul_hi_i32 s27, s16, 0x5800000
	s_waitcnt lgkmcnt(0)
	s_add_u32 s28, s12, s28
	s_addc_u32 s27, s13, s27
	v_lshl_add_u64 v[14:15], v[8:9], 0, s[18:19]
	s_bfe_i32 s18, s21, 0x10002
	s_lshl_b32 s19, s26, 4
	s_and_b32 s18, s18, 0x1600
	s_and_b32 s19, s19, 0x1f80
	s_add_i32 s18, s18, s19
	s_and_b32 s19, s17, 0x60
	s_or_b32 s18, s18, s19
	s_lshl_b32 s18, s18, 2
	s_add_u32 s18, s28, s18
	s_addc_u32 s19, s27, 0
	v_lshlrev_b32_e32 v82, 2, v4
	v_lshl_add_u32 v50, s20, 6, v1
	v_lshl_add_u64 v[48:49], s[18:19], 0, v[82:83]
	s_mov_b32 s21, 0xb000
	v_mad_i64_i32 v[20:21], s[18:19], v50, s21, v[48:49]
	v_add_u32_e32 v24, 8, v50
	global_load_dwordx4 v[20:23], v[20:21], off
	v_mad_i64_i32 v[24:25], s[18:19], v24, s21, v[48:49]
	global_load_dwordx4 v[24:27], v[24:25], off
	v_add_u32_e32 v28, 16, v50
	v_mad_i64_i32 v[28:29], s[18:19], v28, s21, v[48:49]
	global_load_dwordx4 v[28:31], v[28:29], off
	v_add_u32_e32 v32, 24, v50
	v_mad_i64_i32 v[32:33], s[18:19], v32, s21, v[48:49]
	global_load_dwordx4 v[32:35], v[32:33], off
	v_add_u32_e32 v36, 32, v50
	v_mad_i64_i32 v[36:37], s[18:19], v36, s21, v[48:49]
	global_load_dwordx4 v[36:39], v[36:37], off
	v_add_u32_e32 v40, 40, v50
	v_mad_i64_i32 v[40:41], s[18:19], v40, s21, v[48:49]
	global_load_dwordx4 v[40:43], v[40:41], off
	v_add_u32_e32 v44, 48, v50
	v_mad_i64_i32 v[44:45], s[18:19], v44, s21, v[48:49]
	global_load_dwordx4 v[44:47], v[44:45], off
	v_add_u32_e32 v50, 56, v50
	v_mad_i64_i32 v[48:49], s[18:19], v50, s21, v[48:49]
	global_load_dwordx4 v[48:51], v[48:49], off
	v_add_u32_e32 v52, v5, v7
	s_lshl_b32 s70, s20, 7
	v_lshl_add_u64 v[14:15], v[14:15], 0, s[70:71]
	v_lshlrev_b32_e32 v82, 1, v6
	v_lshl_add_u64 v[14:15], v[14:15], 0, v[82:83]
	s_waitcnt vmcnt(7)
	ds_write2_b32 v52, v20, v21 offset1:1
	ds_write2_b32 v52, v22, v23 offset0:2 offset1:3
	v_add_u32_e32 v20, 0x420, v52
	s_waitcnt vmcnt(6)
	ds_write2_b32 v20, v24, v25 offset1:1
	v_add_u32_e32 v20, 0x428, v52
	ds_write2_b32 v20, v26, v27 offset1:1
	v_add_u32_e32 v20, 0x840, v52
	s_waitcnt vmcnt(5)
	ds_write2_b32 v20, v28, v29 offset1:1
	v_add_u32_e32 v20, 0x848, v52
	ds_write2_b32 v20, v30, v31 offset1:1
	v_add_u32_e32 v20, 0xc60, v52
	s_waitcnt vmcnt(4)
	ds_write2_b32 v20, v32, v33 offset1:1
	v_add_u32_e32 v20, 0xc68, v52
	ds_write2_b32 v20, v34, v35 offset1:1
	v_add_u32_e32 v20, 0x1080, v52
	s_waitcnt vmcnt(3)
	ds_write2_b32 v20, v36, v37 offset1:1
	v_add_u32_e32 v20, 0x1088, v52
	ds_write2_b32 v20, v38, v39 offset1:1
	v_add_u32_e32 v20, 0x14a0, v52
	s_waitcnt vmcnt(2)
	ds_write2_b32 v20, v40, v41 offset1:1
	v_add_u32_e32 v20, 0x14a8, v52
	ds_write2_b32 v20, v42, v43 offset1:1
	v_add_u32_e32 v20, 0x18c0, v52
	s_waitcnt vmcnt(1)
	ds_write2_b32 v20, v44, v45 offset1:1
	v_add_u32_e32 v20, 0x18c8, v52
	ds_write2_b32 v20, v46, v47 offset1:1
	v_add_u32_e32 v20, 0x1ce0, v52
	s_waitcnt vmcnt(0)
	ds_write2_b32 v20, v48, v49 offset1:1
	v_add_u32_e32 v20, 0x1ce8, v52
	ds_write2_b32 v20, v50, v51 offset1:1
	s_waitcnt lgkmcnt(0)
	ds_read2_b32 v[24:25], v19 offset0:33 offset1:41
	ds_read2_b32 v[26:27], v19 offset1:8
	ds_read2_b32 v[28:29], v19 offset0:66 offset1:74
	ds_read2_b32 v[30:31], v19 offset0:99 offset1:107
	ds_read2_b32 v[32:33], v19 offset0:132 offset1:140
	ds_read2_b32 v[34:35], v19 offset0:165 offset1:173
	ds_read2_b32 v[36:37], v19 offset0:198 offset1:206
	ds_read2_b32 v[38:39], v19 offset0:231 offset1:239
	s_waitcnt lgkmcnt(7)
	s_waitcnt lgkmcnt(6)
	v_cvt_pk_bf16_f32 v20, v26, v24
	s_waitcnt lgkmcnt(5)
	s_waitcnt lgkmcnt(4)
	v_cvt_pk_bf16_f32 v21, v28, v30
	s_waitcnt lgkmcnt(3)
	s_waitcnt lgkmcnt(2)
	v_cvt_pk_bf16_f32 v22, v32, v34
	s_waitcnt lgkmcnt(1)
	v_add_u32_e32 v40, s17, v1
	s_waitcnt lgkmcnt(0)
	v_ashrrev_i32_e32 v41, 31, v40
	v_lshlrev_b64 v[40:41], 12, v[40:41]
	v_cvt_pk_bf16_f32 v23, v36, v38
	v_lshl_add_u64 v[40:41], v[14:15], 0, v[40:41]
	global_store_dwordx4 v[40:41], v[20:23], off
	s_nop 1
	v_cvt_pk_bf16_f32 v20, v27, v25
	v_cvt_pk_bf16_f32 v21, v29, v31
	v_cvt_pk_bf16_f32 v22, v33, v35
	v_cvt_pk_bf16_f32 v23, v37, v39
	v_add_u32_e32 v24, s17, v16
	v_ashrrev_i32_e32 v25, 31, v24
	v_lshlrev_b64 v[24:25], 12, v[24:25]
	v_lshl_add_u64 v[24:25], v[14:15], 0, v[24:25]
	global_store_dwordx4 v[24:25], v[20:23], off
	s_nop 1
	ds_read2_b32 v[24:25], v19 offset0:49 offset1:57
	ds_read2_b32 v[26:27], v19 offset0:16 offset1:24
	ds_read2_b32 v[28:29], v19 offset0:82 offset1:90
	ds_read2_b32 v[30:31], v19 offset0:115 offset1:123
	ds_read2_b32 v[32:33], v19 offset0:148 offset1:156
	ds_read2_b32 v[34:35], v19 offset0:181 offset1:189
	ds_read2_b32 v[36:37], v19 offset0:214 offset1:222
	ds_read2_b32 v[38:39], v19 offset0:247 offset1:255
	s_waitcnt lgkmcnt(7)
	s_waitcnt lgkmcnt(6)
	v_cvt_pk_bf16_f32 v20, v26, v24
	s_waitcnt lgkmcnt(5)
	s_waitcnt lgkmcnt(4)
	v_cvt_pk_bf16_f32 v21, v28, v30
	s_waitcnt lgkmcnt(3)
	s_waitcnt lgkmcnt(2)
	v_cvt_pk_bf16_f32 v22, v32, v34
	s_waitcnt lgkmcnt(1)
	v_add_u32_e32 v40, s17, v17
	s_waitcnt lgkmcnt(0)
	v_ashrrev_i32_e32 v41, 31, v40
	v_lshlrev_b64 v[40:41], 12, v[40:41]
	v_cvt_pk_bf16_f32 v23, v36, v38
	v_lshl_add_u64 v[40:41], v[14:15], 0, v[40:41]
	global_store_dwordx4 v[40:41], v[20:23], off
	s_nop 1
	v_cvt_pk_bf16_f32 v20, v27, v25
	v_cvt_pk_bf16_f32 v21, v29, v31
	v_cvt_pk_bf16_f32 v22, v33, v35
	v_cvt_pk_bf16_f32 v23, v37, v39
	v_add_u32_e32 v24, s17, v18
	v_ashrrev_i32_e32 v25, 31, v24
	v_lshlrev_b64 v[24:25], 12, v[24:25]
	v_lshl_add_u64 v[14:15], v[14:15], 0, v[24:25]
	global_store_dwordx4 v[14:15], v[20:23], off
	s_waitcnt lgkmcnt(0)

.LBB0_1149:
	s_andn2_b64 vcc, exec, s[18:19]
	s_cbranch_vccnz .LBB0_1151
	s_and_b32 s17, s25, 0x1fc0
	s_add_i32 s70, s17, 0xffffe800
	s_ashr_i32 s17, s16, 31
	s_lshl_b64 s[18:19], s[16:17], 24
	s_waitcnt lgkmcnt(0)
	s_add_u32 s20, s10, s18
	s_addc_u32 s21, s11, s19
	s_lshl_b64 s[18:19], s[16:17], 23
	s_and_b32 s17, s23, 0x7e0
	v_lshl_add_u64 v[14:15], v[10:11], 0, s[18:19]
	s_lshl_b32 s18, s17, 2
	v_add_u32_e32 v20, s70, v1
	s_add_u32 s18, s20, s18
	s_addc_u32 s19, s21, 0
	v_lshlrev_b32_e32 v82, 2, v4
	v_ashrrev_i32_e32 v21, 31, v20
	v_lshl_add_u64 v[22:23], s[18:19], 0, v[82:83]
	v_lshlrev_b64 v[20:21], 13, v[20:21]
	v_lshl_add_u64 v[48:49], v[22:23], 0, v[20:21]
	s_mov_b32 s18, 0x10000
	v_add_co_u32_e32 v24, vcc, s18, v48
	global_load_dwordx4 v[20:23], v[48:49], off
	s_nop 0
	v_addc_co_u32_e32 v25, vcc, 0, v49, vcc
	s_mov_b32 s18, 0x20000
	global_load_dwordx4 v[24:27], v[24:25], off
	v_add_co_u32_e32 v28, vcc, s18, v48
	s_mov_b32 s18, 0x30000
	s_nop 0
	v_addc_co_u32_e32 v29, vcc, 0, v49, vcc
	global_load_dwordx4 v[28:31], v[28:29], off
	v_add_co_u32_e32 v32, vcc, s18, v48
	s_mov_b32 s18, 0x40000
	s_nop 0
	v_addc_co_u32_e32 v33, vcc, 0, v49, vcc
	global_load_dwordx4 v[32:35], v[32:33], off
	v_add_co_u32_e32 v36, vcc, s18, v48
	s_mov_b32 s18, 0x50000
	s_nop 0
	v_addc_co_u32_e32 v37, vcc, 0, v49, vcc
	global_load_dwordx4 v[36:39], v[36:37], off
	v_add_co_u32_e32 v40, vcc, s18, v48
	s_mov_b32 s18, 0x60000
	s_nop 0
	v_addc_co_u32_e32 v41, vcc, 0, v49, vcc
	global_load_dwordx4 v[40:43], v[40:41], off
	v_add_co_u32_e32 v44, vcc, s18, v48
	s_mov_b32 s18, 0x70000
	s_nop 0
	v_addc_co_u32_e32 v45, vcc, 0, v49, vcc
	global_load_dwordx4 v[44:47], v[44:45], off
	v_add_co_u32_e32 v48, vcc, s18, v48
	v_add_u32_e32 v52, v5, v7
	s_nop 0
	v_addc_co_u32_e32 v49, vcc, 0, v49, vcc
	global_load_dwordx4 v[48:51], v[48:49], off
	s_lshl_b64 s[18:19], s[70:71], 1
	v_lshl_add_u64 v[14:15], v[14:15], 0, s[18:19]
	v_lshlrev_b32_e32 v82, 1, v6
	v_lshl_add_u64 v[14:15], v[14:15], 0, v[82:83]
	s_waitcnt vmcnt(7)
	ds_write2_b32 v52, v20, v21 offset1:1
	ds_write2_b32 v52, v22, v23 offset0:2 offset1:3
	v_add_u32_e32 v20, 0x420, v52
	s_waitcnt vmcnt(6)
	ds_write2_b32 v20, v24, v25 offset1:1
	v_add_u32_e32 v20, 0x428, v52
	ds_write2_b32 v20, v26, v27 offset1:1
	v_add_u32_e32 v20, 0x840, v52
	s_waitcnt vmcnt(5)
	ds_write2_b32 v20, v28, v29 offset1:1
	v_add_u32_e32 v20, 0x848, v52
	ds_write2_b32 v20, v30, v31 offset1:1
	v_add_u32_e32 v20, 0xc60, v52
	s_waitcnt vmcnt(4)
	ds_write2_b32 v20, v32, v33 offset1:1
	v_add_u32_e32 v20, 0xc68, v52
	ds_write2_b32 v20, v34, v35 offset1:1
	v_add_u32_e32 v20, 0x1080, v52
	s_waitcnt vmcnt(3)
	ds_write2_b32 v20, v36, v37 offset1:1
	v_add_u32_e32 v20, 0x1088, v52
	ds_write2_b32 v20, v38, v39 offset1:1
	v_add_u32_e32 v20, 0x14a0, v52
	s_waitcnt vmcnt(2)
	ds_write2_b32 v20, v40, v41 offset1:1
	v_add_u32_e32 v20, 0x14a8, v52
	ds_write2_b32 v20, v42, v43 offset1:1
	v_add_u32_e32 v20, 0x18c0, v52
	v_add_u32_e32 v40, s17, v1
	v_ashrrev_i32_e32 v41, 31, v40
	s_waitcnt vmcnt(1)
	ds_write2_b32 v20, v44, v45 offset1:1
	v_add_u32_e32 v20, 0x18c8, v52
	ds_write2_b32 v20, v46, v47 offset1:1
	v_add_u32_e32 v20, 0x1ce0, v52
	v_lshlrev_b64 v[40:41], 12, v[40:41]
	v_lshl_add_u64 v[40:41], v[14:15], 0, v[40:41]
	s_waitcnt vmcnt(0)
	ds_write2_b32 v20, v48, v49 offset1:1
	v_add_u32_e32 v20, 0x1ce8, v52
	ds_write2_b32 v20, v50, v51 offset1:1
	s_waitcnt lgkmcnt(0)
	ds_read2_b32 v[24:25], v19 offset0:33 offset1:41
	ds_read2_b32 v[26:27], v19 offset1:8
	ds_read2_b32 v[28:29], v19 offset0:66 offset1:74
	ds_read2_b32 v[30:31], v19 offset0:99 offset1:107
	ds_read2_b32 v[32:33], v19 offset0:132 offset1:140
	ds_read2_b32 v[34:35], v19 offset0:165 offset1:173
	ds_read2_b32 v[36:37], v19 offset0:198 offset1:206
	ds_read2_b32 v[38:39], v19 offset0:231 offset1:239
	s_waitcnt lgkmcnt(7)
	s_waitcnt lgkmcnt(6)
	v_cvt_pk_bf16_f32 v20, v26, v24
	s_waitcnt lgkmcnt(5)
	s_waitcnt lgkmcnt(4)
	v_cvt_pk_bf16_f32 v21, v28, v30
	s_waitcnt lgkmcnt(3)
	s_waitcnt lgkmcnt(2)
	v_cvt_pk_bf16_f32 v22, v32, v34
	s_waitcnt lgkmcnt(1)
	s_waitcnt lgkmcnt(0)
	v_cvt_pk_bf16_f32 v23, v36, v38
	global_store_dwordx4 v[40:41], v[20:23], off
	s_nop 1
	v_cvt_pk_bf16_f32 v20, v27, v25
	v_cvt_pk_bf16_f32 v21, v29, v31
	v_cvt_pk_bf16_f32 v22, v33, v35
	v_cvt_pk_bf16_f32 v23, v37, v39
	v_add_u32_e32 v24, s17, v16
	v_ashrrev_i32_e32 v25, 31, v24
	v_lshlrev_b64 v[24:25], 12, v[24:25]
	v_lshl_add_u64 v[24:25], v[14:15], 0, v[24:25]
	global_store_dwordx4 v[24:25], v[20:23], off
	s_nop 1
	ds_read2_b32 v[24:25], v19 offset0:49 offset1:57
	ds_read2_b32 v[26:27], v19 offset0:16 offset1:24
	ds_read2_b32 v[28:29], v19 offset0:82 offset1:90
	ds_read2_b32 v[30:31], v19 offset0:115 offset1:123
	ds_read2_b32 v[32:33], v19 offset0:148 offset1:156
	ds_read2_b32 v[34:35], v19 offset0:181 offset1:189
	ds_read2_b32 v[36:37], v19 offset0:214 offset1:222
	ds_read2_b32 v[38:39], v19 offset0:247 offset1:255
	s_waitcnt lgkmcnt(7)
	s_waitcnt lgkmcnt(6)
	v_cvt_pk_bf16_f32 v20, v26, v24
	s_waitcnt lgkmcnt(5)
	s_waitcnt lgkmcnt(4)
	v_cvt_pk_bf16_f32 v21, v28, v30
	s_waitcnt lgkmcnt(3)
	s_waitcnt lgkmcnt(2)
	v_cvt_pk_bf16_f32 v22, v32, v34
	s_waitcnt lgkmcnt(1)
	v_add_u32_e32 v40, s17, v17
	s_waitcnt lgkmcnt(0)
	v_ashrrev_i32_e32 v41, 31, v40
	v_lshlrev_b64 v[40:41], 12, v[40:41]
	v_cvt_pk_bf16_f32 v23, v36, v38
	v_lshl_add_u64 v[40:41], v[14:15], 0, v[40:41]
	global_store_dwordx4 v[40:41], v[20:23], off
	s_nop 1
	v_cvt_pk_bf16_f32 v20, v27, v25
	v_cvt_pk_bf16_f32 v21, v29, v31
	v_cvt_pk_bf16_f32 v22, v33, v35
	v_cvt_pk_bf16_f32 v23, v37, v39
	v_add_u32_e32 v24, s17, v18
	v_ashrrev_i32_e32 v25, 31, v24
	v_lshlrev_b64 v[24:25], 12, v[24:25]
	v_lshl_add_u64 v[14:15], v[14:15], 0, v[24:25]
	global_store_dwordx4 v[14:15], v[20:23], off
	s_waitcnt lgkmcnt(0)

.LBB0_1218:
	v_pk_add_f32 v[2:3], v[58:59], v[68:69]
	v_pk_add_f32 v[4:5], v[60:61], v[66:67]
	v_pk_add_f32 v[6:7], v[64:65], v[56:57]
	v_pk_add_f32 v[2:3], v[2:3], v[4:5]
	v_add_f32_e32 v14, v20, v21
	v_add_f32_e32 v18, v22, v23
	v_and_b32_e32 v26, 64, v249
	v_pk_add_f32 v[4:5], v[6:7], v[6:7] op_sel:[0,1] op_sel_hi:[1,0]
	v_add_f32_e32 v2, 0, v2
	v_add_f32_e32 v28, v36, v37
	v_add_f32_e32 v32, v40, v41
	v_pk_add_f32 v[34:35], v[14:15], v[18:19]
	v_add_u32_e32 v14, 64, v26
	v_mov_b32_e32 v5, v31
	v_add_f32_e32 v26, v2, v3
	v_pk_add_f32 v[6:7], v[28:29], v[32:33]
	v_pk_add_f32 v[2:3], v[26:27], v[4:5]
	v_pk_add_f32 v[8:9], v[62:63], v[24:25]
	v_pk_add_f32 v[2:3], v[2:3], v[6:7]
	v_pk_add_f32 v[8:9], v[8:9], v[8:9] op_sel:[0,1] op_sel_hi:[1,0]
	v_pk_add_f32 v[2:3], v[2:3], v[2:3] op_sel:[0,1] op_sel_hi:[1,0]
	v_xor_b32_e32 v30, 1, v249
	v_mov_b32_e32 v9, v17
	v_mov_b32_e32 v3, v16
	v_cmp_lt_i32_e32 vcc, v30, v14
	v_pk_add_f32 v[2:3], v[2:3], v[8:9]
	v_xor_b32_e32 v38, 2, v249
	v_cndmask_b32_e32 v18, v249, v30, vcc
	v_pk_add_f32 v[2:3], v[2:3], v[34:35]
	v_lshlrev_b32_e32 v82, 2, v18
	v_add_f32_e32 v26, v2, v3
	ds_bpermute_b32 v84, v82, v26
	v_cmp_lt_i32_e32 vcc, v38, v14
	v_xor_b32_e32 v39, 4, v249
	v_xor_b32_e32 v42, 8, v249
	v_cndmask_b32_e32 v28, v249, v38, vcc
	v_lshlrev_b32_e32 v32, 2, v28
	s_waitcnt lgkmcnt(0)
	v_add_f32_e32 v26, v26, v84
	ds_bpermute_b32 v84, v32, v26
	v_cmp_lt_i32_e32 vcc, v39, v14
	v_xor_b32_e32 v43, 16, v249
	s_add_i32 s28, s8, s60
	v_cndmask_b32_e32 v30, v249, v39, vcc
	v_lshlrev_b32_e32 v30, 2, v30
	s_waitcnt lgkmcnt(0)
	v_add_f32_e32 v26, v26, v84
	ds_bpermute_b32 v84, v30, v26
	v_cmp_lt_i32_e32 vcc, v42, v14
	s_cmpk_lt_i32 s28, 0x2000
	v_xor_b32_e32 v44, 32, v249
	v_cndmask_b32_e32 v38, v249, v42, vcc
	v_lshlrev_b32_e32 v28, 2, v38
	s_waitcnt lgkmcnt(0)
	v_add_f32_e32 v26, v26, v84
	ds_bpermute_b32 v84, v28, v26
	v_cmp_lt_i32_e32 vcc, v43, v14
	s_cselect_b32 s8, s28, s8
	s_ashr_i32 s9, s8, 31
	v_cndmask_b32_e32 v39, v249, v43, vcc
	v_lshlrev_b32_e32 v18, 2, v39
	s_waitcnt lgkmcnt(0)
	v_add_f32_e32 v26, v26, v84
	ds_bpermute_b32 v84, v18, v26
	v_cmp_lt_i32_e32 vcc, v44, v14
	s_lshl_b64 s[8:9], s[8:9], 12
	s_add_u32 s30, s14, s20
	v_cndmask_b32_e32 v14, v249, v44, vcc
	v_lshlrev_b32_e32 v14, 2, v14
	s_waitcnt lgkmcnt(0)
	v_add_f32_e32 v26, v26, v84
	v_mov_b32_e32 v70, v1
	v_lshl_add_u64 v[4:5], v[12:13], 0, s[8:9]
	s_addc_u32 s31, s15, s21
	ds_bpermute_b32 v84, v14, v26
	global_load_dwordx2 v[54:55], v[4:5], off
	global_load_dwordx2 v[52:53], v[4:5], off offset:512
	global_load_dwordx2 v[50:51], v[4:5], off offset:1024
	global_load_dwordx2 v[48:49], v[4:5], off offset:1536
	global_load_dwordx2 v[46:47], v[4:5], off offset:2048
	global_load_dwordx2 v[44:45], v[4:5], off offset:2560
	global_load_dwordx2 v[42:43], v[4:5], off offset:3072
	global_load_dwordx2 v[38:39], v[4:5], off offset:3584
	s_add_u32 s8, s14, s18
	v_lshlrev_b32_e32 v4, 2, v70
	s_addc_u32 s9, s15, s19
	v_ashrrev_i32_e32 v5, 31, v4
	v_lshlrev_b64 v[6:7], 2, v[4:5]
	v_lshl_add_u64 v[4:5], v[4:5], 1, s[8:9]
	v_lshl_add_u64 v[76:77], s[16:17], 0, v[6:7]
	v_add_co_u32_e32 v34, vcc, s61, v4
	v_lshl_add_u64 v[74:75], s[10:11], 0, v[6:7]
	v_lshl_add_u64 v[78:79], s[30:31], 0, v[6:7]
	v_lshl_add_u64 v[72:73], s[24:25], 0, v[6:7]
	v_lshl_add_u64 v[70:71], s[22:23], 0, v[6:7]
	v_addc_co_u32_e32 v35, vcc, 0, v5, vcc
	global_load_dwordx4 v[2:5], v[76:77], off
	global_load_dwordx4 v[6:9], v[74:75], off
	s_waitcnt lgkmcnt(0)
	v_add_f32_e32 v26, v26, v84
	v_fmac_f32_e32 v66, 0xba000000, v26
	v_fmac_f32_e32 v68, 0xba000000, v26
	v_fmac_f32_e32 v67, 0xba000000, v26
	v_fmac_f32_e32 v69, 0xba000000, v26
	v_fmac_f32_e32 v64, 0xba000000, v26
	v_fmac_f32_e32 v57, 0xba000000, v26
	v_fmac_f32_e32 v65, 0xba000000, v26
	v_fmac_f32_e32 v60, 0xba000000, v26
	v_fmac_f32_e32 v58, 0xba000000, v26
	v_fmac_f32_e32 v61, 0xba000000, v26
	v_fmac_f32_e32 v59, 0xba000000, v26
	v_fmac_f32_e32 v56, 0xba000000, v26
	v_mov_b32_e32 v85, v69
	v_mov_b32_e32 v87, v68
	v_pk_mul_f32 v[68:69], v[68:69], v[68:69]
	v_mov_b32_e32 v89, v67
	v_mov_b32_e32 v91, v66
	v_pk_mul_f32 v[66:67], v[66:67], v[66:67]
	v_mov_b32_e32 v92, v65
	v_mov_b32_e32 v93, v57
	v_mov_b32_e32 v57, v64
	v_mov_b32_e32 v84, v59
	v_mov_b32_e32 v86, v58
	v_mov_b32_e32 v88, v61
	v_mov_b32_e32 v90, v60
	v_pk_fma_f32 v[58:59], v[58:59], v[58:59], v[68:69]
	v_pk_fma_f32 v[60:61], v[60:61], v[60:61], v[66:67]
	v_pk_mul_f32 v[66:67], v[92:93], v[92:93]
	v_pk_mul_f32 v[68:69], v[56:57], v[56:57]
	v_fmac_f32_e32 v36, 0xba000000, v26
	v_fmac_f32_e32 v40, 0xba000000, v26
	v_pk_add_f32 v[58:59], v[58:59], v[60:61]
	v_pk_mov_b32 v[60:61], v[68:69], v[66:67] op_sel:[1,0]
	v_mov_b32_e32 v69, v67
	v_fmac_f32_e32 v37, 0xba000000, v26
	v_fmac_f32_e32 v41, 0xba000000, v26
	v_fmac_f32_e32 v33, 0xba000000, v26
	v_fmac_f32_e32 v29, 0xba000000, v26
	v_fmac_f32_e32 v31, 0xba000000, v26
	v_fmac_f32_e32 v27, 0xba000000, v26
	v_fmac_f32_e32 v62, 0xba000000, v26
	v_fmac_f32_e32 v24, 0xba000000, v26
	v_fmac_f32_e32 v25, 0xba000000, v26
	v_fmac_f32_e32 v63, 0xba000000, v26
	v_fmac_f32_e32 v21, 0xba000000, v26
	v_fmac_f32_e32 v20, 0xba000000, v26
	v_fmac_f32_e32 v23, 0xba000000, v26
	v_fmac_f32_e32 v22, 0xba000000, v26
	v_fmac_f32_e32 v19, 0xba000000, v26
	v_fmac_f32_e32 v15, 0xba000000, v26
	v_fmac_f32_e32 v17, 0xba000000, v26
	v_fmac_f32_e32 v16, 0xba000000, v26
	v_mul_f32_e32 v26, v36, v36
	v_mul_f32_e32 v94, v40, v40
	v_pk_add_f32 v[60:61], v[60:61], v[68:69]
	v_mov_b32_e32 v64, v63
	v_mov_b32_e32 v65, v25
	v_mov_b32_e32 v25, v62
	v_pk_fma_f32 v[98:99], v[36:37], v[36:37], v[26:27] op_sel_hi:[1,1,0]
	v_pk_fma_f32 v[94:95], v[40:41], v[40:41], v[94:95] op_sel_hi:[1,1,0]
	v_pk_add_f32 v[58:59], v[58:59], v[58:59] op_sel_hi:[0,1]
	v_pk_add_f32 v[60:61], v[60:61], v[60:61] op_sel_hi:[0,1]
	v_pk_mul_f32 v[100:101], v[64:65], v[64:65]
	v_pk_mul_f32 v[102:103], v[24:25], v[24:25]
	v_mul_f32_e32 v98, v27, v27
	v_mul_f32_e32 v94, v31, v31
	v_mul_f32_e32 v58, v33, v33
	v_mul_f32_e32 v60, v29, v29
	v_pk_mov_b32 v[66:67], v[102:103], v[100:101] op_sel:[1,0]
	v_mov_b32_e32 v103, v101
	v_pk_add_f32 v[68:69], v[98:99], v[94:95]
	v_pk_add_f32 v[58:59], v[60:61], v[58:59]
	v_mul_f32_e32 v62, v20, v20
	v_mul_f32_e32 v96, v22, v22
	v_pk_add_f32 v[66:67], v[66:67], v[102:103]
	v_pk_add_f32 v[58:59], v[68:69], v[58:59]
	v_pk_fma_f32 v[62:63], v[20:21], v[20:21], v[62:63] op_sel_hi:[1,1,0]
	v_pk_fma_f32 v[96:97], v[22:23], v[22:23], v[96:97] op_sel_hi:[1,1,0]
	v_pk_add_f32 v[66:67], v[66:67], v[66:67] op_sel_hi:[0,1]
	v_pk_add_f32 v[58:59], v[58:59], v[58:59] op_sel_hi:[0,1]
	v_mul_f32_e32 v62, v16, v16
	v_mul_f32_e32 v96, v17, v17
	v_mul_f32_e32 v66, v15, v15
	v_mul_f32_e32 v58, v19, v19
	v_pk_add_f32 v[62:63], v[62:63], v[96:97]
	v_pk_add_f32 v[58:59], v[66:67], v[58:59]
	s_mov_b32 s8, 0x21b1e000
	v_pk_add_f32 v[58:59], v[62:63], v[58:59]
	v_add_co_u32_e32 v80, vcc, s8, v78
	v_add_f32_e32 v26, v58, v59
	ds_bpermute_b32 v58, v82, v26
	v_addc_co_u32_e32 v81, vcc, 0, v79, vcc
	v_add_co_u32_e32 v78, vcc, s70, v78
	s_waitcnt lgkmcnt(0)
	v_add_f32_e32 v26, v26, v58
	ds_bpermute_b32 v32, v32, v26
	v_addc_co_u32_e32 v79, vcc, 0, v79, vcc
	s_add_u32 s20, s20, s36
	s_addc_u32 s21, s21, s37
	s_waitcnt lgkmcnt(0)
	v_add_f32_e32 v26, v26, v32
	ds_bpermute_b32 v30, v30, v26
	s_add_u32 s18, s18, s38
	s_addc_u32 s19, s19, s39
	s_cmpk_gt_i32 s28, 0x1fff
	s_waitcnt vmcnt(9)
	v_and_b32_e32 v68, 0xffff0000, v54
	s_waitcnt lgkmcnt(0)
	v_add_f32_e32 v26, v26, v30
	ds_bpermute_b32 v28, v28, v26
	s_waitcnt vmcnt(8)
	v_and_b32_e32 v69, 0xffff0000, v52
	s_waitcnt lgkmcnt(0)
	v_add_f32_e32 v26, v26, v28
	ds_bpermute_b32 v18, v18, v26
	s_waitcnt lgkmcnt(0)
	v_add_f32_e32 v18, v26, v18
	ds_bpermute_b32 v14, v14, v18
	s_waitcnt lgkmcnt(0)
	v_add_f32_e32 v14, v18, v14
	v_fmamk_f32 v14, v14, 0x3a000000, v250
	v_mul_f32_e32 v18, 0x4f800000, v14
	v_cmp_gt_f32_e32 vcc, s96, v14
	s_nop 1
	v_cndmask_b32_e32 v14, v14, v18, vcc
	v_sqrt_f32_e32 v18, v14
	s_nop 0
	v_add_u32_e32 v26, -1, v18
	v_add_u32_e32 v28, 1, v18
	v_fma_f32 v30, -v26, v18, v14
	v_fma_f32 v32, -v28, v18, v14
	v_cmp_ge_f32_e64 s[8:9], 0, v30
	s_nop 1
	v_cndmask_b32_e64 v18, v18, v26, s[8:9]
	v_cmp_lt_f32_e64 s[8:9], 0, v32
	s_nop 1
	v_cndmask_b32_e64 v18, v18, v28, s[8:9]
	v_mul_f32_e32 v26, 0x37800000, v18
	v_cndmask_b32_e32 v18, v18, v26, vcc
	v_cmp_class_f32_e32 vcc, v14, v251
	s_nop 1
	v_cndmask_b32_e32 v14, v18, v14, vcc
	v_div_scale_f32 v18, s[8:9], v14, v14, 1.0
	v_rcp_f32_e32 v28, v18
	v_div_scale_f32 v26, vcc, 1.0, v14, 1.0
	s_mov_b32 s8, s28
	v_fma_f32 v30, -v18, v28, 1.0
	v_fmac_f32_e32 v28, v30, v28
	v_mul_f32_e32 v30, v26, v28
	v_fma_f32 v32, -v18, v30, v26
	v_fmac_f32_e32 v30, v32, v28
	v_fma_f32 v18, -v18, v30, v26
	v_div_fmas_f32 v18, v18, v28, v30
	v_div_fixup_f32 v14, v18, v14, 1.0
	v_pk_mul_f32 v[58:59], v[86:87], v[14:15] op_sel_hi:[1,0]
	v_pk_mul_f32 v[60:61], v[90:91], v[14:15] op_sel_hi:[1,0]
	s_waitcnt vmcnt(0)
	v_pk_fma_f32 v[2:3], v[2:3], v[58:59], v[6:7]
	v_pk_fma_f32 v[4:5], v[4:5], v[60:61], v[8:9]
	global_store_dwordx4 v[78:79], v[2:5], off offset:-4096
	global_load_dwordx4 v[6:9], v[72:73], off
	global_load_dwordx4 v[58:61], v[70:71], off
	v_pk_mul_f32 v[62:63], v[88:89], v[14:15] op_sel_hi:[1,0]
	v_pk_mul_f32 v[66:67], v[84:85], v[14:15] op_sel_hi:[1,0]
	v_pk_mul_f32 v[56:57], v[56:57], v[14:15] op_sel_hi:[1,0]
	v_pk_mul_f32 v[40:41], v[40:41], v[14:15] op_sel_hi:[1,0]
	v_pk_mul_f32 v[36:37], v[36:37], v[14:15] op_sel_hi:[1,0]
	v_mov_b32_e32 v32, v29
	v_mov_b32_e32 v30, v27
	v_pk_mul_f32 v[26:27], v[32:33], v[14:15] op_sel_hi:[1,0]
	v_pk_mul_f32 v[28:29], v[30:31], v[14:15] op_sel_hi:[1,0]
	v_pk_mul_f32 v[24:25], v[24:25], v[14:15] op_sel_hi:[1,0]
	v_pk_mul_f32 v[22:23], v[22:23], v[14:15] op_sel_hi:[1,0]
	v_pk_mul_f32 v[20:21], v[20:21], v[14:15] op_sel_hi:[1,0]
	v_mov_b32_e32 v18, v15
	v_pk_mul_f32 v[18:19], v[18:19], v[14:15] op_sel_hi:[1,0]
	v_lshlrev_b32_e32 v30, 16, v49
	v_and_b32_e32 v32, 0xffff0000, v46
	v_and_b32_e32 v33, 0xffff0000, v47
	v_mov_b32_e32 v31, v32
	s_waitcnt vmcnt(1)
	v_pk_add_f32 v[8:9], v[8:9], 1.0 op_sel_hi:[1,0]
	v_pk_add_f32 v[6:7], v[6:7], 1.0 op_sel_hi:[1,0]
	s_waitcnt vmcnt(0)
	v_pk_fma_f32 v[4:5], v[8:9], v[4:5], v[60:61]
	v_pk_fma_f32 v[2:3], v[6:7], v[2:3], v[58:59]
	v_cvt_pk_bf16_f32 v2, v2, v3
	v_cvt_pk_bf16_f32 v3, v4, v5
	global_store_dwordx2 v[34:35], v[2:3], off
	global_load_dwordx4 v[2:5], v[76:77], off offset:1024
	s_nop 0
	global_load_dwordx4 v[6:9], v[74:75], off offset:1024
	s_waitcnt vmcnt(0)
	v_pk_fma_f32 v[2:3], v[2:3], v[66:67], v[6:7]
	v_pk_fma_f32 v[4:5], v[4:5], v[62:63], v[8:9]
	global_store_dwordx4 v[80:81], v[2:5], off offset:1024
	global_load_dwordx4 v[6:9], v[72:73], off offset:1024
	global_load_dwordx4 v[58:61], v[70:71], off offset:1024
	v_and_b32_e32 v62, 0xffff0000, v44
	v_lshlrev_b32_e32 v63, 16, v45
	v_and_b32_e32 v66, 0xffff0000, v55
	v_and_b32_e32 v67, 0xffff0000, v53
	s_waitcnt vmcnt(1)
	v_pk_add_f32 v[8:9], v[8:9], 1.0 op_sel_hi:[1,0]
	v_pk_add_f32 v[6:7], v[6:7], 1.0 op_sel_hi:[1,0]
	s_waitcnt vmcnt(0)
	v_pk_fma_f32 v[4:5], v[8:9], v[4:5], v[60:61]
	v_pk_fma_f32 v[2:3], v[6:7], v[2:3], v[58:59]
	v_cvt_pk_bf16_f32 v2, v2, v3
	v_cvt_pk_bf16_f32 v3, v4, v5
	global_store_dwordx2 v[34:35], v[2:3], off offset:512
	global_load_dwordx4 v[2:5], v[76:77], off offset:2048
	s_nop 0
	global_load_dwordx4 v[6:9], v[74:75], off offset:2048
	v_pk_mul_f32 v[58:59], v[92:93], v[14:15] op_sel_hi:[1,0]
	v_lshlrev_b32_e32 v60, 16, v55
	v_lshlrev_b32_e32 v61, 16, v53
	s_waitcnt vmcnt(0)
	v_pk_fma_f32 v[2:3], v[2:3], v[56:57], v[6:7]
	v_pk_fma_f32 v[4:5], v[4:5], v[58:59], v[8:9]
	global_store_dwordx4 v[80:81], v[2:5], off offset:2048
	global_load_dwordx4 v[6:9], v[72:73], off offset:2048
	global_load_dwordx4 v[56:59], v[70:71], off offset:2048
	s_waitcnt vmcnt(1)
	v_pk_add_f32 v[8:9], v[8:9], 1.0 op_sel_hi:[1,0]
	v_pk_add_f32 v[6:7], v[6:7], 1.0 op_sel_hi:[1,0]
	s_waitcnt vmcnt(0)
	v_pk_fma_f32 v[4:5], v[4:5], v[8:9], v[58:59]
	v_pk_fma_f32 v[2:3], v[2:3], v[6:7], v[56:57]
	v_cvt_pk_bf16_f32 v2, v2, v3
	v_cvt_pk_bf16_f32 v3, v4, v5
	global_store_dwordx2 v[34:35], v[2:3], off offset:1024
	global_load_dwordx4 v[2:5], v[76:77], off offset:3072
	s_nop 0
	global_load_dwordx4 v[6:9], v[74:75], off offset:3072
	s_waitcnt vmcnt(0)
	v_pk_fma_f32 v[2:3], v[36:37], v[2:3], v[6:7]
	v_pk_fma_f32 v[4:5], v[40:41], v[4:5], v[8:9]
	global_store_dwordx4 v[80:81], v[2:5], off offset:3072
	global_load_dwordx4 v[6:9], v[72:73], off offset:3072
	global_load_dwordx4 v[56:59], v[70:71], off offset:3072
	v_add_co_u32_e32 v36, vcc, s82, v76
	s_waitcnt vmcnt(1)
	v_pk_add_f32 v[8:9], v[8:9], 1.0 op_sel_hi:[1,0]
	v_pk_add_f32 v[6:7], v[6:7], 1.0 op_sel_hi:[1,0]
	s_waitcnt vmcnt(0)
	v_pk_fma_f32 v[4:5], v[4:5], v[8:9], v[58:59]
	v_pk_fma_f32 v[2:3], v[2:3], v[6:7], v[56:57]
	v_addc_co_u32_e32 v37, vcc, 0, v77, vcc
	v_cvt_pk_bf16_f32 v2, v2, v3
	v_cvt_pk_bf16_f32 v3, v4, v5
	v_add_co_u32_e32 v40, vcc, s82, v74
	global_store_dwordx2 v[34:35], v[2:3], off offset:1536
	s_nop 0
	v_addc_co_u32_e32 v41, vcc, 0, v75, vcc
	global_load_dwordx4 v[2:5], v[36:37], off
	global_load_dwordx4 v[6:9], v[40:41], off
	v_add_co_u32_e32 v56, vcc, s82, v72
	s_waitcnt vmcnt(0)
	v_pk_fma_f32 v[2:3], v[28:29], v[2:3], v[6:7]
	v_addc_co_u32_e32 v57, vcc, 0, v73, vcc
	v_pk_fma_f32 v[4:5], v[26:27], v[4:5], v[8:9]
	v_add_co_u32_e32 v58, vcc, s82, v70
	global_store_dwordx4 v[78:79], v[2:5], off
	s_nop 0
	v_addc_co_u32_e32 v59, vcc, 0, v71, vcc
	global_load_dwordx4 v[6:9], v[56:57], off
	global_load_dwordx4 v[26:29], v[58:59], off
	s_waitcnt vmcnt(1)
	v_pk_add_f32 v[8:9], v[8:9], 1.0 op_sel_hi:[1,0]
	v_pk_add_f32 v[6:7], v[6:7], 1.0 op_sel_hi:[1,0]
	s_waitcnt vmcnt(0)
	v_pk_fma_f32 v[4:5], v[4:5], v[8:9], v[28:29]
	v_pk_fma_f32 v[2:3], v[2:3], v[6:7], v[26:27]
	v_cvt_pk_bf16_f32 v2, v2, v3
	v_cvt_pk_bf16_f32 v3, v4, v5
	global_store_dwordx2 v[34:35], v[2:3], off offset:2048
	global_load_dwordx4 v[2:5], v[36:37], off offset:1024
	s_nop 0
	global_load_dwordx4 v[6:9], v[40:41], off offset:1024
	v_pk_mul_f32 v[26:27], v[64:65], v[14:15] op_sel_hi:[1,0]
	v_pk_mul_f32 v[14:15], v[16:17], v[14:15] op_sel_hi:[1,0]
	v_and_b32_e32 v28, 0xffff0000, v48
	v_lshlrev_b32_e32 v29, 16, v47
	v_lshlrev_b32_e32 v47, 16, v43
	v_and_b32_e32 v43, 0xffff0000, v43
	v_and_b32_e32 v64, 0xffff0000, v50
	v_lshlrev_b32_e32 v65, 16, v51
	s_waitcnt vmcnt(0)
	v_pk_fma_f32 v[2:3], v[24:25], v[2:3], v[6:7]
	v_pk_fma_f32 v[4:5], v[26:27], v[4:5], v[8:9]
	global_store_dwordx4 v[78:79], v[2:5], off offset:1024
	global_load_dwordx4 v[6:9], v[56:57], off offset:1024
	global_load_dwordx4 v[24:27], v[58:59], off offset:1024
	s_waitcnt vmcnt(1)
	v_pk_add_f32 v[8:9], v[8:9], 1.0 op_sel_hi:[1,0]
	v_pk_add_f32 v[6:7], v[6:7], 1.0 op_sel_hi:[1,0]
	s_waitcnt vmcnt(0)
	v_pk_fma_f32 v[4:5], v[4:5], v[8:9], v[26:27]
	v_pk_fma_f32 v[2:3], v[2:3], v[6:7], v[24:25]
	v_cvt_pk_bf16_f32 v2, v2, v3
	v_cvt_pk_bf16_f32 v3, v4, v5
	global_store_dwordx2 v[34:35], v[2:3], off offset:2560
	global_load_dwordx4 v[2:5], v[36:37], off offset:2048
	s_nop 0
	global_load_dwordx4 v[6:9], v[40:41], off offset:2048
	v_lshlrev_b32_e32 v26, 16, v48
	v_lshlrev_b32_e32 v27, 16, v46
	v_lshlrev_b32_e32 v46, 16, v44
	v_and_b32_e32 v44, 0xffff0000, v45
	v_lshlrev_b32_e32 v45, 16, v42
	v_and_b32_e32 v42, 0xffff0000, v42
	v_lshlrev_b32_e32 v48, 16, v38
	v_and_b32_e32 v38, 0xffff0000, v38
	v_mov_b32_e32 v24, v46
	v_mov_b32_e32 v25, v44
	v_mov_b32_e32 v16, v48
	v_mov_b32_e32 v17, v38
	s_waitcnt vmcnt(0)
	v_pk_fma_f32 v[2:3], v[20:21], v[2:3], v[6:7]
	v_pk_fma_f32 v[4:5], v[22:23], v[4:5], v[8:9]
	global_store_dwordx4 v[78:79], v[2:5], off offset:2048
	global_load_dwordx4 v[6:9], v[56:57], off offset:2048
	global_load_dwordx4 v[20:23], v[58:59], off offset:2048
	s_waitcnt vmcnt(1)
	v_pk_add_f32 v[8:9], v[8:9], 1.0 op_sel_hi:[1,0]
	v_pk_add_f32 v[6:7], v[6:7], 1.0 op_sel_hi:[1,0]
	s_waitcnt vmcnt(0)
	v_pk_fma_f32 v[4:5], v[4:5], v[8:9], v[22:23]
	v_pk_fma_f32 v[2:3], v[2:3], v[6:7], v[20:21]
	v_cvt_pk_bf16_f32 v2, v2, v3
	v_cvt_pk_bf16_f32 v3, v4, v5
	global_store_dwordx2 v[34:35], v[2:3], off offset:3072
	global_load_dwordx4 v[2:5], v[36:37], off offset:3072
	s_nop 0
	global_load_dwordx4 v[6:9], v[40:41], off offset:3072
	v_lshlrev_b32_e32 v40, 16, v39
	v_and_b32_e32 v39, 0xffff0000, v39
	v_and_b32_e32 v41, 0xffff0000, v49
	v_mov_b32_e32 v36, v26
	v_mov_b32_e32 v37, v28
	v_mov_b32_e32 v20, v45
	v_mov_b32_e32 v21, v42
	v_mov_b32_e32 v22, v47
	v_mov_b32_e32 v23, v43
	s_waitcnt vmcnt(0)
	v_pk_fma_f32 v[2:3], v[14:15], v[2:3], v[6:7]
	v_pk_fma_f32 v[4:5], v[18:19], v[4:5], v[8:9]
	global_store_dwordx4 v[78:79], v[2:5], off offset:3072
	global_load_dwordx4 v[6:9], v[56:57], off offset:3072
	global_load_dwordx4 v[70:73], v[58:59], off offset:3072
	v_lshlrev_b32_e32 v58, 16, v54
	v_lshlrev_b32_e32 v59, 16, v52
	v_lshlrev_b32_e32 v56, 16, v50
	v_and_b32_e32 v57, 0xffff0000, v51
	v_mov_b32_e32 v15, v40
	v_mov_b32_e32 v40, v30
	v_mov_b32_e32 v19, v39
	s_waitcnt vmcnt(1)
	v_pk_add_f32 v[8:9], v[8:9], 1.0 op_sel_hi:[1,0]
	v_pk_add_f32 v[6:7], v[6:7], 1.0 op_sel_hi:[1,0]
	s_waitcnt vmcnt(0)
	v_pk_fma_f32 v[4:5], v[4:5], v[8:9], v[72:73]
	v_pk_fma_f32 v[2:3], v[2:3], v[6:7], v[70:71]
	s_nop 0
	s_nop 0
	s_nop 0
	s_nop 0
	s_nop 0
	v_cvt_pk_bf16_f32 v2, v2, v3
	v_cvt_pk_bf16_f32 v3, v4, v5
	global_store_dwordx2 v[34:35], v[2:3], off offset:3584
	s_cbranch_scc0 .LBB0_1218
.LBB0_1219:
	v_readlane_b32 s8, v254, 47
	v_readlane_b32 s9, v254, 48
	s_andn2_b64 vcc, exec, s[8:9]
	s_nop 0
	v_cndmask_b32_e64 v1, 0, 1, s[8:9]
	v_cmp_ne_u32_e64 s[18:19], 1, v1
	s_nop 1
	s_nop 1
	v_writelane_b32 v254, s18, 53
	s_nop 1
	v_writelane_b32 v254, s19, 54
	s_nop 0
	v_readlane_b32 s8, v254, 51
	s_mul_i32 s97, s8, 33
	v_readlane_b32 s9, v254, 52
	s_cbranch_vccnz .LBB0_1224
	v_lshlrev_b64 v[12:13], 2, v[10:11]
	v_lshl_add_u64 v[14:15], s[16:17], 0, v[12:13]
	v_lshl_add_u64 v[16:17], s[10:11], 0, v[12:13]
	s_mov_b64 s[8:9], 0x1000
	v_lshl_add_u64 v[18:19], v[14:15], 0, s[8:9]
	v_lshl_add_u64 v[20:21], v[16:17], 0, s[8:9]
	s_mov_b64 s[8:9], 0x1400
	v_lshl_add_u64 v[22:23], v[14:15], 0, s[8:9]
	v_lshl_add_u64 v[24:25], v[16:17], 0, s[8:9]
	s_mov_b64 s[8:9], 0x1c00
	v_lshl_add_u64 v[30:31], v[14:15], 0, s[8:9]
	v_lshl_add_u64 v[32:33], v[16:17], 0, s[8:9]
	v_lshl_add_u64 v[2:3], s[14:15], 0, v[12:13]
	s_mov_b64 s[8:9], 0x21b1e000
	v_lshl_add_u64 v[34:35], v[2:3], 0, s[8:9]
	v_lshl_add_u64 v[2:3], v[10:11], 1, s[14:15]
	s_mov_b64 s[8:9], 0xcc1b000
	v_lshl_add_u64 v[36:37], v[2:3], 0, s[8:9]
	v_readlane_b32 s8, v254, 34
	v_readlane_b32 s9, v254, 35
	s_add_u32 s12, s12, s8
	s_addc_u32 s13, s13, s9
	s_add_u32 s14, s14, s8
	v_lshl_add_u64 v[26:27], v[14:15], 0, s[52:53]
	v_lshl_add_u64 v[28:29], v[16:17], 0, s[52:53]
	s_addc_u32 s15, s15, s9
	s_mov_b32 s8, s2
	s_branch .LBB0_1222

.LBB0_1222:
	s_abs_i32 s10, s8
	v_readlane_b32 s11, v253, 56
	s_mul_hi_u32 s11, s10, s11
	v_readlane_b32 s18, v253, 57
	s_mul_i32 s16, s11, s18
	s_ashr_i32 s9, s8, 31
	s_sub_i32 s10, s10, s16
	s_xor_b32 s9, s9, s43
	s_add_i32 s16, s11, 1
	s_sub_i32 s17, s10, s18
	s_cmp_ge_u32 s10, s18
	s_cselect_b32 s11, s16, s11
	s_cselect_b32 s10, s17, s10
	s_add_i32 s16, s11, 1
	s_cmp_ge_u32 s10, s18
	s_cselect_b32 s10, s16, s11
	s_xor_b32 s10, s10, s9
	s_sub_i32 s9, s10, s9
	s_add_i32 s9, s8, s9
	s_and_b32 s9, s9, 7
	v_readlane_b32 s10, v253, 15
	s_cmp_lg_u32 s10, s9
	s_cbranch_scc1 .LBB0_1221
	s_lshr_b32 s9, s8, 3
	s_add_i32 s16, s8, 0x2000
	s_add_i32 s9, s9, 1
	s_cmp_gt_i32 s8, -1
	s_cselect_b32 s9, s9, 0
	s_add_i32 s9, s9, s97
	s_mul_hi_u32 s11, s9, 0xc000
	s_mul_i32 s9, s9, 0xc000
	s_add_u32 s10, s26, s9
	v_lshl_add_u64 v[2:3], s[14:15], 0, v[12:13]
	s_mov_b32 s9, 0x3af5e000
	v_add_co_u32_e32 v8, vcc, s9, v2
	s_mov_b32 s9, 0x3af5f000
	s_nop 0
	v_addc_co_u32_e32 v9, vcc, 0, v3, vcc
	v_add_co_u32_e32 v62, vcc, s9, v2
	s_mov_b32 s9, 0x3b15e000
	s_nop 0
	v_addc_co_u32_e32 v63, vcc, 0, v3, vcc
	global_load_dwordx4 v[4:7], v[62:63], off offset:-4096
	global_load_dwordx4 v[38:41], v[8:9], off offset:1024
	global_load_dwordx4 v[42:45], v[8:9], off offset:2048
	global_load_dwordx4 v[46:49], v[8:9], off offset:3072
	global_load_dwordx4 v[50:53], v[62:63], off
	global_load_dwordx4 v[54:57], v[62:63], off offset:1024
	global_load_dwordx4 v[58:61], v[62:63], off offset:2048
	s_nop 0
	global_load_dwordx4 v[62:65], v[62:63], off offset:3072
	v_add_co_u32_e32 v8, vcc, s9, v2
	s_mov_b32 s9, 0x3b15f000
	s_nop 0
	v_addc_co_u32_e32 v9, vcc, 0, v3, vcc
	v_add_co_u32_e32 v96, vcc, s9, v2
	s_mov_b32 s9, 0x3b35e000
	s_nop 0
	v_addc_co_u32_e32 v97, vcc, 0, v3, vcc
	global_load_dwordx4 v[66:69], v[96:97], off offset:-4096
	global_load_dwordx4 v[70:73], v[8:9], off offset:1024
	global_load_dwordx4 v[74:77], v[8:9], off offset:2048
	global_load_dwordx4 v[78:81], v[8:9], off offset:3072
	global_load_dwordx4 v[84:87], v[96:97], off
	global_load_dwordx4 v[88:91], v[96:97], off offset:1024
	global_load_dwordx4 v[92:95], v[96:97], off offset:2048
	s_nop 0
	global_load_dwordx4 v[96:99], v[96:97], off offset:3072
	v_add_co_u32_e32 v8, vcc, s9, v2
	s_mov_b32 s9, 0x3b35f000
	s_nop 0
	v_addc_co_u32_e32 v9, vcc, 0, v3, vcc
	v_add_co_u32_e32 v128, vcc, s9, v2
	s_mov_b32 s9, 0x3b55e000
	s_nop 0
	v_addc_co_u32_e32 v129, vcc, 0, v3, vcc
	global_load_dwordx4 v[100:103], v[128:129], off offset:-4096
	global_load_dwordx4 v[104:107], v[8:9], off offset:1024
	global_load_dwordx4 v[108:111], v[8:9], off offset:2048
	global_load_dwordx4 v[112:115], v[8:9], off offset:3072
	global_load_dwordx4 v[116:119], v[128:129], off
	global_load_dwordx4 v[120:123], v[128:129], off offset:1024
	global_load_dwordx4 v[124:127], v[128:129], off offset:2048
	s_nop 0
	global_load_dwordx4 v[128:131], v[128:129], off offset:3072
	s_addc_u32 s11, s27, s11
	s_ashr_i32 s17, s16, 31
	s_waitcnt vmcnt(15)
	v_pk_add_f32 v[6:7], v[6:7], v[68:69]
	s_waitcnt vmcnt(14)
	v_pk_add_f32 v[8:9], v[40:41], v[72:73]
	s_waitcnt vmcnt(13)
	v_pk_add_f32 v[42:43], v[42:43], v[74:75]
	v_pk_add_f32 v[40:41], v[44:45], v[76:77]
	s_waitcnt vmcnt(12)
	v_pk_add_f32 v[44:45], v[48:49], v[80:81]
	s_waitcnt vmcnt(11)
	v_pk_add_f32 v[48:49], v[52:53], v[86:87]
	s_waitcnt vmcnt(10)
	v_pk_add_f32 v[52:53], v[56:57], v[90:91]
	s_waitcnt vmcnt(9)
	v_pk_add_f32 v[56:57], v[60:61], v[94:95]
	s_waitcnt vmcnt(8)
	v_pk_add_f32 v[60:61], v[64:65], v[98:99]
	v_pk_add_f32 v[58:59], v[58:59], v[92:93]
	v_pk_add_f32 v[4:5], v[4:5], v[66:67]
	v_pk_add_f32 v[38:39], v[38:39], v[70:71]
	v_pk_add_f32 v[50:51], v[50:51], v[84:85]
	s_waitcnt vmcnt(5)
	v_pk_add_f32 v[74:75], v[42:43], v[108:109]
	v_add_co_u32_e32 v42, vcc, s9, v2
	s_mov_b32 s9, 0x3b55f000
	s_nop 0
	v_addc_co_u32_e32 v43, vcc, 0, v3, vcc
	s_waitcnt vmcnt(0)
	v_pk_add_f32 v[92:93], v[60:61], v[130:131]
	v_add_co_u32_e32 v60, vcc, s9, v2
	v_pk_add_f32 v[54:55], v[54:55], v[88:89]
	v_pk_add_f32 v[62:63], v[62:63], v[96:97]
	v_addc_co_u32_e32 v61, vcc, 0, v3, vcc
	v_pk_add_f32 v[46:47], v[46:47], v[78:79]
	v_pk_add_f32 v[64:65], v[6:7], v[102:103]
	v_pk_add_f32 v[66:67], v[4:5], v[100:101]
	v_pk_add_f32 v[68:69], v[8:9], v[106:107]
	v_pk_add_f32 v[70:71], v[38:39], v[104:105]
	v_pk_add_f32 v[72:73], v[40:41], v[110:111]
	v_pk_add_f32 v[76:77], v[44:45], v[114:115]
	v_pk_add_f32 v[78:79], v[48:49], v[118:119]
	v_pk_add_f32 v[80:81], v[50:51], v[116:117]
	v_pk_add_f32 v[84:85], v[52:53], v[122:123]
	v_pk_add_f32 v[86:87], v[54:55], v[120:121]
	v_pk_add_f32 v[88:89], v[56:57], v[126:127]
	v_pk_add_f32 v[90:91], v[58:59], v[124:125]
	v_pk_add_f32 v[94:95], v[62:63], v[128:129]
	global_load_dwordx4 v[2:5], v[60:61], off offset:-4096
	global_load_dwordx4 v[6:9], v[42:43], off offset:1024
	global_load_dwordx4 v[38:41], v[42:43], off offset:2048
	s_nop 0
	global_load_dwordx4 v[42:45], v[42:43], off offset:3072
	s_nop 0
	global_load_dwordx4 v[48:51], v[60:61], off
	global_load_dwordx4 v[52:55], v[60:61], off offset:1024
	global_load_dwordx4 v[56:59], v[60:61], off offset:2048
	s_nop 0
	global_load_dwordx4 v[60:63], v[60:61], off offset:3072
	s_movk_i32 s9, 0x5000
	v_pk_add_f32 v[46:47], v[46:47], v[112:113]
	s_waitcnt vmcnt(7)
	v_pk_add_f32 v[64:65], v[4:5], v[64:65]
	s_waitcnt vmcnt(6)
	v_pk_add_f32 v[96:97], v[8:9], v[68:69]
	v_pk_add_f32 v[98:99], v[6:7], v[70:71]
	v_pk_add_f32 v[66:67], v[2:3], v[66:67]
	s_waitcnt vmcnt(4)
	v_pk_add_f32 v[44:45], v[44:45], v[76:77]
	s_waitcnt vmcnt(2)
	v_pk_add_f32 v[8:9], v[54:55], v[84:85]
	v_lshl_add_u64 v[54:55], v[10:11], 2, s[10:11]
	v_add_co_u32_e32 v6, vcc, s9, v54
	s_waitcnt vmcnt(1)
	v_pk_add_f32 v[2:3], v[58:59], v[88:89]
	v_addc_co_u32_e32 v7, vcc, 0, v55, vcc
	v_pk_add_f32 v[4:5], v[56:57], v[90:91]
	global_load_dwordx4 v[56:59], v[6:7], off offset:-4096
	v_lshl_add_u64 v[76:77], s[12:13], 0, v[12:13]
	v_pk_add_f32 v[72:73], v[40:41], v[72:73]
	v_pk_add_f32 v[46:47], v[42:43], v[46:47]
	v_pk_add_f32 v[40:41], v[50:51], v[78:79]
	v_pk_add_f32 v[42:43], v[48:49], v[80:81]
	global_load_dwordx4 v[48:51], v[76:77], off
	s_mov_b64 s[10:11], 0x4000
	v_pk_add_f32 v[74:75], v[38:39], v[74:75]
	v_pk_add_f32 v[38:39], v[52:53], v[86:87]
	v_lshl_add_u64 v[52:53], v[54:55], 0, s[10:11]
	s_waitcnt vmcnt(2)
	v_pk_add_f32 v[68:69], v[62:63], v[92:93]
	v_pk_add_f32 v[70:71], v[60:61], v[94:95]
	s_mov_b32 s9, 0x9000
	s_waitcnt vmcnt(1)
	v_pk_add_f32 v[58:59], v[58:59], 1.0 op_sel_hi:[1,0]
	v_pk_add_f32 v[56:57], v[56:57], 1.0 op_sel_hi:[1,0]
	v_pk_mul_f32 v[58:59], v[58:59], v[64:65]
	v_pk_mul_f32 v[56:57], v[56:57], v[66:67]
	s_waitcnt vmcnt(0)
	v_pk_fma_f32 v[64:65], v[50:51], s[92:93], v[58:59] op_sel_hi:[1,0,1]
	v_pk_fma_f32 v[66:67], v[48:49], s[92:93], v[56:57] op_sel_hi:[1,0,1]
	global_load_dwordx4 v[48:51], v[76:77], off offset:1024
	global_load_dwordx4 v[56:59], v[52:53], off offset:1024
	s_waitcnt vmcnt(0)
	v_pk_add_f32 v[58:59], v[58:59], 1.0 op_sel_hi:[1,0]
	v_pk_add_f32 v[56:57], v[56:57], 1.0 op_sel_hi:[1,0]
	v_pk_mul_f32 v[58:59], v[96:97], v[58:59]
	v_pk_mul_f32 v[56:57], v[98:99], v[56:57]
	v_pk_fma_f32 v[60:61], v[50:51], s[92:93], v[58:59] op_sel_hi:[1,0,1]
	v_pk_fma_f32 v[62:63], v[48:49], s[92:93], v[56:57] op_sel_hi:[1,0,1]
	global_load_dwordx4 v[48:51], v[76:77], off offset:2048
	global_load_dwordx4 v[56:59], v[52:53], off offset:2048
	s_waitcnt vmcnt(0)
	v_pk_add_f32 v[58:59], v[58:59], 1.0 op_sel_hi:[1,0]
	v_pk_add_f32 v[56:57], v[56:57], 1.0 op_sel_hi:[1,0]
	v_pk_mul_f32 v[58:59], v[58:59], v[72:73]
	v_pk_mul_f32 v[56:57], v[56:57], v[74:75]
	v_pk_fma_f32 v[58:59], v[50:51], s[92:93], v[58:59] op_sel_hi:[1,0,1]
	v_pk_fma_f32 v[56:57], v[48:49], s[92:93], v[56:57] op_sel_hi:[1,0,1]
	global_load_dwordx4 v[48:51], v[76:77], off offset:3072
	global_load_dwordx4 v[72:75], v[52:53], off offset:3072
	v_add_co_u32_e32 v76, vcc, s82, v76
	s_waitcnt vmcnt(0)
	v_pk_add_f32 v[52:53], v[74:75], 1.0 op_sel_hi:[1,0]
	v_pk_add_f32 v[72:73], v[72:73], 1.0 op_sel_hi:[1,0]
	v_pk_mul_f32 v[44:45], v[44:45], v[52:53]
	v_pk_mul_f32 v[46:47], v[46:47], v[72:73]
	v_addc_co_u32_e32 v77, vcc, 0, v77, vcc
	v_pk_fma_f32 v[52:53], v[50:51], s[92:93], v[44:45] op_sel_hi:[1,0,1]
	v_pk_fma_f32 v[50:51], v[48:49], s[92:93], v[46:47] op_sel_hi:[1,0,1]
	global_load_dwordx4 v[44:47], v[76:77], off
	global_load_dwordx4 v[72:75], v[6:7], off
	s_waitcnt vmcnt(0)
	v_pk_add_f32 v[48:49], v[74:75], 1.0 op_sel_hi:[1,0]
	v_pk_add_f32 v[72:73], v[72:73], 1.0 op_sel_hi:[1,0]
	v_pk_mul_f32 v[40:41], v[48:49], v[40:41]
	v_pk_mul_f32 v[42:43], v[72:73], v[42:43]
	v_pk_fma_f32 v[48:49], v[46:47], s[92:93], v[40:41] op_sel_hi:[1,0,1]
	v_pk_fma_f32 v[46:47], v[44:45], s[92:93], v[42:43] op_sel_hi:[1,0,1]
	global_load_dwordx4 v[40:43], v[76:77], off offset:1024
	global_load_dwordx4 v[72:75], v[6:7], off offset:1024
	s_waitcnt vmcnt(0)
	v_pk_add_f32 v[44:45], v[74:75], 1.0 op_sel_hi:[1,0]
	v_pk_add_f32 v[72:73], v[72:73], 1.0 op_sel_hi:[1,0]
	v_pk_mul_f32 v[8:9], v[8:9], v[44:45]
	v_pk_mul_f32 v[38:39], v[38:39], v[72:73]
	v_pk_fma_f32 v[44:45], v[42:43], s[92:93], v[8:9] op_sel_hi:[1,0,1]
	v_pk_fma_f32 v[42:43], v[40:41], s[92:93], v[38:39] op_sel_hi:[1,0,1]
	global_load_dwordx4 v[38:41], v[76:77], off offset:2048
	global_load_dwordx4 v[72:75], v[6:7], off offset:2048
	s_waitcnt vmcnt(0)
	v_pk_add_f32 v[8:9], v[74:75], 1.0 op_sel_hi:[1,0]
	v_pk_add_f32 v[72:73], v[72:73], 1.0 op_sel_hi:[1,0]
	v_pk_mul_f32 v[2:3], v[8:9], v[2:3]
	v_pk_mul_f32 v[4:5], v[72:73], v[4:5]
	v_pk_fma_f32 v[40:41], v[40:41], s[92:93], v[2:3] op_sel_hi:[1,0,1]
	v_pk_fma_f32 v[38:39], v[38:39], s[92:93], v[4:5] op_sel_hi:[1,0,1]
	global_load_dwordx4 v[2:5], v[76:77], off offset:3072
	s_nop 0
	global_load_dwordx4 v[6:9], v[6:7], off offset:3072
	s_waitcnt vmcnt(0)
	v_pk_add_f32 v[8:9], v[8:9], 1.0 op_sel_hi:[1,0]
	v_pk_add_f32 v[6:7], v[6:7], 1.0 op_sel_hi:[1,0]
	v_pk_mul_f32 v[8:9], v[68:69], v[8:9]
	v_pk_mul_f32 v[6:7], v[70:71], v[6:7]
	v_pk_fma_f32 v[4:5], v[4:5], s[92:93], v[8:9] op_sel_hi:[1,0,1]
	v_pk_fma_f32 v[2:3], v[2:3], s[92:93], v[6:7] op_sel_hi:[1,0,1]
	v_mov_b32_e32 v6, v66
	v_mov_b32_e32 v7, v62
	v_mov_b32_e32 v8, v67
	v_mov_b32_e32 v9, v63
	v_pk_add_f32 v[6:7], v[6:7], v[8:9]
	v_mov_b32_e32 v8, v64
	v_mov_b32_e32 v9, v60
	v_mov_b32_e32 v68, v65
	v_mov_b32_e32 v69, v61
	v_pk_add_f32 v[8:9], v[8:9], v[68:69]
	v_mov_b32_e32 v68, v56
	v_pk_add_f32 v[6:7], v[6:7], v[8:9]
	v_pk_mov_b32 v[8:9], v[56:57], v[58:59] op_sel:[1,0]
	v_mov_b32_e32 v69, v59
	v_pk_add_f32 v[8:9], v[8:9], v[68:69]
	v_add_f32_e32 v1, 0, v6
	v_pk_add_f32 v[8:9], v[8:9], v[8:9] op_sel:[0,1] op_sel_hi:[1,0]
	v_add_f32_e32 v6, v1, v7
	v_add_f32_e32 v68, v50, v51
	v_add_f32_e32 v70, v52, v53
	v_mov_b32_e32 v7, v46
	v_mov_b32_e32 v9, v47
	v_mov_b32_e32 v69, v48
	v_mov_b32_e32 v71, v49
	v_pk_add_f32 v[6:7], v[6:7], v[8:9]
	v_pk_add_f32 v[8:9], v[68:69], v[70:71]
	v_mov_b32_e32 v68, v42
	v_pk_add_f32 v[6:7], v[6:7], v[8:9]
	v_pk_mov_b32 v[8:9], v[42:43], v[44:45] op_sel:[1,0]
	v_mov_b32_e32 v69, v45
	v_pk_add_f32 v[8:9], v[8:9], v[68:69]
	v_pk_add_f32 v[6:7], v[6:7], v[6:7] op_sel:[0,1] op_sel_hi:[1,0]
	v_pk_add_f32 v[8:9], v[8:9], v[8:9] op_sel:[0,1] op_sel_hi:[1,0]
	v_add_f32_e32 v68, v38, v39
	v_add_f32_e32 v70, v40, v41
	v_mov_b32_e32 v7, v2
	v_mov_b32_e32 v9, v3
	v_mov_b32_e32 v69, v4
	v_mov_b32_e32 v71, v5
	v_pk_add_f32 v[6:7], v[6:7], v[8:9]
	v_pk_add_f32 v[8:9], v[68:69], v[70:71]
	s_nop 0
	v_pk_add_f32 v[6:7], v[6:7], v[8:9]
	s_nop 0
	v_add_f32_e32 v1, v6, v7
	v_and_b32_e32 v6, 64, v249
	v_add_u32_e32 v6, 64, v6
	v_xor_b32_e32 v7, 1, v249
	v_cmp_lt_i32_e32 vcc, v7, v6
	s_nop 1
	v_cndmask_b32_e32 v7, v249, v7, vcc
	v_lshlrev_b32_e32 v72, 2, v7
	ds_bpermute_b32 v7, v72, v1
	s_waitcnt lgkmcnt(0)
	v_add_f32_e32 v1, v1, v7
	v_xor_b32_e32 v7, 2, v249
	v_cmp_lt_i32_e32 vcc, v7, v6
	s_nop 1
	v_cndmask_b32_e32 v7, v249, v7, vcc
	v_lshlrev_b32_e32 v73, 2, v7
	ds_bpermute_b32 v7, v73, v1
	s_waitcnt lgkmcnt(0)
	v_add_f32_e32 v1, v1, v7
	v_xor_b32_e32 v7, 4, v249
	v_cmp_lt_i32_e32 vcc, v7, v6
	s_nop 1
	v_cndmask_b32_e32 v7, v249, v7, vcc
	v_lshlrev_b32_e32 v74, 2, v7
	ds_bpermute_b32 v7, v74, v1
	s_waitcnt lgkmcnt(0)
	v_add_f32_e32 v1, v1, v7
	v_xor_b32_e32 v7, 8, v249
	v_cmp_lt_i32_e32 vcc, v7, v6
	s_nop 1
	v_cndmask_b32_e32 v7, v249, v7, vcc
	v_lshlrev_b32_e32 v75, 2, v7
	ds_bpermute_b32 v7, v75, v1
	s_waitcnt lgkmcnt(0)
	v_add_f32_e32 v1, v1, v7
	v_xor_b32_e32 v7, 16, v249
	v_cmp_lt_i32_e32 vcc, v7, v6
	s_nop 1
	v_cndmask_b32_e32 v7, v249, v7, vcc
	v_lshlrev_b32_e32 v76, 2, v7
	ds_bpermute_b32 v7, v76, v1
	s_waitcnt lgkmcnt(0)
	v_add_f32_e32 v1, v1, v7
	v_xor_b32_e32 v7, 32, v249
	v_cmp_lt_i32_e32 vcc, v7, v6
	s_nop 1
	v_cndmask_b32_e32 v6, v249, v7, vcc
	v_lshlrev_b32_e32 v77, 2, v6
	ds_bpermute_b32 v6, v77, v1
	s_waitcnt lgkmcnt(0)
	v_add_f32_e32 v1, v1, v6
	v_fmamk_f32 v67, v1, 0xba000000, v67
	v_fmamk_f32 v63, v1, 0xba000000, v63
	v_fmamk_f32 v65, v1, 0xba000000, v65
	v_fmac_f32_e32 v66, 0xba000000, v1
	v_fmamk_f32 v61, v1, 0xba000000, v61
	v_fmac_f32_e32 v62, 0xba000000, v1
	v_mov_b32_e32 v8, v67
	v_mov_b32_e32 v9, v63
	v_fmac_f32_e32 v64, 0xba000000, v1
	v_fmac_f32_e32 v60, 0xba000000, v1
	v_mov_b32_e32 v6, v66
	v_mov_b32_e32 v7, v62
	v_pk_mul_f32 v[8:9], v[8:9], v[8:9]
	v_mov_b32_e32 v68, v65
	v_mov_b32_e32 v69, v61
	v_pk_fma_f32 v[6:7], v[6:7], v[6:7], v[8:9]
	v_mov_b32_e32 v8, v64
	v_mov_b32_e32 v9, v60
	v_pk_mul_f32 v[68:69], v[68:69], v[68:69]
	v_fmamk_f32 v57, v1, 0xba000000, v57
	v_pk_fma_f32 v[8:9], v[8:9], v[8:9], v[68:69]
	v_fmac_f32_e32 v56, 0xba000000, v1
	v_pk_add_f32 v[6:7], v[6:7], v[8:9]
	v_fmamk_f32 v59, v1, 0xba000000, v59
	v_fmac_f32_e32 v58, 0xba000000, v1
	v_pk_add_f32 v[6:7], v[6:7], v[6:7] op_sel_hi:[0,1]
	v_pk_mul_f32 v[8:9], v[58:59], v[58:59]
	v_pk_mul_f32 v[68:69], v[56:57], v[56:57]
	v_fmac_f32_e32 v50, 0xba000000, v1
	v_pk_mov_b32 v[70:71], v[68:69], v[8:9] op_sel:[1,0]
	v_mov_b32_e32 v69, v9
	v_fmamk_f32 v51, v1, 0xba000000, v51
	v_fmac_f32_e32 v52, 0xba000000, v1
	v_mul_f32_e32 v6, v50, v50
	v_pk_add_f32 v[8:9], v[70:71], v[68:69]
	v_fmamk_f32 v53, v1, 0xba000000, v53
	v_pk_fma_f32 v[68:69], v[50:51], v[50:51], v[6:7] op_sel_hi:[1,1,0]
	v_mul_f32_e32 v6, v52, v52
	v_pk_add_f32 v[8:9], v[8:9], v[8:9] op_sel_hi:[0,1]
	v_pk_fma_f32 v[70:71], v[52:53], v[52:53], v[6:7] op_sel_hi:[1,1,0]
	v_fmamk_f32 v49, v1, 0xba000000, v49
	v_fmac_f32_e32 v48, 0xba000000, v1
	v_fmamk_f32 v47, v1, 0xba000000, v47
	v_fmac_f32_e32 v46, 0xba000000, v1
	v_mul_f32_e32 v68, v46, v46
	v_mul_f32_e32 v70, v47, v47
	v_mul_f32_e32 v8, v48, v48
	v_mul_f32_e32 v6, v49, v49
	v_pk_add_f32 v[68:69], v[68:69], v[70:71]
	v_pk_add_f32 v[6:7], v[8:9], v[6:7]
	v_fmamk_f32 v43, v1, 0xba000000, v43
	v_pk_add_f32 v[6:7], v[68:69], v[6:7]
	v_fmac_f32_e32 v42, 0xba000000, v1
	v_fmamk_f32 v45, v1, 0xba000000, v45
	v_fmac_f32_e32 v44, 0xba000000, v1
	v_pk_add_f32 v[6:7], v[6:7], v[6:7] op_sel_hi:[0,1]
	v_pk_mul_f32 v[8:9], v[44:45], v[44:45]
	v_pk_mul_f32 v[68:69], v[42:43], v[42:43]
	v_fmac_f32_e32 v38, 0xba000000, v1
	v_pk_mov_b32 v[70:71], v[68:69], v[8:9] op_sel:[1,0]
	v_mov_b32_e32 v69, v9
	v_fmamk_f32 v39, v1, 0xba000000, v39
	v_fmac_f32_e32 v40, 0xba000000, v1
	v_mul_f32_e32 v6, v38, v38
	v_pk_add_f32 v[8:9], v[70:71], v[68:69]
	v_fmamk_f32 v41, v1, 0xba000000, v41
	v_pk_fma_f32 v[68:69], v[38:39], v[38:39], v[6:7] op_sel_hi:[1,1,0]
	v_mul_f32_e32 v6, v40, v40
	v_pk_add_f32 v[8:9], v[8:9], v[8:9] op_sel_hi:[0,1]
	v_pk_fma_f32 v[70:71], v[40:41], v[40:41], v[6:7] op_sel_hi:[1,1,0]
	v_fmamk_f32 v5, v1, 0xba000000, v5
	v_fmac_f32_e32 v4, 0xba000000, v1
	v_fmamk_f32 v3, v1, 0xba000000, v3
	v_fmac_f32_e32 v2, 0xba000000, v1
	v_mul_f32_e32 v68, v2, v2
	v_mul_f32_e32 v70, v3, v3
	v_mul_f32_e32 v8, v4, v4
	v_mul_f32_e32 v6, v5, v5
	v_pk_add_f32 v[68:69], v[68:69], v[70:71]
	v_pk_add_f32 v[6:7], v[8:9], v[6:7]
	s_nop 0
	v_pk_add_f32 v[6:7], v[68:69], v[6:7]
	s_nop 0
	v_add_f32_e32 v1, v6, v7
	ds_bpermute_b32 v6, v72, v1
	s_waitcnt lgkmcnt(0)
	v_add_f32_e32 v1, v1, v6
	ds_bpermute_b32 v6, v73, v1
	s_waitcnt lgkmcnt(0)
	v_add_f32_e32 v1, v1, v6
	ds_bpermute_b32 v6, v74, v1
	s_waitcnt lgkmcnt(0)
	v_add_f32_e32 v1, v1, v6
	ds_bpermute_b32 v6, v75, v1
	s_waitcnt lgkmcnt(0)
	v_add_f32_e32 v1, v1, v6
	ds_bpermute_b32 v6, v76, v1
	s_waitcnt lgkmcnt(0)
	v_add_f32_e32 v1, v1, v6
	ds_bpermute_b32 v6, v77, v1
	s_waitcnt lgkmcnt(0)
	v_add_f32_e32 v1, v1, v6
	v_fmamk_f32 v1, v1, 0x3a000000, v250
	v_cmp_gt_f32_e32 vcc, s96, v1
	v_mul_f32_e32 v6, 0x4f800000, v1
	s_nop 0
	v_cndmask_b32_e32 v1, v1, v6, vcc
	v_sqrt_f32_e32 v6, v1
	s_nop 0
	v_add_u32_e32 v7, -1, v6
	v_fma_f32 v8, -v7, v6, v1
	v_cmp_ge_f32_e64 s[10:11], 0, v8
	v_add_u32_e32 v8, 1, v6
	s_nop 0
	v_cndmask_b32_e64 v7, v6, v7, s[10:11]
	v_fma_f32 v6, -v8, v6, v1
	v_cmp_lt_f32_e64 s[10:11], 0, v6
	s_nop 1
	v_cndmask_b32_e64 v6, v7, v8, s[10:11]
	v_mul_f32_e32 v7, 0x37800000, v6
	v_cndmask_b32_e32 v6, v6, v7, vcc
	v_cmp_class_f32_e32 vcc, v1, v251
	s_nop 1
	v_cndmask_b32_e32 v1, v6, v1, vcc
	v_div_scale_f32 v6, s[10:11], v1, v1, 1.0
	v_rcp_f32_e32 v7, v6
	s_lshl_b64 s[10:11], s[16:17], 13
	v_fma_f32 v8, -v6, v7, 1.0
	v_fmac_f32_e32 v7, v8, v7
	v_div_scale_f32 v8, vcc, 1.0, v1, 1.0
	v_mul_f32_e32 v9, v8, v7
	v_fma_f32 v68, -v6, v9, v8
	v_fmac_f32_e32 v9, v68, v7
	global_load_dwordx4 v[68:71], v[14:15], off
	global_load_dwordx4 v[72:75], v[16:17], off
	v_fma_f32 v6, -v6, v9, v8
	v_div_fmas_f32 v6, v6, v7, v9
	v_div_fixup_f32 v6, v6, v1, 1.0
	v_pk_mul_f32 v[64:65], v[64:65], v[6:7] op_sel_hi:[1,0]
	v_pk_mul_f32 v[8:9], v[66:67], v[6:7] op_sel_hi:[1,0]
	v_lshl_add_u64 v[66:67], v[34:35], 0, s[10:11]
	s_mov_b64 s[10:11], 0x8000
	v_lshl_add_u64 v[80:81], v[54:55], 0, s[10:11]
	s_mov_b64 s[10:11], 0x6000
	v_lshl_add_u64 v[84:85], v[54:55], 0, s[10:11]
	s_lshl_b64 s[10:11], s[16:17], 12
	s_waitcnt vmcnt(0)
	v_pk_fma_f32 v[70:71], v[70:71], v[64:65], v[74:75]
	v_add_co_u32_e32 v64, vcc, s9, v54
	v_pk_fma_f32 v[68:69], v[68:69], v[8:9], v[72:73]
	s_nop 0
	v_addc_co_u32_e32 v65, vcc, 0, v55, vcc
	s_movk_i32 s9, 0x7000
	global_store_dwordx4 v[66:67], v[68:71], off
	v_add_co_u32_e32 v54, vcc, s9, v54
	global_load_dwordx4 v[72:75], v[64:65], off offset:-4096
	s_nop 0
	v_addc_co_u32_e32 v55, vcc, 0, v55, vcc
	global_load_dwordx4 v[76:79], v[54:55], off offset:-4096
	s_waitcnt vmcnt(1)
	v_pk_add_f32 v[72:73], v[72:73], 1.0 op_sel_hi:[1,0]
	v_pk_add_f32 v[8:9], v[74:75], 1.0 op_sel_hi:[1,0]
	s_waitcnt vmcnt(0)
	v_pk_fma_f32 v[68:69], v[72:73], v[68:69], v[76:77]
	s_nop 0
	v_pk_fma_f32 v[8:9], v[8:9], v[70:71], v[78:79]
	v_cvt_pk_bf16_f32 v68, v68, v69
	v_bfe_u32 v1, v8, 16, 1
	v_add3_u32 v1, v8, v1, s73
	v_bfe_u32 v7, v9, 16, 1
	v_lshrrev_b32_e32 v1, 16, v1
	v_add3_u32 v7, v9, v7, s73
	v_and_or_b32 v69, v7, s33, v1
	v_lshl_add_u64 v[8:9], v[36:37], 0, s[10:11]
	global_store_dwordx2 v[8:9], v[68:69], off
	global_load_dwordx4 v[68:71], v[14:15], off offset:1024
	s_nop 0
	global_load_dwordx4 v[72:75], v[16:17], off offset:1024
	v_pk_mul_f32 v[76:77], v[60:61], v[6:7] op_sel_hi:[1,0]
	v_pk_mul_f32 v[60:61], v[62:63], v[6:7] op_sel_hi:[1,0]
	s_waitcnt vmcnt(0)
	v_pk_fma_f32 v[62:63], v[70:71], v[76:77], v[74:75]
	v_pk_fma_f32 v[60:61], v[68:69], v[60:61], v[72:73]
	global_store_dwordx4 v[66:67], v[60:63], off offset:1024
	global_load_dwordx4 v[68:71], v[80:81], off offset:1024
	global_load_dwordx4 v[72:75], v[84:85], off offset:1024
	s_waitcnt vmcnt(1)
	v_pk_add_f32 v[68:69], v[68:69], 1.0 op_sel_hi:[1,0]
	s_waitcnt vmcnt(0)
	v_pk_fma_f32 v[60:61], v[68:69], v[60:61], v[72:73]
	v_pk_add_f32 v[70:71], v[70:71], 1.0 op_sel_hi:[1,0]
	s_nop 0
	v_pk_fma_f32 v[62:63], v[70:71], v[62:63], v[74:75]
	v_cvt_pk_bf16_f32 v60, v60, v61
	v_bfe_u32 v1, v62, 16, 1
	v_add3_u32 v1, v62, v1, s73
	v_bfe_u32 v7, v63, 16, 1
	v_lshrrev_b32_e32 v1, 16, v1
	v_add3_u32 v7, v63, v7, s73
	v_and_or_b32 v61, v7, s33, v1
	global_store_dwordx2 v[8:9], v[60:61], off offset:512
	global_load_dwordx4 v[60:63], v[14:15], off offset:2048
	s_nop 0
	global_load_dwordx4 v[68:71], v[16:17], off offset:2048
	v_pk_mul_f32 v[58:59], v[58:59], v[6:7] op_sel_hi:[1,0]
	v_pk_mul_f32 v[56:57], v[56:57], v[6:7] op_sel_hi:[1,0]
	s_waitcnt vmcnt(0)
	v_pk_fma_f32 v[58:59], v[62:63], v[58:59], v[70:71]
	v_pk_fma_f32 v[56:57], v[60:61], v[56:57], v[68:69]
	global_store_dwordx4 v[66:67], v[56:59], off offset:2048
	global_load_dwordx4 v[60:63], v[80:81], off offset:2048
	global_load_dwordx4 v[68:71], v[84:85], off offset:2048
	s_waitcnt vmcnt(1)
	v_pk_add_f32 v[60:61], v[60:61], 1.0 op_sel_hi:[1,0]
	s_waitcnt vmcnt(0)
	v_pk_fma_f32 v[56:57], v[56:57], v[60:61], v[68:69]
	v_pk_add_f32 v[62:63], v[62:63], 1.0 op_sel_hi:[1,0]
	s_nop 0
	v_pk_fma_f32 v[58:59], v[58:59], v[62:63], v[70:71]
	v_cvt_pk_bf16_f32 v56, v56, v57
	v_bfe_u32 v1, v58, 16, 1
	v_add3_u32 v1, v58, v1, s73
	v_bfe_u32 v7, v59, 16, 1
	v_lshrrev_b32_e32 v1, 16, v1
	v_add3_u32 v7, v59, v7, s73
	v_and_or_b32 v57, v7, s33, v1
	global_store_dwordx2 v[8:9], v[56:57], off offset:1024
	global_load_dwordx4 v[56:59], v[14:15], off offset:3072
	s_nop 0
	global_load_dwordx4 v[60:63], v[16:17], off offset:3072
	v_pk_mul_f32 v[52:53], v[52:53], v[6:7] op_sel_hi:[1,0]
	v_pk_mul_f32 v[50:51], v[50:51], v[6:7] op_sel_hi:[1,0]
	s_waitcnt vmcnt(0)
	v_pk_fma_f32 v[52:53], v[52:53], v[58:59], v[62:63]
	v_pk_fma_f32 v[50:51], v[50:51], v[56:57], v[60:61]
	global_store_dwordx4 v[66:67], v[50:53], off offset:3072
	global_load_dwordx4 v[56:59], v[80:81], off offset:3072
	global_load_dwordx4 v[60:63], v[84:85], off offset:3072
	s_waitcnt vmcnt(1)
	v_pk_add_f32 v[56:57], v[56:57], 1.0 op_sel_hi:[1,0]
	s_waitcnt vmcnt(0)
	v_pk_fma_f32 v[50:51], v[50:51], v[56:57], v[60:61]
	v_pk_add_f32 v[58:59], v[58:59], 1.0 op_sel_hi:[1,0]
	s_nop 0
	v_pk_fma_f32 v[52:53], v[52:53], v[58:59], v[62:63]
	v_cvt_pk_bf16_f32 v50, v50, v51
	v_bfe_u32 v1, v52, 16, 1
	v_add3_u32 v1, v52, v1, s73
	v_bfe_u32 v7, v53, 16, 1
	v_lshrrev_b32_e32 v1, 16, v1
	v_add3_u32 v7, v53, v7, s73
	v_and_or_b32 v51, v7, s33, v1
	global_store_dwordx2 v[8:9], v[50:51], off offset:1536
	global_load_dwordx4 v[50:53], v[18:19], off
	s_nop 0
	global_load_dwordx4 v[56:59], v[20:21], off
	v_pk_mul_f32 v[46:47], v[46:47], v[6:7] op_sel_hi:[1,0]
	v_pk_mul_f32 v[60:61], v[48:49], v[6:7] op_sel_hi:[1,0]
	s_waitcnt vmcnt(0)
	v_pk_fma_f32 v[48:49], v[46:47], v[50:51], v[56:57]
	v_add_co_u32_e32 v46, vcc, s82, v66
	v_pk_fma_f32 v[50:51], v[60:61], v[52:53], v[58:59]
	s_nop 0
	v_addc_co_u32_e32 v47, vcc, 0, v67, vcc
	global_store_dwordx4 v[46:47], v[48:51], off
	global_load_dwordx4 v[56:59], v[64:65], off
	global_load_dwordx4 v[60:63], v[54:55], off
	s_waitcnt vmcnt(1)
	v_pk_add_f32 v[56:57], v[56:57], 1.0 op_sel_hi:[1,0]
	s_waitcnt vmcnt(0)
	v_pk_fma_f32 v[48:49], v[48:49], v[56:57], v[60:61]
	v_pk_add_f32 v[52:53], v[58:59], 1.0 op_sel_hi:[1,0]
	s_nop 0
	v_pk_fma_f32 v[50:51], v[50:51], v[52:53], v[62:63]
	v_cvt_pk_bf16_f32 v48, v48, v49
	v_bfe_u32 v1, v50, 16, 1
	v_add3_u32 v1, v50, v1, s73
	v_bfe_u32 v7, v51, 16, 1
	v_lshrrev_b32_e32 v1, 16, v1
	v_add3_u32 v7, v51, v7, s73
	v_and_or_b32 v49, v7, s33, v1
	global_store_dwordx2 v[8:9], v[48:49], off offset:2048
	global_load_dwordx4 v[48:51], v[22:23], off
	s_nop 0
	global_load_dwordx4 v[56:59], v[24:25], off
	v_pk_mul_f32 v[44:45], v[44:45], v[6:7] op_sel_hi:[1,0]
	v_pk_mul_f32 v[42:43], v[42:43], v[6:7] op_sel_hi:[1,0]
	s_waitcnt vmcnt(0)
	v_pk_fma_f32 v[44:45], v[44:45], v[50:51], v[58:59]
	v_pk_fma_f32 v[42:43], v[42:43], v[48:49], v[56:57]
	global_store_dwordx4 v[46:47], v[42:45], off offset:1024
	global_load_dwordx4 v[48:51], v[64:65], off offset:1024
	global_load_dwordx4 v[56:59], v[54:55], off offset:1024
	s_waitcnt vmcnt(1)
	v_pk_add_f32 v[48:49], v[48:49], 1.0 op_sel_hi:[1,0]
	s_waitcnt vmcnt(0)
	v_pk_fma_f32 v[42:43], v[42:43], v[48:49], v[56:57]
	v_pk_add_f32 v[50:51], v[50:51], 1.0 op_sel_hi:[1,0]
	s_nop 0
	v_pk_fma_f32 v[44:45], v[44:45], v[50:51], v[58:59]
	v_cvt_pk_bf16_f32 v42, v42, v43
	v_bfe_u32 v1, v44, 16, 1
	v_add3_u32 v1, v44, v1, s73
	v_bfe_u32 v7, v45, 16, 1
	v_lshrrev_b32_e32 v1, 16, v1
	v_add3_u32 v7, v45, v7, s73
	v_and_or_b32 v43, v7, s33, v1
	global_store_dwordx2 v[8:9], v[42:43], off offset:2560
	global_load_dwordx4 v[42:45], v[26:27], off
	s_nop 0
	global_load_dwordx4 v[48:51], v[28:29], off
	v_pk_mul_f32 v[40:41], v[40:41], v[6:7] op_sel_hi:[1,0]
	v_pk_mul_f32 v[38:39], v[38:39], v[6:7] op_sel_hi:[1,0]
	s_waitcnt vmcnt(0)
	v_pk_fma_f32 v[40:41], v[40:41], v[44:45], v[50:51]
	v_pk_fma_f32 v[38:39], v[38:39], v[42:43], v[48:49]
	global_store_dwordx4 v[46:47], v[38:41], off offset:2048
	global_load_dwordx4 v[42:45], v[64:65], off offset:2048
	global_load_dwordx4 v[48:51], v[54:55], off offset:2048
	s_waitcnt vmcnt(1)
	v_pk_add_f32 v[42:43], v[42:43], 1.0 op_sel_hi:[1,0]
	s_waitcnt vmcnt(0)
	v_pk_fma_f32 v[38:39], v[38:39], v[42:43], v[48:49]
	v_pk_add_f32 v[44:45], v[44:45], 1.0 op_sel_hi:[1,0]
	s_nop 0
	v_pk_fma_f32 v[40:41], v[40:41], v[44:45], v[50:51]
	v_cvt_pk_bf16_f32 v38, v38, v39
	v_bfe_u32 v1, v40, 16, 1
	v_add3_u32 v1, v40, v1, s73
	v_bfe_u32 v7, v41, 16, 1
	v_lshrrev_b32_e32 v1, 16, v1
	v_add3_u32 v7, v41, v7, s73
	v_and_or_b32 v39, v7, s33, v1
	global_store_dwordx2 v[8:9], v[38:39], off offset:3072
	global_load_dwordx4 v[38:41], v[30:31], off
	s_nop 0
	global_load_dwordx4 v[42:45], v[32:33], off
	v_pk_mul_f32 v[4:5], v[4:5], v[6:7] op_sel_hi:[1,0]
	v_pk_mul_f32 v[2:3], v[2:3], v[6:7] op_sel_hi:[1,0]
	s_waitcnt vmcnt(0)
	v_pk_fma_f32 v[4:5], v[4:5], v[40:41], v[44:45]
	v_pk_fma_f32 v[2:3], v[2:3], v[38:39], v[42:43]
	global_store_dwordx4 v[46:47], v[2:5], off offset:3072
	global_load_dwordx4 v[38:41], v[64:65], off offset:3072
	global_load_dwordx4 v[42:45], v[54:55], off offset:3072
	s_waitcnt vmcnt(1)
	v_pk_add_f32 v[38:39], v[38:39], 1.0 op_sel_hi:[1,0]
	s_waitcnt vmcnt(0)
	v_pk_fma_f32 v[2:3], v[2:3], v[38:39], v[42:43]
	v_pk_add_f32 v[6:7], v[40:41], 1.0 op_sel_hi:[1,0]
	s_nop 0
	v_pk_fma_f32 v[4:5], v[4:5], v[6:7], v[44:45]
	v_cvt_pk_bf16_f32 v2, v2, v3
	s_nop 0
	s_nop 0
	s_nop 0
	s_nop 0
	s_nop 0
	v_cvt_pk_bf16_f32 v3, v4, v5
	global_store_dwordx2 v[8:9], v[2:3], off offset:3584
	s_branch .LBB0_1221

.LBB0_1398:
	global_store_dwordx4 v[84:85], v[174:177], off offset:16
	s_or_b64 exec, exec, s[78:79]
	s_nop 0
	v_lshl_add_u64 v[84:85], v[222:223], 1, s[54:55]
	s_and_saveexec_b64 s[22:23], s[24:25]
	s_cbranch_execnz .LBB0_1326
	s_branch .LBB0_1327

.LBB0_1513:
	s_mul_i32 s22, s18, 0x3020000
	s_sext_i32_i16 s21, s19
	s_mul_hi_i32 s19, s18, 0x3020000
	s_waitcnt lgkmcnt(0)
	s_add_u32 s22, s10, s22
	s_addc_u32 s23, s11, s19
	s_mul_hi_i32 s19, s18, 0x1800000
	s_mul_i32 s18, s18, 0x1800000
	v_lshl_add_u64 v[14:15], v[12:13], 0, s[18:19]
	s_lshl_b32 s18, s21, 6
	s_ashr_i32 s21, s20, 31
	s_lshl_b64 s[20:21], s[20:21], 2
	s_add_u32 s20, s22, s20
	s_addc_u32 s21, s23, s21
	v_lshlrev_b32_e32 v82, 2, v4
	v_add_u32_e32 v50, s18, v1
	v_lshl_add_u64 v[48:49], s[20:21], 0, v[82:83]
	v_mad_i64_i32 v[20:21], s[20:21], v50, s40, v[48:49]
	v_add_u32_e32 v24, 8, v50
	global_load_dwordx4 v[20:23], v[20:21], off
	v_mad_i64_i32 v[24:25], s[20:21], v24, s40, v[48:49]
	global_load_dwordx4 v[24:27], v[24:25], off
	v_add_u32_e32 v28, 16, v50
	v_mad_i64_i32 v[28:29], s[20:21], v28, s40, v[48:49]
	global_load_dwordx4 v[28:31], v[28:29], off
	v_add_u32_e32 v32, 24, v50
	v_mad_i64_i32 v[32:33], s[20:21], v32, s40, v[48:49]
	global_load_dwordx4 v[32:35], v[32:33], off
	v_add_u32_e32 v36, 32, v50
	v_mad_i64_i32 v[36:37], s[20:21], v36, s40, v[48:49]
	global_load_dwordx4 v[36:39], v[36:37], off
	v_add_u32_e32 v40, 40, v50
	v_mad_i64_i32 v[40:41], s[20:21], v40, s40, v[48:49]
	global_load_dwordx4 v[40:43], v[40:41], off
	v_add_u32_e32 v44, 48, v50
	v_mad_i64_i32 v[44:45], s[20:21], v44, s40, v[48:49]
	global_load_dwordx4 v[44:47], v[44:45], off
	v_add_u32_e32 v50, 56, v50
	v_mad_i64_i32 v[48:49], s[20:21], v50, s40, v[48:49]
	global_load_dwordx4 v[48:51], v[48:49], off
	v_add_u32_e32 v52, v5, v7
	s_ashr_i32 s19, s18, 31
	s_lshl_b64 s[18:19], s[18:19], 1
	v_lshl_add_u64 v[14:15], v[14:15], 0, s[18:19]
	v_lshlrev_b32_e32 v82, 1, v6
	v_lshl_add_u64 v[14:15], v[14:15], 0, v[82:83]
	s_waitcnt vmcnt(7)
	ds_write2_b32 v52, v20, v21 offset1:1
	ds_write2_b32 v52, v22, v23 offset0:2 offset1:3
	v_add_u32_e32 v20, 0x420, v52
	s_waitcnt vmcnt(6)
	ds_write2_b32 v20, v24, v25 offset1:1
	v_add_u32_e32 v20, 0x428, v52
	ds_write2_b32 v20, v26, v27 offset1:1
	v_add_u32_e32 v20, 0x840, v52
	s_waitcnt vmcnt(5)
	ds_write2_b32 v20, v28, v29 offset1:1
	v_add_u32_e32 v20, 0x848, v52
	ds_write2_b32 v20, v30, v31 offset1:1
	v_add_u32_e32 v20, 0xc60, v52
	s_waitcnt vmcnt(4)
	ds_write2_b32 v20, v32, v33 offset1:1
	v_add_u32_e32 v20, 0xc68, v52
	ds_write2_b32 v20, v34, v35 offset1:1
	v_add_u32_e32 v20, 0x1080, v52
	s_waitcnt vmcnt(3)
	ds_write2_b32 v20, v36, v37 offset1:1
	v_add_u32_e32 v20, 0x1088, v52
	ds_write2_b32 v20, v38, v39 offset1:1
	v_add_u32_e32 v20, 0x14a0, v52
	s_waitcnt vmcnt(2)
	ds_write2_b32 v20, v40, v41 offset1:1
	v_add_u32_e32 v20, 0x14a8, v52
	ds_write2_b32 v20, v42, v43 offset1:1
	v_add_u32_e32 v20, 0x18c0, v52
	s_waitcnt vmcnt(1)
	ds_write2_b32 v20, v44, v45 offset1:1
	v_add_u32_e32 v20, 0x18c8, v52
	ds_write2_b32 v20, v46, v47 offset1:1
	v_add_u32_e32 v20, 0x1ce0, v52
	s_waitcnt vmcnt(0)
	ds_write2_b32 v20, v48, v49 offset1:1
	v_add_u32_e32 v20, 0x1ce8, v52
	ds_write2_b32 v20, v50, v51 offset1:1
	s_waitcnt lgkmcnt(0)
	ds_read2_b32 v[24:25], v19 offset0:33 offset1:41
	ds_read2_b32 v[26:27], v19 offset1:8
	ds_read2_b32 v[28:29], v19 offset0:66 offset1:74
	ds_read2_b32 v[30:31], v19 offset0:99 offset1:107
	ds_read2_b32 v[32:33], v19 offset0:132 offset1:140
	ds_read2_b32 v[34:35], v19 offset0:165 offset1:173
	ds_read2_b32 v[36:37], v19 offset0:198 offset1:206
	ds_read2_b32 v[38:39], v19 offset0:231 offset1:239
	s_waitcnt lgkmcnt(7)
	s_waitcnt lgkmcnt(6)
	v_cvt_pk_bf16_f32 v20, v26, v24
	s_waitcnt lgkmcnt(5)
	s_waitcnt lgkmcnt(4)
	v_cvt_pk_bf16_f32 v21, v28, v30
	s_waitcnt lgkmcnt(3)
	s_waitcnt lgkmcnt(2)
	v_cvt_pk_bf16_f32 v22, v32, v34
	s_waitcnt lgkmcnt(1)
	v_add_u32_e32 v40, s26, v1
	s_waitcnt lgkmcnt(0)
	v_ashrrev_i32_e32 v41, 31, v40
	v_lshlrev_b64 v[40:41], 12, v[40:41]
	v_cvt_pk_bf16_f32 v23, v36, v38
	v_lshl_add_u64 v[40:41], v[14:15], 0, v[40:41]
	global_store_dwordx4 v[40:41], v[20:23], off
	s_nop 1
	v_cvt_pk_bf16_f32 v20, v27, v25
	v_cvt_pk_bf16_f32 v21, v29, v31
	v_cvt_pk_bf16_f32 v22, v33, v35
	v_cvt_pk_bf16_f32 v23, v37, v39
	v_add_u32_e32 v24, s26, v16
	v_ashrrev_i32_e32 v25, 31, v24
	v_lshlrev_b64 v[24:25], 12, v[24:25]
	v_lshl_add_u64 v[24:25], v[14:15], 0, v[24:25]
	global_store_dwordx4 v[24:25], v[20:23], off
	s_nop 1
	ds_read2_b32 v[24:25], v19 offset0:49 offset1:57
	ds_read2_b32 v[26:27], v19 offset0:16 offset1:24
	ds_read2_b32 v[28:29], v19 offset0:82 offset1:90
	ds_read2_b32 v[30:31], v19 offset0:115 offset1:123
	ds_read2_b32 v[32:33], v19 offset0:148 offset1:156
	ds_read2_b32 v[34:35], v19 offset0:181 offset1:189
	ds_read2_b32 v[36:37], v19 offset0:214 offset1:222
	ds_read2_b32 v[38:39], v19 offset0:247 offset1:255
	s_waitcnt lgkmcnt(7)
	s_waitcnt lgkmcnt(6)
	v_cvt_pk_bf16_f32 v20, v26, v24
	s_waitcnt lgkmcnt(5)
	s_waitcnt lgkmcnt(4)
	v_cvt_pk_bf16_f32 v21, v28, v30
	s_waitcnt lgkmcnt(3)
	s_waitcnt lgkmcnt(2)
	v_cvt_pk_bf16_f32 v22, v32, v34
	s_waitcnt lgkmcnt(1)
	v_add_u32_e32 v40, s26, v17
	s_waitcnt lgkmcnt(0)
	v_ashrrev_i32_e32 v41, 31, v40
	v_lshlrev_b64 v[40:41], 12, v[40:41]
	v_cvt_pk_bf16_f32 v23, v36, v38
	v_lshl_add_u64 v[40:41], v[14:15], 0, v[40:41]
	global_store_dwordx4 v[40:41], v[20:23], off
	s_nop 1
	v_cvt_pk_bf16_f32 v20, v27, v25
	v_cvt_pk_bf16_f32 v21, v29, v31
	v_cvt_pk_bf16_f32 v22, v33, v35
	v_cvt_pk_bf16_f32 v23, v37, v39
	v_add_u32_e32 v24, s26, v18
	v_ashrrev_i32_e32 v25, 31, v24
	v_lshlrev_b64 v[24:25], 12, v[24:25]
	v_lshl_add_u64 v[14:15], v[14:15], 0, v[24:25]
	global_store_dwordx4 v[14:15], v[20:23], off
	s_waitcnt lgkmcnt(0)

.LBB0_1515:
	s_mul_hi_i32 s18, s9, 0x5397829d
	s_lshr_b32 s19, s18, 31
	s_ashr_i32 s18, s18, 13
	s_add_i32 s18, s18, s19
	s_mul_i32 s19, s18, 0xffff9e00
	s_add_i32 s26, s9, s19
	s_cmpk_gt_i32 s26, 0x17ff
	s_mov_b64 s[20:21], -1
	s_cbranch_scc0 .LBB0_1525
	s_cmpk_gt_u32 s26, 0x1fff
	s_cbranch_scc0 .LBB0_1522
	s_mov_b64 s[22:23], -1
	s_cmpk_gt_u32 s26, 0x4bff
	s_mul_hi_i32 s21, s18, 0x2c00000
	s_mul_i32 s20, s18, 0x2c00000
	s_cbranch_scc0 .LBB0_1519
	s_and_b32 s19, s26, 0x7fffffc0
	s_add_i32 s70, s19, 0xffffb400
	s_waitcnt lgkmcnt(0)
	s_add_u32 s27, s16, s20
	s_addc_u32 s28, s17, s21
	s_mul_hi_i32 s23, s18, 0x1600000
	s_mul_i32 s22, s18, 0x1600000
	s_and_b32 s19, s24, 0x7e0
	v_lshl_add_u64 v[14:15], v[2:3], 0, s[22:23]
	s_lshl_b32 s22, s19, 2
	v_add_u32_e32 v20, s70, v1
	s_add_u32 s22, s27, s22
	s_addc_u32 s23, s28, 0
	v_lshlrev_b32_e32 v82, 2, v4
	v_ashrrev_i32_e32 v21, 31, v20
	v_lshl_add_u64 v[22:23], s[22:23], 0, v[82:83]
	v_lshlrev_b64 v[20:21], 13, v[20:21]
	v_lshl_add_u64 v[48:49], v[22:23], 0, v[20:21]
	s_mov_b32 s22, 0x10000
	v_add_co_u32_e32 v24, vcc, s22, v48
	global_load_dwordx4 v[20:23], v[48:49], off
	s_nop 0
	v_addc_co_u32_e32 v25, vcc, 0, v49, vcc
	s_mov_b32 s22, 0x20000
	global_load_dwordx4 v[24:27], v[24:25], off
	v_add_co_u32_e32 v28, vcc, s22, v48
	s_mov_b32 s22, 0x30000
	s_nop 0
	v_addc_co_u32_e32 v29, vcc, 0, v49, vcc
	global_load_dwordx4 v[28:31], v[28:29], off
	v_add_co_u32_e32 v32, vcc, s22, v48
	s_mov_b32 s22, 0x40000
	s_nop 0
	v_addc_co_u32_e32 v33, vcc, 0, v49, vcc
	global_load_dwordx4 v[32:35], v[32:33], off
	v_add_co_u32_e32 v36, vcc, s22, v48
	s_mov_b32 s22, 0x50000
	s_nop 0
	v_addc_co_u32_e32 v37, vcc, 0, v49, vcc
	global_load_dwordx4 v[36:39], v[36:37], off
	v_add_co_u32_e32 v40, vcc, s22, v48
	s_mov_b32 s22, 0x60000
	s_nop 0
	v_addc_co_u32_e32 v41, vcc, 0, v49, vcc
	global_load_dwordx4 v[40:43], v[40:41], off
	v_add_co_u32_e32 v44, vcc, s22, v48
	s_mov_b32 s22, 0x70000
	s_nop 0
	v_addc_co_u32_e32 v45, vcc, 0, v49, vcc
	global_load_dwordx4 v[44:47], v[44:45], off
	v_add_co_u32_e32 v48, vcc, s22, v48
	v_add_u32_e32 v52, v5, v7
	s_nop 0
	v_addc_co_u32_e32 v49, vcc, 0, v49, vcc
	global_load_dwordx4 v[48:51], v[48:49], off
	s_lshl_b64 s[22:23], s[70:71], 1
	v_lshl_add_u64 v[14:15], v[14:15], 0, s[22:23]
	v_lshlrev_b32_e32 v82, 1, v6
	v_lshl_add_u64 v[14:15], v[14:15], 0, v[82:83]
	s_movk_i32 s27, 0x2c00
	s_mov_b32 s70, 0x21b1f000
	s_waitcnt vmcnt(7)
	ds_write2_b32 v52, v20, v21 offset1:1
	ds_write2_b32 v52, v22, v23 offset0:2 offset1:3
	v_add_u32_e32 v20, 0x420, v52
	s_waitcnt vmcnt(6)
	ds_write2_b32 v20, v24, v25 offset1:1
	v_add_u32_e32 v20, 0x428, v52
	ds_write2_b32 v20, v26, v27 offset1:1
	v_add_u32_e32 v20, 0x840, v52
	s_waitcnt vmcnt(5)
	ds_write2_b32 v20, v28, v29 offset1:1
	v_add_u32_e32 v20, 0x848, v52
	ds_write2_b32 v20, v30, v31 offset1:1
	v_add_u32_e32 v20, 0xc60, v52
	s_waitcnt vmcnt(4)
	ds_write2_b32 v20, v32, v33 offset1:1
	v_add_u32_e32 v20, 0xc68, v52
	ds_write2_b32 v20, v34, v35 offset1:1
	v_add_u32_e32 v20, 0x1080, v52
	s_waitcnt vmcnt(3)
	ds_write2_b32 v20, v36, v37 offset1:1
	v_add_u32_e32 v20, 0x1088, v52
	ds_write2_b32 v20, v38, v39 offset1:1
	v_add_u32_e32 v20, 0x14a0, v52
	s_waitcnt vmcnt(2)
	ds_write2_b32 v20, v40, v41 offset1:1
	v_add_u32_e32 v20, 0x14a8, v52
	ds_write2_b32 v20, v42, v43 offset1:1
	v_add_u32_e32 v20, 0x18c0, v52
	s_waitcnt vmcnt(1)
	ds_write2_b32 v20, v44, v45 offset1:1
	v_add_u32_e32 v20, 0x18c8, v52
	ds_write2_b32 v20, v46, v47 offset1:1
	v_add_u32_e32 v20, 0x1ce0, v52
	s_waitcnt vmcnt(0)
	ds_write2_b32 v20, v48, v49 offset1:1
	v_add_u32_e32 v20, 0x1ce8, v52
	ds_write2_b32 v20, v50, v51 offset1:1
	s_waitcnt lgkmcnt(0)
	ds_read2_b32 v[24:25], v19 offset0:33 offset1:41
	ds_read2_b32 v[26:27], v19 offset1:8
	ds_read2_b32 v[28:29], v19 offset0:66 offset1:74
	ds_read2_b32 v[30:31], v19 offset0:99 offset1:107
	ds_read2_b32 v[32:33], v19 offset0:132 offset1:140
	ds_read2_b32 v[34:35], v19 offset0:165 offset1:173
	ds_read2_b32 v[36:37], v19 offset0:198 offset1:206
	ds_read2_b32 v[38:39], v19 offset0:231 offset1:239
	s_waitcnt lgkmcnt(7)
	s_waitcnt lgkmcnt(6)
	v_cvt_pk_bf16_f32 v20, v26, v24
	s_waitcnt lgkmcnt(5)
	s_waitcnt lgkmcnt(4)
	v_cvt_pk_bf16_f32 v21, v28, v30
	s_waitcnt lgkmcnt(3)
	s_waitcnt lgkmcnt(2)
	v_cvt_pk_bf16_f32 v22, v32, v34
	s_waitcnt lgkmcnt(1)
	s_waitcnt lgkmcnt(0)
	v_cvt_pk_bf16_f32 v23, v36, v38
	v_add_u32_e32 v24, s19, v1
	v_mad_i64_i32 v[40:41], s[22:23], v24, s27, v[14:15]
	global_store_dwordx4 v[40:41], v[20:23], off
	s_nop 1
	v_cvt_pk_bf16_f32 v20, v27, v25
	v_cvt_pk_bf16_f32 v21, v29, v31
	v_cvt_pk_bf16_f32 v22, v33, v35
	v_cvt_pk_bf16_f32 v23, v37, v39
	v_add_u32_e32 v24, s19, v16
	v_mad_i64_i32 v[24:25], s[22:23], v24, s27, v[14:15]
	global_store_dwordx4 v[24:25], v[20:23], off
	s_nop 1
	ds_read2_b32 v[24:25], v19 offset0:49 offset1:57
	ds_read2_b32 v[26:27], v19 offset0:16 offset1:24
	ds_read2_b32 v[28:29], v19 offset0:82 offset1:90
	ds_read2_b32 v[30:31], v19 offset0:115 offset1:123
	ds_read2_b32 v[32:33], v19 offset0:148 offset1:156
	ds_read2_b32 v[34:35], v19 offset0:181 offset1:189
	ds_read2_b32 v[36:37], v19 offset0:214 offset1:222
	ds_read2_b32 v[38:39], v19 offset0:247 offset1:255
	s_waitcnt lgkmcnt(7)
	s_waitcnt lgkmcnt(6)
	v_cvt_pk_bf16_f32 v20, v26, v24
	s_waitcnt lgkmcnt(5)
	s_waitcnt lgkmcnt(4)
	v_cvt_pk_bf16_f32 v21, v28, v30
	s_waitcnt lgkmcnt(3)
	s_waitcnt lgkmcnt(2)
	v_cvt_pk_bf16_f32 v22, v32, v34
	s_waitcnt lgkmcnt(1)
	s_waitcnt lgkmcnt(0)
	v_cvt_pk_bf16_f32 v23, v36, v38
	v_add_u32_e32 v24, s19, v17
	v_mad_i64_i32 v[40:41], s[22:23], v24, s27, v[14:15]
	global_store_dwordx4 v[40:41], v[20:23], off
	s_nop 1
	v_cvt_pk_bf16_f32 v20, v27, v25
	v_cvt_pk_bf16_f32 v21, v29, v31
	v_cvt_pk_bf16_f32 v22, v33, v35
	s_nop 0
	v_cvt_pk_bf16_f32 v23, v37, v39
	v_add_u32_e32 v24, s19, v18
	v_mad_i64_i32 v[14:15], s[22:23], v24, s27, v[14:15]
	global_store_dwordx4 v[14:15], v[20:23], off
	s_waitcnt lgkmcnt(0)
	s_mov_b64 s[22:23], 0
.LBB0_1519:
	s_andn2_b64 vcc, exec, s[22:23]
	s_cbranch_vccnz .LBB0_1521
	s_add_i32 s19, s26, 0xe000
	s_and_b32 s22, s19, 0xffff
	s_mul_i32 s22, s22, 0xba2f
	s_lshr_b32 s22, s22, 24
	s_mul_i32 s23, s22, 0x160
	s_sub_i32 s23, s19, s23
	s_and_b32 s27, s23, 0xffff
	s_lshl_b32 s19, s27, 5
	s_mul_i32 s29, s18, 0x5800000
	s_mul_hi_i32 s28, s18, 0x5800000
	s_waitcnt lgkmcnt(0)
	s_add_u32 s29, s14, s29
	s_addc_u32 s28, s15, s28
	v_lshl_add_u64 v[14:15], v[8:9], 0, s[20:21]
	s_bfe_i32 s20, s23, 0x10002
	s_lshl_b32 s21, s27, 4
	s_and_b32 s20, s20, 0x1600
	s_and_b32 s21, s21, 0x1f80
	s_add_i32 s20, s20, s21
	s_and_b32 s21, s19, 0x60
	s_or_b32 s20, s20, s21
	s_lshl_b32 s20, s20, 2
	s_add_u32 s20, s29, s20
	s_addc_u32 s21, s28, 0
	v_lshlrev_b32_e32 v82, 2, v4
	v_lshl_add_u32 v50, s22, 6, v1
	v_lshl_add_u64 v[48:49], s[20:21], 0, v[82:83]
	s_mov_b32 s23, 0xb000
	v_mad_i64_i32 v[20:21], s[20:21], v50, s23, v[48:49]
	v_add_u32_e32 v24, 8, v50
	global_load_dwordx4 v[20:23], v[20:21], off
	v_mad_i64_i32 v[24:25], s[20:21], v24, s23, v[48:49]
	global_load_dwordx4 v[24:27], v[24:25], off
	v_add_u32_e32 v28, 16, v50
	v_mad_i64_i32 v[28:29], s[20:21], v28, s23, v[48:49]
	global_load_dwordx4 v[28:31], v[28:29], off
	v_add_u32_e32 v32, 24, v50
	v_mad_i64_i32 v[32:33], s[20:21], v32, s23, v[48:49]
	global_load_dwordx4 v[32:35], v[32:33], off
	v_add_u32_e32 v36, 32, v50
	v_mad_i64_i32 v[36:37], s[20:21], v36, s23, v[48:49]
	global_load_dwordx4 v[36:39], v[36:37], off
	v_add_u32_e32 v40, 40, v50
	v_mad_i64_i32 v[40:41], s[20:21], v40, s23, v[48:49]
	global_load_dwordx4 v[40:43], v[40:41], off
	v_add_u32_e32 v44, 48, v50
	v_mad_i64_i32 v[44:45], s[20:21], v44, s23, v[48:49]
	global_load_dwordx4 v[44:47], v[44:45], off
	v_add_u32_e32 v50, 56, v50
	v_mad_i64_i32 v[48:49], s[20:21], v50, s23, v[48:49]
	global_load_dwordx4 v[48:51], v[48:49], off
	v_add_u32_e32 v52, v5, v7
	s_lshl_b32 s70, s22, 7
	v_lshl_add_u64 v[14:15], v[14:15], 0, s[70:71]
	v_lshlrev_b32_e32 v82, 1, v6
	v_lshl_add_u64 v[14:15], v[14:15], 0, v[82:83]
	s_mov_b32 s70, 0x21b1f000
	s_waitcnt vmcnt(7)
	ds_write2_b32 v52, v20, v21 offset1:1
	ds_write2_b32 v52, v22, v23 offset0:2 offset1:3
	v_add_u32_e32 v20, 0x420, v52
	s_waitcnt vmcnt(6)
	ds_write2_b32 v20, v24, v25 offset1:1
	v_add_u32_e32 v20, 0x428, v52
	ds_write2_b32 v20, v26, v27 offset1:1
	v_add_u32_e32 v20, 0x840, v52
	s_waitcnt vmcnt(5)
	ds_write2_b32 v20, v28, v29 offset1:1
	v_add_u32_e32 v20, 0x848, v52
	ds_write2_b32 v20, v30, v31 offset1:1
	v_add_u32_e32 v20, 0xc60, v52
	s_waitcnt vmcnt(4)
	ds_write2_b32 v20, v32, v33 offset1:1
	v_add_u32_e32 v20, 0xc68, v52
	ds_write2_b32 v20, v34, v35 offset1:1
	v_add_u32_e32 v20, 0x1080, v52
	s_waitcnt vmcnt(3)
	ds_write2_b32 v20, v36, v37 offset1:1
	v_add_u32_e32 v20, 0x1088, v52
	ds_write2_b32 v20, v38, v39 offset1:1
	v_add_u32_e32 v20, 0x14a0, v52
	s_waitcnt vmcnt(2)
	ds_write2_b32 v20, v40, v41 offset1:1
	v_add_u32_e32 v20, 0x14a8, v52
	ds_write2_b32 v20, v42, v43 offset1:1
	v_add_u32_e32 v20, 0x18c0, v52
	s_waitcnt vmcnt(1)
	ds_write2_b32 v20, v44, v45 offset1:1
	v_add_u32_e32 v20, 0x18c8, v52
	ds_write2_b32 v20, v46, v47 offset1:1
	v_add_u32_e32 v20, 0x1ce0, v52
	s_waitcnt vmcnt(0)
	ds_write2_b32 v20, v48, v49 offset1:1
	v_add_u32_e32 v20, 0x1ce8, v52
	ds_write2_b32 v20, v50, v51 offset1:1
	s_waitcnt lgkmcnt(0)
	ds_read2_b32 v[24:25], v19 offset0:33 offset1:41
	ds_read2_b32 v[26:27], v19 offset1:8
	ds_read2_b32 v[28:29], v19 offset0:66 offset1:74
	ds_read2_b32 v[30:31], v19 offset0:99 offset1:107
	ds_read2_b32 v[32:33], v19 offset0:132 offset1:140
	ds_read2_b32 v[34:35], v19 offset0:165 offset1:173
	ds_read2_b32 v[36:37], v19 offset0:198 offset1:206
	ds_read2_b32 v[38:39], v19 offset0:231 offset1:239
	s_waitcnt lgkmcnt(7)
	s_waitcnt lgkmcnt(6)
	v_cvt_pk_bf16_f32 v20, v26, v24
	s_waitcnt lgkmcnt(5)
	s_waitcnt lgkmcnt(4)
	v_cvt_pk_bf16_f32 v21, v28, v30
	s_waitcnt lgkmcnt(3)
	s_waitcnt lgkmcnt(2)
	v_cvt_pk_bf16_f32 v22, v32, v34
	s_waitcnt lgkmcnt(1)
	v_add_u32_e32 v40, s19, v1
	s_waitcnt lgkmcnt(0)
	v_ashrrev_i32_e32 v41, 31, v40
	v_lshlrev_b64 v[40:41], 12, v[40:41]
	v_cvt_pk_bf16_f32 v23, v36, v38
	v_lshl_add_u64 v[40:41], v[14:15], 0, v[40:41]
	global_store_dwordx4 v[40:41], v[20:23], off
	s_nop 1
	v_cvt_pk_bf16_f32 v20, v27, v25
	v_cvt_pk_bf16_f32 v21, v29, v31
	v_cvt_pk_bf16_f32 v22, v33, v35
	v_cvt_pk_bf16_f32 v23, v37, v39
	v_add_u32_e32 v24, s19, v16
	v_ashrrev_i32_e32 v25, 31, v24
	v_lshlrev_b64 v[24:25], 12, v[24:25]
	v_lshl_add_u64 v[24:25], v[14:15], 0, v[24:25]
	global_store_dwordx4 v[24:25], v[20:23], off
	s_nop 1
	ds_read2_b32 v[24:25], v19 offset0:49 offset1:57
	ds_read2_b32 v[26:27], v19 offset0:16 offset1:24
	ds_read2_b32 v[28:29], v19 offset0:82 offset1:90
	ds_read2_b32 v[30:31], v19 offset0:115 offset1:123
	ds_read2_b32 v[32:33], v19 offset0:148 offset1:156
	ds_read2_b32 v[34:35], v19 offset0:181 offset1:189
	ds_read2_b32 v[36:37], v19 offset0:214 offset1:222
	ds_read2_b32 v[38:39], v19 offset0:247 offset1:255
	s_waitcnt lgkmcnt(7)
	s_waitcnt lgkmcnt(6)
	v_cvt_pk_bf16_f32 v20, v26, v24
	s_waitcnt lgkmcnt(5)
	s_waitcnt lgkmcnt(4)
	v_cvt_pk_bf16_f32 v21, v28, v30
	s_waitcnt lgkmcnt(3)
	s_waitcnt lgkmcnt(2)
	v_cvt_pk_bf16_f32 v22, v32, v34
	s_waitcnt lgkmcnt(1)
	v_add_u32_e32 v40, s19, v17
	s_waitcnt lgkmcnt(0)
	v_ashrrev_i32_e32 v41, 31, v40
	v_lshlrev_b64 v[40:41], 12, v[40:41]
	v_cvt_pk_bf16_f32 v23, v36, v38
	v_lshl_add_u64 v[40:41], v[14:15], 0, v[40:41]
	global_store_dwordx4 v[40:41], v[20:23], off
	s_nop 1
	v_cvt_pk_bf16_f32 v20, v27, v25
	v_cvt_pk_bf16_f32 v21, v29, v31
	v_cvt_pk_bf16_f32 v22, v33, v35
	v_cvt_pk_bf16_f32 v23, v37, v39
	v_add_u32_e32 v24, s19, v18
	v_ashrrev_i32_e32 v25, 31, v24
	v_lshlrev_b64 v[24:25], 12, v[24:25]
	v_lshl_add_u64 v[14:15], v[14:15], 0, v[24:25]
	global_store_dwordx4 v[14:15], v[20:23], off
	s_waitcnt lgkmcnt(0)

.LBB0_1522:
	s_andn2_b64 vcc, exec, s[20:21]
	s_cbranch_vccnz .LBB0_1524
	s_and_b32 s19, s26, 0x1fc0
	s_add_i32 s70, s19, 0xffffe800
	s_ashr_i32 s19, s18, 31
	s_lshl_b64 s[20:21], s[18:19], 24
	s_waitcnt lgkmcnt(0)
	s_add_u32 s22, s12, s20
	s_addc_u32 s23, s13, s21
	s_lshl_b64 s[20:21], s[18:19], 23
	s_and_b32 s19, s24, 0x7e0
	v_lshl_add_u64 v[14:15], v[10:11], 0, s[20:21]
	s_lshl_b32 s20, s19, 2
	v_add_u32_e32 v20, s70, v1
	s_add_u32 s20, s22, s20
	s_addc_u32 s21, s23, 0
	v_lshlrev_b32_e32 v82, 2, v4
	v_ashrrev_i32_e32 v21, 31, v20
	v_lshl_add_u64 v[22:23], s[20:21], 0, v[82:83]
	v_lshlrev_b64 v[20:21], 13, v[20:21]
	v_lshl_add_u64 v[48:49], v[22:23], 0, v[20:21]
	s_mov_b32 s20, 0x10000
	v_add_co_u32_e32 v24, vcc, s20, v48
	global_load_dwordx4 v[20:23], v[48:49], off
	s_nop 0
	v_addc_co_u32_e32 v25, vcc, 0, v49, vcc
	s_mov_b32 s20, 0x20000
	global_load_dwordx4 v[24:27], v[24:25], off
	v_add_co_u32_e32 v28, vcc, s20, v48
	s_mov_b32 s20, 0x30000
	s_nop 0
	v_addc_co_u32_e32 v29, vcc, 0, v49, vcc
	global_load_dwordx4 v[28:31], v[28:29], off
	v_add_co_u32_e32 v32, vcc, s20, v48
	s_mov_b32 s20, 0x40000
	s_nop 0
	v_addc_co_u32_e32 v33, vcc, 0, v49, vcc
	global_load_dwordx4 v[32:35], v[32:33], off
	v_add_co_u32_e32 v36, vcc, s20, v48
	s_mov_b32 s20, 0x50000
	s_nop 0
	v_addc_co_u32_e32 v37, vcc, 0, v49, vcc
	global_load_dwordx4 v[36:39], v[36:37], off
	v_add_co_u32_e32 v40, vcc, s20, v48
	s_mov_b32 s20, 0x60000
	s_nop 0
	v_addc_co_u32_e32 v41, vcc, 0, v49, vcc
	global_load_dwordx4 v[40:43], v[40:41], off
	v_add_co_u32_e32 v44, vcc, s20, v48
	s_mov_b32 s20, 0x70000
	s_nop 0
	v_addc_co_u32_e32 v45, vcc, 0, v49, vcc
	global_load_dwordx4 v[44:47], v[44:45], off
	v_add_co_u32_e32 v48, vcc, s20, v48
	v_add_u32_e32 v52, v5, v7
	s_nop 0
	v_addc_co_u32_e32 v49, vcc, 0, v49, vcc
	global_load_dwordx4 v[48:51], v[48:49], off
	s_lshl_b64 s[20:21], s[70:71], 1
	v_lshl_add_u64 v[14:15], v[14:15], 0, s[20:21]
	v_lshlrev_b32_e32 v82, 1, v6
	v_lshl_add_u64 v[14:15], v[14:15], 0, v[82:83]
	s_mov_b32 s70, 0x21b1f000
	s_waitcnt vmcnt(7)
	ds_write2_b32 v52, v20, v21 offset1:1
	ds_write2_b32 v52, v22, v23 offset0:2 offset1:3
	v_add_u32_e32 v20, 0x420, v52
	s_waitcnt vmcnt(6)
	ds_write2_b32 v20, v24, v25 offset1:1
	v_add_u32_e32 v20, 0x428, v52
	ds_write2_b32 v20, v26, v27 offset1:1
	v_add_u32_e32 v20, 0x840, v52
	s_waitcnt vmcnt(5)
	ds_write2_b32 v20, v28, v29 offset1:1
	v_add_u32_e32 v20, 0x848, v52
	ds_write2_b32 v20, v30, v31 offset1:1
	v_add_u32_e32 v20, 0xc60, v52
	s_waitcnt vmcnt(4)
	ds_write2_b32 v20, v32, v33 offset1:1
	v_add_u32_e32 v20, 0xc68, v52
	ds_write2_b32 v20, v34, v35 offset1:1
	v_add_u32_e32 v20, 0x1080, v52
	s_waitcnt vmcnt(3)
	ds_write2_b32 v20, v36, v37 offset1:1
	v_add_u32_e32 v20, 0x1088, v52
	ds_write2_b32 v20, v38, v39 offset1:1
	v_add_u32_e32 v20, 0x14a0, v52
	s_waitcnt vmcnt(2)
	ds_write2_b32 v20, v40, v41 offset1:1
	v_add_u32_e32 v20, 0x14a8, v52
	ds_write2_b32 v20, v42, v43 offset1:1
	v_add_u32_e32 v20, 0x18c0, v52
	v_add_u32_e32 v40, s19, v1
	v_ashrrev_i32_e32 v41, 31, v40
	s_waitcnt vmcnt(1)
	ds_write2_b32 v20, v44, v45 offset1:1
	v_add_u32_e32 v20, 0x18c8, v52
	ds_write2_b32 v20, v46, v47 offset1:1
	v_add_u32_e32 v20, 0x1ce0, v52
	v_lshlrev_b64 v[40:41], 12, v[40:41]
	v_lshl_add_u64 v[40:41], v[14:15], 0, v[40:41]
	s_waitcnt vmcnt(0)
	ds_write2_b32 v20, v48, v49 offset1:1
	v_add_u32_e32 v20, 0x1ce8, v52
	ds_write2_b32 v20, v50, v51 offset1:1
	s_waitcnt lgkmcnt(0)
	ds_read2_b32 v[24:25], v19 offset0:33 offset1:41
	ds_read2_b32 v[26:27], v19 offset1:8
	ds_read2_b32 v[28:29], v19 offset0:66 offset1:74
	ds_read2_b32 v[30:31], v19 offset0:99 offset1:107
	ds_read2_b32 v[32:33], v19 offset0:132 offset1:140
	ds_read2_b32 v[34:35], v19 offset0:165 offset1:173
	ds_read2_b32 v[36:37], v19 offset0:198 offset1:206
	ds_read2_b32 v[38:39], v19 offset0:231 offset1:239
	s_waitcnt lgkmcnt(7)
	s_waitcnt lgkmcnt(6)
	v_cvt_pk_bf16_f32 v20, v26, v24
	s_waitcnt lgkmcnt(5)
	s_waitcnt lgkmcnt(4)
	v_cvt_pk_bf16_f32 v21, v28, v30
	s_waitcnt lgkmcnt(3)
	s_waitcnt lgkmcnt(2)
	v_cvt_pk_bf16_f32 v22, v32, v34
	s_waitcnt lgkmcnt(1)
	s_waitcnt lgkmcnt(0)
	v_cvt_pk_bf16_f32 v23, v36, v38
	global_store_dwordx4 v[40:41], v[20:23], off
	s_nop 1
	v_cvt_pk_bf16_f32 v20, v27, v25
	v_cvt_pk_bf16_f32 v21, v29, v31
	v_cvt_pk_bf16_f32 v22, v33, v35
	v_cvt_pk_bf16_f32 v23, v37, v39
	v_add_u32_e32 v24, s19, v16
	v_ashrrev_i32_e32 v25, 31, v24
	v_lshlrev_b64 v[24:25], 12, v[24:25]
	v_lshl_add_u64 v[24:25], v[14:15], 0, v[24:25]
	global_store_dwordx4 v[24:25], v[20:23], off
	s_nop 1
	ds_read2_b32 v[24:25], v19 offset0:49 offset1:57
	ds_read2_b32 v[26:27], v19 offset0:16 offset1:24
	ds_read2_b32 v[28:29], v19 offset0:82 offset1:90
	ds_read2_b32 v[30:31], v19 offset0:115 offset1:123
	ds_read2_b32 v[32:33], v19 offset0:148 offset1:156
	ds_read2_b32 v[34:35], v19 offset0:181 offset1:189
	ds_read2_b32 v[36:37], v19 offset0:214 offset1:222
	ds_read2_b32 v[38:39], v19 offset0:247 offset1:255
	s_waitcnt lgkmcnt(7)
	s_waitcnt lgkmcnt(6)
	v_cvt_pk_bf16_f32 v20, v26, v24
	s_waitcnt lgkmcnt(5)
	s_waitcnt lgkmcnt(4)
	v_cvt_pk_bf16_f32 v21, v28, v30
	s_waitcnt lgkmcnt(3)
	s_waitcnt lgkmcnt(2)
	v_cvt_pk_bf16_f32 v22, v32, v34
	s_waitcnt lgkmcnt(1)
	v_add_u32_e32 v40, s19, v17
	s_waitcnt lgkmcnt(0)
	v_ashrrev_i32_e32 v41, 31, v40
	v_lshlrev_b64 v[40:41], 12, v[40:41]
	v_cvt_pk_bf16_f32 v23, v36, v38
	v_lshl_add_u64 v[40:41], v[14:15], 0, v[40:41]
	global_store_dwordx4 v[40:41], v[20:23], off
	s_nop 1
	v_cvt_pk_bf16_f32 v20, v27, v25
	v_cvt_pk_bf16_f32 v21, v29, v31
	v_cvt_pk_bf16_f32 v22, v33, v35
	v_cvt_pk_bf16_f32 v23, v37, v39
	v_add_u32_e32 v24, s19, v18
	v_ashrrev_i32_e32 v25, 31, v24
	v_lshlrev_b64 v[24:25], 12, v[24:25]
	v_lshl_add_u64 v[14:15], v[14:15], 0, v[24:25]
	global_store_dwordx4 v[14:15], v[20:23], off
	s_waitcnt lgkmcnt(0)

.LBB0_1621:
	s_lshl_b32 s34, s86, 8
	v_mov_b32_e32 v132, v1
	v_mov_b32_e32 v133, v200
	s_or_b32 s34, s34, s72
	s_cmp_lt_i32 s21, 32
	v_lshl_add_u32 v176, v132, 3, s34
	v_add_u32_e32 v174, s65, v133
	s_mov_b64 s[34:35], -1
	v_ashrrev_i32_e32 v177, 31, v176
	s_cbranch_scc0 .LBB0_1624
	v_lshlrev_b32_e32 v178, 2, v176
	v_lshl_add_u32 v179, s21, 8, v174
	v_lshl_add_u32 v179, v179, 13, v178
	global_load_dwordx4 v[132:135], v178, s[16:17]
	global_load_dwordx4 v[136:139], v178, s[16:17] offset:16
	global_load_dwordx4 v[140:143], v178, s[16:17] offset:512
	global_load_dwordx4 v[144:147], v178, s[16:17] offset:528
	global_load_dwordx4 v[148:151], v179, s[14:15]
	global_load_dwordx4 v[152:155], v179, s[14:15] offset:16
	global_load_dwordx4 v[156:159], v179, s[14:15] offset:512
	global_load_dwordx4 v[160:163], v179, s[14:15] offset:528
	v_add_u32_e32 v178, 0x20000, v179
	global_load_dwordx4 v[180:183], v178, s[14:15]
	global_load_dwordx4 v[184:187], v178, s[14:15] offset:16
	global_load_dwordx4 v[188:191], v178, s[14:15] offset:512
	global_load_dwordx4 v[192:195], v178, s[14:15] offset:528
	v_add_u32_e32 v178, 0x40000, v179
	global_load_dwordx4 v[196:199], v178, s[14:15]
	global_load_dwordx4 v[204:207], v178, s[14:15] offset:16
	global_load_dwordx4 v[208:211], v178, s[14:15] offset:512
	global_load_dwordx4 v[212:215], v178, s[14:15] offset:528
	s_waitcnt vmcnt(12)
	v_pk_add_f32 v[132:133], v[132:133], 1.0 op_sel_hi:[1,0]
	v_pk_add_f32 v[134:135], v[134:135], 1.0 op_sel_hi:[1,0]
	v_pk_add_f32 v[136:137], v[136:137], 1.0 op_sel_hi:[1,0]
	v_pk_add_f32 v[138:139], v[138:139], 1.0 op_sel_hi:[1,0]
	v_pk_add_f32 v[140:141], v[140:141], 1.0 op_sel_hi:[1,0]
	v_pk_add_f32 v[142:143], v[142:143], 1.0 op_sel_hi:[1,0]
	v_pk_add_f32 v[144:145], v[144:145], 1.0 op_sel_hi:[1,0]
	v_pk_add_f32 v[146:147], v[146:147], 1.0 op_sel_hi:[1,0]
	s_waitcnt vmcnt(8)
	v_pk_mul_f32 v[148:149], v[148:149], s[92:93] op_sel_hi:[1,0]
	v_pk_mul_f32 v[150:151], v[150:151], s[92:93] op_sel_hi:[1,0]
	v_pk_fma_f32 v[148:149], v[128:129], v[132:133], v[148:149]
	v_pk_fma_f32 v[150:151], v[130:131], v[134:135], v[150:151]
	v_pk_mul_f32 v[152:153], v[152:153], s[92:93] op_sel_hi:[1,0]
	v_pk_mul_f32 v[154:155], v[154:155], s[92:93] op_sel_hi:[1,0]
	v_pk_fma_f32 v[152:153], v[124:125], v[136:137], v[152:153]
	v_pk_fma_f32 v[154:155], v[126:127], v[138:139], v[154:155]
	v_pk_mul_f32 v[156:157], v[156:157], s[92:93] op_sel_hi:[1,0]
	v_pk_mul_f32 v[158:159], v[158:159], s[92:93] op_sel_hi:[1,0]
	v_pk_fma_f32 v[156:157], v[112:113], v[140:141], v[156:157]
	v_pk_fma_f32 v[158:159], v[114:115], v[142:143], v[158:159]
	v_pk_mul_f32 v[160:161], v[160:161], s[92:93] op_sel_hi:[1,0]
	v_pk_mul_f32 v[162:163], v[162:163], s[92:93] op_sel_hi:[1,0]
	v_pk_fma_f32 v[160:161], v[104:105], v[144:145], v[160:161]
	v_pk_fma_f32 v[162:163], v[106:107], v[146:147], v[162:163]
	v_cvt_pk_bf16_f32 v128, v148, v149
	v_cvt_pk_bf16_f32 v129, v150, v151
	v_cvt_pk_bf16_f32 v130, v152, v153
	v_cvt_pk_bf16_f32 v131, v154, v155
	v_cvt_pk_bf16_f32 v112, v156, v157
	v_cvt_pk_bf16_f32 v113, v158, v159
	v_cvt_pk_bf16_f32 v114, v160, v161
	v_cvt_pk_bf16_f32 v115, v162, v163
	v_add_u32_e32 v178, 0x60000, v179
	global_load_dwordx4 v[148:151], v178, s[14:15]
	global_load_dwordx4 v[152:155], v178, s[14:15] offset:16
	global_load_dwordx4 v[156:159], v178, s[14:15] offset:512
	global_load_dwordx4 v[160:163], v178, s[14:15] offset:528
	s_waitcnt vmcnt(8)
	v_pk_mul_f32 v[180:181], v[180:181], s[92:93] op_sel_hi:[1,0]
	v_pk_mul_f32 v[182:183], v[182:183], s[92:93] op_sel_hi:[1,0]
	v_pk_fma_f32 v[180:181], v[120:121], v[132:133], v[180:181]
	v_pk_fma_f32 v[182:183], v[122:123], v[134:135], v[182:183]
	v_pk_mul_f32 v[184:185], v[184:185], s[92:93] op_sel_hi:[1,0]
	v_pk_mul_f32 v[186:187], v[186:187], s[92:93] op_sel_hi:[1,0]
	v_pk_fma_f32 v[184:185], v[116:117], v[136:137], v[184:185]
	v_pk_fma_f32 v[186:187], v[118:119], v[138:139], v[186:187]
	v_pk_mul_f32 v[188:189], v[188:189], s[92:93] op_sel_hi:[1,0]
	v_pk_mul_f32 v[190:191], v[190:191], s[92:93] op_sel_hi:[1,0]
	v_pk_fma_f32 v[188:189], v[96:97], v[140:141], v[188:189]
	v_pk_fma_f32 v[190:191], v[98:99], v[142:143], v[190:191]
	v_pk_mul_f32 v[192:193], v[192:193], s[92:93] op_sel_hi:[1,0]
	v_pk_mul_f32 v[194:195], v[194:195], s[92:93] op_sel_hi:[1,0]
	v_pk_fma_f32 v[192:193], v[88:89], v[144:145], v[192:193]
	v_pk_fma_f32 v[194:195], v[90:91], v[146:147], v[194:195]
	v_cvt_pk_bf16_f32 v120, v180, v181
	v_cvt_pk_bf16_f32 v121, v182, v183
	v_cvt_pk_bf16_f32 v122, v184, v185
	v_cvt_pk_bf16_f32 v123, v186, v187
	v_cvt_pk_bf16_f32 v96, v188, v189
	v_cvt_pk_bf16_f32 v97, v190, v191
	v_cvt_pk_bf16_f32 v98, v192, v193
	v_cvt_pk_bf16_f32 v99, v194, v195
	v_add_u32_e32 v178, 0x100000, v179
	global_load_dwordx4 v[180:183], v178, s[14:15]
	global_load_dwordx4 v[184:187], v178, s[14:15] offset:16
	global_load_dwordx4 v[188:191], v178, s[14:15] offset:512
	global_load_dwordx4 v[192:195], v178, s[14:15] offset:528
	s_waitcnt vmcnt(8)
	v_pk_mul_f32 v[196:197], v[196:197], s[92:93] op_sel_hi:[1,0]
	v_pk_mul_f32 v[198:199], v[198:199], s[92:93] op_sel_hi:[1,0]
	v_pk_fma_f32 v[196:197], v[108:109], v[132:133], v[196:197]
	v_pk_fma_f32 v[198:199], v[110:111], v[134:135], v[198:199]
	v_pk_mul_f32 v[204:205], v[204:205], s[92:93] op_sel_hi:[1,0]
	v_pk_mul_f32 v[206:207], v[206:207], s[92:93] op_sel_hi:[1,0]
	v_pk_fma_f32 v[204:205], v[100:101], v[136:137], v[204:205]
	v_pk_fma_f32 v[206:207], v[102:103], v[138:139], v[206:207]
	v_pk_mul_f32 v[208:209], v[208:209], s[92:93] op_sel_hi:[1,0]
	v_pk_mul_f32 v[210:211], v[210:211], s[92:93] op_sel_hi:[1,0]
	v_pk_fma_f32 v[208:209], v[78:79], v[140:141], v[208:209]
	v_pk_fma_f32 v[210:211], v[80:81], v[142:143], v[210:211]
	v_pk_mul_f32 v[212:213], v[212:213], s[92:93] op_sel_hi:[1,0]
	v_pk_mul_f32 v[214:215], v[214:215], s[92:93] op_sel_hi:[1,0]
	v_pk_fma_f32 v[212:213], v[74:75], v[144:145], v[212:213]
	v_pk_fma_f32 v[214:215], v[76:77], v[146:147], v[214:215]
	v_cvt_pk_bf16_f32 v108, v196, v197
	v_cvt_pk_bf16_f32 v109, v198, v199
	v_cvt_pk_bf16_f32 v110, v204, v205
	v_cvt_pk_bf16_f32 v111, v206, v207
	v_cvt_pk_bf16_f32 v78, v208, v209
	v_cvt_pk_bf16_f32 v79, v210, v211
	v_cvt_pk_bf16_f32 v80, v212, v213
	v_cvt_pk_bf16_f32 v81, v214, v215
	v_add_u32_e32 v178, 0x120000, v179
	global_load_dwordx4 v[196:199], v178, s[14:15]
	global_load_dwordx4 v[204:207], v178, s[14:15] offset:16
	global_load_dwordx4 v[208:211], v178, s[14:15] offset:512
	global_load_dwordx4 v[212:215], v178, s[14:15] offset:528
	s_waitcnt vmcnt(8)
	v_pk_mul_f32 v[148:149], v[148:149], s[92:93] op_sel_hi:[1,0]
	v_pk_mul_f32 v[150:151], v[150:151], s[92:93] op_sel_hi:[1,0]
	v_pk_fma_f32 v[148:149], v[92:93], v[132:133], v[148:149]
	v_pk_fma_f32 v[150:151], v[94:95], v[134:135], v[150:151]
	v_pk_mul_f32 v[152:153], v[152:153], s[92:93] op_sel_hi:[1,0]
	v_pk_mul_f32 v[154:155], v[154:155], s[92:93] op_sel_hi:[1,0]
	v_pk_fma_f32 v[152:153], v[84:85], v[136:137], v[152:153]
	v_pk_fma_f32 v[154:155], v[86:87], v[138:139], v[154:155]
	v_pk_mul_f32 v[156:157], v[156:157], s[92:93] op_sel_hi:[1,0]
	v_pk_mul_f32 v[158:159], v[158:159], s[92:93] op_sel_hi:[1,0]
	v_pk_fma_f32 v[156:157], v[70:71], v[140:141], v[156:157]
	v_pk_fma_f32 v[158:159], v[72:73], v[142:143], v[158:159]
	v_pk_mul_f32 v[160:161], v[160:161], s[92:93] op_sel_hi:[1,0]
	v_pk_mul_f32 v[162:163], v[162:163], s[92:93] op_sel_hi:[1,0]
	v_pk_fma_f32 v[160:161], v[66:67], v[144:145], v[160:161]
	v_pk_fma_f32 v[162:163], v[68:69], v[146:147], v[162:163]
	v_cvt_pk_bf16_f32 v92, v148, v149
	v_cvt_pk_bf16_f32 v93, v150, v151
	v_cvt_pk_bf16_f32 v94, v152, v153
	v_cvt_pk_bf16_f32 v95, v154, v155
	v_cvt_pk_bf16_f32 v70, v156, v157
	v_cvt_pk_bf16_f32 v71, v158, v159
	v_cvt_pk_bf16_f32 v72, v160, v161
	v_cvt_pk_bf16_f32 v73, v162, v163
	v_add_u32_e32 v178, 0x140000, v179
	global_load_dwordx4 v[148:151], v178, s[14:15]
	global_load_dwordx4 v[152:155], v178, s[14:15] offset:16
	global_load_dwordx4 v[156:159], v178, s[14:15] offset:512
	global_load_dwordx4 v[160:163], v178, s[14:15] offset:528
	s_waitcnt vmcnt(8)
	v_pk_mul_f32 v[180:181], v[180:181], s[92:93] op_sel_hi:[1,0]
	v_pk_mul_f32 v[182:183], v[182:183], s[92:93] op_sel_hi:[1,0]
	v_pk_fma_f32 v[180:181], v[62:63], v[132:133], v[180:181]
	v_pk_fma_f32 v[182:183], v[64:65], v[134:135], v[182:183]
	v_pk_mul_f32 v[184:185], v[184:185], s[92:93] op_sel_hi:[1,0]
	v_pk_mul_f32 v[186:187], v[186:187], s[92:93] op_sel_hi:[1,0]
	v_pk_fma_f32 v[184:185], v[58:59], v[136:137], v[184:185]
	v_pk_fma_f32 v[186:187], v[60:61], v[138:139], v[186:187]
	v_pk_mul_f32 v[188:189], v[188:189], s[92:93] op_sel_hi:[1,0]
	v_pk_mul_f32 v[190:191], v[190:191], s[92:93] op_sel_hi:[1,0]
	v_pk_fma_f32 v[188:189], v[46:47], v[140:141], v[188:189]
	v_pk_fma_f32 v[190:191], v[48:49], v[142:143], v[190:191]
	v_pk_mul_f32 v[192:193], v[192:193], s[92:93] op_sel_hi:[1,0]
	v_pk_mul_f32 v[194:195], v[194:195], s[92:93] op_sel_hi:[1,0]
	v_pk_fma_f32 v[192:193], v[42:43], v[144:145], v[192:193]
	v_pk_fma_f32 v[194:195], v[44:45], v[146:147], v[194:195]
	v_cvt_pk_bf16_f32 v62, v180, v181
	v_cvt_pk_bf16_f32 v63, v182, v183
	v_cvt_pk_bf16_f32 v64, v184, v185
	v_cvt_pk_bf16_f32 v65, v186, v187
	v_cvt_pk_bf16_f32 v46, v188, v189
	v_cvt_pk_bf16_f32 v47, v190, v191
	v_cvt_pk_bf16_f32 v48, v192, v193
	v_cvt_pk_bf16_f32 v49, v194, v195
	v_add_u32_e32 v178, 0x160000, v179
	global_load_dwordx4 v[180:183], v178, s[14:15]
	global_load_dwordx4 v[184:187], v178, s[14:15] offset:16
	global_load_dwordx4 v[188:191], v178, s[14:15] offset:512
	global_load_dwordx4 v[192:195], v178, s[14:15] offset:528
	s_waitcnt vmcnt(8)
	v_pk_mul_f32 v[196:197], v[196:197], s[92:93] op_sel_hi:[1,0]
	v_pk_mul_f32 v[198:199], v[198:199], s[92:93] op_sel_hi:[1,0]
	v_pk_fma_f32 v[196:197], v[54:55], v[132:133], v[196:197]
	v_pk_fma_f32 v[198:199], v[56:57], v[134:135], v[198:199]
	v_pk_mul_f32 v[204:205], v[204:205], s[92:93] op_sel_hi:[1,0]
	v_pk_mul_f32 v[206:207], v[206:207], s[92:93] op_sel_hi:[1,0]
	v_pk_fma_f32 v[204:205], v[50:51], v[136:137], v[204:205]
	v_pk_fma_f32 v[206:207], v[52:53], v[138:139], v[206:207]
	v_pk_mul_f32 v[208:209], v[208:209], s[92:93] op_sel_hi:[1,0]
	v_pk_mul_f32 v[210:211], v[210:211], s[92:93] op_sel_hi:[1,0]
	v_pk_fma_f32 v[208:209], v[30:31], v[140:141], v[208:209]
	v_pk_fma_f32 v[210:211], v[32:33], v[142:143], v[210:211]
	v_pk_mul_f32 v[212:213], v[212:213], s[92:93] op_sel_hi:[1,0]
	v_pk_mul_f32 v[214:215], v[214:215], s[92:93] op_sel_hi:[1,0]
	v_pk_fma_f32 v[212:213], v[26:27], v[144:145], v[212:213]
	v_pk_fma_f32 v[214:215], v[28:29], v[146:147], v[214:215]
	v_cvt_pk_bf16_f32 v54, v196, v197
	v_cvt_pk_bf16_f32 v55, v198, v199
	v_cvt_pk_bf16_f32 v56, v204, v205
	v_cvt_pk_bf16_f32 v57, v206, v207
	v_cvt_pk_bf16_f32 v30, v208, v209
	v_cvt_pk_bf16_f32 v31, v210, v211
	v_cvt_pk_bf16_f32 v32, v212, v213
	v_cvt_pk_bf16_f32 v33, v214, v215
	s_waitcnt vmcnt(4)
	v_pk_mul_f32 v[148:149], v[148:149], s[92:93] op_sel_hi:[1,0]
	v_pk_mul_f32 v[150:151], v[150:151], s[92:93] op_sel_hi:[1,0]
	v_pk_fma_f32 v[148:149], v[38:39], v[132:133], v[148:149]
	v_pk_fma_f32 v[150:151], v[40:41], v[134:135], v[150:151]
	v_pk_mul_f32 v[152:153], v[152:153], s[92:93] op_sel_hi:[1,0]
	v_pk_mul_f32 v[154:155], v[154:155], s[92:93] op_sel_hi:[1,0]
	v_pk_fma_f32 v[152:153], v[34:35], v[136:137], v[152:153]
	v_pk_fma_f32 v[154:155], v[36:37], v[138:139], v[154:155]
	v_pk_mul_f32 v[156:157], v[156:157], s[92:93] op_sel_hi:[1,0]
	v_pk_mul_f32 v[158:159], v[158:159], s[92:93] op_sel_hi:[1,0]
	v_pk_fma_f32 v[156:157], v[14:15], v[140:141], v[156:157]
	v_pk_fma_f32 v[158:159], v[16:17], v[142:143], v[158:159]
	v_pk_mul_f32 v[160:161], v[160:161], s[92:93] op_sel_hi:[1,0]
	v_pk_mul_f32 v[162:163], v[162:163], s[92:93] op_sel_hi:[1,0]
	v_pk_fma_f32 v[160:161], v[10:11], v[144:145], v[160:161]
	v_pk_fma_f32 v[162:163], v[12:13], v[146:147], v[162:163]
	v_cvt_pk_bf16_f32 v38, v148, v149
	v_cvt_pk_bf16_f32 v39, v150, v151
	v_cvt_pk_bf16_f32 v40, v152, v153
	v_cvt_pk_bf16_f32 v41, v154, v155
	v_cvt_pk_bf16_f32 v14, v156, v157
	v_cvt_pk_bf16_f32 v15, v158, v159
	v_cvt_pk_bf16_f32 v16, v160, v161
	v_cvt_pk_bf16_f32 v17, v162, v163
	s_waitcnt vmcnt(0)
	v_pk_mul_f32 v[180:181], v[180:181], s[92:93] op_sel_hi:[1,0]
	v_pk_mul_f32 v[182:183], v[182:183], s[92:93] op_sel_hi:[1,0]
	v_pk_fma_f32 v[180:181], v[22:23], v[132:133], v[180:181]
	v_pk_fma_f32 v[182:183], v[24:25], v[134:135], v[182:183]
	v_pk_mul_f32 v[184:185], v[184:185], s[92:93] op_sel_hi:[1,0]
	v_pk_mul_f32 v[186:187], v[186:187], s[92:93] op_sel_hi:[1,0]
	v_pk_fma_f32 v[184:185], v[18:19], v[136:137], v[184:185]
	v_pk_fma_f32 v[186:187], v[20:21], v[138:139], v[186:187]
	v_pk_mul_f32 v[188:189], v[188:189], s[92:93] op_sel_hi:[1,0]
	v_pk_mul_f32 v[190:191], v[190:191], s[92:93] op_sel_hi:[1,0]
	v_pk_fma_f32 v[188:189], v[6:7], v[140:141], v[188:189]
	v_pk_fma_f32 v[190:191], v[8:9], v[142:143], v[190:191]
	v_pk_mul_f32 v[192:193], v[192:193], s[92:93] op_sel_hi:[1,0]
	v_pk_mul_f32 v[194:195], v[194:195], s[92:93] op_sel_hi:[1,0]
	v_pk_fma_f32 v[192:193], v[2:3], v[144:145], v[192:193]
	v_pk_fma_f32 v[194:195], v[4:5], v[146:147], v[194:195]
	v_cvt_pk_bf16_f32 v22, v180, v181
	v_cvt_pk_bf16_f32 v23, v182, v183
	v_cvt_pk_bf16_f32 v24, v184, v185
	v_cvt_pk_bf16_f32 v25, v186, v187
	v_cvt_pk_bf16_f32 v6, v188, v189
	v_cvt_pk_bf16_f32 v7, v190, v191
	v_cvt_pk_bf16_f32 v8, v192, v193
	v_cvt_pk_bf16_f32 v9, v194, v195
	v_lshrrev_b32_e32 v179, 1, v179
	global_store_dwordx4 v179, v[128:131], s[12:13]
	global_store_dwordx4 v179, v[112:115], s[12:13] offset:256
	v_add_u32_e32 v178, 0x10000, v179
	global_store_dwordx4 v178, v[120:123], s[12:13]
	global_store_dwordx4 v178, v[96:99], s[12:13] offset:256
	s_nop 1
	v_add_u32_e32 v178, 0x20000, v179
	global_store_dwordx4 v178, v[108:111], s[12:13]
	global_store_dwordx4 v178, v[78:81], s[12:13] offset:256
	s_nop 1
	v_add_u32_e32 v178, 0x30000, v179
	global_store_dwordx4 v178, v[92:95], s[12:13]
	global_store_dwordx4 v178, v[70:73], s[12:13] offset:256
	s_nop 1
	v_add_u32_e32 v178, 0x80000, v179
	global_store_dwordx4 v178, v[62:65], s[12:13]
	global_store_dwordx4 v178, v[46:49], s[12:13] offset:256
	s_nop 1
	v_add_u32_e32 v178, 0x90000, v179
	global_store_dwordx4 v178, v[54:57], s[12:13]
	global_store_dwordx4 v178, v[30:33], s[12:13] offset:256
	s_nop 1
	v_add_u32_e32 v178, 0xa0000, v179
	global_store_dwordx4 v178, v[38:41], s[12:13]
	global_store_dwordx4 v178, v[14:17], s[12:13] offset:256
	s_nop 1
	v_add_u32_e32 v178, 0xb0000, v179
	global_store_dwordx4 v178, v[22:25], s[12:13]
	global_store_dwordx4 v178, v[6:9], s[12:13] offset:256
	s_nop 1
	s_cbranch_execz .LBB0_1625

.LBB0_1631:
	s_mul_i32 s22, s18, 0x3020000
	s_sext_i32_i16 s21, s19
	s_mul_hi_i32 s19, s18, 0x3020000
	s_waitcnt lgkmcnt(0)
	s_add_u32 s22, s10, s22
	s_addc_u32 s23, s11, s19
	s_mul_hi_i32 s19, s18, 0x1800000
	s_mul_i32 s18, s18, 0x1800000
	v_lshl_add_u64 v[14:15], v[12:13], 0, s[18:19]
	s_lshl_b32 s18, s21, 6
	s_ashr_i32 s21, s20, 31
	s_lshl_b64 s[20:21], s[20:21], 2
	s_add_u32 s20, s22, s20
	s_addc_u32 s21, s23, s21
	v_lshlrev_b32_e32 v82, 2, v4
	v_add_u32_e32 v50, s18, v1
	v_lshl_add_u64 v[48:49], s[20:21], 0, v[82:83]
	v_mad_i64_i32 v[20:21], s[20:21], v50, s40, v[48:49]
	v_add_u32_e32 v24, 8, v50
	global_load_dwordx4 v[20:23], v[20:21], off
	v_mad_i64_i32 v[24:25], s[20:21], v24, s40, v[48:49]
	global_load_dwordx4 v[24:27], v[24:25], off
	v_add_u32_e32 v28, 16, v50
	v_mad_i64_i32 v[28:29], s[20:21], v28, s40, v[48:49]
	global_load_dwordx4 v[28:31], v[28:29], off
	v_add_u32_e32 v32, 24, v50
	v_mad_i64_i32 v[32:33], s[20:21], v32, s40, v[48:49]
	global_load_dwordx4 v[32:35], v[32:33], off
	v_add_u32_e32 v36, 32, v50
	v_mad_i64_i32 v[36:37], s[20:21], v36, s40, v[48:49]
	global_load_dwordx4 v[36:39], v[36:37], off
	v_add_u32_e32 v40, 40, v50
	v_mad_i64_i32 v[40:41], s[20:21], v40, s40, v[48:49]
	global_load_dwordx4 v[40:43], v[40:41], off
	v_add_u32_e32 v44, 48, v50
	v_mad_i64_i32 v[44:45], s[20:21], v44, s40, v[48:49]
	global_load_dwordx4 v[44:47], v[44:45], off
	v_add_u32_e32 v50, 56, v50
	v_mad_i64_i32 v[48:49], s[20:21], v50, s40, v[48:49]
	global_load_dwordx4 v[48:51], v[48:49], off
	v_add_u32_e32 v52, v5, v7
	s_ashr_i32 s19, s18, 31
	s_lshl_b64 s[18:19], s[18:19], 1
	v_lshl_add_u64 v[14:15], v[14:15], 0, s[18:19]
	v_lshlrev_b32_e32 v82, 1, v6
	v_lshl_add_u64 v[14:15], v[14:15], 0, v[82:83]
	s_waitcnt vmcnt(7)
	ds_write2_b32 v52, v20, v21 offset1:1
	ds_write2_b32 v52, v22, v23 offset0:2 offset1:3
	v_add_u32_e32 v20, 0x420, v52
	s_waitcnt vmcnt(6)
	ds_write2_b32 v20, v24, v25 offset1:1
	v_add_u32_e32 v20, 0x428, v52
	ds_write2_b32 v20, v26, v27 offset1:1
	v_add_u32_e32 v20, 0x840, v52
	s_waitcnt vmcnt(5)
	ds_write2_b32 v20, v28, v29 offset1:1
	v_add_u32_e32 v20, 0x848, v52
	ds_write2_b32 v20, v30, v31 offset1:1
	v_add_u32_e32 v20, 0xc60, v52
	s_waitcnt vmcnt(4)
	ds_write2_b32 v20, v32, v33 offset1:1
	v_add_u32_e32 v20, 0xc68, v52
	ds_write2_b32 v20, v34, v35 offset1:1
	v_add_u32_e32 v20, 0x1080, v52
	s_waitcnt vmcnt(3)
	ds_write2_b32 v20, v36, v37 offset1:1
	v_add_u32_e32 v20, 0x1088, v52
	ds_write2_b32 v20, v38, v39 offset1:1
	v_add_u32_e32 v20, 0x14a0, v52
	s_waitcnt vmcnt(2)
	ds_write2_b32 v20, v40, v41 offset1:1
	v_add_u32_e32 v20, 0x14a8, v52
	ds_write2_b32 v20, v42, v43 offset1:1
	v_add_u32_e32 v20, 0x18c0, v52
	s_waitcnt vmcnt(1)
	ds_write2_b32 v20, v44, v45 offset1:1
	v_add_u32_e32 v20, 0x18c8, v52
	ds_write2_b32 v20, v46, v47 offset1:1
	v_add_u32_e32 v20, 0x1ce0, v52
	s_waitcnt vmcnt(0)
	ds_write2_b32 v20, v48, v49 offset1:1
	v_add_u32_e32 v20, 0x1ce8, v52
	ds_write2_b32 v20, v50, v51 offset1:1
	s_waitcnt lgkmcnt(0)
	ds_read2_b32 v[24:25], v19 offset0:33 offset1:41
	ds_read2_b32 v[26:27], v19 offset1:8
	ds_read2_b32 v[28:29], v19 offset0:66 offset1:74
	ds_read2_b32 v[30:31], v19 offset0:99 offset1:107
	ds_read2_b32 v[32:33], v19 offset0:132 offset1:140
	ds_read2_b32 v[34:35], v19 offset0:165 offset1:173
	ds_read2_b32 v[36:37], v19 offset0:198 offset1:206
	ds_read2_b32 v[38:39], v19 offset0:231 offset1:239
	s_waitcnt lgkmcnt(7)
	s_waitcnt lgkmcnt(6)
	v_cvt_pk_bf16_f32 v20, v26, v24
	s_waitcnt lgkmcnt(5)
	s_waitcnt lgkmcnt(4)
	v_cvt_pk_bf16_f32 v21, v28, v30
	s_waitcnt lgkmcnt(3)
	s_waitcnt lgkmcnt(2)
	v_cvt_pk_bf16_f32 v22, v32, v34
	s_waitcnt lgkmcnt(1)
	v_add_u32_e32 v40, s25, v1
	s_waitcnt lgkmcnt(0)
	v_ashrrev_i32_e32 v41, 31, v40
	v_lshlrev_b64 v[40:41], 12, v[40:41]
	v_cvt_pk_bf16_f32 v23, v36, v38
	v_lshl_add_u64 v[40:41], v[14:15], 0, v[40:41]
	global_store_dwordx4 v[40:41], v[20:23], off
	s_nop 1
	v_cvt_pk_bf16_f32 v20, v27, v25
	v_cvt_pk_bf16_f32 v21, v29, v31
	v_cvt_pk_bf16_f32 v22, v33, v35
	v_cvt_pk_bf16_f32 v23, v37, v39
	v_add_u32_e32 v24, s25, v16
	v_ashrrev_i32_e32 v25, 31, v24
	v_lshlrev_b64 v[24:25], 12, v[24:25]
	v_lshl_add_u64 v[24:25], v[14:15], 0, v[24:25]
	global_store_dwordx4 v[24:25], v[20:23], off
	s_nop 1
	ds_read2_b32 v[24:25], v19 offset0:49 offset1:57
	ds_read2_b32 v[26:27], v19 offset0:16 offset1:24
	ds_read2_b32 v[28:29], v19 offset0:82 offset1:90
	ds_read2_b32 v[30:31], v19 offset0:115 offset1:123
	ds_read2_b32 v[32:33], v19 offset0:148 offset1:156
	ds_read2_b32 v[34:35], v19 offset0:181 offset1:189
	ds_read2_b32 v[36:37], v19 offset0:214 offset1:222
	ds_read2_b32 v[38:39], v19 offset0:247 offset1:255
	s_waitcnt lgkmcnt(7)
	s_waitcnt lgkmcnt(6)
	v_cvt_pk_bf16_f32 v20, v26, v24
	s_waitcnt lgkmcnt(5)
	s_waitcnt lgkmcnt(4)
	v_cvt_pk_bf16_f32 v21, v28, v30
	s_waitcnt lgkmcnt(3)
	s_waitcnt lgkmcnt(2)
	v_cvt_pk_bf16_f32 v22, v32, v34
	s_waitcnt lgkmcnt(1)
	v_add_u32_e32 v40, s25, v17
	s_waitcnt lgkmcnt(0)
	v_ashrrev_i32_e32 v41, 31, v40
	v_lshlrev_b64 v[40:41], 12, v[40:41]
	v_cvt_pk_bf16_f32 v23, v36, v38
	v_lshl_add_u64 v[40:41], v[14:15], 0, v[40:41]
	global_store_dwordx4 v[40:41], v[20:23], off
	s_nop 1
	v_cvt_pk_bf16_f32 v20, v27, v25
	v_cvt_pk_bf16_f32 v21, v29, v31
	v_cvt_pk_bf16_f32 v22, v33, v35
	v_cvt_pk_bf16_f32 v23, v37, v39
	v_add_u32_e32 v24, s25, v18
	v_ashrrev_i32_e32 v25, 31, v24
	v_lshlrev_b64 v[24:25], 12, v[24:25]
	v_lshl_add_u64 v[14:15], v[14:15], 0, v[24:25]
	global_store_dwordx4 v[14:15], v[20:23], off
	s_waitcnt lgkmcnt(0)

.LBB0_1633:
	s_mul_hi_i32 s18, s24, 0x5397829d
	s_lshr_b32 s19, s18, 31
	s_ashr_i32 s18, s18, 13
	s_add_i32 s18, s18, s19
	s_mul_i32 s19, s18, 0xffff9e00
	s_add_i32 s25, s24, s19
	s_cmpk_gt_i32 s25, 0x17ff
	s_mov_b64 s[20:21], -1
	s_cbranch_scc0 .LBB0_1643
	s_cmpk_gt_u32 s25, 0x1fff
	s_cbranch_scc0 .LBB0_1640
	s_mov_b64 s[22:23], -1
	s_cmpk_gt_u32 s25, 0x4bff
	s_mul_hi_i32 s21, s18, 0x2c00000
	s_mul_i32 s20, s18, 0x2c00000
	s_cbranch_scc0 .LBB0_1637
	s_and_b32 s19, s25, 0x7fffffc0
	s_add_i32 s70, s19, 0xffffb400
	s_waitcnt lgkmcnt(0)
	s_add_u32 s26, s16, s20
	s_addc_u32 s27, s17, s21
	s_mul_hi_i32 s23, s18, 0x1600000
	s_mul_i32 s22, s18, 0x1600000
	s_and_b32 s19, s8, 0x7e0
	v_lshl_add_u64 v[14:15], v[2:3], 0, s[22:23]
	s_lshl_b32 s22, s19, 2
	v_add_u32_e32 v20, s70, v1
	s_add_u32 s22, s26, s22
	s_addc_u32 s23, s27, 0
	v_lshlrev_b32_e32 v82, 2, v4
	v_ashrrev_i32_e32 v21, 31, v20
	v_lshl_add_u64 v[22:23], s[22:23], 0, v[82:83]
	v_lshlrev_b64 v[20:21], 13, v[20:21]
	v_lshl_add_u64 v[48:49], v[22:23], 0, v[20:21]
	s_mov_b32 s22, 0x10000
	v_add_co_u32_e32 v24, vcc, s22, v48
	global_load_dwordx4 v[20:23], v[48:49], off
	s_nop 0
	v_addc_co_u32_e32 v25, vcc, 0, v49, vcc
	s_mov_b32 s22, 0x20000
	global_load_dwordx4 v[24:27], v[24:25], off
	v_add_co_u32_e32 v28, vcc, s22, v48
	s_mov_b32 s22, 0x30000
	s_nop 0
	v_addc_co_u32_e32 v29, vcc, 0, v49, vcc
	global_load_dwordx4 v[28:31], v[28:29], off
	v_add_co_u32_e32 v32, vcc, s22, v48
	s_mov_b32 s22, 0x40000
	s_nop 0
	v_addc_co_u32_e32 v33, vcc, 0, v49, vcc
	global_load_dwordx4 v[32:35], v[32:33], off
	v_add_co_u32_e32 v36, vcc, s22, v48
	s_mov_b32 s22, 0x50000
	s_nop 0
	v_addc_co_u32_e32 v37, vcc, 0, v49, vcc
	global_load_dwordx4 v[36:39], v[36:37], off
	v_add_co_u32_e32 v40, vcc, s22, v48
	s_mov_b32 s22, 0x60000
	s_nop 0
	v_addc_co_u32_e32 v41, vcc, 0, v49, vcc
	global_load_dwordx4 v[40:43], v[40:41], off
	v_add_co_u32_e32 v44, vcc, s22, v48
	s_mov_b32 s22, 0x70000
	s_nop 0
	v_addc_co_u32_e32 v45, vcc, 0, v49, vcc
	global_load_dwordx4 v[44:47], v[44:45], off
	v_add_co_u32_e32 v48, vcc, s22, v48
	v_add_u32_e32 v52, v5, v7
	s_nop 0
	v_addc_co_u32_e32 v49, vcc, 0, v49, vcc
	global_load_dwordx4 v[48:51], v[48:49], off
	s_lshl_b64 s[22:23], s[70:71], 1
	v_lshl_add_u64 v[14:15], v[14:15], 0, s[22:23]
	v_lshlrev_b32_e32 v82, 1, v6
	v_lshl_add_u64 v[14:15], v[14:15], 0, v[82:83]
	s_movk_i32 s26, 0x2c00
	s_mov_b32 s70, 0x21b1f000
	s_waitcnt vmcnt(7)
	ds_write2_b32 v52, v20, v21 offset1:1
	ds_write2_b32 v52, v22, v23 offset0:2 offset1:3
	v_add_u32_e32 v20, 0x420, v52
	s_waitcnt vmcnt(6)
	ds_write2_b32 v20, v24, v25 offset1:1
	v_add_u32_e32 v20, 0x428, v52
	ds_write2_b32 v20, v26, v27 offset1:1
	v_add_u32_e32 v20, 0x840, v52
	s_waitcnt vmcnt(5)
	ds_write2_b32 v20, v28, v29 offset1:1
	v_add_u32_e32 v20, 0x848, v52
	ds_write2_b32 v20, v30, v31 offset1:1
	v_add_u32_e32 v20, 0xc60, v52
	s_waitcnt vmcnt(4)
	ds_write2_b32 v20, v32, v33 offset1:1
	v_add_u32_e32 v20, 0xc68, v52
	ds_write2_b32 v20, v34, v35 offset1:1
	v_add_u32_e32 v20, 0x1080, v52
	s_waitcnt vmcnt(3)
	ds_write2_b32 v20, v36, v37 offset1:1
	v_add_u32_e32 v20, 0x1088, v52
	ds_write2_b32 v20, v38, v39 offset1:1
	v_add_u32_e32 v20, 0x14a0, v52
	s_waitcnt vmcnt(2)
	ds_write2_b32 v20, v40, v41 offset1:1
	v_add_u32_e32 v20, 0x14a8, v52
	ds_write2_b32 v20, v42, v43 offset1:1
	v_add_u32_e32 v20, 0x18c0, v52
	s_waitcnt vmcnt(1)
	ds_write2_b32 v20, v44, v45 offset1:1
	v_add_u32_e32 v20, 0x18c8, v52
	ds_write2_b32 v20, v46, v47 offset1:1
	v_add_u32_e32 v20, 0x1ce0, v52
	s_waitcnt vmcnt(0)
	ds_write2_b32 v20, v48, v49 offset1:1
	v_add_u32_e32 v20, 0x1ce8, v52
	ds_write2_b32 v20, v50, v51 offset1:1
	s_waitcnt lgkmcnt(0)
	ds_read2_b32 v[24:25], v19 offset0:33 offset1:41
	ds_read2_b32 v[26:27], v19 offset1:8
	ds_read2_b32 v[28:29], v19 offset0:66 offset1:74
	ds_read2_b32 v[30:31], v19 offset0:99 offset1:107
	ds_read2_b32 v[32:33], v19 offset0:132 offset1:140
	ds_read2_b32 v[34:35], v19 offset0:165 offset1:173
	ds_read2_b32 v[36:37], v19 offset0:198 offset1:206
	ds_read2_b32 v[38:39], v19 offset0:231 offset1:239
	s_waitcnt lgkmcnt(7)
	s_waitcnt lgkmcnt(6)
	v_cvt_pk_bf16_f32 v20, v26, v24
	s_waitcnt lgkmcnt(5)
	s_waitcnt lgkmcnt(4)
	v_cvt_pk_bf16_f32 v21, v28, v30
	s_waitcnt lgkmcnt(3)
	s_waitcnt lgkmcnt(2)
	v_cvt_pk_bf16_f32 v22, v32, v34
	s_waitcnt lgkmcnt(1)
	s_waitcnt lgkmcnt(0)
	v_cvt_pk_bf16_f32 v23, v36, v38
	v_add_u32_e32 v24, s19, v1
	v_mad_i64_i32 v[40:41], s[22:23], v24, s26, v[14:15]
	global_store_dwordx4 v[40:41], v[20:23], off
	s_nop 1
	v_cvt_pk_bf16_f32 v20, v27, v25
	v_cvt_pk_bf16_f32 v21, v29, v31
	v_cvt_pk_bf16_f32 v22, v33, v35
	v_cvt_pk_bf16_f32 v23, v37, v39
	v_add_u32_e32 v24, s19, v16
	v_mad_i64_i32 v[24:25], s[22:23], v24, s26, v[14:15]
	global_store_dwordx4 v[24:25], v[20:23], off
	s_nop 1
	ds_read2_b32 v[24:25], v19 offset0:49 offset1:57
	ds_read2_b32 v[26:27], v19 offset0:16 offset1:24
	ds_read2_b32 v[28:29], v19 offset0:82 offset1:90
	ds_read2_b32 v[30:31], v19 offset0:115 offset1:123
	ds_read2_b32 v[32:33], v19 offset0:148 offset1:156
	ds_read2_b32 v[34:35], v19 offset0:181 offset1:189
	ds_read2_b32 v[36:37], v19 offset0:214 offset1:222
	ds_read2_b32 v[38:39], v19 offset0:247 offset1:255
	s_waitcnt lgkmcnt(7)
	s_waitcnt lgkmcnt(6)
	v_cvt_pk_bf16_f32 v20, v26, v24
	s_waitcnt lgkmcnt(5)
	s_waitcnt lgkmcnt(4)
	v_cvt_pk_bf16_f32 v21, v28, v30
	s_waitcnt lgkmcnt(3)
	s_waitcnt lgkmcnt(2)
	v_cvt_pk_bf16_f32 v22, v32, v34
	s_waitcnt lgkmcnt(1)
	s_waitcnt lgkmcnt(0)
	v_cvt_pk_bf16_f32 v23, v36, v38
	v_add_u32_e32 v24, s19, v17
	v_mad_i64_i32 v[40:41], s[22:23], v24, s26, v[14:15]
	global_store_dwordx4 v[40:41], v[20:23], off
	s_nop 1
	v_cvt_pk_bf16_f32 v20, v27, v25
	v_cvt_pk_bf16_f32 v21, v29, v31
	v_cvt_pk_bf16_f32 v22, v33, v35
	s_nop 0
	v_cvt_pk_bf16_f32 v23, v37, v39
	v_add_u32_e32 v24, s19, v18
	v_mad_i64_i32 v[14:15], s[22:23], v24, s26, v[14:15]
	global_store_dwordx4 v[14:15], v[20:23], off
	s_waitcnt lgkmcnt(0)
	s_mov_b64 s[22:23], 0
.LBB0_1637:
	s_andn2_b64 vcc, exec, s[22:23]
	s_cbranch_vccnz .LBB0_1639
	s_add_i32 s19, s25, 0xe000
	s_and_b32 s22, s19, 0xffff
	s_mul_i32 s22, s22, 0xba2f
	s_lshr_b32 s22, s22, 24
	s_mul_i32 s23, s22, 0x160
	s_sub_i32 s23, s19, s23
	s_and_b32 s26, s23, 0xffff
	s_lshl_b32 s19, s26, 5
	s_mul_i32 s28, s18, 0x5800000
	s_mul_hi_i32 s27, s18, 0x5800000
	s_waitcnt lgkmcnt(0)
	s_add_u32 s28, s14, s28
	s_addc_u32 s27, s15, s27
	v_lshl_add_u64 v[14:15], v[8:9], 0, s[20:21]
	s_bfe_i32 s20, s23, 0x10002
	s_lshl_b32 s21, s26, 4
	s_and_b32 s20, s20, 0x1600
	s_and_b32 s21, s21, 0x1f80
	s_add_i32 s20, s20, s21
	s_and_b32 s21, s19, 0x60
	s_or_b32 s20, s20, s21
	s_lshl_b32 s20, s20, 2
	s_add_u32 s20, s28, s20
	s_addc_u32 s21, s27, 0
	v_lshlrev_b32_e32 v82, 2, v4
	v_lshl_add_u32 v50, s22, 6, v1
	v_lshl_add_u64 v[48:49], s[20:21], 0, v[82:83]
	s_mov_b32 s23, 0xb000
	v_mad_i64_i32 v[20:21], s[20:21], v50, s23, v[48:49]
	v_add_u32_e32 v24, 8, v50
	global_load_dwordx4 v[20:23], v[20:21], off
	v_mad_i64_i32 v[24:25], s[20:21], v24, s23, v[48:49]
	global_load_dwordx4 v[24:27], v[24:25], off
	v_add_u32_e32 v28, 16, v50
	v_mad_i64_i32 v[28:29], s[20:21], v28, s23, v[48:49]
	global_load_dwordx4 v[28:31], v[28:29], off
	v_add_u32_e32 v32, 24, v50
	v_mad_i64_i32 v[32:33], s[20:21], v32, s23, v[48:49]
	global_load_dwordx4 v[32:35], v[32:33], off
	v_add_u32_e32 v36, 32, v50
	v_mad_i64_i32 v[36:37], s[20:21], v36, s23, v[48:49]
	global_load_dwordx4 v[36:39], v[36:37], off
	v_add_u32_e32 v40, 40, v50
	v_mad_i64_i32 v[40:41], s[20:21], v40, s23, v[48:49]
	global_load_dwordx4 v[40:43], v[40:41], off
	v_add_u32_e32 v44, 48, v50
	v_mad_i64_i32 v[44:45], s[20:21], v44, s23, v[48:49]
	global_load_dwordx4 v[44:47], v[44:45], off
	v_add_u32_e32 v50, 56, v50
	v_mad_i64_i32 v[48:49], s[20:21], v50, s23, v[48:49]
	global_load_dwordx4 v[48:51], v[48:49], off
	v_add_u32_e32 v52, v5, v7
	s_lshl_b32 s70, s22, 7
	v_lshl_add_u64 v[14:15], v[14:15], 0, s[70:71]
	v_lshlrev_b32_e32 v82, 1, v6
	v_lshl_add_u64 v[14:15], v[14:15], 0, v[82:83]
	s_mov_b32 s70, 0x21b1f000
	s_waitcnt vmcnt(7)
	ds_write2_b32 v52, v20, v21 offset1:1
	ds_write2_b32 v52, v22, v23 offset0:2 offset1:3
	v_add_u32_e32 v20, 0x420, v52
	s_waitcnt vmcnt(6)
	ds_write2_b32 v20, v24, v25 offset1:1
	v_add_u32_e32 v20, 0x428, v52
	ds_write2_b32 v20, v26, v27 offset1:1
	v_add_u32_e32 v20, 0x840, v52
	s_waitcnt vmcnt(5)
	ds_write2_b32 v20, v28, v29 offset1:1
	v_add_u32_e32 v20, 0x848, v52
	ds_write2_b32 v20, v30, v31 offset1:1
	v_add_u32_e32 v20, 0xc60, v52
	s_waitcnt vmcnt(4)
	ds_write2_b32 v20, v32, v33 offset1:1
	v_add_u32_e32 v20, 0xc68, v52
	ds_write2_b32 v20, v34, v35 offset1:1
	v_add_u32_e32 v20, 0x1080, v52
	s_waitcnt vmcnt(3)
	ds_write2_b32 v20, v36, v37 offset1:1
	v_add_u32_e32 v20, 0x1088, v52
	ds_write2_b32 v20, v38, v39 offset1:1
	v_add_u32_e32 v20, 0x14a0, v52
	s_waitcnt vmcnt(2)
	ds_write2_b32 v20, v40, v41 offset1:1
	v_add_u32_e32 v20, 0x14a8, v52
	ds_write2_b32 v20, v42, v43 offset1:1
	v_add_u32_e32 v20, 0x18c0, v52
	s_waitcnt vmcnt(1)
	ds_write2_b32 v20, v44, v45 offset1:1
	v_add_u32_e32 v20, 0x18c8, v52
	ds_write2_b32 v20, v46, v47 offset1:1
	v_add_u32_e32 v20, 0x1ce0, v52
	s_waitcnt vmcnt(0)
	ds_write2_b32 v20, v48, v49 offset1:1
	v_add_u32_e32 v20, 0x1ce8, v52
	ds_write2_b32 v20, v50, v51 offset1:1
	s_waitcnt lgkmcnt(0)
	ds_read2_b32 v[24:25], v19 offset0:33 offset1:41
	ds_read2_b32 v[26:27], v19 offset1:8
	ds_read2_b32 v[28:29], v19 offset0:66 offset1:74
	ds_read2_b32 v[30:31], v19 offset0:99 offset1:107
	ds_read2_b32 v[32:33], v19 offset0:132 offset1:140
	ds_read2_b32 v[34:35], v19 offset0:165 offset1:173
	ds_read2_b32 v[36:37], v19 offset0:198 offset1:206
	ds_read2_b32 v[38:39], v19 offset0:231 offset1:239
	s_waitcnt lgkmcnt(7)
	s_waitcnt lgkmcnt(6)
	v_cvt_pk_bf16_f32 v20, v26, v24
	s_waitcnt lgkmcnt(5)
	s_waitcnt lgkmcnt(4)
	v_cvt_pk_bf16_f32 v21, v28, v30
	s_waitcnt lgkmcnt(3)
	s_waitcnt lgkmcnt(2)
	v_cvt_pk_bf16_f32 v22, v32, v34
	s_waitcnt lgkmcnt(1)
	v_add_u32_e32 v40, s19, v1
	s_waitcnt lgkmcnt(0)
	v_ashrrev_i32_e32 v41, 31, v40
	v_lshlrev_b64 v[40:41], 12, v[40:41]
	v_cvt_pk_bf16_f32 v23, v36, v38
	v_lshl_add_u64 v[40:41], v[14:15], 0, v[40:41]
	global_store_dwordx4 v[40:41], v[20:23], off
	s_nop 1
	v_cvt_pk_bf16_f32 v20, v27, v25
	v_cvt_pk_bf16_f32 v21, v29, v31
	v_cvt_pk_bf16_f32 v22, v33, v35
	v_cvt_pk_bf16_f32 v23, v37, v39
	v_add_u32_e32 v24, s19, v16
	v_ashrrev_i32_e32 v25, 31, v24
	v_lshlrev_b64 v[24:25], 12, v[24:25]
	v_lshl_add_u64 v[24:25], v[14:15], 0, v[24:25]
	global_store_dwordx4 v[24:25], v[20:23], off
	s_nop 1
	ds_read2_b32 v[24:25], v19 offset0:49 offset1:57
	ds_read2_b32 v[26:27], v19 offset0:16 offset1:24
	ds_read2_b32 v[28:29], v19 offset0:82 offset1:90
	ds_read2_b32 v[30:31], v19 offset0:115 offset1:123
	ds_read2_b32 v[32:33], v19 offset0:148 offset1:156
	ds_read2_b32 v[34:35], v19 offset0:181 offset1:189
	ds_read2_b32 v[36:37], v19 offset0:214 offset1:222
	ds_read2_b32 v[38:39], v19 offset0:247 offset1:255
	s_waitcnt lgkmcnt(7)
	s_waitcnt lgkmcnt(6)
	v_cvt_pk_bf16_f32 v20, v26, v24
	s_waitcnt lgkmcnt(5)
	s_waitcnt lgkmcnt(4)
	v_cvt_pk_bf16_f32 v21, v28, v30
	s_waitcnt lgkmcnt(3)
	s_waitcnt lgkmcnt(2)
	v_cvt_pk_bf16_f32 v22, v32, v34
	s_waitcnt lgkmcnt(1)
	v_add_u32_e32 v40, s19, v17
	s_waitcnt lgkmcnt(0)
	v_ashrrev_i32_e32 v41, 31, v40
	v_lshlrev_b64 v[40:41], 12, v[40:41]
	v_cvt_pk_bf16_f32 v23, v36, v38
	v_lshl_add_u64 v[40:41], v[14:15], 0, v[40:41]
	global_store_dwordx4 v[40:41], v[20:23], off
	s_nop 1
	v_cvt_pk_bf16_f32 v20, v27, v25
	v_cvt_pk_bf16_f32 v21, v29, v31
	v_cvt_pk_bf16_f32 v22, v33, v35
	v_cvt_pk_bf16_f32 v23, v37, v39
	v_add_u32_e32 v24, s19, v18
	v_ashrrev_i32_e32 v25, 31, v24
	v_lshlrev_b64 v[24:25], 12, v[24:25]
	v_lshl_add_u64 v[14:15], v[14:15], 0, v[24:25]
	global_store_dwordx4 v[14:15], v[20:23], off
	s_waitcnt lgkmcnt(0)

.LBB0_1640:
	s_andn2_b64 vcc, exec, s[20:21]
	s_cbranch_vccnz .LBB0_1642
	s_and_b32 s19, s25, 0x1fc0
	s_add_i32 s70, s19, 0xffffe800
	s_ashr_i32 s19, s18, 31
	s_lshl_b64 s[20:21], s[18:19], 24
	s_waitcnt lgkmcnt(0)
	s_add_u32 s22, s12, s20
	s_addc_u32 s23, s13, s21
	s_lshl_b64 s[20:21], s[18:19], 23
	s_and_b32 s19, s8, 0x7e0
	v_lshl_add_u64 v[14:15], v[10:11], 0, s[20:21]
	s_lshl_b32 s20, s19, 2
	v_add_u32_e32 v20, s70, v1
	s_add_u32 s20, s22, s20
	s_addc_u32 s21, s23, 0
	v_lshlrev_b32_e32 v82, 2, v4
	v_ashrrev_i32_e32 v21, 31, v20
	v_lshl_add_u64 v[22:23], s[20:21], 0, v[82:83]
	v_lshlrev_b64 v[20:21], 13, v[20:21]
	v_lshl_add_u64 v[48:49], v[22:23], 0, v[20:21]
	s_mov_b32 s20, 0x10000
	v_add_co_u32_e32 v24, vcc, s20, v48
	global_load_dwordx4 v[20:23], v[48:49], off
	s_nop 0
	v_addc_co_u32_e32 v25, vcc, 0, v49, vcc
	s_mov_b32 s20, 0x20000
	global_load_dwordx4 v[24:27], v[24:25], off
	v_add_co_u32_e32 v28, vcc, s20, v48
	s_mov_b32 s20, 0x30000
	s_nop 0
	v_addc_co_u32_e32 v29, vcc, 0, v49, vcc
	global_load_dwordx4 v[28:31], v[28:29], off
	v_add_co_u32_e32 v32, vcc, s20, v48
	s_mov_b32 s20, 0x40000
	s_nop 0
	v_addc_co_u32_e32 v33, vcc, 0, v49, vcc
	global_load_dwordx4 v[32:35], v[32:33], off
	v_add_co_u32_e32 v36, vcc, s20, v48
	s_mov_b32 s20, 0x50000
	s_nop 0
	v_addc_co_u32_e32 v37, vcc, 0, v49, vcc
	global_load_dwordx4 v[36:39], v[36:37], off
	v_add_co_u32_e32 v40, vcc, s20, v48
	s_mov_b32 s20, 0x60000
	s_nop 0
	v_addc_co_u32_e32 v41, vcc, 0, v49, vcc
	global_load_dwordx4 v[40:43], v[40:41], off
	v_add_co_u32_e32 v44, vcc, s20, v48
	s_mov_b32 s20, 0x70000
	s_nop 0
	v_addc_co_u32_e32 v45, vcc, 0, v49, vcc
	global_load_dwordx4 v[44:47], v[44:45], off
	v_add_co_u32_e32 v48, vcc, s20, v48
	v_add_u32_e32 v52, v5, v7
	s_nop 0
	v_addc_co_u32_e32 v49, vcc, 0, v49, vcc
	global_load_dwordx4 v[48:51], v[48:49], off
	s_lshl_b64 s[20:21], s[70:71], 1
	v_lshl_add_u64 v[14:15], v[14:15], 0, s[20:21]
	v_lshlrev_b32_e32 v82, 1, v6
	v_lshl_add_u64 v[14:15], v[14:15], 0, v[82:83]
	s_mov_b32 s70, 0x21b1f000
	s_waitcnt vmcnt(7)
	ds_write2_b32 v52, v20, v21 offset1:1
	ds_write2_b32 v52, v22, v23 offset0:2 offset1:3
	v_add_u32_e32 v20, 0x420, v52
	s_waitcnt vmcnt(6)
	ds_write2_b32 v20, v24, v25 offset1:1
	v_add_u32_e32 v20, 0x428, v52
	ds_write2_b32 v20, v26, v27 offset1:1
	v_add_u32_e32 v20, 0x840, v52
	s_waitcnt vmcnt(5)
	ds_write2_b32 v20, v28, v29 offset1:1
	v_add_u32_e32 v20, 0x848, v52
	ds_write2_b32 v20, v30, v31 offset1:1
	v_add_u32_e32 v20, 0xc60, v52
	s_waitcnt vmcnt(4)
	ds_write2_b32 v20, v32, v33 offset1:1
	v_add_u32_e32 v20, 0xc68, v52
	ds_write2_b32 v20, v34, v35 offset1:1
	v_add_u32_e32 v20, 0x1080, v52
	s_waitcnt vmcnt(3)
	ds_write2_b32 v20, v36, v37 offset1:1
	v_add_u32_e32 v20, 0x1088, v52
	ds_write2_b32 v20, v38, v39 offset1:1
	v_add_u32_e32 v20, 0x14a0, v52
	s_waitcnt vmcnt(2)
	ds_write2_b32 v20, v40, v41 offset1:1
	v_add_u32_e32 v20, 0x14a8, v52
	ds_write2_b32 v20, v42, v43 offset1:1
	v_add_u32_e32 v20, 0x18c0, v52
	v_add_u32_e32 v40, s19, v1
	v_ashrrev_i32_e32 v41, 31, v40
	s_waitcnt vmcnt(1)
	ds_write2_b32 v20, v44, v45 offset1:1
	v_add_u32_e32 v20, 0x18c8, v52
	ds_write2_b32 v20, v46, v47 offset1:1
	v_add_u32_e32 v20, 0x1ce0, v52
	v_lshlrev_b64 v[40:41], 12, v[40:41]
	v_lshl_add_u64 v[40:41], v[14:15], 0, v[40:41]
	s_waitcnt vmcnt(0)
	ds_write2_b32 v20, v48, v49 offset1:1
	v_add_u32_e32 v20, 0x1ce8, v52
	ds_write2_b32 v20, v50, v51 offset1:1
	s_waitcnt lgkmcnt(0)
	ds_read2_b32 v[24:25], v19 offset0:33 offset1:41
	ds_read2_b32 v[26:27], v19 offset1:8
	ds_read2_b32 v[28:29], v19 offset0:66 offset1:74
	ds_read2_b32 v[30:31], v19 offset0:99 offset1:107
	ds_read2_b32 v[32:33], v19 offset0:132 offset1:140
	ds_read2_b32 v[34:35], v19 offset0:165 offset1:173
	ds_read2_b32 v[36:37], v19 offset0:198 offset1:206
	ds_read2_b32 v[38:39], v19 offset0:231 offset1:239
	s_waitcnt lgkmcnt(7)
	s_waitcnt lgkmcnt(6)
	v_cvt_pk_bf16_f32 v20, v26, v24
	s_waitcnt lgkmcnt(5)
	s_waitcnt lgkmcnt(4)
	v_cvt_pk_bf16_f32 v21, v28, v30
	s_waitcnt lgkmcnt(3)
	s_waitcnt lgkmcnt(2)
	v_cvt_pk_bf16_f32 v22, v32, v34
	s_waitcnt lgkmcnt(1)
	s_waitcnt lgkmcnt(0)
	v_cvt_pk_bf16_f32 v23, v36, v38
	global_store_dwordx4 v[40:41], v[20:23], off
	s_nop 1
	v_cvt_pk_bf16_f32 v20, v27, v25
	v_cvt_pk_bf16_f32 v21, v29, v31
	v_cvt_pk_bf16_f32 v22, v33, v35
	v_cvt_pk_bf16_f32 v23, v37, v39
	v_add_u32_e32 v24, s19, v16
	v_ashrrev_i32_e32 v25, 31, v24
	v_lshlrev_b64 v[24:25], 12, v[24:25]
	v_lshl_add_u64 v[24:25], v[14:15], 0, v[24:25]
	global_store_dwordx4 v[24:25], v[20:23], off
	s_nop 1
	ds_read2_b32 v[24:25], v19 offset0:49 offset1:57
	ds_read2_b32 v[26:27], v19 offset0:16 offset1:24
	ds_read2_b32 v[28:29], v19 offset0:82 offset1:90
	ds_read2_b32 v[30:31], v19 offset0:115 offset1:123
	ds_read2_b32 v[32:33], v19 offset0:148 offset1:156
	ds_read2_b32 v[34:35], v19 offset0:181 offset1:189
	ds_read2_b32 v[36:37], v19 offset0:214 offset1:222
	ds_read2_b32 v[38:39], v19 offset0:247 offset1:255
	s_waitcnt lgkmcnt(7)
	s_waitcnt lgkmcnt(6)
	v_cvt_pk_bf16_f32 v20, v26, v24
	s_waitcnt lgkmcnt(5)
	s_waitcnt lgkmcnt(4)
	v_cvt_pk_bf16_f32 v21, v28, v30
	s_waitcnt lgkmcnt(3)
	s_waitcnt lgkmcnt(2)
	v_cvt_pk_bf16_f32 v22, v32, v34
	s_waitcnt lgkmcnt(1)
	v_add_u32_e32 v40, s19, v17
	s_waitcnt lgkmcnt(0)
	v_ashrrev_i32_e32 v41, 31, v40
	v_lshlrev_b64 v[40:41], 12, v[40:41]
	v_cvt_pk_bf16_f32 v23, v36, v38
	v_lshl_add_u64 v[40:41], v[14:15], 0, v[40:41]
	global_store_dwordx4 v[40:41], v[20:23], off
	s_nop 1
	v_cvt_pk_bf16_f32 v20, v27, v25
	v_cvt_pk_bf16_f32 v21, v29, v31
	v_cvt_pk_bf16_f32 v22, v33, v35
	v_cvt_pk_bf16_f32 v23, v37, v39
	v_add_u32_e32 v24, s19, v18
	v_ashrrev_i32_e32 v25, 31, v24
	v_lshlrev_b64 v[24:25], 12, v[24:25]
	v_lshl_add_u64 v[14:15], v[14:15], 0, v[24:25]
	global_store_dwordx4 v[14:15], v[20:23], off
	s_waitcnt lgkmcnt(0)

.LBB0_1705:
	s_mov_b64 s[10:11], s[0:1]
	v_mov_b32_e32 v2, v0
	s_mov_b64 s[22:23], s[44:45]
	v_mov_b32_e32 v1, v232
	s_mov_b64 s[18:19], s[46:47]
	s_add_i32 s9, s60, s8
	v_lshlrev_b32_e32 v2, 2, v1
	v_ashrrev_i32_e32 v3, 31, v2
	v_lshlrev_b64 v[4:5], 1, v[2:3]
	v_lshl_add_u64 v[8:9], s[18:19], 0, v[4:5]
	v_lshl_add_u64 v[8:9], v[8:9], 0, s[16:17]
	global_load_dwordx2 v[56:57], v[8:9], off offset:-3584
	global_load_dwordx2 v[62:63], v[8:9], off offset:-3072
	global_load_dwordx2 v[66:67], v[8:9], off offset:-2560
	global_load_dwordx2 v[10:11], v[8:9], off offset:-2048
	s_cmpk_lt_i32 s9, 0x2000
	s_cselect_b32 s24, s9, s8
	s_ashr_i32 s25, s24, 31
	s_lshl_b64 s[20:21], s[24:25], 12
	s_add_u32 s18, s18, s20
	s_addc_u32 s19, s19, s21
	v_lshl_add_u64 v[4:5], s[18:19], 0, v[4:5]
	v_and_b32_e32 v7, 64, v249
	v_add_u32_e32 v12, 64, v7
	v_xor_b32_e32 v7, 1, v249
	s_waitcnt vmcnt(3)
	v_lshlrev_b32_e32 v68, 16, v56
	s_waitcnt vmcnt(2)
	v_lshlrev_b32_e32 v69, 16, v62
	v_and_b32_e32 v71, 0xffff0000, v62
	s_waitcnt vmcnt(0)
	v_lshlrev_b32_e32 v58, 16, v10
	v_and_b32_e32 v59, 0xffff0000, v10
	v_lshlrev_b32_e32 v60, 16, v11
	v_and_b32_e32 v61, 0xffff0000, v11
	global_load_dwordx2 v[10:11], v[8:9], off offset:-1536
	v_and_b32_e32 v70, 0xffff0000, v56
	v_lshlrev_b32_e32 v65, 16, v63
	v_lshlrev_b32_e32 v64, 16, v57
	v_and_b32_e32 v75, 0xffff0000, v63
	v_and_b32_e32 v74, 0xffff0000, v57
	v_pk_add_f32 v[56:57], v[64:65], v[74:75]
	v_lshlrev_b32_e32 v63, 16, v67
	v_lshlrev_b32_e32 v62, 16, v66
	v_and_b32_e32 v73, 0xffff0000, v67
	v_and_b32_e32 v72, 0xffff0000, v66
	v_add_f32_e32 v54, v58, v59
	v_add_f32_e32 v52, v60, v61
	s_waitcnt vmcnt(0)
	v_lshlrev_b32_e32 v51, 16, v10
	v_and_b32_e32 v49, 0xffff0000, v10
	v_lshlrev_b32_e32 v55, 16, v11
	v_and_b32_e32 v53, 0xffff0000, v11
	global_load_dwordx2 v[76:77], v[8:9], off offset:-1024
	global_load_dwordx2 v[10:11], v[8:9], off offset:-512
	s_waitcnt vmcnt(0)
	v_lshlrev_b32_e32 v46, 16, v11
	global_load_dwordx2 v[8:9], v[8:9], off
	v_and_b32_e32 v47, 0xffff0000, v11
	v_lshlrev_b32_e32 v40, 16, v10
	v_and_b32_e32 v41, 0xffff0000, v10
	v_add_f32_e32 v44, v40, v41
	v_add_f32_e32 v42, v46, v47
	s_waitcnt vmcnt(0)
	v_lshlrev_b32_e32 v38, 16, v8
	v_and_b32_e32 v39, 0xffff0000, v8
	v_lshlrev_b32_e32 v45, 16, v9
	v_and_b32_e32 v43, 0xffff0000, v9
	v_lshl_add_u64 v[8:9], v[4:5], 0, s[54:55]
	v_add_co_u32_e32 v4, vcc, s27, v4
	s_nop 1
	v_addc_co_u32_e32 v5, vcc, 0, v5, vcc
	global_load_dwordx2 v[34:35], v[4:5], off
	global_load_dwordx2 v[36:37], v[8:9], off offset:512
	global_load_dwordx2 v[32:33], v[8:9], off offset:1024
	s_nop 0
	global_load_dwordx2 v[4:5], v[8:9], off offset:1536
	v_cmp_lt_i32_e32 vcc, v7, v12
	s_waitcnt vmcnt(0)
	v_lshlrev_b32_e32 v26, 16, v4
	v_and_b32_e32 v27, 0xffff0000, v4
	v_lshlrev_b32_e32 v28, 16, v5
	v_and_b32_e32 v29, 0xffff0000, v5
	global_load_dwordx2 v[4:5], v[8:9], off offset:2048
	v_cndmask_b32_e32 v7, v249, v7, vcc
	v_lshlrev_b32_e32 v7, 2, v7
	v_add_f32_e32 v24, v26, v27
	s_waitcnt vmcnt(0)
	v_lshlrev_b32_e32 v21, 16, v4
	v_and_b32_e32 v19, 0xffff0000, v4
	v_lshlrev_b32_e32 v25, 16, v5
	v_and_b32_e32 v23, 0xffff0000, v5
	global_load_dwordx2 v[30:31], v[8:9], off offset:2560
	global_load_dwordx2 v[4:5], v[8:9], off offset:3072
	s_load_dwordx4 s[28:31], s[10:11], 0xb0
	s_waitcnt lgkmcnt(0)
	s_add_u32 s20, s28, 0x2000
	s_addc_u32 s21, s29, 0
	s_add_u32 s18, s30, 0x2000
	s_addc_u32 s19, s31, 0
	s_waitcnt vmcnt(0)
	v_lshlrev_b32_e32 v14, 16, v4
	v_and_b32_e32 v15, 0xffff0000, v4
	v_lshlrev_b32_e32 v16, 16, v5
	v_and_b32_e32 v17, 0xffff0000, v5
	global_load_dwordx2 v[4:5], v[8:9], off offset:3584
	s_waitcnt vmcnt(0)
	v_lshlrev_b32_e32 v8, 16, v4
	v_and_b32_e32 v9, 0xffff0000, v4
	v_lshlrev_b32_e32 v13, 16, v5
	v_and_b32_e32 v11, 0xffff0000, v5
	v_pk_add_f32 v[4:5], v[68:69], v[70:71]
	s_nop 0
	v_pk_add_f32 v[4:5], v[4:5], v[56:57]
	v_pk_add_f32 v[56:57], v[54:55], v[52:53]
	v_add_f32_e32 v4, 0, v4
	v_add_f32_e32 v50, v4, v5
	v_pk_add_f32 v[4:5], v[62:63], v[72:73]
	s_nop 0
	v_pk_add_f32 v[4:5], v[4:5], v[4:5] op_sel:[0,1] op_sel_hi:[1,0]
	s_nop 0
	v_mov_b32_e32 v5, v49
	v_pk_add_f32 v[4:5], v[50:51], v[4:5]
	s_nop 0
	v_pk_add_f32 v[66:67], v[4:5], v[56:57]
	v_lshlrev_b32_e32 v57, 16, v77
	v_lshlrev_b32_e32 v56, 16, v76
	v_and_b32_e32 v5, 0xffff0000, v77
	v_and_b32_e32 v4, 0xffff0000, v76
	v_pk_add_f32 v[76:77], v[56:57], v[4:5]
	v_pk_add_f32 v[66:67], v[66:67], v[66:67] op_sel:[0,1] op_sel_hi:[1,0]
	v_pk_add_f32 v[76:77], v[76:77], v[76:77] op_sel:[0,1] op_sel_hi:[1,0]
	v_mov_b32_e32 v67, v38
	v_mov_b32_e32 v77, v39
	v_pk_add_f32 v[66:67], v[66:67], v[76:77]
	v_pk_add_f32 v[76:77], v[44:45], v[42:43]
	v_lshlrev_b32_e32 v44, 16, v35
	v_pk_add_f32 v[66:67], v[66:67], v[76:77]
	s_nop 0
	v_add_f32_e32 v10, v66, v67
	ds_bpermute_b32 v18, v7, v10
	s_waitcnt lgkmcnt(0)
	v_add_f32_e32 v10, v10, v18
	v_xor_b32_e32 v18, 2, v249
	v_cmp_lt_i32_e32 vcc, v18, v12
	s_nop 1
	v_cndmask_b32_e32 v18, v249, v18, vcc
	v_lshlrev_b32_e32 v18, 2, v18
	ds_bpermute_b32 v20, v18, v10
	s_waitcnt lgkmcnt(0)
	v_add_f32_e32 v10, v10, v20
	v_xor_b32_e32 v20, 4, v249
	v_cmp_lt_i32_e32 vcc, v20, v12
	s_nop 1
	v_cndmask_b32_e32 v20, v249, v20, vcc
	v_lshlrev_b32_e32 v50, 2, v20
	ds_bpermute_b32 v20, v50, v10
	s_waitcnt lgkmcnt(0)
	v_add_f32_e32 v10, v10, v20
	v_xor_b32_e32 v20, 8, v249
	v_cmp_lt_i32_e32 vcc, v20, v12
	s_nop 1
	v_cndmask_b32_e32 v20, v249, v20, vcc
	v_lshlrev_b32_e32 v54, 2, v20
	ds_bpermute_b32 v20, v54, v10
	s_waitcnt lgkmcnt(0)
	v_add_f32_e32 v10, v10, v20
	v_xor_b32_e32 v20, 16, v249
	v_cmp_lt_i32_e32 vcc, v20, v12
	s_nop 1
	v_cndmask_b32_e32 v20, v249, v20, vcc
	v_lshlrev_b32_e32 v82, 2, v20
	ds_bpermute_b32 v20, v82, v10
	s_waitcnt lgkmcnt(0)
	v_add_f32_e32 v10, v10, v20
	v_xor_b32_e32 v20, 32, v249
	v_cmp_lt_i32_e32 vcc, v20, v12
	s_nop 1
	v_cndmask_b32_e32 v12, v249, v20, vcc
	v_lshlrev_b32_e32 v84, 2, v12
	ds_bpermute_b32 v12, v84, v10
	s_waitcnt lgkmcnt(0)
	v_add_f32_e32 v12, v10, v12
	v_fmac_f32_e32 v70, 0xba000000, v12
	v_fmac_f32_e32 v71, 0xba000000, v12
	v_fmac_f32_e32 v74, 0xba000000, v12
	v_fmac_f32_e32 v68, 0xba000000, v12
	v_fmac_f32_e32 v75, 0xba000000, v12
	v_fmac_f32_e32 v69, 0xba000000, v12
	v_mov_b32_e32 v67, v71
	v_mov_b32_e32 v79, v70
	v_pk_mul_f32 v[70:71], v[70:71], v[70:71]
	v_fmac_f32_e32 v64, 0xba000000, v12
	v_fmac_f32_e32 v65, 0xba000000, v12
	v_mov_b32_e32 v66, v69
	v_mov_b32_e32 v78, v68
	v_pk_fma_f32 v[68:69], v[68:69], v[68:69], v[70:71]
	v_mov_b32_e32 v71, v75
	v_mov_b32_e32 v81, v74
	v_pk_mul_f32 v[74:75], v[74:75], v[74:75]
	v_mov_b32_e32 v70, v65
	v_mov_b32_e32 v80, v64
	v_pk_fma_f32 v[64:65], v[64:65], v[64:65], v[74:75]
	v_fmac_f32_e32 v72, 0xba000000, v12
	v_fmac_f32_e32 v73, 0xba000000, v12
	v_fmac_f32_e32 v63, 0xba000000, v12
	v_pk_add_f32 v[64:65], v[68:69], v[64:65]
	v_fmac_f32_e32 v62, 0xba000000, v12
	v_mov_b32_e32 v68, v63
	v_mov_b32_e32 v69, v73
	v_mov_b32_e32 v63, v72
	v_pk_mul_f32 v[74:75], v[68:69], v[68:69]
	v_pk_mul_f32 v[72:73], v[62:63], v[62:63]
	v_fmac_f32_e32 v58, 0xba000000, v12
	v_pk_mov_b32 v[76:77], v[72:73], v[74:75] op_sel:[1,0]
	v_mov_b32_e32 v73, v75
	v_fmac_f32_e32 v59, 0xba000000, v12
	v_fmac_f32_e32 v60, 0xba000000, v12
	v_mul_f32_e32 v10, v58, v58
	v_pk_add_f32 v[72:73], v[76:77], v[72:73]
	v_fmac_f32_e32 v61, 0xba000000, v12
	v_pk_fma_f32 v[74:75], v[58:59], v[58:59], v[10:11] op_sel_hi:[1,1,0]
	v_mul_f32_e32 v10, v60, v60
	v_pk_add_f32 v[64:65], v[64:65], v[64:65] op_sel_hi:[0,1]
	v_pk_add_f32 v[72:73], v[72:73], v[72:73] op_sel_hi:[0,1]
	v_pk_fma_f32 v[76:77], v[60:61], v[60:61], v[10:11] op_sel_hi:[1,1,0]
	v_fmac_f32_e32 v53, 0xba000000, v12
	v_fmac_f32_e32 v55, 0xba000000, v12
	v_fmac_f32_e32 v49, 0xba000000, v12
	v_fmac_f32_e32 v51, 0xba000000, v12
	v_mul_f32_e32 v74, v51, v51
	v_mul_f32_e32 v76, v49, v49
	v_mul_f32_e32 v72, v55, v55
	v_mul_f32_e32 v64, v53, v53
	v_pk_add_f32 v[74:75], v[74:75], v[76:77]
	v_pk_add_f32 v[64:65], v[72:73], v[64:65]
	v_fmac_f32_e32 v4, 0xba000000, v12
	v_pk_add_f32 v[64:65], v[74:75], v[64:65]
	v_fmac_f32_e32 v5, 0xba000000, v12
	v_fmac_f32_e32 v57, 0xba000000, v12
	v_pk_add_f32 v[72:73], v[64:65], v[64:65] op_sel_hi:[0,1]
	v_fmac_f32_e32 v56, 0xba000000, v12
	v_mov_b32_e32 v64, v57
	v_mov_b32_e32 v65, v5
	v_mov_b32_e32 v57, v4
	v_pk_mul_f32 v[74:75], v[64:65], v[64:65]
	v_pk_mul_f32 v[4:5], v[56:57], v[56:57]
	v_fmac_f32_e32 v40, 0xba000000, v12
	v_pk_mov_b32 v[76:77], v[4:5], v[74:75] op_sel:[1,0]
	v_mov_b32_e32 v5, v75
	v_pk_add_f32 v[4:5], v[76:77], v[4:5]
	v_fmac_f32_e32 v41, 0xba000000, v12
	v_pk_add_f32 v[4:5], v[4:5], v[4:5] op_sel_hi:[0,1]
	v_fmac_f32_e32 v46, 0xba000000, v12
	v_mul_f32_e32 v4, v40, v40
	v_fmac_f32_e32 v47, 0xba000000, v12
	v_pk_fma_f32 v[74:75], v[40:41], v[40:41], v[4:5] op_sel_hi:[1,1,0]
	v_mul_f32_e32 v4, v46, v46
	v_pk_fma_f32 v[76:77], v[46:47], v[46:47], v[4:5] op_sel_hi:[1,1,0]
	v_fmac_f32_e32 v43, 0xba000000, v12
	v_fmac_f32_e32 v45, 0xba000000, v12
	v_fmac_f32_e32 v39, 0xba000000, v12
	v_fmac_f32_e32 v38, 0xba000000, v12
	v_mul_f32_e32 v74, v38, v38
	v_mul_f32_e32 v76, v39, v39
	v_mul_f32_e32 v4, v45, v45
	v_mul_f32_e32 v72, v43, v43
	v_pk_add_f32 v[74:75], v[74:75], v[76:77]
	v_pk_add_f32 v[4:5], v[4:5], v[72:73]
	v_lshlrev_b64 v[72:73], 2, v[2:3]
	v_pk_add_f32 v[4:5], v[74:75], v[4:5]
	v_lshl_add_u64 v[76:77], s[20:21], 0, v[72:73]
	v_add_f32_e32 v4, v4, v5
	ds_bpermute_b32 v5, v7, v4
	v_lshl_add_u64 v[74:75], s[18:19], 0, v[72:73]
	global_load_dwordx4 v[86:89], v[74:75], off
	v_lshl_add_u64 v[72:73], s[22:23], 0, v[72:73]
	v_lshl_add_u64 v[72:73], v[72:73], 0, s[14:15]
	s_waitcnt lgkmcnt(0)
	v_add_f32_e32 v4, v4, v5
	ds_bpermute_b32 v5, v18, v4
	v_mov_b32_e32 v52, v55
	v_mov_b32_e32 v48, v51
	v_mov_b32_e32 v42, v45
	v_lshlrev_b32_e32 v45, 16, v37
	s_waitcnt lgkmcnt(0)
	v_add_f32_e32 v4, v4, v5
	ds_bpermute_b32 v5, v50, v4
	s_waitcnt lgkmcnt(0)
	v_add_f32_e32 v4, v4, v5
	ds_bpermute_b32 v5, v54, v4
	s_waitcnt lgkmcnt(0)
	v_add_f32_e32 v4, v4, v5
	ds_bpermute_b32 v5, v82, v4
	s_waitcnt lgkmcnt(0)
	v_add_f32_e32 v4, v4, v5
	ds_bpermute_b32 v5, v84, v4
	s_waitcnt lgkmcnt(0)
	v_add_f32_e32 v4, v4, v5
	v_fmamk_f32 v4, v4, 0x3a000000, v250
	v_cmp_gt_f32_e32 vcc, s96, v4
	v_mul_f32_e32 v5, 0x4f800000, v4
	s_nop 0
	v_cndmask_b32_e32 v4, v4, v5, vcc
	v_sqrt_f32_e32 v5, v4
	s_nop 0
	v_add_u32_e32 v10, -1, v5
	v_fma_f32 v12, -v10, v5, v4
	v_cmp_ge_f32_e64 s[10:11], 0, v12
	v_add_u32_e32 v12, 1, v5
	s_nop 0
	v_cndmask_b32_e64 v10, v5, v10, s[10:11]
	v_fma_f32 v5, -v12, v5, v4
	v_cmp_lt_f32_e64 s[10:11], 0, v5
	s_nop 1
	v_cndmask_b32_e64 v5, v10, v12, s[10:11]
	v_mul_f32_e32 v10, 0x37800000, v5
	v_cndmask_b32_e32 v5, v5, v10, vcc
	v_cmp_class_f32_e32 vcc, v4, v251
	s_nop 1
	v_cndmask_b32_e32 v4, v5, v4, vcc
	v_div_scale_f32 v5, s[10:11], v4, v4, 1.0
	v_rcp_f32_e32 v10, v5
	s_lshl_b64 s[10:11], s[24:25], 13
	s_add_u32 s22, s22, s10
	s_addc_u32 s23, s23, s11
	v_fma_f32 v12, -v5, v10, 1.0
	v_fmac_f32_e32 v10, v12, v10
	v_div_scale_f32 v12, vcc, 1.0, v4, 1.0
	v_mul_f32_e32 v20, v12, v10
	v_fma_f32 v22, -v5, v20, v12
	v_fmac_f32_e32 v20, v22, v10
	v_fma_f32 v5, -v5, v20, v12
	v_div_fmas_f32 v5, v5, v10, v20
	v_div_fixup_f32 v10, v5, v4, 1.0
	global_load_dwordx4 v[2:5], v[76:77], off
	v_pk_mul_f32 v[78:79], v[78:79], v[10:11] op_sel_hi:[1,0]
	v_pk_mul_f32 v[80:81], v[80:81], v[10:11] op_sel_hi:[1,0]
	v_pk_mul_f32 v[70:71], v[70:71], v[10:11] op_sel_hi:[1,0]
	v_pk_mul_f32 v[66:67], v[66:67], v[10:11] op_sel_hi:[1,0]
	v_pk_mul_f32 v[62:63], v[62:63], v[10:11] op_sel_hi:[1,0]
	v_pk_mul_f32 v[60:61], v[60:61], v[10:11] op_sel_hi:[1,0]
	v_pk_mul_f32 v[58:59], v[58:59], v[10:11] op_sel_hi:[1,0]
	v_pk_mul_f32 v[52:53], v[52:53], v[10:11] op_sel_hi:[1,0]
	v_pk_mul_f32 v[48:49], v[48:49], v[10:11] op_sel_hi:[1,0]
	v_pk_mul_f32 v[46:47], v[46:47], v[10:11] op_sel_hi:[1,0]
	v_pk_mul_f32 v[40:41], v[40:41], v[10:11] op_sel_hi:[1,0]
	v_pk_mul_f32 v[38:39], v[38:39], v[10:11] op_sel_hi:[1,0]
	v_add_f32_e32 v22, v28, v29
	v_add_f32_e32 v12, v14, v15
	s_add_i32 s8, s8, s26
	s_add_u32 s16, s16, s34
	s_addc_u32 s17, s17, s35
	s_add_u32 s14, s14, s36
	s_addc_u32 s15, s15, s37
	s_cmpk_lt_i32 s8, 0x2000
	s_waitcnt vmcnt(0)
	v_pk_fma_f32 v[2:3], v[2:3], v[78:79], v[86:87]
	v_add_co_u32_e32 v78, vcc, s38, v72
	v_pk_fma_f32 v[4:5], v[4:5], v[80:81], v[88:89]
	s_nop 0
	v_addc_co_u32_e32 v79, vcc, -1, v73, vcc
	global_store_dwordx4 v[78:79], v[2:5], off offset:-3072
	s_nop 1
	global_load_dwordx4 v[2:5], v[76:77], off offset:1024
	s_nop 0
	global_load_dwordx4 v[86:89], v[74:75], off offset:1024
	s_waitcnt vmcnt(0)
	v_pk_fma_f32 v[2:3], v[2:3], v[66:67], v[86:87]
	v_pk_fma_f32 v[4:5], v[4:5], v[70:71], v[88:89]
	global_store_dwordx4 v[78:79], v[2:5], off offset:-2048
	s_nop 1
	global_load_dwordx4 v[2:5], v[76:77], off offset:2048
	global_load_dwordx4 v[86:89], v[74:75], off offset:2048
	v_pk_mul_f32 v[66:67], v[68:69], v[10:11] op_sel_hi:[1,0]
	s_waitcnt vmcnt(0)
	v_pk_fma_f32 v[2:3], v[2:3], v[62:63], v[86:87]
	v_pk_fma_f32 v[4:5], v[4:5], v[66:67], v[88:89]
	global_store_dwordx4 v[78:79], v[2:5], off offset:-1024
	s_nop 1
	global_load_dwordx4 v[2:5], v[76:77], off offset:3072
	s_nop 0
	global_load_dwordx4 v[66:69], v[74:75], off offset:3072
	v_add_co_u32_e32 v62, vcc, s82, v76
	s_waitcnt vmcnt(0)
	v_pk_fma_f32 v[2:3], v[2:3], v[58:59], v[66:67]
	v_pk_fma_f32 v[4:5], v[4:5], v[60:61], v[68:69]
	v_addc_co_u32_e32 v63, vcc, 0, v77, vcc
	global_store_dwordx4 v[72:73], v[2:5], off offset:-4096
	v_add_co_u32_e32 v66, vcc, s82, v74
	s_nop 0
	global_load_dwordx4 v[2:5], v[62:63], off
	s_nop 0
	v_addc_co_u32_e32 v67, vcc, 0, v75, vcc
	global_load_dwordx4 v[58:61], v[66:67], off
	s_waitcnt vmcnt(0)
	v_pk_fma_f32 v[2:3], v[2:3], v[48:49], v[58:59]
	v_pk_fma_f32 v[4:5], v[4:5], v[52:53], v[60:61]
	global_store_dwordx4 v[72:73], v[2:5], off offset:-3072
	s_nop 1
	global_load_dwordx4 v[2:5], v[62:63], off offset:1024
	s_nop 0
	global_load_dwordx4 v[58:61], v[66:67], off offset:1024
	v_pk_mul_f32 v[48:49], v[64:65], v[10:11] op_sel_hi:[1,0]
	v_pk_mul_f32 v[52:53], v[56:57], v[10:11] op_sel_hi:[1,0]
	s_waitcnt vmcnt(0)
	v_pk_fma_f32 v[4:5], v[4:5], v[48:49], v[60:61]
	v_pk_fma_f32 v[2:3], v[2:3], v[52:53], v[58:59]
	global_store_dwordx4 v[72:73], v[2:5], off offset:-2048
	s_nop 1
	global_load_dwordx4 v[2:5], v[62:63], off offset:2048
	global_load_dwordx4 v[56:59], v[66:67], off offset:2048
	s_waitcnt vmcnt(0)
	v_pk_fma_f32 v[2:3], v[2:3], v[40:41], v[56:57]
	v_pk_fma_f32 v[4:5], v[4:5], v[46:47], v[58:59]
	global_store_dwordx4 v[72:73], v[2:5], off offset:-1024
	s_nop 1
	global_load_dwordx4 v[2:5], v[62:63], off offset:3072
	s_nop 0
	global_load_dwordx4 v[46:49], v[66:67], off offset:3072
	v_pk_mul_f32 v[40:41], v[42:43], v[10:11] op_sel_hi:[1,0]
	v_and_b32_e32 v43, 0xffff0000, v31
	v_and_b32_e32 v42, 0xffff0000, v30
	v_add_f32_e32 v10, v16, v17
	s_waitcnt vmcnt(0)
	v_pk_fma_f32 v[2:3], v[38:39], v[2:3], v[46:47]
	v_pk_fma_f32 v[4:5], v[40:41], v[4:5], v[48:49]
	v_lshlrev_b32_e32 v38, 16, v34
	v_lshlrev_b32_e32 v39, 16, v36
	v_and_b32_e32 v47, 0xffff0000, v36
	v_and_b32_e32 v46, 0xffff0000, v34
	v_and_b32_e32 v49, 0xffff0000, v37
	v_and_b32_e32 v48, 0xffff0000, v35
	global_store_dwordx4 v[72:73], v[2:5], off
	v_and_b32_e32 v41, 0xffff0000, v33
	v_and_b32_e32 v40, 0xffff0000, v32
	v_pk_add_f32 v[2:3], v[38:39], v[46:47]
	v_pk_add_f32 v[4:5], v[44:45], v[48:49]
	s_nop 0
	v_pk_add_f32 v[2:3], v[2:3], v[4:5]
	v_lshlrev_b32_e32 v5, 16, v33
	v_add_f32_e32 v2, 0, v2
	v_lshlrev_b32_e32 v4, 16, v32
	v_add_f32_e32 v20, v2, v3
	v_pk_add_f32 v[2:3], v[4:5], v[40:41]
	v_pk_add_f32 v[32:33], v[24:25], v[22:23]
	v_pk_add_f32 v[2:3], v[2:3], v[2:3] op_sel:[0,1] op_sel_hi:[1,0]
	s_nop 0
	v_mov_b32_e32 v3, v19
	v_pk_add_f32 v[2:3], v[20:21], v[2:3]
	s_nop 0
	v_pk_add_f32 v[32:33], v[2:3], v[32:33]
	v_lshlrev_b32_e32 v3, 16, v31
	v_lshlrev_b32_e32 v2, 16, v30
	v_pk_add_f32 v[30:31], v[2:3], v[42:43]
	v_pk_add_f32 v[32:33], v[32:33], v[32:33] op_sel:[0,1] op_sel_hi:[1,0]
	v_pk_add_f32 v[30:31], v[30:31], v[30:31] op_sel:[0,1] op_sel_hi:[1,0]
	v_mov_b32_e32 v33, v8
	v_mov_b32_e32 v31, v9
	v_pk_add_f32 v[30:31], v[32:33], v[30:31]
	v_pk_add_f32 v[32:33], v[12:13], v[10:11]
	s_nop 0
	v_pk_add_f32 v[30:31], v[30:31], v[32:33]
	s_nop 0
	v_add_f32_e32 v10, v30, v31
	ds_bpermute_b32 v12, v7, v10
	s_waitcnt lgkmcnt(0)
	v_add_f32_e32 v10, v10, v12
	ds_bpermute_b32 v12, v18, v10
	s_waitcnt lgkmcnt(0)
	v_add_f32_e32 v10, v10, v12
	ds_bpermute_b32 v12, v50, v10
	s_waitcnt lgkmcnt(0)
	v_add_f32_e32 v10, v10, v12
	ds_bpermute_b32 v12, v54, v10
	s_waitcnt lgkmcnt(0)
	v_add_f32_e32 v10, v10, v12
	ds_bpermute_b32 v12, v82, v10
	s_waitcnt lgkmcnt(0)
	v_add_f32_e32 v10, v10, v12
	ds_bpermute_b32 v12, v84, v10
	s_waitcnt lgkmcnt(0)
	v_add_f32_e32 v12, v10, v12
	v_fmac_f32_e32 v48, 0xba000000, v12
	v_fmac_f32_e32 v46, 0xba000000, v12
	v_fmac_f32_e32 v49, 0xba000000, v12
	v_fmac_f32_e32 v47, 0xba000000, v12
	v_fmac_f32_e32 v44, 0xba000000, v12
	v_fmac_f32_e32 v38, 0xba000000, v12
	v_fmac_f32_e32 v45, 0xba000000, v12
	v_fmac_f32_e32 v39, 0xba000000, v12
	v_mov_b32_e32 v31, v47
	v_mov_b32_e32 v35, v46
	v_pk_mul_f32 v[32:33], v[46:47], v[46:47]
	v_pk_mul_f32 v[46:47], v[48:49], v[48:49]
	v_mov_b32_e32 v30, v39
	v_mov_b32_e32 v34, v38
	v_pk_fma_f32 v[38:39], v[38:39], v[38:39], v[32:33]
	v_mov_b32_e32 v32, v45
	v_mov_b32_e32 v36, v44
	v_pk_fma_f32 v[44:45], v[44:45], v[44:45], v[46:47]
	v_fmac_f32_e32 v40, 0xba000000, v12
	v_pk_add_f32 v[38:39], v[38:39], v[44:45]
	v_fmac_f32_e32 v41, 0xba000000, v12
	v_fmac_f32_e32 v5, 0xba000000, v12
	v_pk_add_f32 v[44:45], v[38:39], v[38:39] op_sel_hi:[0,1]
	v_fmac_f32_e32 v4, 0xba000000, v12
	v_mov_b32_e32 v38, v5
	v_mov_b32_e32 v39, v41
	v_mov_b32_e32 v5, v40
	v_pk_mul_f32 v[46:47], v[38:39], v[38:39]
	v_pk_mul_f32 v[40:41], v[4:5], v[4:5]
	v_fmac_f32_e32 v26, 0xba000000, v12
	v_mov_b32_e32 v33, v49
	v_mov_b32_e32 v37, v48
	v_pk_mov_b32 v[48:49], v[40:41], v[46:47] op_sel:[1,0]
	v_mov_b32_e32 v41, v47
	v_fmac_f32_e32 v27, 0xba000000, v12
	v_fmac_f32_e32 v28, 0xba000000, v12
	v_mul_f32_e32 v10, v26, v26
	v_pk_add_f32 v[40:41], v[48:49], v[40:41]
	v_fmac_f32_e32 v29, 0xba000000, v12
	v_pk_fma_f32 v[46:47], v[26:27], v[26:27], v[10:11] op_sel_hi:[1,1,0]
	v_mul_f32_e32 v10, v28, v28
	v_pk_add_f32 v[40:41], v[40:41], v[40:41] op_sel_hi:[0,1]
	v_pk_fma_f32 v[48:49], v[28:29], v[28:29], v[10:11] op_sel_hi:[1,1,0]
	v_fmac_f32_e32 v23, 0xba000000, v12
	v_fmac_f32_e32 v25, 0xba000000, v12
	v_fmac_f32_e32 v19, 0xba000000, v12
	v_fmac_f32_e32 v21, 0xba000000, v12
	v_mul_f32_e32 v46, v21, v21
	v_mul_f32_e32 v48, v19, v19
	v_mul_f32_e32 v40, v25, v25
	v_mul_f32_e32 v44, v23, v23
	v_pk_add_f32 v[46:47], v[46:47], v[48:49]
	v_pk_add_f32 v[40:41], v[40:41], v[44:45]
	v_fmac_f32_e32 v42, 0xba000000, v12
	v_pk_add_f32 v[40:41], v[46:47], v[40:41]
	v_fmac_f32_e32 v43, 0xba000000, v12
	v_fmac_f32_e32 v3, 0xba000000, v12
	v_pk_add_f32 v[44:45], v[40:41], v[40:41] op_sel_hi:[0,1]
	v_fmac_f32_e32 v2, 0xba000000, v12
	v_mov_b32_e32 v40, v3
	v_mov_b32_e32 v41, v43
	v_mov_b32_e32 v3, v42
	v_pk_mul_f32 v[46:47], v[40:41], v[40:41]
	v_pk_mul_f32 v[42:43], v[2:3], v[2:3]
	v_fmac_f32_e32 v14, 0xba000000, v12
	v_pk_mov_b32 v[48:49], v[42:43], v[46:47] op_sel:[1,0]
	v_mov_b32_e32 v43, v47
	v_fmac_f32_e32 v15, 0xba000000, v12
	v_fmac_f32_e32 v16, 0xba000000, v12
	v_mul_f32_e32 v10, v14, v14
	v_pk_add_f32 v[42:43], v[48:49], v[42:43]
	v_fmac_f32_e32 v17, 0xba000000, v12
	v_pk_fma_f32 v[46:47], v[14:15], v[14:15], v[10:11] op_sel_hi:[1,1,0]
	v_mul_f32_e32 v10, v16, v16
	v_pk_add_f32 v[42:43], v[42:43], v[42:43] op_sel_hi:[0,1]
	v_pk_fma_f32 v[48:49], v[16:17], v[16:17], v[10:11] op_sel_hi:[1,1,0]
	v_fmac_f32_e32 v11, 0xba000000, v12
	v_fmac_f32_e32 v13, 0xba000000, v12
	v_fmac_f32_e32 v9, 0xba000000, v12
	v_fmac_f32_e32 v8, 0xba000000, v12
	v_mul_f32_e32 v46, v8, v8
	v_mul_f32_e32 v48, v9, v9
	v_mul_f32_e32 v42, v13, v13
	v_mul_f32_e32 v44, v11, v11
	v_pk_add_f32 v[46:47], v[46:47], v[48:49]
	v_pk_add_f32 v[42:43], v[42:43], v[44:45]
	s_nop 0
	v_pk_add_f32 v[42:43], v[46:47], v[42:43]
	s_nop 0
	v_add_f32_e32 v10, v42, v43
	ds_bpermute_b32 v7, v7, v10
	v_lshlrev_b32_e32 v42, 2, v1
	v_ashrrev_i32_e32 v43, 31, v42
	s_waitcnt lgkmcnt(0)
	v_add_f32_e32 v7, v10, v7
	ds_bpermute_b32 v10, v18, v7
	s_waitcnt lgkmcnt(0)
	v_add_f32_e32 v7, v7, v10
	ds_bpermute_b32 v10, v50, v7
	s_waitcnt lgkmcnt(0)
	v_add_f32_e32 v7, v7, v10
	ds_bpermute_b32 v10, v54, v7
	v_lshlrev_b64 v[54:55], 2, v[42:43]
	v_lshl_add_u64 v[44:45], s[20:21], 0, v[54:55]
	v_lshl_add_u64 v[42:43], s[18:19], 0, v[54:55]
	global_load_dwordx4 v[46:49], v[44:45], off
	global_load_dwordx4 v[50:53], v[42:43], off
	s_waitcnt lgkmcnt(0)
	v_add_f32_e32 v7, v7, v10
	ds_bpermute_b32 v10, v82, v7
	s_waitcnt lgkmcnt(0)
	v_add_f32_e32 v7, v7, v10
	ds_bpermute_b32 v10, v84, v7
	s_waitcnt lgkmcnt(0)
	v_add_f32_e32 v7, v7, v10
	v_fmamk_f32 v7, v7, 0x3a000000, v250
	v_cmp_gt_f32_e32 vcc, s96, v7
	v_mul_f32_e32 v10, 0x4f800000, v7
	s_nop 0
	v_cndmask_b32_e32 v7, v7, v10, vcc
	v_sqrt_f32_e32 v10, v7
	s_nop 0
	v_add_u32_e32 v12, -1, v10
	v_fma_f32 v18, -v12, v10, v7
	v_cmp_ge_f32_e64 s[10:11], 0, v18
	v_add_u32_e32 v18, 1, v10
	s_nop 0
	v_cndmask_b32_e64 v12, v10, v12, s[10:11]
	v_fma_f32 v10, -v18, v10, v7
	v_cmp_lt_f32_e64 s[10:11], 0, v10
	s_nop 1
	v_cndmask_b32_e64 v10, v12, v18, s[10:11]
	v_mul_f32_e32 v12, 0x37800000, v10
	v_cndmask_b32_e32 v10, v10, v12, vcc
	v_cmp_class_f32_e32 vcc, v7, v251
	s_nop 1
	v_cndmask_b32_e32 v7, v10, v7, vcc
	v_div_scale_f32 v10, s[10:11], v7, v7, 1.0
	v_rcp_f32_e32 v12, v10
	s_nop 0
	v_fma_f32 v18, -v10, v12, 1.0
	v_fmac_f32_e32 v12, v18, v12
	v_div_scale_f32 v18, vcc, 1.0, v7, 1.0
	v_mul_f32_e32 v20, v18, v12
	v_fma_f32 v22, -v10, v20, v18
	v_fmac_f32_e32 v20, v22, v12
	v_fma_f32 v10, -v10, v20, v18
	v_div_fmas_f32 v10, v10, v12, v20
	v_div_fixup_f32 v12, v10, v7, 1.0
	v_pk_mul_f32 v[36:37], v[36:37], v[12:13] op_sel_hi:[1,0]
	v_pk_mul_f32 v[34:35], v[34:35], v[12:13] op_sel_hi:[1,0]
	v_pk_mul_f32 v[32:33], v[32:33], v[12:13] op_sel_hi:[1,0]
	v_pk_mul_f32 v[30:31], v[30:31], v[12:13] op_sel_hi:[1,0]
	v_pk_mul_f32 v[38:39], v[38:39], v[12:13] op_sel_hi:[1,0]
	v_pk_mul_f32 v[4:5], v[4:5], v[12:13] op_sel_hi:[1,0]
	v_pk_mul_f32 v[26:27], v[26:27], v[12:13] op_sel_hi:[1,0]
	v_mov_b32_e32 v18, v21
	v_mov_b32_e32 v22, v25
	v_pk_mul_f32 v[18:19], v[18:19], v[12:13] op_sel_hi:[1,0]
	v_pk_mul_f32 v[2:3], v[2:3], v[12:13] op_sel_hi:[1,0]
	v_pk_mul_f32 v[16:17], v[16:17], v[12:13] op_sel_hi:[1,0]
	v_pk_mul_f32 v[14:15], v[14:15], v[12:13] op_sel_hi:[1,0]
	v_mov_b32_e32 v10, v13
	v_pk_mul_f32 v[10:11], v[10:11], v[12:13] op_sel_hi:[1,0]
	v_pk_mul_f32 v[8:9], v[8:9], v[12:13] op_sel_hi:[1,0]
	s_waitcnt vmcnt(0)
	v_pk_fma_f32 v[34:35], v[46:47], v[34:35], v[50:51]
	v_pk_fma_f32 v[36:37], v[48:49], v[36:37], v[52:53]
	v_lshl_add_u64 v[50:51], s[22:23], 0, v[54:55]
	global_store_dwordx4 v[50:51], v[34:37], off
	s_nop 1
	global_load_dwordx4 v[34:37], v[44:45], off offset:1024
	s_nop 0
	global_load_dwordx4 v[46:49], v[42:43], off offset:1024
	s_waitcnt vmcnt(0)
	v_pk_fma_f32 v[30:31], v[34:35], v[30:31], v[46:47]
	v_pk_fma_f32 v[32:33], v[36:37], v[32:33], v[48:49]
	global_store_dwordx4 v[50:51], v[30:33], off offset:1024
	s_nop 1
	global_load_dwordx4 v[30:33], v[44:45], off offset:2048
	global_load_dwordx4 v[34:37], v[42:43], off offset:2048
	s_waitcnt vmcnt(0)
	v_pk_fma_f32 v[30:31], v[30:31], v[4:5], v[34:35]
	v_pk_fma_f32 v[32:33], v[32:33], v[38:39], v[36:37]
	global_store_dwordx4 v[50:51], v[30:33], off offset:2048
	s_nop 1
	global_load_dwordx4 v[30:33], v[44:45], off offset:3072
	s_nop 0
	global_load_dwordx4 v[34:37], v[42:43], off offset:3072
	v_pk_mul_f32 v[4:5], v[28:29], v[12:13] op_sel_hi:[1,0]
	s_waitcnt vmcnt(0)
	v_pk_fma_f32 v[26:27], v[30:31], v[26:27], v[34:35]
	v_add_co_u32_e32 v34, vcc, s82, v44
	v_pk_fma_f32 v[28:29], v[32:33], v[4:5], v[36:37]
	s_nop 0
	v_addc_co_u32_e32 v35, vcc, 0, v45, vcc
	global_store_dwordx4 v[50:51], v[26:29], off offset:3072
	v_add_co_u32_e32 v36, vcc, s82, v42
	s_nop 0
	global_load_dwordx4 v[26:29], v[34:35], off
	s_nop 0
	v_addc_co_u32_e32 v37, vcc, 0, v43, vcc
	global_load_dwordx4 v[30:33], v[36:37], off
	v_pk_mul_f32 v[4:5], v[22:23], v[12:13] op_sel_hi:[1,0]
	s_waitcnt vmcnt(0)
	v_pk_fma_f32 v[18:19], v[26:27], v[18:19], v[30:31]
	v_add_co_u32_e32 v26, vcc, s82, v50
	v_pk_fma_f32 v[20:21], v[28:29], v[4:5], v[32:33]
	s_nop 0
	v_addc_co_u32_e32 v27, vcc, 0, v51, vcc
	global_store_dwordx4 v[26:27], v[18:21], off
	s_nop 1
	global_load_dwordx4 v[18:21], v[34:35], off offset:1024
	s_nop 0
	global_load_dwordx4 v[22:25], v[36:37], off offset:1024
	v_pk_mul_f32 v[4:5], v[40:41], v[12:13] op_sel_hi:[1,0]
	s_waitcnt vmcnt(0)
	v_pk_fma_f32 v[2:3], v[18:19], v[2:3], v[22:23]
	v_pk_fma_f32 v[4:5], v[20:21], v[4:5], v[24:25]
	global_store_dwordx4 v[26:27], v[2:5], off offset:1024
	s_nop 1
	global_load_dwordx4 v[2:5], v[34:35], off offset:2048
	global_load_dwordx4 v[18:21], v[36:37], off offset:2048
	s_waitcnt vmcnt(0)
	v_pk_fma_f32 v[2:3], v[2:3], v[14:15], v[18:19]
	v_pk_fma_f32 v[4:5], v[4:5], v[16:17], v[20:21]
	global_store_dwordx4 v[26:27], v[2:5], off offset:2048
	s_nop 1
	global_load_dwordx4 v[2:5], v[34:35], off offset:3072
	s_nop 0
	global_load_dwordx4 v[14:17], v[36:37], off offset:3072
	s_waitcnt vmcnt(0)
	v_pk_fma_f32 v[2:3], v[8:9], v[2:3], v[14:15]
	v_pk_fma_f32 v[4:5], v[10:11], v[4:5], v[16:17]
	global_store_dwordx4 v[26:27], v[2:5], off offset:3072
	s_cbranch_scc1 .LBB0_1705

.LBB0_1743:
	v_mov_b32_e32 v2, v0
	s_mov_b64 s[8:9], s[44:45]
	v_mov_b32_e32 v1, v232
	s_mov_b64 s[34:35], s[46:47]
	s_mov_b64 s[10:11], s[0:1]
	s_add_i32 s8, s60, s30
	v_lshlrev_b32_e32 v2, 2, v1
	s_waitcnt lgkmcnt(0)
	v_ashrrev_i32_e32 v3, 31, v2
	v_lshlrev_b64 v[4:5], 1, v[2:3]
	v_lshl_add_u64 v[6:7], s[34:35], 0, v[4:5]
	v_lshl_add_u64 v[32:33], v[6:7], 0, s[24:25]
	global_load_dwordx2 v[6:7], v[32:33], off offset:-3584
	global_load_dwordx2 v[34:35], v[32:33], off offset:-3072
	global_load_dwordx2 v[44:45], v[32:33], off offset:-2560
	global_load_dwordx2 v[8:9], v[32:33], off offset:-2048
	s_cmpk_lt_i32 s8, 0x2000
	s_cselect_b32 s36, s8, s30
	s_add_u32 s18, s34, 0x28c000
	s_addc_u32 s19, s35, 0
	s_ashr_i32 s37, s36, 31
	s_ashr_i32 s31, s30, 31
	s_lshl_b64 s[8:9], s[36:37], 12
	s_add_u32 s16, s34, s8
	s_addc_u32 s17, s35, s9
	v_lshl_add_u64 v[4:5], s[16:17], 0, v[4:5]
	s_mov_b64 s[8:9], 0x1d91e000
	v_and_b32_e32 v14, 64, v249
	v_add_u32_e32 v14, 64, v14
	v_xor_b32_e32 v20, 1, v249
	v_lshlrev_b64 v[86:87], 2, v[2:3]
	s_add_u32 s20, s34, 0x28e000
	s_addc_u32 s21, s35, 0
	v_lshl_add_u64 v[88:89], s[20:21], 0, v[86:87]
	s_add_u32 s58, s34, 0x1515b000
	s_addc_u32 s59, s35, 0
	s_waitcnt vmcnt(3)
	v_lshlrev_b32_e32 v68, 16, v6
	s_waitcnt vmcnt(2)
	v_lshlrev_b32_e32 v69, 16, v34
	v_and_b32_e32 v75, 0xffff0000, v34
	s_waitcnt vmcnt(0)
	v_lshlrev_b32_e32 v36, 16, v8
	v_and_b32_e32 v37, 0xffff0000, v8
	v_lshlrev_b32_e32 v38, 16, v9
	v_and_b32_e32 v39, 0xffff0000, v9
	global_load_dwordx2 v[8:9], v[32:33], off offset:-1536
	v_and_b32_e32 v74, 0xffff0000, v6
	v_and_b32_e32 v73, 0xffff0000, v35
	v_and_b32_e32 v72, 0xffff0000, v7
	v_lshlrev_b32_e32 v34, 16, v44
	v_add_f32_e32 v66, v36, v37
	v_add_f32_e32 v46, v38, v39
	s_waitcnt vmcnt(0)
	v_lshlrev_b32_e32 v43, 16, v8
	v_and_b32_e32 v41, 0xffff0000, v8
	v_lshlrev_b32_e32 v67, 16, v9
	v_and_b32_e32 v47, 0xffff0000, v9
	global_load_dwordx2 v[70:71], v[32:33], off offset:-1024
	global_load_dwordx2 v[8:9], v[32:33], off offset:-512
	s_waitcnt vmcnt(0)
	v_lshlrev_b32_e32 v48, 16, v8
	v_and_b32_e32 v49, 0xffff0000, v8
	v_lshlrev_b32_e32 v50, 16, v9
	v_and_b32_e32 v51, 0xffff0000, v9
	global_load_dwordx2 v[8:9], v[32:33], off
	v_add_f32_e32 v64, v48, v49
	v_add_f32_e32 v54, v50, v51
	s_waitcnt vmcnt(0)
	v_lshlrev_b32_e32 v52, 16, v8
	v_and_b32_e32 v53, 0xffff0000, v8
	v_lshlrev_b32_e32 v65, 16, v9
	v_and_b32_e32 v55, 0xffff0000, v9
	v_lshl_add_u64 v[8:9], v[4:5], 0, s[8:9]
	s_mov_b32 s8, 0x1d91e000
	v_add_co_u32_e32 v4, vcc, s8, v4
	s_nop 1
	v_addc_co_u32_e32 v5, vcc, 0, v5, vcc
	global_load_dwordx2 v[60:61], v[4:5], off
	global_load_dwordx2 v[62:63], v[8:9], off offset:512
	global_load_dwordx2 v[58:59], v[8:9], off offset:1024
	s_nop 0
	global_load_dwordx2 v[4:5], v[8:9], off offset:1536
	v_cmp_lt_i32_e32 vcc, v20, v14
	s_waitcnt vmcnt(0)
	v_lshlrev_b32_e32 v28, 16, v4
	v_and_b32_e32 v29, 0xffff0000, v4
	v_lshlrev_b32_e32 v30, 16, v5
	v_and_b32_e32 v31, 0xffff0000, v5
	global_load_dwordx2 v[4:5], v[8:9], off offset:2048
	v_cndmask_b32_e32 v20, v249, v20, vcc
	v_lshlrev_b32_e32 v90, 2, v20
	v_add_f32_e32 v26, v28, v29
	v_add_f32_e32 v24, v30, v31
	s_waitcnt vmcnt(0)
	v_lshlrev_b32_e32 v23, 16, v4
	v_and_b32_e32 v21, 0xffff0000, v4
	v_lshlrev_b32_e32 v27, 16, v5
	v_and_b32_e32 v25, 0xffff0000, v5
	global_load_dwordx2 v[56:57], v[8:9], off offset:2560
	global_load_dwordx2 v[4:5], v[8:9], off offset:3072
	s_load_dwordx4 s[12:15], s[10:11], 0xb0
	s_load_dwordx2 s[38:39], s[10:11], 0x68
	s_waitcnt lgkmcnt(0)
	v_lshl_add_u64 v[84:85], s[12:13], 0, v[86:87]
	s_waitcnt vmcnt(0)
	v_lshlrev_b32_e32 v16, 16, v4
	v_and_b32_e32 v17, 0xffff0000, v4
	v_lshlrev_b32_e32 v18, 16, v5
	v_and_b32_e32 v19, 0xffff0000, v5
	global_load_dwordx2 v[4:5], v[8:9], off offset:3584
	v_lshlrev_b32_e32 v9, 16, v35
	v_lshlrev_b32_e32 v8, 16, v7
	v_pk_add_f32 v[6:7], v[8:9], v[72:73]
	v_lshlrev_b32_e32 v35, 16, v45
	s_waitcnt vmcnt(0)
	v_lshlrev_b32_e32 v10, 16, v4
	v_and_b32_e32 v11, 0xffff0000, v4
	v_lshlrev_b32_e32 v15, 16, v5
	v_and_b32_e32 v13, 0xffff0000, v5
	v_pk_add_f32 v[4:5], v[68:69], v[74:75]
	s_nop 0
	v_pk_add_f32 v[4:5], v[4:5], v[6:7]
	v_and_b32_e32 v7, 0xffff0000, v45
	v_add_f32_e32 v4, 0, v4
	v_and_b32_e32 v6, 0xffff0000, v44
	v_add_f32_e32 v42, v4, v5
	v_pk_add_f32 v[4:5], v[34:35], v[6:7]
	v_pk_add_f32 v[44:45], v[66:67], v[46:47]
	v_pk_add_f32 v[4:5], v[4:5], v[4:5] op_sel:[0,1] op_sel_hi:[1,0]
	s_nop 0
	v_mov_b32_e32 v5, v41
	v_pk_add_f32 v[4:5], v[42:43], v[4:5]
	s_nop 0
	v_pk_add_f32 v[76:77], v[4:5], v[44:45]
	v_lshlrev_b32_e32 v45, 16, v71
	v_lshlrev_b32_e32 v44, 16, v70
	v_and_b32_e32 v5, 0xffff0000, v71
	v_and_b32_e32 v4, 0xffff0000, v70
	v_pk_add_f32 v[70:71], v[44:45], v[4:5]
	v_pk_add_f32 v[76:77], v[76:77], v[76:77] op_sel:[0,1] op_sel_hi:[1,0]
	v_pk_add_f32 v[70:71], v[70:71], v[70:71] op_sel:[0,1] op_sel_hi:[1,0]
	v_mov_b32_e32 v77, v52
	v_mov_b32_e32 v71, v53
	v_pk_add_f32 v[70:71], v[76:77], v[70:71]
	v_pk_add_f32 v[76:77], v[64:65], v[54:55]
	s_nop 0
	v_pk_add_f32 v[70:71], v[70:71], v[76:77]
	s_nop 0
	v_add_f32_e32 v12, v70, v71
	ds_bpermute_b32 v20, v90, v12
	s_waitcnt lgkmcnt(0)
	v_add_f32_e32 v12, v12, v20
	v_xor_b32_e32 v20, 2, v249
	v_cmp_lt_i32_e32 vcc, v20, v14
	s_nop 1
	v_cndmask_b32_e32 v20, v249, v20, vcc
	v_lshlrev_b32_e32 v91, 2, v20
	ds_bpermute_b32 v20, v91, v12
	s_waitcnt lgkmcnt(0)
	v_add_f32_e32 v12, v12, v20
	v_xor_b32_e32 v20, 4, v249
	v_cmp_lt_i32_e32 vcc, v20, v14
	s_nop 1
	v_cndmask_b32_e32 v20, v249, v20, vcc
	v_lshlrev_b32_e32 v92, 2, v20
	ds_bpermute_b32 v20, v92, v12
	s_waitcnt lgkmcnt(0)
	v_add_f32_e32 v12, v12, v20
	v_xor_b32_e32 v20, 8, v249
	v_cmp_lt_i32_e32 vcc, v20, v14
	s_nop 1
	v_cndmask_b32_e32 v20, v249, v20, vcc
	v_lshlrev_b32_e32 v93, 2, v20
	ds_bpermute_b32 v20, v93, v12
	s_waitcnt lgkmcnt(0)
	v_add_f32_e32 v12, v12, v20
	v_xor_b32_e32 v20, 16, v249
	v_cmp_lt_i32_e32 vcc, v20, v14
	s_nop 1
	v_cndmask_b32_e32 v20, v249, v20, vcc
	v_lshlrev_b32_e32 v94, 2, v20
	ds_bpermute_b32 v20, v94, v12
	s_waitcnt lgkmcnt(0)
	v_add_f32_e32 v12, v12, v20
	v_xor_b32_e32 v20, 32, v249
	v_cmp_lt_i32_e32 vcc, v20, v14
	s_nop 1
	v_cndmask_b32_e32 v14, v249, v20, vcc
	v_lshlrev_b32_e32 v95, 2, v14
	ds_bpermute_b32 v14, v95, v12
	s_waitcnt lgkmcnt(0)
	v_add_f32_e32 v12, v12, v14
	v_fmac_f32_e32 v74, 0xba000000, v12
	v_fmac_f32_e32 v75, 0xba000000, v12
	v_fmac_f32_e32 v72, 0xba000000, v12
	v_fmac_f32_e32 v68, 0xba000000, v12
	v_fmac_f32_e32 v73, 0xba000000, v12
	v_fmac_f32_e32 v69, 0xba000000, v12
	v_mov_b32_e32 v71, v75
	v_mov_b32_e32 v77, v74
	v_pk_mul_f32 v[74:75], v[74:75], v[74:75]
	v_fmac_f32_e32 v8, 0xba000000, v12
	v_fmac_f32_e32 v9, 0xba000000, v12
	v_mov_b32_e32 v70, v69
	v_mov_b32_e32 v76, v68
	v_pk_fma_f32 v[68:69], v[68:69], v[68:69], v[74:75]
	v_mov_b32_e32 v75, v73
	v_mov_b32_e32 v79, v72
	v_pk_mul_f32 v[72:73], v[72:73], v[72:73]
	v_fmac_f32_e32 v6, 0xba000000, v12
	v_fmac_f32_e32 v7, 0xba000000, v12
	v_fmac_f32_e32 v35, 0xba000000, v12
	v_mov_b32_e32 v74, v9
	v_mov_b32_e32 v78, v8
	v_pk_fma_f32 v[8:9], v[8:9], v[8:9], v[72:73]
	v_fmac_f32_e32 v34, 0xba000000, v12
	v_mov_b32_e32 v72, v35
	v_mov_b32_e32 v73, v7
	v_mov_b32_e32 v35, v6
	v_pk_add_f32 v[8:9], v[68:69], v[8:9]
	v_pk_mul_f32 v[68:69], v[72:73], v[72:73]
	v_pk_mul_f32 v[6:7], v[34:35], v[34:35]
	v_fmac_f32_e32 v36, 0xba000000, v12
	v_pk_mov_b32 v[80:81], v[6:7], v[68:69] op_sel:[1,0]
	v_mov_b32_e32 v7, v69
	v_pk_add_f32 v[6:7], v[80:81], v[6:7]
	v_fmac_f32_e32 v37, 0xba000000, v12
	v_pk_add_f32 v[6:7], v[6:7], v[6:7] op_sel_hi:[0,1]
	v_fmac_f32_e32 v38, 0xba000000, v12
	v_mul_f32_e32 v6, v36, v36
	v_fmac_f32_e32 v39, 0xba000000, v12
	v_pk_fma_f32 v[68:69], v[36:37], v[36:37], v[6:7] op_sel_hi:[1,1,0]
	v_mul_f32_e32 v6, v38, v38
	v_pk_add_f32 v[8:9], v[8:9], v[8:9] op_sel_hi:[0,1]
	v_pk_fma_f32 v[80:81], v[38:39], v[38:39], v[6:7] op_sel_hi:[1,1,0]
	v_fmac_f32_e32 v47, 0xba000000, v12
	v_fmac_f32_e32 v67, 0xba000000, v12
	v_fmac_f32_e32 v41, 0xba000000, v12
	v_fmac_f32_e32 v43, 0xba000000, v12
	v_mul_f32_e32 v68, v43, v43
	v_mul_f32_e32 v80, v41, v41
	v_mul_f32_e32 v6, v67, v67
	v_mul_f32_e32 v8, v47, v47
	v_pk_add_f32 v[68:69], v[68:69], v[80:81]
	v_pk_add_f32 v[6:7], v[6:7], v[8:9]
	v_fmac_f32_e32 v4, 0xba000000, v12
	v_fmac_f32_e32 v5, 0xba000000, v12
	v_fmac_f32_e32 v45, 0xba000000, v12
	v_pk_add_f32 v[6:7], v[68:69], v[6:7]
	v_fmac_f32_e32 v44, 0xba000000, v12
	v_mov_b32_e32 v68, v45
	v_mov_b32_e32 v69, v5
	v_mov_b32_e32 v45, v4
	v_pk_mul_f32 v[8:9], v[68:69], v[68:69]
	v_pk_mul_f32 v[4:5], v[44:45], v[44:45]
	v_fmac_f32_e32 v48, 0xba000000, v12
	v_pk_mov_b32 v[80:81], v[4:5], v[8:9] op_sel:[1,0]
	v_mov_b32_e32 v5, v9
	v_pk_add_f32 v[4:5], v[80:81], v[4:5]
	v_fmac_f32_e32 v49, 0xba000000, v12
	v_pk_add_f32 v[4:5], v[4:5], v[4:5] op_sel_hi:[0,1]
	v_fmac_f32_e32 v50, 0xba000000, v12
	v_mul_f32_e32 v4, v48, v48
	v_fmac_f32_e32 v51, 0xba000000, v12
	v_pk_fma_f32 v[8:9], v[48:49], v[48:49], v[4:5] op_sel_hi:[1,1,0]
	v_mul_f32_e32 v4, v50, v50
	v_pk_add_f32 v[6:7], v[6:7], v[6:7] op_sel_hi:[0,1]
	v_pk_fma_f32 v[80:81], v[50:51], v[50:51], v[4:5] op_sel_hi:[1,1,0]
	v_fmac_f32_e32 v55, 0xba000000, v12
	v_fmac_f32_e32 v65, 0xba000000, v12
	v_fmac_f32_e32 v53, 0xba000000, v12
	v_fmac_f32_e32 v52, 0xba000000, v12
	v_mul_f32_e32 v8, v52, v52
	v_mul_f32_e32 v80, v53, v53
	v_mul_f32_e32 v4, v65, v65
	v_mul_f32_e32 v6, v55, v55
	v_pk_add_f32 v[8:9], v[8:9], v[80:81]
	v_pk_add_f32 v[4:5], v[4:5], v[6:7]
	v_lshl_add_u64 v[80:81], s[14:15], 0, v[86:87]
	v_pk_add_f32 v[4:5], v[8:9], v[4:5]
	v_mov_b32_e32 v46, v67
	v_add_f32_e32 v4, v4, v5
	ds_bpermute_b32 v5, v90, v4
	v_mov_b32_e32 v40, v43
	v_mov_b32_e32 v54, v65
	s_waitcnt lgkmcnt(0)
	v_add_f32_e32 v4, v4, v5
	ds_bpermute_b32 v5, v91, v4
	s_waitcnt lgkmcnt(0)
	v_add_f32_e32 v4, v4, v5
	ds_bpermute_b32 v5, v92, v4
	s_waitcnt lgkmcnt(0)
	v_add_f32_e32 v4, v4, v5
	ds_bpermute_b32 v5, v93, v4
	s_waitcnt lgkmcnt(0)
	v_add_f32_e32 v4, v4, v5
	ds_bpermute_b32 v5, v94, v4
	s_waitcnt lgkmcnt(0)
	v_add_f32_e32 v4, v4, v5
	ds_bpermute_b32 v5, v95, v4
	s_waitcnt lgkmcnt(0)
	v_add_f32_e32 v4, v4, v5
	v_fmamk_f32 v4, v4, 0x3a000000, v250
	v_cmp_gt_f32_e32 vcc, s96, v4
	v_mul_f32_e32 v5, 0x4f800000, v4
	s_nop 0
	v_cndmask_b32_e32 v4, v4, v5, vcc
	v_sqrt_f32_e32 v5, v4
	s_nop 0
	v_add_u32_e32 v6, -1, v5
	v_fma_f32 v7, -v6, v5, v4
	v_cmp_ge_f32_e64 s[10:11], 0, v7
	v_add_u32_e32 v7, 1, v5
	s_nop 0
	v_cndmask_b32_e64 v6, v5, v6, s[10:11]
	v_fma_f32 v5, -v7, v5, v4
	v_cmp_lt_f32_e64 s[10:11], 0, v5
	s_nop 1
	v_cndmask_b32_e64 v5, v6, v7, s[10:11]
	v_mul_f32_e32 v6, 0x37800000, v5
	v_cndmask_b32_e32 v5, v5, v6, vcc
	v_cmp_class_f32_e32 vcc, v4, v251
	s_nop 1
	v_cndmask_b32_e32 v4, v5, v4, vcc
	v_div_scale_f32 v5, s[8:9], v4, v4, 1.0
	v_rcp_f32_e32 v6, v5
	s_movk_i32 s8, 0xf000
	v_fma_f32 v7, -v5, v6, 1.0
	v_fmac_f32_e32 v6, v7, v6
	v_div_scale_f32 v7, vcc, 1.0, v4, 1.0
	v_mul_f32_e32 v8, v7, v6
	v_fma_f32 v9, -v5, v8, v7
	v_fmac_f32_e32 v8, v9, v6
	v_fma_f32 v5, -v5, v8, v7
	v_div_fmas_f32 v5, v5, v6, v8
	v_div_fixup_f32 v12, v5, v4, 1.0
	global_load_dwordx4 v[2:5], v[84:85], off
	global_load_dwordx4 v[6:9], v[80:81], off
	v_pk_mul_f32 v[76:77], v[76:77], v[12:13] op_sel_hi:[1,0]
	v_pk_mul_f32 v[78:79], v[78:79], v[12:13] op_sel_hi:[1,0]
	v_pk_mul_f32 v[70:71], v[70:71], v[12:13] op_sel_hi:[1,0]
	v_pk_mul_f32 v[34:35], v[34:35], v[12:13] op_sel_hi:[1,0]
	v_pk_mul_f32 v[38:39], v[38:39], v[12:13] op_sel_hi:[1,0]
	v_pk_mul_f32 v[36:37], v[36:37], v[12:13] op_sel_hi:[1,0]
	v_pk_mul_f32 v[46:47], v[46:47], v[12:13] op_sel_hi:[1,0]
	v_pk_mul_f32 v[40:41], v[40:41], v[12:13] op_sel_hi:[1,0]
	v_pk_mul_f32 v[44:45], v[44:45], v[12:13] op_sel_hi:[1,0]
	v_pk_mul_f32 v[50:51], v[50:51], v[12:13] op_sel_hi:[1,0]
	v_pk_mul_f32 v[48:49], v[48:49], v[12:13] op_sel_hi:[1,0]
	v_pk_mul_f32 v[54:55], v[54:55], v[12:13] op_sel_hi:[1,0]
	v_pk_mul_f32 v[52:53], v[52:53], v[12:13] op_sel_hi:[1,0]
	s_waitcnt vmcnt(0)
	v_pk_fma_f32 v[6:7], v[2:3], v[76:77], v[6:7]
	v_lshl_add_u64 v[2:3], s[34:35], 0, v[86:87]
	v_lshl_add_u64 v[76:77], v[2:3], 0, s[22:23]
	v_add_co_u32_e32 v104, vcc, s8, v76
	v_pk_fma_f32 v[8:9], v[4:5], v[78:79], v[8:9]
	s_nop 0
	v_addc_co_u32_e32 v105, vcc, -1, v77, vcc
	global_store_dwordx4 v[104:105], v[6:9], off offset:-3072
	global_load_dwordx4 v[2:5], v[88:89], off
	v_lshl_add_u64 v[86:87], s[18:19], 0, v[86:87]
	global_load_dwordx4 v[96:99], v[86:87], off
	s_mov_b32 s8, 0xef2fd000
	s_waitcnt vmcnt(1)
	v_pk_add_f32 v[4:5], v[4:5], 1.0 op_sel_hi:[1,0]
	v_pk_add_f32 v[78:79], v[2:3], 1.0 op_sel_hi:[1,0]
	s_waitcnt vmcnt(0)
	v_pk_fma_f32 v[2:3], v[4:5], v[8:9], v[98:99]
	v_pk_fma_f32 v[4:5], v[78:79], v[6:7], v[96:97]
	v_cvt_pk_bf16_f32 v6, v4, v5
	v_add_co_u32_e32 v78, vcc, s8, v32
	v_cvt_pk_bf16_f32 v7, v2, v3
	s_nop 0
	v_addc_co_u32_e32 v79, vcc, -1, v33, vcc
	global_store_dwordx2 v[78:79], v[6:7], off offset:-3584
	global_load_dwordx4 v[6:9], v[84:85], off offset:1024
	s_nop 0
	global_load_dwordx4 v[96:99], v[80:81], off offset:1024
	v_pk_mul_f32 v[32:33], v[74:75], v[12:13] op_sel_hi:[1,0]
	s_lshl_b64 s[8:9], s[36:37], 13
	s_add_u32 s40, s34, s8
	s_addc_u32 s41, s35, s9
	s_waitcnt vmcnt(0)
	v_pk_fma_f32 v[96:97], v[6:7], v[70:71], v[96:97]
	v_pk_fma_f32 v[98:99], v[8:9], v[32:33], v[98:99]
	global_store_dwordx4 v[104:105], v[96:99], off offset:-2048
	global_load_dwordx4 v[6:9], v[88:89], off offset:1024
	global_load_dwordx4 v[100:103], v[86:87], off offset:1024
	s_waitcnt vmcnt(1)
	v_pk_add_f32 v[8:9], v[8:9], 1.0 op_sel_hi:[1,0]
	v_pk_add_f32 v[32:33], v[6:7], 1.0 op_sel_hi:[1,0]
	s_waitcnt vmcnt(0)
	v_pk_fma_f32 v[6:7], v[8:9], v[98:99], v[102:103]
	v_pk_fma_f32 v[8:9], v[32:33], v[96:97], v[100:101]
	s_nop 0
	v_cvt_pk_bf16_f32 v32, v8, v9
	v_cvt_pk_bf16_f32 v33, v6, v7
	global_store_dwordx2 v[78:79], v[32:33], off offset:-3072
	global_load_dwordx4 v[96:99], v[84:85], off offset:2048
	global_load_dwordx4 v[100:103], v[80:81], off offset:2048
	v_pk_mul_f32 v[32:33], v[72:73], v[12:13] op_sel_hi:[1,0]
	s_waitcnt vmcnt(0)
	v_pk_fma_f32 v[70:71], v[96:97], v[34:35], v[100:101]
	v_pk_fma_f32 v[72:73], v[98:99], v[32:33], v[102:103]
	global_store_dwordx4 v[104:105], v[70:73], off offset:-1024
	global_load_dwordx4 v[32:35], v[88:89], off offset:2048
	global_load_dwordx4 v[96:99], v[86:87], off offset:2048
	s_waitcnt vmcnt(1)
	v_pk_add_f32 v[34:35], v[34:35], 1.0 op_sel_hi:[1,0]
	v_pk_add_f32 v[74:75], v[32:33], 1.0 op_sel_hi:[1,0]
	s_waitcnt vmcnt(0)
	v_pk_fma_f32 v[32:33], v[34:35], v[72:73], v[98:99]
	v_pk_fma_f32 v[34:35], v[74:75], v[70:71], v[96:97]
	s_nop 0
	v_cvt_pk_bf16_f32 v70, v34, v35
	v_cvt_pk_bf16_f32 v71, v32, v33
	global_store_dwordx2 v[78:79], v[70:71], off offset:-2560
	global_load_dwordx4 v[70:73], v[84:85], off offset:3072
	s_nop 0
	global_load_dwordx4 v[96:99], v[80:81], off offset:3072
	s_waitcnt vmcnt(0)
	v_pk_fma_f32 v[70:71], v[70:71], v[36:37], v[96:97]
	v_pk_fma_f32 v[72:73], v[72:73], v[38:39], v[98:99]
	global_store_dwordx4 v[76:77], v[70:73], off offset:-4096
	global_load_dwordx4 v[36:39], v[88:89], off offset:3072
	global_load_dwordx4 v[96:99], v[86:87], off offset:3072
	s_waitcnt vmcnt(1)
	v_pk_add_f32 v[38:39], v[38:39], 1.0 op_sel_hi:[1,0]
	v_pk_add_f32 v[74:75], v[36:37], 1.0 op_sel_hi:[1,0]
	s_waitcnt vmcnt(0)
	v_pk_fma_f32 v[36:37], v[38:39], v[72:73], v[98:99]
	v_pk_fma_f32 v[38:39], v[74:75], v[70:71], v[96:97]
	s_nop 0
	v_cvt_pk_bf16_f32 v70, v38, v39
	v_cvt_pk_bf16_f32 v71, v36, v37
	global_store_dwordx2 v[78:79], v[70:71], off offset:-2048
	v_add_co_u32_e32 v70, vcc, s82, v84
	s_nop 1
	v_addc_co_u32_e32 v71, vcc, 0, v85, vcc
	v_add_co_u32_e32 v72, vcc, s82, v80
	global_load_dwordx4 v[96:99], v[70:71], off
	s_nop 0
	v_addc_co_u32_e32 v73, vcc, 0, v81, vcc
	global_load_dwordx4 v[100:103], v[72:73], off
	v_add_co_u32_e32 v66, vcc, s82, v88
	s_waitcnt vmcnt(0)
	v_pk_fma_f32 v[96:97], v[40:41], v[96:97], v[100:101]
	v_pk_fma_f32 v[98:99], v[46:47], v[98:99], v[102:103]
	v_addc_co_u32_e32 v67, vcc, 0, v89, vcc
	global_store_dwordx4 v[76:77], v[96:99], off offset:-3072
	v_add_co_u32_e32 v80, vcc, s82, v86
	global_load_dwordx4 v[40:43], v[66:67], off
	s_nop 0
	v_addc_co_u32_e32 v81, vcc, 0, v87, vcc
	global_load_dwordx4 v[84:87], v[80:81], off
	s_waitcnt vmcnt(1)
	v_pk_add_f32 v[42:43], v[42:43], 1.0 op_sel_hi:[1,0]
	v_pk_add_f32 v[46:47], v[40:41], 1.0 op_sel_hi:[1,0]
	s_waitcnt vmcnt(0)
	v_pk_fma_f32 v[40:41], v[98:99], v[42:43], v[86:87]
	v_pk_fma_f32 v[42:43], v[96:97], v[46:47], v[84:85]
	s_nop 0
	v_cvt_pk_bf16_f32 v46, v42, v43
	v_cvt_pk_bf16_f32 v47, v40, v41
	global_store_dwordx2 v[78:79], v[46:47], off offset:-1536
	global_load_dwordx4 v[84:87], v[70:71], off offset:1024
	global_load_dwordx4 v[96:99], v[72:73], off offset:1024
	v_pk_mul_f32 v[46:47], v[68:69], v[12:13] op_sel_hi:[1,0]
	s_waitcnt vmcnt(0)
	v_pk_fma_f32 v[84:85], v[44:45], v[84:85], v[96:97]
	v_pk_fma_f32 v[86:87], v[46:47], v[86:87], v[98:99]
	global_store_dwordx4 v[76:77], v[84:87], off offset:-2048
	global_load_dwordx4 v[44:47], v[66:67], off offset:1024
	global_load_dwordx4 v[96:99], v[80:81], off offset:1024
	s_waitcnt vmcnt(1)
	v_pk_add_f32 v[46:47], v[46:47], 1.0 op_sel_hi:[1,0]
	v_pk_add_f32 v[68:69], v[44:45], 1.0 op_sel_hi:[1,0]
	s_waitcnt vmcnt(0)
	v_pk_fma_f32 v[44:45], v[86:87], v[46:47], v[98:99]
	v_pk_fma_f32 v[46:47], v[84:85], v[68:69], v[96:97]
	s_nop 0
	v_cvt_pk_bf16_f32 v68, v46, v47
	v_cvt_pk_bf16_f32 v69, v44, v45
	global_store_dwordx2 v[78:79], v[68:69], off offset:-1024
	global_load_dwordx4 v[84:87], v[70:71], off offset:2048
	global_load_dwordx4 v[96:99], v[72:73], off offset:2048
	s_waitcnt vmcnt(0)
	v_pk_fma_f32 v[84:85], v[48:49], v[84:85], v[96:97]
	v_pk_fma_f32 v[86:87], v[50:51], v[86:87], v[98:99]
	global_store_dwordx4 v[76:77], v[84:87], off offset:-1024
	global_load_dwordx4 v[48:51], v[66:67], off offset:2048
	global_load_dwordx4 v[96:99], v[80:81], off offset:2048
	s_waitcnt vmcnt(1)
	v_pk_add_f32 v[50:51], v[50:51], 1.0 op_sel_hi:[1,0]
	v_pk_add_f32 v[68:69], v[48:49], 1.0 op_sel_hi:[1,0]
	s_waitcnt vmcnt(0)
	v_pk_fma_f32 v[48:49], v[86:87], v[50:51], v[98:99]
	v_pk_fma_f32 v[50:51], v[84:85], v[68:69], v[96:97]
	s_nop 0
	v_cvt_pk_bf16_f32 v68, v50, v51
	v_cvt_pk_bf16_f32 v69, v48, v49
	global_store_dwordx2 v[78:79], v[68:69], off offset:-512
	global_load_dwordx4 v[68:71], v[70:71], off offset:3072
	s_nop 0
	global_load_dwordx4 v[72:75], v[72:73], off offset:3072
	s_waitcnt vmcnt(0)
	v_pk_fma_f32 v[68:69], v[52:53], v[68:69], v[72:73]
	v_pk_fma_f32 v[70:71], v[54:55], v[70:71], v[74:75]
	global_store_dwordx4 v[76:77], v[68:71], off
	global_load_dwordx4 v[52:55], v[66:67], off offset:3072
	s_nop 0
	global_load_dwordx4 v[64:67], v[80:81], off offset:3072
	v_and_b32_e32 v77, 0xffff0000, v63
	v_and_b32_e32 v76, 0xffff0000, v61
	v_and_b32_e32 v75, 0xffff0000, v59
	v_and_b32_e32 v74, 0xffff0000, v58
	s_waitcnt vmcnt(1)
	v_pk_add_f32 v[54:55], v[54:55], 1.0 op_sel_hi:[1,0]
	v_pk_add_f32 v[72:73], v[52:53], 1.0 op_sel_hi:[1,0]
	s_waitcnt vmcnt(0)
	v_pk_fma_f32 v[52:53], v[70:71], v[54:55], v[66:67]
	v_pk_fma_f32 v[54:55], v[68:69], v[72:73], v[64:65]
	v_and_b32_e32 v67, 0xffff0000, v62
	v_cvt_pk_bf16_f32 v64, v54, v55
	v_cvt_pk_bf16_f32 v65, v52, v53
	global_store_dwordx2 v[78:79], v[64:65], off
	v_lshlrev_b32_e32 v64, 16, v60
	v_lshlrev_b32_e32 v65, 16, v62
	v_and_b32_e32 v66, 0xffff0000, v60
	v_lshlrev_b32_e32 v70, 16, v61
	v_lshlrev_b32_e32 v71, 16, v63
	v_pk_add_f32 v[60:61], v[64:65], v[66:67]
	v_pk_add_f32 v[62:63], v[70:71], v[76:77]
	v_lshlrev_b32_e32 v69, 16, v59
	v_lshlrev_b32_e32 v68, 16, v58
	v_pk_add_f32 v[60:61], v[60:61], v[62:63]
	v_pk_add_f32 v[58:59], v[68:69], v[74:75]
	v_add_f32_e32 v12, 0, v60
	v_pk_add_f32 v[58:59], v[58:59], v[58:59] op_sel:[0,1] op_sel_hi:[1,0]
	v_add_f32_e32 v22, v12, v61
	v_mov_b32_e32 v59, v21
	v_pk_add_f32 v[58:59], v[22:23], v[58:59]
	v_pk_add_f32 v[60:61], v[26:27], v[24:25]
	v_and_b32_e32 v73, 0xffff0000, v57
	v_pk_add_f32 v[58:59], v[58:59], v[60:61]
	v_lshlrev_b32_e32 v61, 16, v57
	v_lshlrev_b32_e32 v60, 16, v56
	v_and_b32_e32 v72, 0xffff0000, v56
	v_pk_add_f32 v[56:57], v[60:61], v[72:73]
	v_pk_add_f32 v[58:59], v[58:59], v[58:59] op_sel:[0,1] op_sel_hi:[1,0]
	v_pk_add_f32 v[56:57], v[56:57], v[56:57] op_sel:[0,1] op_sel_hi:[1,0]
	v_add_f32_e32 v14, v16, v17
	v_add_f32_e32 v12, v18, v19
	v_mov_b32_e32 v59, v10
	v_mov_b32_e32 v57, v11
	v_pk_add_f32 v[56:57], v[58:59], v[56:57]
	v_pk_add_f32 v[58:59], v[14:15], v[12:13]
	s_nop 0
	v_pk_add_f32 v[56:57], v[56:57], v[58:59]
	s_nop 0
	v_add_f32_e32 v12, v56, v57
	ds_bpermute_b32 v14, v90, v12
	s_waitcnt lgkmcnt(0)
	v_add_f32_e32 v12, v12, v14
	ds_bpermute_b32 v14, v91, v12
	s_waitcnt lgkmcnt(0)
	v_add_f32_e32 v12, v12, v14
	ds_bpermute_b32 v14, v92, v12
	s_waitcnt lgkmcnt(0)
	v_add_f32_e32 v12, v12, v14
	ds_bpermute_b32 v14, v93, v12
	s_waitcnt lgkmcnt(0)
	v_add_f32_e32 v12, v12, v14
	ds_bpermute_b32 v14, v94, v12
	s_waitcnt lgkmcnt(0)
	v_add_f32_e32 v12, v12, v14
	ds_bpermute_b32 v14, v95, v12
	s_waitcnt lgkmcnt(0)
	v_add_f32_e32 v14, v12, v14
	v_fmac_f32_e32 v66, 0xba000000, v14
	v_fmac_f32_e32 v67, 0xba000000, v14
	v_fmac_f32_e32 v76, 0xba000000, v14
	v_fmac_f32_e32 v64, 0xba000000, v14
	v_fmac_f32_e32 v77, 0xba000000, v14
	v_fmac_f32_e32 v65, 0xba000000, v14
	v_pk_mul_f32 v[58:59], v[66:67], v[66:67]
	v_fmac_f32_e32 v70, 0xba000000, v14
	v_fmac_f32_e32 v71, 0xba000000, v14
	v_mov_b32_e32 v62, v65
	v_mov_b32_e32 v63, v67
	v_mov_b32_e32 v56, v64
	v_pk_fma_f32 v[64:65], v[64:65], v[64:65], v[58:59]
	v_mov_b32_e32 v67, v77
	v_mov_b32_e32 v59, v76
	v_pk_mul_f32 v[76:77], v[76:77], v[76:77]
	v_mov_b32_e32 v57, v66
	v_mov_b32_e32 v66, v71
	v_mov_b32_e32 v58, v70
	v_pk_fma_f32 v[70:71], v[70:71], v[70:71], v[76:77]
	v_fmac_f32_e32 v74, 0xba000000, v14
	v_fmac_f32_e32 v75, 0xba000000, v14
	v_fmac_f32_e32 v69, 0xba000000, v14
	v_pk_add_f32 v[64:65], v[64:65], v[70:71]
	v_fmac_f32_e32 v68, 0xba000000, v14
	v_mov_b32_e32 v70, v69
	v_mov_b32_e32 v71, v75
	v_mov_b32_e32 v69, v74
	v_pk_mul_f32 v[76:77], v[70:71], v[70:71]
	v_pk_mul_f32 v[74:75], v[68:69], v[68:69]
	v_fmac_f32_e32 v28, 0xba000000, v14
	v_pk_mov_b32 v[78:79], v[74:75], v[76:77] op_sel:[1,0]
	v_mov_b32_e32 v75, v77
	v_fmac_f32_e32 v29, 0xba000000, v14
	v_fmac_f32_e32 v30, 0xba000000, v14
	v_mul_f32_e32 v12, v28, v28
	v_pk_add_f32 v[74:75], v[78:79], v[74:75]
	v_fmac_f32_e32 v31, 0xba000000, v14
	v_pk_fma_f32 v[76:77], v[28:29], v[28:29], v[12:13] op_sel_hi:[1,1,0]
	v_mul_f32_e32 v12, v30, v30
	v_pk_add_f32 v[64:65], v[64:65], v[64:65] op_sel_hi:[0,1]
	v_pk_add_f32 v[74:75], v[74:75], v[74:75] op_sel_hi:[0,1]
	v_pk_fma_f32 v[78:79], v[30:31], v[30:31], v[12:13] op_sel_hi:[1,1,0]
	v_fmac_f32_e32 v25, 0xba000000, v14
	v_fmac_f32_e32 v27, 0xba000000, v14
	v_fmac_f32_e32 v21, 0xba000000, v14
	v_fmac_f32_e32 v23, 0xba000000, v14
	v_mul_f32_e32 v76, v23, v23
	v_mul_f32_e32 v78, v21, v21
	v_mul_f32_e32 v74, v27, v27
	v_mul_f32_e32 v64, v25, v25
	v_pk_add_f32 v[76:77], v[76:77], v[78:79]
	v_pk_add_f32 v[64:65], v[74:75], v[64:65]
	v_fmac_f32_e32 v72, 0xba000000, v14
	v_pk_add_f32 v[64:65], v[76:77], v[64:65]
	v_fmac_f32_e32 v73, 0xba000000, v14
	v_fmac_f32_e32 v61, 0xba000000, v14
	v_pk_add_f32 v[74:75], v[64:65], v[64:65] op_sel_hi:[0,1]
	v_fmac_f32_e32 v60, 0xba000000, v14
	v_mov_b32_e32 v64, v61
	v_mov_b32_e32 v65, v73
	v_mov_b32_e32 v61, v72
	v_pk_mul_f32 v[76:77], v[64:65], v[64:65]
	v_pk_mul_f32 v[72:73], v[60:61], v[60:61]
	v_fmac_f32_e32 v16, 0xba000000, v14
	v_pk_mov_b32 v[78:79], v[72:73], v[76:77] op_sel:[1,0]
	v_mov_b32_e32 v73, v77
	v_fmac_f32_e32 v17, 0xba000000, v14
	v_fmac_f32_e32 v18, 0xba000000, v14
	v_mul_f32_e32 v12, v16, v16
	v_pk_add_f32 v[72:73], v[78:79], v[72:73]
	v_fmac_f32_e32 v19, 0xba000000, v14
	v_pk_fma_f32 v[76:77], v[16:17], v[16:17], v[12:13] op_sel_hi:[1,1,0]
	v_mul_f32_e32 v12, v18, v18
	v_pk_add_f32 v[72:73], v[72:73], v[72:73] op_sel_hi:[0,1]
	v_pk_fma_f32 v[78:79], v[18:19], v[18:19], v[12:13] op_sel_hi:[1,1,0]
	v_fmac_f32_e32 v13, 0xba000000, v14
	v_fmac_f32_e32 v15, 0xba000000, v14
	v_fmac_f32_e32 v11, 0xba000000, v14
	v_fmac_f32_e32 v10, 0xba000000, v14
	v_mul_f32_e32 v72, v15, v15
	v_mul_f32_e32 v74, v13, v13
	v_mul_f32_e32 v76, v10, v10
	v_mul_f32_e32 v78, v11, v11
	v_pk_add_f32 v[72:73], v[72:73], v[74:75]
	v_lshlrev_b32_e32 v74, 2, v1
	v_pk_add_f32 v[76:77], v[76:77], v[78:79]
	v_ashrrev_i32_e32 v75, 31, v74
	v_pk_add_f32 v[72:73], v[76:77], v[72:73]
	v_lshlrev_b64 v[76:77], 2, v[74:75]
	v_lshl_add_u64 v[80:81], s[12:13], 0, v[76:77]
	v_lshl_add_u64 v[78:79], s[14:15], 0, v[76:77]
	global_load_dwordx4 v[84:87], v[80:81], off
	global_load_dwordx4 v[96:99], v[78:79], off
	v_add_f32_e32 v12, v72, v73
	ds_bpermute_b32 v14, v90, v12
	s_waitcnt lgkmcnt(0)
	v_add_f32_e32 v12, v12, v14
	ds_bpermute_b32 v14, v91, v12
	s_waitcnt lgkmcnt(0)
	v_add_f32_e32 v12, v12, v14
	ds_bpermute_b32 v14, v92, v12
	s_waitcnt lgkmcnt(0)
	v_add_f32_e32 v12, v12, v14
	ds_bpermute_b32 v14, v93, v12
	s_waitcnt lgkmcnt(0)
	v_add_f32_e32 v12, v12, v14
	ds_bpermute_b32 v14, v94, v12
	s_waitcnt lgkmcnt(0)
	v_add_f32_e32 v12, v12, v14
	ds_bpermute_b32 v14, v95, v12
	s_waitcnt lgkmcnt(0)
	v_add_f32_e32 v12, v12, v14
	v_fmamk_f32 v12, v12, 0x3a000000, v250
	v_cmp_gt_f32_e32 vcc, s96, v12
	v_mul_f32_e32 v14, 0x4f800000, v12
	s_nop 0
	v_cndmask_b32_e32 v12, v12, v14, vcc
	v_sqrt_f32_e32 v14, v12
	s_nop 0
	v_add_u32_e32 v20, -1, v14
	v_fma_f32 v22, -v20, v14, v12
	v_cmp_ge_f32_e64 s[10:11], 0, v22
	v_add_u32_e32 v22, 1, v14
	s_nop 0
	v_cndmask_b32_e64 v20, v14, v20, s[10:11]
	v_fma_f32 v14, -v22, v14, v12
	v_cmp_lt_f32_e64 s[10:11], 0, v14
	s_nop 1
	v_cndmask_b32_e64 v14, v20, v22, s[10:11]
	v_mul_f32_e32 v20, 0x37800000, v14
	v_cndmask_b32_e32 v14, v14, v20, vcc
	v_cmp_class_f32_e32 vcc, v12, v251
	s_nop 1
	v_cndmask_b32_e32 v12, v14, v12, vcc
	v_div_scale_f32 v14, s[8:9], v12, v12, 1.0
	v_rcp_f32_e32 v20, v14
	s_mov_b64 s[8:9], 0x25d1e000
	v_fma_f32 v22, -v14, v20, 1.0
	v_fmac_f32_e32 v20, v22, v20
	v_div_scale_f32 v22, vcc, 1.0, v12, 1.0
	v_mul_f32_e32 v24, v22, v20
	v_fma_f32 v26, -v14, v24, v22
	v_fmac_f32_e32 v24, v26, v20
	v_fma_f32 v14, -v14, v24, v22
	v_div_fmas_f32 v14, v14, v20, v24
	v_div_fixup_f32 v14, v14, v12, 1.0
	v_pk_mul_f32 v[56:57], v[56:57], v[14:15] op_sel_hi:[1,0]
	v_pk_mul_f32 v[58:59], v[58:59], v[14:15] op_sel_hi:[1,0]
	s_waitcnt vmcnt(0)
	v_pk_fma_f32 v[96:97], v[84:85], v[56:57], v[96:97]
	v_lshl_add_u64 v[56:57], s[40:41], 0, v[76:77]
	v_pk_fma_f32 v[98:99], v[86:87], v[58:59], v[98:99]
	v_lshl_add_u64 v[86:87], v[56:57], 0, s[8:9]
	s_mov_b32 s8, 0x25d1f000
	v_add_co_u32_e32 v72, vcc, s8, v56
	v_lshl_add_u64 v[84:85], s[20:21], 0, v[76:77]
	s_nop 0
	v_addc_co_u32_e32 v73, vcc, 0, v57, vcc
	global_load_dwordx4 v[56:59], v[84:85], off
	v_lshl_add_u64 v[76:77], s[18:19], 0, v[76:77]
	global_load_dwordx4 v[100:103], v[76:77], off
	s_mov_b64 s[8:9], 0xcc1b000
	global_store_dwordx4 v[72:73], v[96:99], off offset:-4096
	v_pk_mul_f32 v[66:67], v[66:67], v[14:15] op_sel_hi:[1,0]
	v_pk_mul_f32 v[62:63], v[62:63], v[14:15] op_sel_hi:[1,0]
	v_pk_mul_f32 v[70:71], v[70:71], v[14:15] op_sel_hi:[1,0]
	v_pk_mul_f32 v[68:69], v[68:69], v[14:15] op_sel_hi:[1,0]
	v_pk_mul_f32 v[30:31], v[30:31], v[14:15] op_sel_hi:[1,0]
	v_pk_mul_f32 v[28:29], v[28:29], v[14:15] op_sel_hi:[1,0]
	v_mov_b32_e32 v24, v27
	v_pk_mul_f32 v[24:25], v[24:25], v[14:15] op_sel_hi:[1,0]
	v_pk_mul_f32 v[64:65], v[64:65], v[14:15] op_sel_hi:[1,0]
	v_pk_mul_f32 v[60:61], v[60:61], v[14:15] op_sel_hi:[1,0]
	v_pk_mul_f32 v[18:19], v[18:19], v[14:15] op_sel_hi:[1,0]
	v_pk_mul_f32 v[16:17], v[16:17], v[14:15] op_sel_hi:[1,0]
	v_pk_mul_f32 v[10:11], v[10:11], v[14:15] op_sel_hi:[1,0]
	s_waitcnt vmcnt(2)
	v_pk_add_f32 v[58:59], v[58:59], 1.0 op_sel_hi:[1,0]
	v_pk_add_f32 v[88:89], v[56:57], 1.0 op_sel_hi:[1,0]
	s_waitcnt vmcnt(1)
	v_pk_fma_f32 v[56:57], v[58:59], v[98:99], v[102:103]
	v_pk_fma_f32 v[58:59], v[88:89], v[96:97], v[100:101]
	v_lshl_add_u64 v[96:97], v[74:75], 1, s[16:17]
	v_cvt_pk_bf16_f32 v88, v58, v59
	v_lshl_add_u64 v[74:75], v[96:97], 0, s[8:9]
	v_add_co_u32_e32 v96, vcc, s61, v96
	v_cvt_pk_bf16_f32 v89, v56, v57
	s_nop 0
	v_addc_co_u32_e32 v97, vcc, 0, v97, vcc
	global_store_dwordx2 v[96:97], v[88:89], off
	global_load_dwordx4 v[96:99], v[80:81], off offset:1024
	s_nop 0
	global_load_dwordx4 v[100:103], v[78:79], off offset:1024
	s_waitcnt vmcnt(0)
	v_pk_fma_f32 v[96:97], v[96:97], v[62:63], v[100:101]
	v_pk_fma_f32 v[98:99], v[98:99], v[66:67], v[102:103]
	global_store_dwordx4 v[86:87], v[96:99], off offset:1024
	global_load_dwordx4 v[100:103], v[84:85], off offset:1024
	global_load_dwordx4 v[104:107], v[76:77], off offset:1024
	s_waitcnt vmcnt(1)
	v_pk_add_f32 v[66:67], v[100:101], 1.0 op_sel_hi:[1,0]
	s_waitcnt vmcnt(0)
	v_pk_fma_f32 v[66:67], v[66:67], v[96:97], v[104:105]
	v_pk_add_f32 v[62:63], v[102:103], 1.0 op_sel_hi:[1,0]
	s_nop 0
	v_pk_fma_f32 v[62:63], v[62:63], v[98:99], v[106:107]
	v_cvt_pk_bf16_f32 v88, v66, v67
	v_cvt_pk_bf16_f32 v89, v62, v63
	global_store_dwordx2 v[74:75], v[88:89], off offset:512
	global_load_dwordx4 v[96:99], v[80:81], off offset:2048
	global_load_dwordx4 v[100:103], v[78:79], off offset:2048
	s_waitcnt vmcnt(0)
	v_pk_fma_f32 v[96:97], v[96:97], v[68:69], v[100:101]
	v_pk_fma_f32 v[98:99], v[98:99], v[70:71], v[102:103]
	global_store_dwordx4 v[86:87], v[96:99], off offset:2048
	global_load_dwordx4 v[68:71], v[84:85], off offset:2048
	global_load_dwordx4 v[100:103], v[76:77], off offset:2048
	s_waitcnt vmcnt(1)
	v_pk_add_f32 v[70:71], v[70:71], 1.0 op_sel_hi:[1,0]
	v_pk_add_f32 v[88:89], v[68:69], 1.0 op_sel_hi:[1,0]
	s_waitcnt vmcnt(0)
	v_pk_fma_f32 v[68:69], v[70:71], v[98:99], v[102:103]
	v_pk_fma_f32 v[70:71], v[88:89], v[96:97], v[100:101]
	s_nop 0
	v_cvt_pk_bf16_f32 v88, v70, v71
	v_cvt_pk_bf16_f32 v89, v68, v69
	global_store_dwordx2 v[74:75], v[88:89], off offset:1024
	global_load_dwordx4 v[96:99], v[80:81], off offset:3072
	global_load_dwordx4 v[100:103], v[78:79], off offset:3072
	v_add_co_u32_e32 v80, vcc, s82, v80
	s_waitcnt vmcnt(0)
	v_pk_fma_f32 v[96:97], v[96:97], v[28:29], v[100:101]
	v_pk_fma_f32 v[98:99], v[98:99], v[30:31], v[102:103]
	global_store_dwordx4 v[86:87], v[96:99], off offset:3072
	global_load_dwordx4 v[28:31], v[84:85], off offset:3072
	s_nop 0
	global_load_dwordx4 v[86:89], v[76:77], off offset:3072
	v_addc_co_u32_e32 v81, vcc, 0, v81, vcc
	v_add_co_u32_e32 v78, vcc, s82, v78
	s_waitcnt vmcnt(1)
	v_pk_add_f32 v[30:31], v[30:31], 1.0 op_sel_hi:[1,0]
	v_pk_add_f32 v[100:101], v[28:29], 1.0 op_sel_hi:[1,0]
	s_waitcnt vmcnt(0)
	v_pk_fma_f32 v[28:29], v[30:31], v[98:99], v[88:89]
	v_pk_fma_f32 v[30:31], v[100:101], v[96:97], v[86:87]
	v_addc_co_u32_e32 v79, vcc, 0, v79, vcc
	v_cvt_pk_bf16_f32 v86, v30, v31
	v_cvt_pk_bf16_f32 v87, v28, v29
	global_store_dwordx2 v[74:75], v[86:87], off offset:1536
	global_load_dwordx4 v[86:89], v[80:81], off
	global_load_dwordx4 v[96:99], v[78:79], off
	v_add_co_u32_e32 v84, vcc, s82, v84
	v_mov_b32_e32 v20, v23
	s_nop 0
	v_addc_co_u32_e32 v85, vcc, 0, v85, vcc
	v_pk_mul_f32 v[20:21], v[20:21], v[14:15] op_sel_hi:[1,0]
	v_add_co_u32_e32 v76, vcc, s82, v76
	s_waitcnt vmcnt(0)
	v_pk_fma_f32 v[22:23], v[20:21], v[86:87], v[96:97]
	v_pk_fma_f32 v[24:25], v[24:25], v[88:89], v[98:99]
	global_load_dwordx4 v[86:89], v[84:85], off
	v_addc_co_u32_e32 v77, vcc, 0, v77, vcc
	global_load_dwordx4 v[96:99], v[76:77], off
	s_waitcnt vmcnt(1)
	v_pk_add_f32 v[26:27], v[86:87], 1.0 op_sel_hi:[1,0]
	global_store_dwordx4 v[72:73], v[22:25], off
	v_pk_add_f32 v[20:21], v[88:89], 1.0 op_sel_hi:[1,0]
	s_waitcnt vmcnt(1)
	v_pk_fma_f32 v[22:23], v[22:23], v[26:27], v[96:97]
	v_pk_fma_f32 v[20:21], v[24:25], v[20:21], v[98:99]
	v_cvt_pk_bf16_f32 v24, v22, v23
	v_cvt_pk_bf16_f32 v25, v20, v21
	global_store_dwordx2 v[74:75], v[24:25], off offset:2048
	global_load_dwordx4 v[24:27], v[80:81], off offset:1024
	s_nop 0
	global_load_dwordx4 v[86:89], v[78:79], off offset:1024
	s_waitcnt vmcnt(0)
	v_pk_fma_f32 v[86:87], v[60:61], v[24:25], v[86:87]
	v_pk_fma_f32 v[88:89], v[64:65], v[26:27], v[88:89]
	global_store_dwordx4 v[72:73], v[86:89], off offset:1024
	global_load_dwordx4 v[24:27], v[84:85], off offset:1024
	global_load_dwordx4 v[96:99], v[76:77], off offset:1024
	s_waitcnt vmcnt(1)
	v_pk_add_f32 v[26:27], v[26:27], 1.0 op_sel_hi:[1,0]
	v_pk_add_f32 v[60:61], v[24:25], 1.0 op_sel_hi:[1,0]
	s_waitcnt vmcnt(0)
	v_pk_fma_f32 v[24:25], v[88:89], v[26:27], v[98:99]
	v_pk_fma_f32 v[26:27], v[86:87], v[60:61], v[96:97]
	v_cvt_pk_bf16_f32 v60, v26, v27
	v_cvt_pk_bf16_f32 v61, v24, v25
	global_store_dwordx2 v[74:75], v[60:61], off offset:2560
	global_load_dwordx4 v[86:89], v[80:81], off offset:2048
	global_load_dwordx4 v[96:99], v[78:79], off offset:2048
	s_waitcnt vmcnt(0)
	v_pk_fma_f32 v[86:87], v[16:17], v[86:87], v[96:97]
	v_pk_fma_f32 v[88:89], v[18:19], v[88:89], v[98:99]
	global_store_dwordx4 v[72:73], v[86:89], off offset:2048
	global_load_dwordx4 v[16:19], v[84:85], off offset:2048
	global_load_dwordx4 v[96:99], v[76:77], off offset:2048
	s_waitcnt vmcnt(1)
	v_pk_add_f32 v[18:19], v[18:19], 1.0 op_sel_hi:[1,0]
	v_pk_add_f32 v[60:61], v[16:17], 1.0 op_sel_hi:[1,0]
	s_waitcnt vmcnt(0)
	v_pk_fma_f32 v[16:17], v[88:89], v[18:19], v[98:99]
	v_pk_fma_f32 v[18:19], v[86:87], v[60:61], v[96:97]
	v_cvt_pk_bf16_f32 v60, v18, v19
	v_cvt_pk_bf16_f32 v61, v16, v17
	global_store_dwordx2 v[74:75], v[60:61], off offset:3072
	global_load_dwordx4 v[86:89], v[80:81], off offset:3072
	s_nop 0
	global_load_dwordx4 v[78:81], v[78:79], off offset:3072
	v_mov_b32_e32 v12, v15
	v_pk_mul_f32 v[60:61], v[12:13], v[14:15] op_sel_hi:[1,0]
	s_waitcnt vmcnt(0)
	v_pk_fma_f32 v[12:13], v[10:11], v[86:87], v[78:79]
	v_pk_fma_f32 v[14:15], v[60:61], v[88:89], v[80:81]
	global_store_dwordx4 v[72:73], v[12:15], off offset:3072
	global_load_dwordx4 v[78:81], v[84:85], off offset:3072
	s_nop 0
	global_load_dwordx4 v[84:87], v[76:77], off offset:3072
	s_waitcnt vmcnt(1)
	v_pk_add_f32 v[60:61], v[78:79], 1.0 op_sel_hi:[1,0]
	v_pk_add_f32 v[10:11], v[80:81], 1.0 op_sel_hi:[1,0]
	s_waitcnt vmcnt(0)
	v_pk_fma_f32 v[12:13], v[12:13], v[60:61], v[84:85]
	v_pk_fma_f32 v[10:11], v[14:15], v[10:11], v[86:87]
	v_cvt_pk_bf16_f32 v14, v12, v13
	v_cvt_pk_bf16_f32 v15, v10, v11
	global_store_dwordx2 v[74:75], v[14:15], off offset:3584
	s_nop 0
	v_lshl_add_u32 v103, v1, 4, 0
	ds_read_b128 v[72:75], v103
	v_add_u32_e32 v80, 0x18400, v103
	s_waitcnt lgkmcnt(0)
	v_pk_fma_f32 v[14:15], v[4:5], v[72:73], 0 op_sel_hi:[1,1,0]
	v_pk_fma_f32 v[60:61], v[58:59], v[72:73], 0 op_sel_hi:[1,1,0]
	v_pk_fma_f32 v[14:15], v[2:3], v[74:75], v[14:15]
	v_pk_fma_f32 v[60:61], v[56:57], v[74:75], v[60:61]
	ds_read_b128 v[72:75], v103 offset:1024
	s_waitcnt lgkmcnt(0)
	v_pk_fma_f32 v[14:15], v[8:9], v[72:73], v[14:15]
	v_pk_fma_f32 v[60:61], v[66:67], v[72:73], v[60:61]
	v_pk_fma_f32 v[14:15], v[6:7], v[74:75], v[14:15]
	v_pk_fma_f32 v[60:61], v[62:63], v[74:75], v[60:61]
	ds_read_b128 v[72:75], v103 offset:2048
	s_waitcnt lgkmcnt(0)
	v_pk_fma_f32 v[14:15], v[34:35], v[72:73], v[14:15]
	v_pk_fma_f32 v[60:61], v[70:71], v[72:73], v[60:61]
	v_pk_fma_f32 v[14:15], v[32:33], v[74:75], v[14:15]
	v_pk_fma_f32 v[60:61], v[68:69], v[74:75], v[60:61]
	ds_read_b128 v[72:75], v103 offset:3072
	s_waitcnt lgkmcnt(0)
	v_pk_fma_f32 v[14:15], v[38:39], v[72:73], v[14:15]
	v_pk_fma_f32 v[60:61], v[30:31], v[72:73], v[60:61]
	v_pk_fma_f32 v[14:15], v[36:37], v[74:75], v[14:15]
	v_pk_fma_f32 v[60:61], v[28:29], v[74:75], v[60:61]
	ds_read_b128 v[72:75], v103 offset:4096
	s_waitcnt lgkmcnt(0)
	v_pk_fma_f32 v[14:15], v[42:43], v[72:73], v[14:15]
	v_pk_fma_f32 v[60:61], v[22:23], v[72:73], v[60:61]
	v_pk_fma_f32 v[14:15], v[40:41], v[74:75], v[14:15]
	v_pk_fma_f32 v[60:61], v[20:21], v[74:75], v[60:61]
	ds_read_b128 v[72:75], v103 offset:5120
	s_waitcnt lgkmcnt(0)
	v_pk_fma_f32 v[14:15], v[46:47], v[72:73], v[14:15]
	v_pk_fma_f32 v[60:61], v[26:27], v[72:73], v[60:61]
	v_pk_fma_f32 v[14:15], v[44:45], v[74:75], v[14:15]
	v_pk_fma_f32 v[60:61], v[24:25], v[74:75], v[60:61]
	ds_read_b128 v[72:75], v103 offset:6144
	s_waitcnt lgkmcnt(0)
	v_pk_fma_f32 v[14:15], v[50:51], v[72:73], v[14:15]
	v_pk_fma_f32 v[60:61], v[18:19], v[72:73], v[60:61]
	v_pk_fma_f32 v[14:15], v[48:49], v[74:75], v[14:15]
	v_pk_fma_f32 v[60:61], v[16:17], v[74:75], v[60:61]
	ds_read_b128 v[72:75], v103 offset:7168
	s_waitcnt lgkmcnt(0)
	v_pk_fma_f32 v[14:15], v[54:55], v[72:73], v[14:15]
	v_pk_fma_f32 v[60:61], v[12:13], v[72:73], v[60:61]
	v_pk_fma_f32 v[14:15], v[52:53], v[74:75], v[14:15]
	v_pk_fma_f32 v[60:61], v[10:11], v[74:75], v[60:61]
	v_add_f32_e32 v81, v14, v15
	v_add_f32_e32 v14, v60, v61
	ds_read_b128 v[72:75], v103 offset:8192
	s_waitcnt lgkmcnt(0)
	v_pk_fma_f32 v[60:61], v[4:5], v[72:73], 0 op_sel_hi:[1,1,0]
	v_pk_fma_f32 v[64:65], v[58:59], v[72:73], 0 op_sel_hi:[1,1,0]
	v_pk_fma_f32 v[60:61], v[2:3], v[74:75], v[60:61]
	v_pk_fma_f32 v[64:65], v[56:57], v[74:75], v[64:65]
	ds_read_b128 v[72:75], v103 offset:9216
	s_waitcnt lgkmcnt(0)
	v_pk_fma_f32 v[60:61], v[8:9], v[72:73], v[60:61]
	v_pk_fma_f32 v[64:65], v[66:67], v[72:73], v[64:65]
	v_pk_fma_f32 v[60:61], v[6:7], v[74:75], v[60:61]
	v_pk_fma_f32 v[64:65], v[62:63], v[74:75], v[64:65]
	ds_read_b128 v[72:75], v103 offset:10240
	s_waitcnt lgkmcnt(0)
	v_pk_fma_f32 v[60:61], v[34:35], v[72:73], v[60:61]
	v_pk_fma_f32 v[64:65], v[70:71], v[72:73], v[64:65]
	v_pk_fma_f32 v[60:61], v[32:33], v[74:75], v[60:61]
	v_pk_fma_f32 v[64:65], v[68:69], v[74:75], v[64:65]
	ds_read_b128 v[72:75], v103 offset:11264
	s_waitcnt lgkmcnt(0)
	v_pk_fma_f32 v[60:61], v[38:39], v[72:73], v[60:61]
	v_pk_fma_f32 v[64:65], v[30:31], v[72:73], v[64:65]
	v_pk_fma_f32 v[60:61], v[36:37], v[74:75], v[60:61]
	v_pk_fma_f32 v[64:65], v[28:29], v[74:75], v[64:65]
	ds_read_b128 v[72:75], v103 offset:12288
	s_waitcnt lgkmcnt(0)
	v_pk_fma_f32 v[60:61], v[42:43], v[72:73], v[60:61]
	v_pk_fma_f32 v[64:65], v[22:23], v[72:73], v[64:65]
	v_pk_fma_f32 v[60:61], v[40:41], v[74:75], v[60:61]
	v_pk_fma_f32 v[64:65], v[20:21], v[74:75], v[64:65]
	ds_read_b128 v[72:75], v103 offset:13312
	s_waitcnt lgkmcnt(0)
	v_pk_fma_f32 v[60:61], v[46:47], v[72:73], v[60:61]
	v_pk_fma_f32 v[64:65], v[26:27], v[72:73], v[64:65]
	v_pk_fma_f32 v[60:61], v[44:45], v[74:75], v[60:61]
	v_pk_fma_f32 v[64:65], v[24:25], v[74:75], v[64:65]
	ds_read_b128 v[72:75], v103 offset:14336
	s_waitcnt lgkmcnt(0)
	v_pk_fma_f32 v[60:61], v[50:51], v[72:73], v[60:61]
	v_pk_fma_f32 v[64:65], v[18:19], v[72:73], v[64:65]
	v_pk_fma_f32 v[60:61], v[48:49], v[74:75], v[60:61]
	v_pk_fma_f32 v[64:65], v[16:17], v[74:75], v[64:65]
	ds_read_b128 v[72:75], v103 offset:15360
	s_waitcnt lgkmcnt(0)
	v_pk_fma_f32 v[60:61], v[54:55], v[72:73], v[60:61]
	v_pk_fma_f32 v[64:65], v[12:13], v[72:73], v[64:65]
	v_pk_fma_f32 v[60:61], v[52:53], v[74:75], v[60:61]
	v_pk_fma_f32 v[64:65], v[10:11], v[74:75], v[64:65]
	v_add_f32_e32 v82, v60, v61
	v_add_f32_e32 v15, v64, v65
	ds_read_b128 v[72:75], v103 offset:16384
	s_waitcnt lgkmcnt(0)
	v_pk_fma_f32 v[60:61], v[4:5], v[72:73], 0 op_sel_hi:[1,1,0]
	v_pk_fma_f32 v[64:65], v[58:59], v[72:73], 0 op_sel_hi:[1,1,0]
	v_pk_fma_f32 v[60:61], v[2:3], v[74:75], v[60:61]
	v_pk_fma_f32 v[64:65], v[56:57], v[74:75], v[64:65]
	ds_read_b128 v[72:75], v103 offset:17408
	s_waitcnt lgkmcnt(0)
	v_pk_fma_f32 v[60:61], v[8:9], v[72:73], v[60:61]
	v_pk_fma_f32 v[64:65], v[66:67], v[72:73], v[64:65]
	v_pk_fma_f32 v[60:61], v[6:7], v[74:75], v[60:61]
	v_pk_fma_f32 v[64:65], v[62:63], v[74:75], v[64:65]
	ds_read_b128 v[72:75], v103 offset:18432
	s_waitcnt lgkmcnt(0)
	v_pk_fma_f32 v[60:61], v[34:35], v[72:73], v[60:61]
	v_pk_fma_f32 v[64:65], v[70:71], v[72:73], v[64:65]
	v_pk_fma_f32 v[60:61], v[32:33], v[74:75], v[60:61]
	v_pk_fma_f32 v[64:65], v[68:69], v[74:75], v[64:65]
	ds_read_b128 v[72:75], v103 offset:19456
	s_waitcnt lgkmcnt(0)
	v_pk_fma_f32 v[60:61], v[38:39], v[72:73], v[60:61]
	v_pk_fma_f32 v[64:65], v[30:31], v[72:73], v[64:65]
	v_pk_fma_f32 v[60:61], v[36:37], v[74:75], v[60:61]
	v_pk_fma_f32 v[64:65], v[28:29], v[74:75], v[64:65]
	ds_read_b128 v[72:75], v103 offset:20480
	s_waitcnt lgkmcnt(0)
	v_pk_fma_f32 v[60:61], v[42:43], v[72:73], v[60:61]
	v_pk_fma_f32 v[64:65], v[22:23], v[72:73], v[64:65]
	v_pk_fma_f32 v[60:61], v[40:41], v[74:75], v[60:61]
	v_pk_fma_f32 v[64:65], v[20:21], v[74:75], v[64:65]
	ds_read_b128 v[72:75], v103 offset:21504
	s_waitcnt lgkmcnt(0)
	v_pk_fma_f32 v[60:61], v[46:47], v[72:73], v[60:61]
	v_pk_fma_f32 v[64:65], v[26:27], v[72:73], v[64:65]
	v_pk_fma_f32 v[60:61], v[44:45], v[74:75], v[60:61]
	v_pk_fma_f32 v[64:65], v[24:25], v[74:75], v[64:65]
	ds_read_b128 v[72:75], v103 offset:22528
	s_waitcnt lgkmcnt(0)
	v_pk_fma_f32 v[60:61], v[50:51], v[72:73], v[60:61]
	v_pk_fma_f32 v[64:65], v[18:19], v[72:73], v[64:65]
	v_pk_fma_f32 v[60:61], v[48:49], v[74:75], v[60:61]
	v_pk_fma_f32 v[64:65], v[16:17], v[74:75], v[64:65]
	ds_read_b128 v[72:75], v103 offset:23552
	s_waitcnt lgkmcnt(0)
	v_pk_fma_f32 v[60:61], v[54:55], v[72:73], v[60:61]
	v_pk_fma_f32 v[64:65], v[12:13], v[72:73], v[64:65]
	v_pk_fma_f32 v[60:61], v[52:53], v[74:75], v[60:61]
	v_pk_fma_f32 v[64:65], v[10:11], v[74:75], v[64:65]
	v_add_f32_e32 v84, v60, v61
	v_add_f32_e32 v60, v64, v65
	ds_read_b128 v[72:75], v103 offset:24576
	s_waitcnt lgkmcnt(0)
	v_pk_fma_f32 v[64:65], v[4:5], v[72:73], 0 op_sel_hi:[1,1,0]
	v_pk_fma_f32 v[72:73], v[58:59], v[72:73], 0 op_sel_hi:[1,1,0]
	v_pk_fma_f32 v[64:65], v[2:3], v[74:75], v[64:65]
	v_pk_fma_f32 v[76:77], v[56:57], v[74:75], v[72:73]
	ds_read_b128 v[72:75], v103 offset:25600
	s_waitcnt lgkmcnt(0)
	v_pk_fma_f32 v[64:65], v[8:9], v[72:73], v[64:65]
	v_pk_fma_f32 v[72:73], v[66:67], v[72:73], v[76:77]
	v_pk_fma_f32 v[64:65], v[6:7], v[74:75], v[64:65]
	v_pk_fma_f32 v[76:77], v[62:63], v[74:75], v[72:73]
	ds_read_b128 v[72:75], v103 offset:26624
	s_waitcnt lgkmcnt(0)
	v_pk_fma_f32 v[64:65], v[34:35], v[72:73], v[64:65]
	v_pk_fma_f32 v[72:73], v[70:71], v[72:73], v[76:77]
	v_pk_fma_f32 v[64:65], v[32:33], v[74:75], v[64:65]
	v_pk_fma_f32 v[76:77], v[68:69], v[74:75], v[72:73]
	ds_read_b128 v[72:75], v103 offset:27648
	s_waitcnt lgkmcnt(0)
	v_pk_fma_f32 v[64:65], v[38:39], v[72:73], v[64:65]
	v_pk_fma_f32 v[72:73], v[30:31], v[72:73], v[76:77]
	v_pk_fma_f32 v[64:65], v[36:37], v[74:75], v[64:65]
	v_pk_fma_f32 v[76:77], v[28:29], v[74:75], v[72:73]
	ds_read_b128 v[72:75], v103 offset:28672
	s_waitcnt lgkmcnt(0)
	v_pk_fma_f32 v[64:65], v[42:43], v[72:73], v[64:65]
	v_pk_fma_f32 v[72:73], v[22:23], v[72:73], v[76:77]
	v_pk_fma_f32 v[64:65], v[40:41], v[74:75], v[64:65]
	v_pk_fma_f32 v[76:77], v[20:21], v[74:75], v[72:73]
	ds_read_b128 v[72:75], v103 offset:29696
	s_waitcnt lgkmcnt(0)
	v_pk_fma_f32 v[64:65], v[46:47], v[72:73], v[64:65]
	v_pk_fma_f32 v[72:73], v[26:27], v[72:73], v[76:77]
	v_pk_fma_f32 v[64:65], v[44:45], v[74:75], v[64:65]
	v_pk_fma_f32 v[76:77], v[24:25], v[74:75], v[72:73]
	ds_read_b128 v[72:75], v103 offset:30720
	s_waitcnt lgkmcnt(0)
	v_pk_fma_f32 v[64:65], v[50:51], v[72:73], v[64:65]
	v_pk_fma_f32 v[72:73], v[18:19], v[72:73], v[76:77]
	v_pk_fma_f32 v[64:65], v[48:49], v[74:75], v[64:65]
	v_pk_fma_f32 v[76:77], v[16:17], v[74:75], v[72:73]
	ds_read_b128 v[72:75], v103 offset:31744
	s_waitcnt lgkmcnt(0)
	v_pk_fma_f32 v[64:65], v[54:55], v[72:73], v[64:65]
	v_pk_fma_f32 v[72:73], v[12:13], v[72:73], v[76:77]
	v_pk_fma_f32 v[64:65], v[52:53], v[74:75], v[64:65]
	v_pk_fma_f32 v[72:73], v[10:11], v[74:75], v[72:73]
	v_add_f32_e32 v85, v64, v65
	v_add_f32_e32 v61, v72, v73
	ds_read_b128 v[72:75], v103 offset:32768
	s_waitcnt lgkmcnt(0)
	v_pk_fma_f32 v[64:65], v[4:5], v[72:73], 0 op_sel_hi:[1,1,0]
	v_pk_fma_f32 v[72:73], v[58:59], v[72:73], 0 op_sel_hi:[1,1,0]
	v_pk_fma_f32 v[64:65], v[2:3], v[74:75], v[64:65]
	v_pk_fma_f32 v[76:77], v[56:57], v[74:75], v[72:73]
	ds_read_b128 v[72:75], v103 offset:33792
	s_waitcnt lgkmcnt(0)
	v_pk_fma_f32 v[64:65], v[8:9], v[72:73], v[64:65]
	v_pk_fma_f32 v[72:73], v[66:67], v[72:73], v[76:77]
	v_pk_fma_f32 v[64:65], v[6:7], v[74:75], v[64:65]
	v_pk_fma_f32 v[76:77], v[62:63], v[74:75], v[72:73]
	ds_read_b128 v[72:75], v103 offset:34816
	s_waitcnt lgkmcnt(0)
	v_pk_fma_f32 v[64:65], v[34:35], v[72:73], v[64:65]
	v_pk_fma_f32 v[72:73], v[70:71], v[72:73], v[76:77]
	v_pk_fma_f32 v[64:65], v[32:33], v[74:75], v[64:65]
	v_pk_fma_f32 v[76:77], v[68:69], v[74:75], v[72:73]
	ds_read_b128 v[72:75], v103 offset:35840
	s_waitcnt lgkmcnt(0)
	v_pk_fma_f32 v[64:65], v[38:39], v[72:73], v[64:65]
	v_pk_fma_f32 v[72:73], v[30:31], v[72:73], v[76:77]
	v_pk_fma_f32 v[64:65], v[36:37], v[74:75], v[64:65]
	v_pk_fma_f32 v[76:77], v[28:29], v[74:75], v[72:73]
	ds_read_b128 v[72:75], v103 offset:36864
	s_waitcnt lgkmcnt(0)
	v_pk_fma_f32 v[64:65], v[42:43], v[72:73], v[64:65]
	v_pk_fma_f32 v[72:73], v[22:23], v[72:73], v[76:77]
	v_pk_fma_f32 v[64:65], v[40:41], v[74:75], v[64:65]
	v_pk_fma_f32 v[76:77], v[20:21], v[74:75], v[72:73]
	ds_read_b128 v[72:75], v103 offset:37888
	s_waitcnt lgkmcnt(0)
	v_pk_fma_f32 v[64:65], v[46:47], v[72:73], v[64:65]
	v_pk_fma_f32 v[72:73], v[26:27], v[72:73], v[76:77]
	v_pk_fma_f32 v[64:65], v[44:45], v[74:75], v[64:65]
	v_pk_fma_f32 v[76:77], v[24:25], v[74:75], v[72:73]
	ds_read_b128 v[72:75], v103 offset:38912
	s_waitcnt lgkmcnt(0)
	v_pk_fma_f32 v[64:65], v[50:51], v[72:73], v[64:65]
	v_pk_fma_f32 v[72:73], v[18:19], v[72:73], v[76:77]
	v_pk_fma_f32 v[64:65], v[48:49], v[74:75], v[64:65]
	v_pk_fma_f32 v[76:77], v[16:17], v[74:75], v[72:73]
	ds_read_b128 v[72:75], v103 offset:39936
	s_waitcnt lgkmcnt(0)
	v_pk_fma_f32 v[64:65], v[54:55], v[72:73], v[64:65]
	v_pk_fma_f32 v[72:73], v[12:13], v[72:73], v[76:77]
	v_pk_fma_f32 v[64:65], v[52:53], v[74:75], v[64:65]
	v_pk_fma_f32 v[72:73], v[10:11], v[74:75], v[72:73]
	v_add_f32_e32 v86, v64, v65
	v_add_f32_e32 v64, v72, v73
	ds_read_b128 v[72:75], v103 offset:40960
	s_waitcnt lgkmcnt(0)
	v_pk_fma_f32 v[76:77], v[4:5], v[72:73], 0 op_sel_hi:[1,1,0]
	v_pk_fma_f32 v[72:73], v[58:59], v[72:73], 0 op_sel_hi:[1,1,0]
	v_pk_fma_f32 v[76:77], v[2:3], v[74:75], v[76:77]
	v_pk_fma_f32 v[78:79], v[56:57], v[74:75], v[72:73]
	ds_read_b128 v[72:75], v103 offset:41984
	s_waitcnt lgkmcnt(0)
	v_pk_fma_f32 v[76:77], v[8:9], v[72:73], v[76:77]
	v_pk_fma_f32 v[72:73], v[66:67], v[72:73], v[78:79]
	v_pk_fma_f32 v[76:77], v[6:7], v[74:75], v[76:77]
	v_pk_fma_f32 v[78:79], v[62:63], v[74:75], v[72:73]
	ds_read_b128 v[72:75], v103 offset:43008
	s_waitcnt lgkmcnt(0)
	v_pk_fma_f32 v[76:77], v[34:35], v[72:73], v[76:77]
	v_pk_fma_f32 v[72:73], v[70:71], v[72:73], v[78:79]
	v_pk_fma_f32 v[76:77], v[32:33], v[74:75], v[76:77]
	v_pk_fma_f32 v[78:79], v[68:69], v[74:75], v[72:73]
	ds_read_b128 v[72:75], v103 offset:44032
	s_waitcnt lgkmcnt(0)
	v_pk_fma_f32 v[76:77], v[38:39], v[72:73], v[76:77]
	v_pk_fma_f32 v[72:73], v[30:31], v[72:73], v[78:79]
	v_pk_fma_f32 v[76:77], v[36:37], v[74:75], v[76:77]
	v_pk_fma_f32 v[78:79], v[28:29], v[74:75], v[72:73]
	ds_read_b128 v[72:75], v103 offset:45056
	s_waitcnt lgkmcnt(0)
	v_pk_fma_f32 v[76:77], v[42:43], v[72:73], v[76:77]
	v_pk_fma_f32 v[72:73], v[22:23], v[72:73], v[78:79]
	v_pk_fma_f32 v[76:77], v[40:41], v[74:75], v[76:77]
	v_pk_fma_f32 v[78:79], v[20:21], v[74:75], v[72:73]
	ds_read_b128 v[72:75], v103 offset:46080
	s_waitcnt lgkmcnt(0)
	v_pk_fma_f32 v[76:77], v[46:47], v[72:73], v[76:77]
	v_pk_fma_f32 v[72:73], v[26:27], v[72:73], v[78:79]
	v_pk_fma_f32 v[76:77], v[44:45], v[74:75], v[76:77]
	v_pk_fma_f32 v[78:79], v[24:25], v[74:75], v[72:73]
	ds_read_b128 v[72:75], v103 offset:47104
	s_waitcnt lgkmcnt(0)
	v_pk_fma_f32 v[76:77], v[50:51], v[72:73], v[76:77]
	v_pk_fma_f32 v[72:73], v[18:19], v[72:73], v[78:79]
	v_pk_fma_f32 v[76:77], v[48:49], v[74:75], v[76:77]
	v_pk_fma_f32 v[78:79], v[16:17], v[74:75], v[72:73]
	ds_read_b128 v[72:75], v103 offset:48128
	s_waitcnt lgkmcnt(0)
	v_pk_fma_f32 v[76:77], v[54:55], v[72:73], v[76:77]
	v_pk_fma_f32 v[72:73], v[12:13], v[72:73], v[78:79]
	v_pk_fma_f32 v[76:77], v[52:53], v[74:75], v[76:77]
	v_pk_fma_f32 v[72:73], v[10:11], v[74:75], v[72:73]
	v_add_f32_e32 v87, v76, v77
	v_add_f32_e32 v65, v72, v73
	ds_read_b128 v[72:75], v103 offset:49152
	s_waitcnt lgkmcnt(0)
	v_pk_fma_f32 v[76:77], v[4:5], v[72:73], 0 op_sel_hi:[1,1,0]
	v_pk_fma_f32 v[72:73], v[58:59], v[72:73], 0 op_sel_hi:[1,1,0]
	v_pk_fma_f32 v[76:77], v[2:3], v[74:75], v[76:77]
	v_pk_fma_f32 v[78:79], v[56:57], v[74:75], v[72:73]
	ds_read_b128 v[72:75], v103 offset:50176
	s_waitcnt lgkmcnt(0)
	v_pk_fma_f32 v[76:77], v[8:9], v[72:73], v[76:77]
	v_pk_fma_f32 v[72:73], v[66:67], v[72:73], v[78:79]
	v_pk_fma_f32 v[76:77], v[6:7], v[74:75], v[76:77]
	v_pk_fma_f32 v[78:79], v[62:63], v[74:75], v[72:73]
	ds_read_b128 v[72:75], v103 offset:51200
	s_waitcnt lgkmcnt(0)
	v_pk_fma_f32 v[76:77], v[34:35], v[72:73], v[76:77]
	v_pk_fma_f32 v[72:73], v[70:71], v[72:73], v[78:79]
	v_pk_fma_f32 v[76:77], v[32:33], v[74:75], v[76:77]
	v_pk_fma_f32 v[78:79], v[68:69], v[74:75], v[72:73]
	ds_read_b128 v[72:75], v103 offset:52224
	s_waitcnt lgkmcnt(0)
	v_pk_fma_f32 v[76:77], v[38:39], v[72:73], v[76:77]
	v_pk_fma_f32 v[72:73], v[30:31], v[72:73], v[78:79]
	v_pk_fma_f32 v[76:77], v[36:37], v[74:75], v[76:77]
	v_pk_fma_f32 v[78:79], v[28:29], v[74:75], v[72:73]
	ds_read_b128 v[72:75], v103 offset:53248
	s_waitcnt lgkmcnt(0)
	v_pk_fma_f32 v[76:77], v[42:43], v[72:73], v[76:77]
	v_pk_fma_f32 v[72:73], v[22:23], v[72:73], v[78:79]
	v_pk_fma_f32 v[76:77], v[40:41], v[74:75], v[76:77]
	v_pk_fma_f32 v[78:79], v[20:21], v[74:75], v[72:73]
	ds_read_b128 v[72:75], v103 offset:54272
	s_waitcnt lgkmcnt(0)
	v_pk_fma_f32 v[76:77], v[46:47], v[72:73], v[76:77]
	v_pk_fma_f32 v[72:73], v[26:27], v[72:73], v[78:79]
	v_pk_fma_f32 v[76:77], v[44:45], v[74:75], v[76:77]
	v_pk_fma_f32 v[78:79], v[24:25], v[74:75], v[72:73]
	ds_read_b128 v[72:75], v103 offset:55296
	s_waitcnt lgkmcnt(0)
	v_pk_fma_f32 v[76:77], v[50:51], v[72:73], v[76:77]
	v_pk_fma_f32 v[72:73], v[18:19], v[72:73], v[78:79]
	v_pk_fma_f32 v[76:77], v[48:49], v[74:75], v[76:77]
	v_pk_fma_f32 v[78:79], v[16:17], v[74:75], v[72:73]
	ds_read_b128 v[72:75], v103 offset:56320
	s_waitcnt lgkmcnt(0)
	v_pk_fma_f32 v[76:77], v[54:55], v[72:73], v[76:77]
	v_pk_fma_f32 v[72:73], v[12:13], v[72:73], v[78:79]
	v_pk_fma_f32 v[76:77], v[52:53], v[74:75], v[76:77]
	v_pk_fma_f32 v[72:73], v[10:11], v[74:75], v[72:73]
	v_add_f32_e32 v88, v76, v77
	v_add_f32_e32 v72, v72, v73
	ds_read_b128 v[74:77], v103 offset:57344
	s_waitcnt lgkmcnt(0)
	v_pk_fma_f32 v[78:79], v[4:5], v[74:75], 0 op_sel_hi:[1,1,0]
	v_pk_fma_f32 v[74:75], v[58:59], v[74:75], 0 op_sel_hi:[1,1,0]
	v_pk_fma_f32 v[78:79], v[2:3], v[76:77], v[78:79]
	v_pk_fma_f32 v[96:97], v[56:57], v[76:77], v[74:75]
	ds_read_b128 v[74:77], v103 offset:58368
	s_waitcnt lgkmcnt(0)
	v_pk_fma_f32 v[78:79], v[8:9], v[74:75], v[78:79]
	v_pk_fma_f32 v[74:75], v[66:67], v[74:75], v[96:97]
	v_pk_fma_f32 v[78:79], v[6:7], v[76:77], v[78:79]
	v_pk_fma_f32 v[96:97], v[62:63], v[76:77], v[74:75]
	ds_read_b128 v[74:77], v103 offset:59392
	s_waitcnt lgkmcnt(0)
	v_pk_fma_f32 v[78:79], v[34:35], v[74:75], v[78:79]
	v_pk_fma_f32 v[74:75], v[70:71], v[74:75], v[96:97]
	v_pk_fma_f32 v[78:79], v[32:33], v[76:77], v[78:79]
	v_pk_fma_f32 v[96:97], v[68:69], v[76:77], v[74:75]
	ds_read_b128 v[74:77], v103 offset:60416
	s_waitcnt lgkmcnt(0)
	v_pk_fma_f32 v[78:79], v[38:39], v[74:75], v[78:79]
	v_pk_fma_f32 v[74:75], v[30:31], v[74:75], v[96:97]
	v_pk_fma_f32 v[78:79], v[36:37], v[76:77], v[78:79]
	v_pk_fma_f32 v[96:97], v[28:29], v[76:77], v[74:75]
	ds_read_b128 v[74:77], v103 offset:61440
	s_waitcnt lgkmcnt(0)
	v_pk_fma_f32 v[78:79], v[42:43], v[74:75], v[78:79]
	v_pk_fma_f32 v[74:75], v[22:23], v[74:75], v[96:97]
	v_pk_fma_f32 v[78:79], v[40:41], v[76:77], v[78:79]
	v_pk_fma_f32 v[96:97], v[20:21], v[76:77], v[74:75]
	ds_read_b128 v[74:77], v103 offset:62464
	s_waitcnt lgkmcnt(0)
	v_pk_fma_f32 v[78:79], v[46:47], v[74:75], v[78:79]
	v_pk_fma_f32 v[74:75], v[26:27], v[74:75], v[96:97]
	v_pk_fma_f32 v[78:79], v[44:45], v[76:77], v[78:79]
	v_pk_fma_f32 v[96:97], v[24:25], v[76:77], v[74:75]
	ds_read_b128 v[74:77], v103 offset:63488
	s_waitcnt lgkmcnt(0)
	v_pk_fma_f32 v[78:79], v[50:51], v[74:75], v[78:79]
	v_pk_fma_f32 v[74:75], v[18:19], v[74:75], v[96:97]
	v_pk_fma_f32 v[78:79], v[48:49], v[76:77], v[78:79]
	v_pk_fma_f32 v[96:97], v[16:17], v[76:77], v[74:75]
	ds_read_b128 v[74:77], v103 offset:64512
	s_waitcnt lgkmcnt(0)
	v_pk_fma_f32 v[78:79], v[54:55], v[74:75], v[78:79]
	v_pk_fma_f32 v[74:75], v[12:13], v[74:75], v[96:97]
	v_pk_fma_f32 v[78:79], v[52:53], v[76:77], v[78:79]
	v_pk_fma_f32 v[74:75], v[10:11], v[76:77], v[74:75]
	v_add_f32_e32 v89, v78, v79
	v_add_f32_e32 v73, v74, v75
	v_add_u32_e32 v74, 0x10000, v103
	ds_read_b128 v[74:77], v74
	s_waitcnt lgkmcnt(0)
	v_pk_fma_f32 v[78:79], v[4:5], v[74:75], 0 op_sel_hi:[1,1,0]
	v_pk_fma_f32 v[74:75], v[58:59], v[74:75], 0 op_sel_hi:[1,1,0]
	v_pk_fma_f32 v[78:79], v[2:3], v[76:77], v[78:79]
	v_pk_fma_f32 v[96:97], v[56:57], v[76:77], v[74:75]
	v_add_u32_e32 v74, 0x10400, v103
	ds_read_b128 v[74:77], v74
	s_waitcnt lgkmcnt(0)
	v_pk_fma_f32 v[78:79], v[8:9], v[74:75], v[78:79]
	v_pk_fma_f32 v[74:75], v[66:67], v[74:75], v[96:97]
	v_pk_fma_f32 v[78:79], v[6:7], v[76:77], v[78:79]
	v_pk_fma_f32 v[96:97], v[62:63], v[76:77], v[74:75]
	v_add_u32_e32 v74, 0x10800, v103
	ds_read_b128 v[74:77], v74
	s_waitcnt lgkmcnt(0)
	v_pk_fma_f32 v[78:79], v[34:35], v[74:75], v[78:79]
	v_pk_fma_f32 v[74:75], v[70:71], v[74:75], v[96:97]
	v_pk_fma_f32 v[78:79], v[32:33], v[76:77], v[78:79]
	v_pk_fma_f32 v[96:97], v[68:69], v[76:77], v[74:75]
	v_add_u32_e32 v74, 0x10c00, v103
	ds_read_b128 v[74:77], v74
	s_waitcnt lgkmcnt(0)
	v_pk_fma_f32 v[78:79], v[38:39], v[74:75], v[78:79]
	v_pk_fma_f32 v[74:75], v[30:31], v[74:75], v[96:97]
	v_pk_fma_f32 v[78:79], v[36:37], v[76:77], v[78:79]
	v_pk_fma_f32 v[96:97], v[28:29], v[76:77], v[74:75]
	v_add_u32_e32 v74, 0x11000, v103
	ds_read_b128 v[74:77], v74
	s_waitcnt lgkmcnt(0)
	v_pk_fma_f32 v[78:79], v[42:43], v[74:75], v[78:79]
	v_pk_fma_f32 v[74:75], v[22:23], v[74:75], v[96:97]
	v_pk_fma_f32 v[78:79], v[40:41], v[76:77], v[78:79]
	v_pk_fma_f32 v[96:97], v[20:21], v[76:77], v[74:75]
	v_add_u32_e32 v74, 0x11400, v103
	ds_read_b128 v[74:77], v74
	s_waitcnt lgkmcnt(0)
	v_pk_fma_f32 v[78:79], v[46:47], v[74:75], v[78:79]
	v_pk_fma_f32 v[74:75], v[26:27], v[74:75], v[96:97]
	v_pk_fma_f32 v[78:79], v[44:45], v[76:77], v[78:79]
	v_pk_fma_f32 v[96:97], v[24:25], v[76:77], v[74:75]
	v_add_u32_e32 v74, 0x11800, v103
	ds_read_b128 v[74:77], v74
	s_waitcnt lgkmcnt(0)
	v_pk_fma_f32 v[78:79], v[50:51], v[74:75], v[78:79]
	v_pk_fma_f32 v[74:75], v[18:19], v[74:75], v[96:97]
	v_pk_fma_f32 v[78:79], v[48:49], v[76:77], v[78:79]
	v_pk_fma_f32 v[96:97], v[16:17], v[76:77], v[74:75]
	v_add_u32_e32 v74, 0x11c00, v103
	ds_read_b128 v[74:77], v74
	s_waitcnt lgkmcnt(0)
	v_pk_fma_f32 v[78:79], v[54:55], v[74:75], v[78:79]
	v_pk_fma_f32 v[74:75], v[12:13], v[74:75], v[96:97]
	v_pk_fma_f32 v[78:79], v[52:53], v[76:77], v[78:79]
	v_pk_fma_f32 v[74:75], v[10:11], v[76:77], v[74:75]
	v_add_f32_e32 v96, v78, v79
	v_add_f32_e32 v74, v74, v75
	v_add_u32_e32 v75, 0x12000, v103
	ds_read_b128 v[76:79], v75
	v_add_u32_e32 v75, 0x12400, v103
	s_waitcnt lgkmcnt(0)
	v_pk_fma_f32 v[98:99], v[4:5], v[76:77], 0 op_sel_hi:[1,1,0]
	v_pk_fma_f32 v[76:77], v[58:59], v[76:77], 0 op_sel_hi:[1,1,0]
	v_pk_fma_f32 v[98:99], v[2:3], v[78:79], v[98:99]
	v_pk_fma_f32 v[100:101], v[56:57], v[78:79], v[76:77]
	ds_read_b128 v[76:79], v75
	v_add_u32_e32 v75, 0x12800, v103
	s_waitcnt lgkmcnt(0)
	v_pk_fma_f32 v[98:99], v[8:9], v[76:77], v[98:99]
	v_pk_fma_f32 v[76:77], v[66:67], v[76:77], v[100:101]
	v_pk_fma_f32 v[98:99], v[6:7], v[78:79], v[98:99]
	v_pk_fma_f32 v[100:101], v[62:63], v[78:79], v[76:77]
	ds_read_b128 v[76:79], v75
	v_add_u32_e32 v75, 0x12c00, v103
	s_waitcnt lgkmcnt(0)
	v_pk_fma_f32 v[98:99], v[34:35], v[76:77], v[98:99]
	v_pk_fma_f32 v[76:77], v[70:71], v[76:77], v[100:101]
	v_pk_fma_f32 v[98:99], v[32:33], v[78:79], v[98:99]
	v_pk_fma_f32 v[100:101], v[68:69], v[78:79], v[76:77]
	ds_read_b128 v[76:79], v75
	v_add_u32_e32 v75, 0x13000, v103
	s_waitcnt lgkmcnt(0)
	v_pk_fma_f32 v[98:99], v[38:39], v[76:77], v[98:99]
	v_pk_fma_f32 v[76:77], v[30:31], v[76:77], v[100:101]
	v_pk_fma_f32 v[98:99], v[36:37], v[78:79], v[98:99]
	v_pk_fma_f32 v[100:101], v[28:29], v[78:79], v[76:77]
	ds_read_b128 v[76:79], v75
	v_add_u32_e32 v75, 0x13400, v103
	s_waitcnt lgkmcnt(0)
	v_pk_fma_f32 v[98:99], v[42:43], v[76:77], v[98:99]
	v_pk_fma_f32 v[76:77], v[22:23], v[76:77], v[100:101]
	v_pk_fma_f32 v[98:99], v[40:41], v[78:79], v[98:99]
	v_pk_fma_f32 v[100:101], v[20:21], v[78:79], v[76:77]
	ds_read_b128 v[76:79], v75
	v_add_u32_e32 v75, 0x13800, v103
	s_waitcnt lgkmcnt(0)
	v_pk_fma_f32 v[98:99], v[46:47], v[76:77], v[98:99]
	v_pk_fma_f32 v[76:77], v[26:27], v[76:77], v[100:101]
	v_pk_fma_f32 v[98:99], v[44:45], v[78:79], v[98:99]
	v_pk_fma_f32 v[100:101], v[24:25], v[78:79], v[76:77]
	ds_read_b128 v[76:79], v75
	v_add_u32_e32 v75, 0x13c00, v103
	s_waitcnt lgkmcnt(0)
	v_pk_fma_f32 v[98:99], v[50:51], v[76:77], v[98:99]
	v_pk_fma_f32 v[76:77], v[18:19], v[76:77], v[100:101]
	v_pk_fma_f32 v[98:99], v[48:49], v[78:79], v[98:99]
	v_pk_fma_f32 v[100:101], v[16:17], v[78:79], v[76:77]
	ds_read_b128 v[76:79], v75
	s_waitcnt lgkmcnt(0)
	v_pk_fma_f32 v[98:99], v[54:55], v[76:77], v[98:99]
	v_pk_fma_f32 v[76:77], v[12:13], v[76:77], v[100:101]
	v_pk_fma_f32 v[98:99], v[52:53], v[78:79], v[98:99]
	v_pk_fma_f32 v[76:77], v[10:11], v[78:79], v[76:77]
	v_add_f32_e32 v97, v98, v99
	v_add_f32_e32 v75, v76, v77
	v_add_u32_e32 v76, 0x14000, v103
	ds_read_b128 v[76:79], v76
	s_waitcnt lgkmcnt(0)
	v_pk_fma_f32 v[98:99], v[4:5], v[76:77], 0 op_sel_hi:[1,1,0]
	v_pk_fma_f32 v[76:77], v[58:59], v[76:77], 0 op_sel_hi:[1,1,0]
	v_pk_fma_f32 v[98:99], v[2:3], v[78:79], v[98:99]
	v_pk_fma_f32 v[100:101], v[56:57], v[78:79], v[76:77]
	v_add_u32_e32 v76, 0x14400, v103
	ds_read_b128 v[76:79], v76
	s_waitcnt lgkmcnt(0)
	v_pk_fma_f32 v[98:99], v[8:9], v[76:77], v[98:99]
	v_pk_fma_f32 v[76:77], v[66:67], v[76:77], v[100:101]
	v_pk_fma_f32 v[98:99], v[6:7], v[78:79], v[98:99]
	v_pk_fma_f32 v[100:101], v[62:63], v[78:79], v[76:77]
	v_add_u32_e32 v76, 0x14800, v103
	ds_read_b128 v[76:79], v76
	s_waitcnt lgkmcnt(0)
	v_pk_fma_f32 v[98:99], v[34:35], v[76:77], v[98:99]
	v_pk_fma_f32 v[76:77], v[70:71], v[76:77], v[100:101]
	v_pk_fma_f32 v[98:99], v[32:33], v[78:79], v[98:99]
	v_pk_fma_f32 v[100:101], v[68:69], v[78:79], v[76:77]
	v_add_u32_e32 v76, 0x14c00, v103
	ds_read_b128 v[76:79], v76
	s_waitcnt lgkmcnt(0)
	v_pk_fma_f32 v[98:99], v[38:39], v[76:77], v[98:99]
	v_pk_fma_f32 v[76:77], v[30:31], v[76:77], v[100:101]
	v_pk_fma_f32 v[98:99], v[36:37], v[78:79], v[98:99]
	v_pk_fma_f32 v[100:101], v[28:29], v[78:79], v[76:77]
	v_add_u32_e32 v76, 0x15000, v103
	ds_read_b128 v[76:79], v76
	s_waitcnt lgkmcnt(0)
	v_pk_fma_f32 v[98:99], v[42:43], v[76:77], v[98:99]
	v_pk_fma_f32 v[76:77], v[22:23], v[76:77], v[100:101]
	v_pk_fma_f32 v[98:99], v[40:41], v[78:79], v[98:99]
	v_pk_fma_f32 v[100:101], v[20:21], v[78:79], v[76:77]
	v_add_u32_e32 v76, 0x15400, v103
	ds_read_b128 v[76:79], v76
	s_waitcnt lgkmcnt(0)
	v_pk_fma_f32 v[98:99], v[46:47], v[76:77], v[98:99]
	v_pk_fma_f32 v[76:77], v[26:27], v[76:77], v[100:101]
	v_pk_fma_f32 v[98:99], v[44:45], v[78:79], v[98:99]
	v_pk_fma_f32 v[100:101], v[24:25], v[78:79], v[76:77]
	v_add_u32_e32 v76, 0x15800, v103
	ds_read_b128 v[76:79], v76
	s_waitcnt lgkmcnt(0)
	v_pk_fma_f32 v[98:99], v[50:51], v[76:77], v[98:99]
	v_pk_fma_f32 v[76:77], v[18:19], v[76:77], v[100:101]
	v_pk_fma_f32 v[98:99], v[48:49], v[78:79], v[98:99]
	v_pk_fma_f32 v[100:101], v[16:17], v[78:79], v[76:77]
	v_add_u32_e32 v76, 0x15c00, v103
	ds_read_b128 v[76:79], v76
	s_waitcnt lgkmcnt(0)
	v_pk_fma_f32 v[98:99], v[54:55], v[76:77], v[98:99]
	v_pk_fma_f32 v[76:77], v[12:13], v[76:77], v[100:101]
	v_pk_fma_f32 v[98:99], v[52:53], v[78:79], v[98:99]
	v_pk_fma_f32 v[76:77], v[10:11], v[78:79], v[76:77]
	v_add_f32_e32 v98, v98, v99
	v_add_f32_e32 v76, v76, v77
	v_add_u32_e32 v77, 0x16000, v103
	ds_read_b128 v[104:107], v77
	v_add_u32_e32 v77, 0x16400, v103
	s_waitcnt lgkmcnt(0)
	v_pk_fma_f32 v[78:79], v[4:5], v[104:105], 0 op_sel_hi:[1,1,0]
	v_pk_fma_f32 v[100:101], v[58:59], v[104:105], 0 op_sel_hi:[1,1,0]
	v_pk_fma_f32 v[78:79], v[2:3], v[106:107], v[78:79]
	v_pk_fma_f32 v[100:101], v[56:57], v[106:107], v[100:101]
	ds_read_b128 v[104:107], v77
	v_add_u32_e32 v77, 0x16800, v103
	s_waitcnt lgkmcnt(0)
	v_pk_fma_f32 v[78:79], v[8:9], v[104:105], v[78:79]
	v_pk_fma_f32 v[100:101], v[66:67], v[104:105], v[100:101]
	v_pk_fma_f32 v[78:79], v[6:7], v[106:107], v[78:79]
	v_pk_fma_f32 v[100:101], v[62:63], v[106:107], v[100:101]
	ds_read_b128 v[104:107], v77
	v_add_u32_e32 v77, 0x16c00, v103
	s_waitcnt lgkmcnt(0)
	v_pk_fma_f32 v[78:79], v[34:35], v[104:105], v[78:79]
	v_pk_fma_f32 v[100:101], v[70:71], v[104:105], v[100:101]
	v_pk_fma_f32 v[78:79], v[32:33], v[106:107], v[78:79]
	v_pk_fma_f32 v[100:101], v[68:69], v[106:107], v[100:101]
	ds_read_b128 v[104:107], v77
	v_add_u32_e32 v77, 0x17000, v103
	s_waitcnt lgkmcnt(0)
	v_pk_fma_f32 v[78:79], v[38:39], v[104:105], v[78:79]
	v_pk_fma_f32 v[100:101], v[30:31], v[104:105], v[100:101]
	v_pk_fma_f32 v[78:79], v[36:37], v[106:107], v[78:79]
	v_pk_fma_f32 v[100:101], v[28:29], v[106:107], v[100:101]
	ds_read_b128 v[104:107], v77
	v_add_u32_e32 v77, 0x17400, v103
	s_waitcnt lgkmcnt(0)
	v_pk_fma_f32 v[78:79], v[42:43], v[104:105], v[78:79]
	v_pk_fma_f32 v[100:101], v[22:23], v[104:105], v[100:101]
	v_pk_fma_f32 v[78:79], v[40:41], v[106:107], v[78:79]
	v_pk_fma_f32 v[100:101], v[20:21], v[106:107], v[100:101]
	ds_read_b128 v[104:107], v77
	v_add_u32_e32 v77, 0x17800, v103
	s_waitcnt lgkmcnt(0)
	v_pk_fma_f32 v[78:79], v[46:47], v[104:105], v[78:79]
	v_pk_fma_f32 v[100:101], v[26:27], v[104:105], v[100:101]
	v_pk_fma_f32 v[78:79], v[44:45], v[106:107], v[78:79]
	v_pk_fma_f32 v[100:101], v[24:25], v[106:107], v[100:101]
	ds_read_b128 v[104:107], v77
	v_add_u32_e32 v77, 0x17c00, v103
	s_waitcnt lgkmcnt(0)
	v_pk_fma_f32 v[78:79], v[50:51], v[104:105], v[78:79]
	v_pk_fma_f32 v[100:101], v[18:19], v[104:105], v[100:101]
	v_pk_fma_f32 v[78:79], v[48:49], v[106:107], v[78:79]
	v_pk_fma_f32 v[100:101], v[16:17], v[106:107], v[100:101]
	ds_read_b128 v[104:107], v77
	s_waitcnt lgkmcnt(0)
	v_pk_fma_f32 v[78:79], v[54:55], v[104:105], v[78:79]
	v_pk_fma_f32 v[100:101], v[12:13], v[104:105], v[100:101]
	v_pk_fma_f32 v[78:79], v[52:53], v[106:107], v[78:79]
	v_pk_fma_f32 v[100:101], v[10:11], v[106:107], v[100:101]
	v_add_f32_e32 v99, v78, v79
	v_add_f32_e32 v77, v100, v101
	v_add_u32_e32 v78, 0x18000, v103
	ds_read_b128 v[104:107], v78
	s_waitcnt lgkmcnt(0)
	v_pk_fma_f32 v[78:79], v[4:5], v[104:105], 0 op_sel_hi:[1,1,0]
	v_pk_fma_f32 v[100:101], v[58:59], v[104:105], 0 op_sel_hi:[1,1,0]
	v_pk_fma_f32 v[78:79], v[2:3], v[106:107], v[78:79]
	v_pk_fma_f32 v[100:101], v[56:57], v[106:107], v[100:101]
	ds_read_b128 v[104:107], v80
	v_add_u32_e32 v80, 0x18800, v103
	s_waitcnt lgkmcnt(0)
	v_pk_fma_f32 v[78:79], v[8:9], v[104:105], v[78:79]
	v_pk_fma_f32 v[100:101], v[66:67], v[104:105], v[100:101]
	v_pk_fma_f32 v[78:79], v[6:7], v[106:107], v[78:79]
	v_pk_fma_f32 v[100:101], v[62:63], v[106:107], v[100:101]
	ds_read_b128 v[104:107], v80
	v_add_u32_e32 v80, 0x18c00, v103
	s_waitcnt lgkmcnt(0)
	v_pk_fma_f32 v[78:79], v[34:35], v[104:105], v[78:79]
	v_pk_fma_f32 v[100:101], v[70:71], v[104:105], v[100:101]
	v_pk_fma_f32 v[78:79], v[32:33], v[106:107], v[78:79]
	v_pk_fma_f32 v[100:101], v[68:69], v[106:107], v[100:101]
	ds_read_b128 v[104:107], v80
	v_add_u32_e32 v80, 0x19000, v103
	s_waitcnt lgkmcnt(0)
	v_pk_fma_f32 v[78:79], v[38:39], v[104:105], v[78:79]
	v_pk_fma_f32 v[100:101], v[30:31], v[104:105], v[100:101]
	v_pk_fma_f32 v[78:79], v[36:37], v[106:107], v[78:79]
	v_pk_fma_f32 v[100:101], v[28:29], v[106:107], v[100:101]
	ds_read_b128 v[104:107], v80
	v_add_u32_e32 v80, 0x19400, v103
	s_waitcnt lgkmcnt(0)
	v_pk_fma_f32 v[78:79], v[42:43], v[104:105], v[78:79]
	v_pk_fma_f32 v[100:101], v[22:23], v[104:105], v[100:101]
	v_pk_fma_f32 v[78:79], v[40:41], v[106:107], v[78:79]
	v_pk_fma_f32 v[100:101], v[20:21], v[106:107], v[100:101]
	ds_read_b128 v[104:107], v80
	v_add_u32_e32 v80, 0x19800, v103
	s_waitcnt lgkmcnt(0)
	v_pk_fma_f32 v[78:79], v[46:47], v[104:105], v[78:79]
	v_pk_fma_f32 v[100:101], v[26:27], v[104:105], v[100:101]
	v_pk_fma_f32 v[78:79], v[44:45], v[106:107], v[78:79]
	v_pk_fma_f32 v[100:101], v[24:25], v[106:107], v[100:101]
	ds_read_b128 v[104:107], v80
	v_add_u32_e32 v80, 0x19c00, v103
	s_waitcnt lgkmcnt(0)
	v_pk_fma_f32 v[78:79], v[50:51], v[104:105], v[78:79]
	v_pk_fma_f32 v[100:101], v[18:19], v[104:105], v[100:101]
	v_pk_fma_f32 v[78:79], v[48:49], v[106:107], v[78:79]
	v_pk_fma_f32 v[100:101], v[16:17], v[106:107], v[100:101]
	ds_read_b128 v[104:107], v80
	v_add_u32_e32 v80, 0x1c000, v103
	s_waitcnt lgkmcnt(0)
	v_pk_fma_f32 v[78:79], v[54:55], v[104:105], v[78:79]
	v_pk_fma_f32 v[100:101], v[12:13], v[104:105], v[100:101]
	v_pk_fma_f32 v[78:79], v[52:53], v[106:107], v[78:79]
	v_pk_fma_f32 v[104:105], v[10:11], v[106:107], v[100:101]
	v_add_f32_e32 v100, v78, v79
	v_add_f32_e32 v78, v104, v105
	v_add_u32_e32 v79, 0x1a000, v103
	ds_read_b128 v[104:107], v79
	v_add_u32_e32 v79, 0x1a400, v103
	s_waitcnt lgkmcnt(0)
	v_pk_fma_f32 v[108:109], v[4:5], v[104:105], 0 op_sel_hi:[1,1,0]
	v_pk_fma_f32 v[104:105], v[58:59], v[104:105], 0 op_sel_hi:[1,1,0]
	v_pk_fma_f32 v[108:109], v[2:3], v[106:107], v[108:109]
	v_pk_fma_f32 v[110:111], v[56:57], v[106:107], v[104:105]
	ds_read_b128 v[104:107], v79
	v_add_u32_e32 v79, 0x1a800, v103
	s_waitcnt lgkmcnt(0)
	v_pk_fma_f32 v[108:109], v[8:9], v[104:105], v[108:109]
	v_pk_fma_f32 v[104:105], v[66:67], v[104:105], v[110:111]
	v_pk_fma_f32 v[108:109], v[6:7], v[106:107], v[108:109]
	v_pk_fma_f32 v[110:111], v[62:63], v[106:107], v[104:105]
	ds_read_b128 v[104:107], v79
	v_add_u32_e32 v79, 0x1ac00, v103
	s_waitcnt lgkmcnt(0)
	v_pk_fma_f32 v[108:109], v[34:35], v[104:105], v[108:109]
	v_pk_fma_f32 v[104:105], v[70:71], v[104:105], v[110:111]
	v_pk_fma_f32 v[108:109], v[32:33], v[106:107], v[108:109]
	v_pk_fma_f32 v[110:111], v[68:69], v[106:107], v[104:105]
	ds_read_b128 v[104:107], v79
	v_add_u32_e32 v79, 0x1b000, v103
	s_waitcnt lgkmcnt(0)
	v_pk_fma_f32 v[108:109], v[38:39], v[104:105], v[108:109]
	v_pk_fma_f32 v[104:105], v[30:31], v[104:105], v[110:111]
	v_pk_fma_f32 v[108:109], v[36:37], v[106:107], v[108:109]
	v_pk_fma_f32 v[110:111], v[28:29], v[106:107], v[104:105]
	ds_read_b128 v[104:107], v79
	v_add_u32_e32 v79, 0x1b400, v103
	s_waitcnt lgkmcnt(0)
	v_pk_fma_f32 v[108:109], v[42:43], v[104:105], v[108:109]
	v_pk_fma_f32 v[104:105], v[22:23], v[104:105], v[110:111]
	v_pk_fma_f32 v[108:109], v[40:41], v[106:107], v[108:109]
	v_pk_fma_f32 v[110:111], v[20:21], v[106:107], v[104:105]
	ds_read_b128 v[104:107], v79
	v_add_u32_e32 v79, 0x1b800, v103
	s_waitcnt lgkmcnt(0)
	v_pk_fma_f32 v[108:109], v[46:47], v[104:105], v[108:109]
	v_pk_fma_f32 v[104:105], v[26:27], v[104:105], v[110:111]
	v_pk_fma_f32 v[108:109], v[44:45], v[106:107], v[108:109]
	v_pk_fma_f32 v[110:111], v[24:25], v[106:107], v[104:105]
	ds_read_b128 v[104:107], v79
	v_add_u32_e32 v79, 0x1bc00, v103
	s_waitcnt lgkmcnt(0)
	v_pk_fma_f32 v[108:109], v[50:51], v[104:105], v[108:109]
	v_pk_fma_f32 v[104:105], v[18:19], v[104:105], v[110:111]
	v_pk_fma_f32 v[108:109], v[48:49], v[106:107], v[108:109]
	v_pk_fma_f32 v[110:111], v[16:17], v[106:107], v[104:105]
	ds_read_b128 v[104:107], v79
	s_waitcnt lgkmcnt(0)
	v_pk_fma_f32 v[108:109], v[54:55], v[104:105], v[108:109]
	v_pk_fma_f32 v[104:105], v[12:13], v[104:105], v[110:111]
	v_pk_fma_f32 v[108:109], v[52:53], v[106:107], v[108:109]
	v_pk_fma_f32 v[104:105], v[10:11], v[106:107], v[104:105]
	v_add_f32_e32 v101, v108, v109
	v_add_f32_e32 v79, v104, v105
	ds_read_b128 v[104:107], v80
	v_add_u32_e32 v80, 0x1c400, v103
	s_waitcnt lgkmcnt(0)
	v_pk_fma_f32 v[108:109], v[4:5], v[104:105], 0 op_sel_hi:[1,1,0]
	v_pk_fma_f32 v[104:105], v[58:59], v[104:105], 0 op_sel_hi:[1,1,0]
	v_pk_fma_f32 v[108:109], v[2:3], v[106:107], v[108:109]
	v_pk_fma_f32 v[110:111], v[56:57], v[106:107], v[104:105]
	ds_read_b128 v[104:107], v80
	v_add_u32_e32 v80, 0x1c800, v103
	s_waitcnt lgkmcnt(0)
	v_pk_fma_f32 v[108:109], v[8:9], v[104:105], v[108:109]
	v_pk_fma_f32 v[104:105], v[66:67], v[104:105], v[110:111]
	v_pk_fma_f32 v[108:109], v[6:7], v[106:107], v[108:109]
	v_pk_fma_f32 v[110:111], v[62:63], v[106:107], v[104:105]
	ds_read_b128 v[104:107], v80
	v_add_u32_e32 v80, 0x1cc00, v103
	s_waitcnt lgkmcnt(0)
	v_pk_fma_f32 v[108:109], v[34:35], v[104:105], v[108:109]
	v_pk_fma_f32 v[104:105], v[70:71], v[104:105], v[110:111]
	v_pk_fma_f32 v[108:109], v[32:33], v[106:107], v[108:109]
	v_pk_fma_f32 v[110:111], v[68:69], v[106:107], v[104:105]
	ds_read_b128 v[104:107], v80
	v_add_u32_e32 v80, 0x1d000, v103
	s_waitcnt lgkmcnt(0)
	v_pk_fma_f32 v[108:109], v[38:39], v[104:105], v[108:109]
	v_pk_fma_f32 v[104:105], v[30:31], v[104:105], v[110:111]
	v_pk_fma_f32 v[108:109], v[36:37], v[106:107], v[108:109]
	v_pk_fma_f32 v[110:111], v[28:29], v[106:107], v[104:105]
	ds_read_b128 v[104:107], v80
	v_add_u32_e32 v80, 0x1d400, v103
	s_waitcnt lgkmcnt(0)
	v_pk_fma_f32 v[108:109], v[42:43], v[104:105], v[108:109]
	v_pk_fma_f32 v[104:105], v[22:23], v[104:105], v[110:111]
	v_pk_fma_f32 v[108:109], v[40:41], v[106:107], v[108:109]
	v_pk_fma_f32 v[110:111], v[20:21], v[106:107], v[104:105]
	ds_read_b128 v[104:107], v80
	v_add_u32_e32 v80, 0x1d800, v103
	s_waitcnt lgkmcnt(0)
	v_pk_fma_f32 v[108:109], v[46:47], v[104:105], v[108:109]
	v_pk_fma_f32 v[104:105], v[26:27], v[104:105], v[110:111]
	v_pk_fma_f32 v[108:109], v[44:45], v[106:107], v[108:109]
	v_pk_fma_f32 v[110:111], v[24:25], v[106:107], v[104:105]
	ds_read_b128 v[104:107], v80
	v_add_u32_e32 v80, 0x1dc00, v103
	s_waitcnt lgkmcnt(0)
	v_pk_fma_f32 v[108:109], v[50:51], v[104:105], v[108:109]
	v_pk_fma_f32 v[104:105], v[18:19], v[104:105], v[110:111]
	v_pk_fma_f32 v[108:109], v[48:49], v[106:107], v[108:109]
	v_pk_fma_f32 v[110:111], v[16:17], v[106:107], v[104:105]
	ds_read_b128 v[104:107], v80
	s_waitcnt lgkmcnt(0)
	v_pk_fma_f32 v[108:109], v[54:55], v[104:105], v[108:109]
	v_pk_fma_f32 v[104:105], v[12:13], v[104:105], v[110:111]
	v_pk_fma_f32 v[108:109], v[52:53], v[106:107], v[108:109]
	v_pk_fma_f32 v[104:105], v[10:11], v[106:107], v[104:105]
	v_add_f32_e32 v102, v108, v109
	v_add_f32_e32 v80, v104, v105
	v_add_u32_e32 v104, 0x1e000, v103
	ds_read_b128 v[104:107], v104
	s_waitcnt lgkmcnt(0)
	v_pk_fma_f32 v[4:5], v[4:5], v[104:105], 0 op_sel_hi:[1,1,0]
	s_nop 0
	v_pk_fma_f32 v[108:109], v[2:3], v[106:107], v[4:5]
	v_pk_fma_f32 v[2:3], v[58:59], v[104:105], 0 op_sel_hi:[1,1,0]
	s_nop 0
	v_pk_fma_f32 v[56:57], v[56:57], v[106:107], v[2:3]
	v_add_u32_e32 v2, 0x1e400, v103
	ds_read_b128 v[2:5], v2
	s_waitcnt lgkmcnt(0)
	v_pk_fma_f32 v[8:9], v[8:9], v[2:3], v[108:109]
	v_pk_fma_f32 v[2:3], v[66:67], v[2:3], v[56:57]
	v_pk_fma_f32 v[6:7], v[6:7], v[4:5], v[8:9]
	v_pk_fma_f32 v[8:9], v[62:63], v[4:5], v[2:3]
	v_add_u32_e32 v2, 0x1e800, v103
	ds_read_b128 v[2:5], v2
	s_waitcnt lgkmcnt(0)
	v_pk_fma_f32 v[6:7], v[34:35], v[2:3], v[6:7]
	v_pk_fma_f32 v[2:3], v[70:71], v[2:3], v[8:9]
	v_pk_fma_f32 v[6:7], v[32:33], v[4:5], v[6:7]
	v_pk_fma_f32 v[8:9], v[68:69], v[4:5], v[2:3]
	v_add_u32_e32 v2, 0x1ec00, v103
	ds_read_b128 v[2:5], v2
	s_waitcnt lgkmcnt(0)
	v_pk_fma_f32 v[6:7], v[38:39], v[2:3], v[6:7]
	v_pk_fma_f32 v[2:3], v[30:31], v[2:3], v[8:9]
	v_pk_fma_f32 v[6:7], v[36:37], v[4:5], v[6:7]
	v_pk_fma_f32 v[8:9], v[28:29], v[4:5], v[2:3]
	v_add_u32_e32 v2, 0x1f000, v103
	ds_read_b128 v[2:5], v2
	s_waitcnt lgkmcnt(0)
	v_pk_fma_f32 v[6:7], v[42:43], v[2:3], v[6:7]
	v_pk_fma_f32 v[2:3], v[22:23], v[2:3], v[8:9]
	v_pk_fma_f32 v[6:7], v[40:41], v[4:5], v[6:7]
	v_pk_fma_f32 v[8:9], v[20:21], v[4:5], v[2:3]
	v_add_u32_e32 v2, 0x1f400, v103
	ds_read_b128 v[2:5], v2
	s_waitcnt lgkmcnt(0)
	v_pk_fma_f32 v[6:7], v[46:47], v[2:3], v[6:7]
	v_pk_fma_f32 v[2:3], v[26:27], v[2:3], v[8:9]
	v_pk_fma_f32 v[6:7], v[44:45], v[4:5], v[6:7]
	v_pk_fma_f32 v[8:9], v[24:25], v[4:5], v[2:3]
	v_add_u32_e32 v2, 0x1f800, v103
	ds_read_b128 v[2:5], v2
	s_waitcnt lgkmcnt(0)
	v_pk_fma_f32 v[6:7], v[50:51], v[2:3], v[6:7]
	v_pk_fma_f32 v[2:3], v[18:19], v[2:3], v[8:9]
	v_pk_fma_f32 v[6:7], v[48:49], v[4:5], v[6:7]
	v_pk_fma_f32 v[8:9], v[16:17], v[4:5], v[2:3]
	v_add_u32_e32 v2, 0x1fc00, v103
	ds_read_b128 v[2:5], v2
	s_waitcnt lgkmcnt(0)
	v_pk_fma_f32 v[6:7], v[54:55], v[2:3], v[6:7]
	v_pk_fma_f32 v[2:3], v[12:13], v[2:3], v[8:9]
	v_pk_fma_f32 v[6:7], v[52:53], v[4:5], v[6:7]
	v_pk_fma_f32 v[4:5], v[10:11], v[4:5], v[2:3]
	v_and_b32_e32 v3, 32, v1
	v_cmp_eq_u32_e32 vcc, 0, v3
	v_add_f32_e32 v4, v4, v5
	v_add_f32_e32 v2, v6, v7
	v_cndmask_b32_e32 v5, v81, v96, vcc
	ds_bpermute_b32 v5, v95, v5
	v_cndmask_b32_e32 v6, v82, v97, vcc
	ds_bpermute_b32 v6, v95, v6
	v_cndmask_b32_e32 v7, v84, v98, vcc
	ds_bpermute_b32 v7, v95, v7
	v_cndmask_b32_e32 v8, v85, v99, vcc
	ds_bpermute_b32 v8, v95, v8
	v_cndmask_b32_e32 v9, v86, v100, vcc
	v_cndmask_b32_e32 v3, v96, v81, vcc
	ds_bpermute_b32 v9, v95, v9
	v_cndmask_b32_e32 v10, v87, v101, vcc
	s_waitcnt lgkmcnt(4)
	v_add_f32_e32 v3, v3, v5
	v_cndmask_b32_e32 v5, v97, v82, vcc
	ds_bpermute_b32 v10, v95, v10
	v_cndmask_b32_e32 v11, v88, v102, vcc
	s_waitcnt lgkmcnt(4)
	v_add_f32_e32 v6, v5, v6
	v_cndmask_b32_e32 v5, v98, v84, vcc
	ds_bpermute_b32 v11, v95, v11
	s_waitcnt lgkmcnt(4)
	v_add_f32_e32 v7, v5, v7
	v_cndmask_b32_e32 v5, v99, v85, vcc
	s_waitcnt lgkmcnt(3)
	v_add_f32_e32 v8, v5, v8
	v_cndmask_b32_e32 v5, v100, v86, vcc
	s_waitcnt lgkmcnt(2)
	v_add_f32_e32 v5, v5, v9
	v_cndmask_b32_e32 v9, v101, v87, vcc
	s_waitcnt lgkmcnt(1)
	v_add_f32_e32 v9, v9, v10
	v_cndmask_b32_e32 v10, v102, v88, vcc
	s_waitcnt lgkmcnt(0)
	v_add_f32_e32 v10, v10, v11
	v_cndmask_b32_e32 v11, v2, v89, vcc
	v_cndmask_b32_e32 v2, v89, v2, vcc
	ds_bpermute_b32 v2, v95, v2
	s_waitcnt lgkmcnt(0)
	v_add_f32_e32 v11, v11, v2
	v_and_b32_e32 v2, 16, v1
	v_cmp_eq_u32_e64 s[10:11], 0, v2
	s_nop 1
	v_cndmask_b32_e64 v2, v5, v3, s[10:11]
	v_cndmask_b32_e64 v3, v3, v5, s[10:11]
	ds_bpermute_b32 v3, v94, v3
	s_waitcnt lgkmcnt(0)
	v_add_f32_e32 v5, v2, v3
	v_cndmask_b32_e64 v3, v6, v9, s[10:11]
	ds_bpermute_b32 v3, v94, v3
	v_cndmask_b32_e64 v2, v9, v6, s[10:11]
	v_cndmask_b32_e64 v6, v7, v10, s[10:11]
	ds_bpermute_b32 v6, v94, v6
	s_waitcnt lgkmcnt(1)
	v_add_f32_e32 v2, v2, v3
	v_cndmask_b32_e64 v3, v10, v7, s[10:11]
	v_cndmask_b32_e64 v7, v8, v11, s[10:11]
	ds_bpermute_b32 v7, v94, v7
	s_waitcnt lgkmcnt(1)
	v_add_f32_e32 v6, v3, v6
	v_cndmask_b32_e64 v3, v11, v8, s[10:11]
	s_waitcnt lgkmcnt(0)
	v_add_f32_e32 v3, v3, v7
	v_and_b32_e32 v7, 8, v1
	v_cmp_eq_u32_e64 s[12:13], 0, v7
	s_nop 1
	v_cndmask_b32_e64 v7, v6, v5, s[12:13]
	v_cndmask_b32_e64 v5, v5, v6, s[12:13]
	v_cndmask_b32_e64 v6, v3, v2, s[12:13]
	v_cndmask_b32_e64 v2, v2, v3, s[12:13]
	ds_bpermute_b32 v5, v93, v5
	ds_bpermute_b32 v2, v93, v2
	v_and_b32_e32 v3, 4, v1
	v_cmp_eq_u32_e64 s[14:15], 0, v3
	s_waitcnt lgkmcnt(1)
	v_add_f32_e32 v5, v7, v5
	s_waitcnt lgkmcnt(0)
	v_add_f32_e32 v2, v6, v2
	v_cndmask_b32_e64 v3, v2, v5, s[14:15]
	v_cndmask_b32_e64 v2, v5, v2, s[14:15]
	ds_bpermute_b32 v2, v92, v2
	v_and_b32_e32 v5, 3, v1
	v_bfe_u32 v1, v1, 2, 4
	v_cmp_eq_u32_e64 s[16:17], 0, v5
	v_lshlrev_b32_e32 v82, 2, v1
	s_waitcnt lgkmcnt(0)
	v_add_f32_e32 v2, v3, v2
	ds_bpermute_b32 v3, v91, v2
	s_waitcnt lgkmcnt(0)
	v_add_f32_e32 v2, v2, v3
	ds_bpermute_b32 v3, v90, v2
	s_and_saveexec_b64 s[40:41], s[16:17]
	s_cbranch_execz .LBB0_1749
	s_waitcnt lgkmcnt(0)
	v_add_f32_e32 v2, v2, v3
	global_load_dword v3, v82, s[38:39] offset:64
	v_cmp_lt_u32_e64 s[18:19], 7, v1
	s_waitcnt vmcnt(0)
	v_add_f32_e32 v5, v2, v3
	s_and_saveexec_b64 s[8:9], s[18:19]
	s_xor_b64 s[54:55], exec, s[8:9]
	s_cbranch_execz .LBB0_1746
	s_mov_b32 s18, 0xbfb8aa3b
	v_mul_f32_e64 v2, |v5|, s18
	v_exp_f32_e32 v6, v2
	s_lshl_b64 s[8:9], s[30:31], 5
	s_add_u32 s8, s58, s8
	s_addc_u32 s9, s59, s9
	v_lshl_add_u64 v[2:3], s[8:9], 0, v[82:83]
	v_add_f32_e32 v6, 1.0, v6
	s_mov_b32 s8, 0x800000
	v_cmp_gt_f32_e64 s[18:19], s8, v6
	s_movk_i32 s8, 0xffe0
	s_mov_b32 s9, -1
	v_cndmask_b32_e64 v7, 0, 32, s[18:19]
	v_ldexp_f32 v6, v6, v7
	v_log_f32_e32 v6, v6
	v_lshl_add_u64 v[2:3], v[2:3], 0, s[8:9]
	s_mov_b32 s8, 0x3f317217
	v_max_f32_e32 v5, v5, v5
	v_mul_f32_e32 v7, 0x3f317217, v6
	v_fma_f32 v7, v6, s8, -v7
	v_fmac_f32_e32 v7, 0x3377d1cf, v6
	s_mov_b32 s8, 0x7f800000
	v_fmac_f32_e32 v7, 0x3f317217, v6
	v_cmp_lt_f32_e64 s[20:21], |v6|, s8
	v_min_f32_e32 v5, 0, v5
	s_nop 0
	v_cndmask_b32_e64 v6, v6, v7, s[20:21]
	v_mov_b32_e32 v7, 0x41b17218
	v_cndmask_b32_e64 v7, 0, v7, s[18:19]
	v_sub_f32_e32 v6, v6, v7
	v_sub_f32_e32 v5, v5, v6

.LBB0_1757:
	s_abs_i32 s9, s28
	v_readlane_b32 s12, v253, 56
	s_mul_hi_u32 s12, s9, s12
	v_readlane_b32 s15, v253, 57
	s_mul_i32 s13, s12, s15
	s_ashr_i32 s8, s28, 31
	s_sub_i32 s9, s9, s13
	s_xor_b32 s8, s8, s43
	s_add_i32 s13, s12, 1
	s_sub_i32 s14, s9, s15
	s_cmp_ge_u32 s9, s15
	s_cselect_b32 s12, s13, s12
	s_cselect_b32 s9, s14, s9
	s_add_i32 s13, s12, 1
	s_cmp_ge_u32 s9, s15
	s_cselect_b32 s9, s13, s12
	s_xor_b32 s9, s9, s8
	s_sub_i32 s8, s9, s8
	s_add_i32 s8, s28, s8
	s_and_b32 s8, s8, 7
	v_readlane_b32 s9, v253, 15
	s_cmp_lg_u32 s9, s8
	s_cbranch_scc1 .LBB0_1756
	s_add_i32 s14, s28, 0x2000
	v_mov_b32_e32 v1, v232
	s_mov_b64 s[12:13], s[46:47]
	s_mov_b64 s[8:9], s[0:1]
	v_mov_b32_e32 v2, v0
	s_mov_b64 s[16:17], s[44:45]
	s_add_u32 s15, s12, 0x25d1e000
	v_readlane_b32 s34, v254, 40
	s_addc_u32 s20, s13, 0
	v_readlane_b32 s35, v254, 41
	s_and_b64 s[18:19], s[34:35], exec
	s_cselect_b32 s27, s20, s17
	s_cselect_b32 s30, s15, s16
	s_add_u32 s15, s12, 0xcc1b000
	s_addc_u32 s18, s13, 0
	s_and_b64 s[16:17], s[34:35], exec
	s_cselect_b32 s26, s18, 0
	s_cselect_b32 s29, s15, 0
	s_add_u32 s16, s12, 0x100000
	s_addc_u32 s17, s13, 0
	s_lshr_b32 s15, s28, 3
	s_add_i32 s15, s15, 1
	s_cmp_gt_i32 s28, -1
	v_lshlrev_b32_e32 v40, 2, v1
	s_cselect_b32 s15, s15, 0
	v_ashrrev_i32_e32 v41, 31, v40
	s_add_i32 s18, s15, 33
	s_waitcnt lgkmcnt(0)
	v_mov_b64_e32 v[2:3], s[16:17]
	v_mov_b32_e32 v4, 0xc000
	s_add_i32 s15, s15, s97
	v_lshlrev_b64 v[42:43], 2, v[40:41]
	v_mad_u64_u32 v[38:39], s[16:17], s18, v4, v[2:3]
	v_mad_u64_u32 v[2:3], s[16:17], s15, v4, v[2:3]
	v_lshl_add_u64 v[4:5], s[12:13], 0, v[42:43]
	v_lshl_add_u64 v[4:5], v[4:5], 0, s[10:11]
	s_mov_b32 s22, 0xfebff000
	v_add_co_u32_e32 v14, vcc, s22, v4
	s_mov_b32 s22, 0xfec00000
	s_nop 0
	v_addc_co_u32_e32 v15, vcc, -1, v5, vcc
	v_add_co_u32_e32 v34, vcc, s22, v4
	s_mov_b32 s22, 0xfedff000
	s_nop 0
	v_addc_co_u32_e32 v35, vcc, -1, v5, vcc
	v_add_co_u32_e32 v52, vcc, s22, v4
	s_mov_b32 s22, 0xfee00000
	s_nop 0
	v_addc_co_u32_e32 v53, vcc, -1, v5, vcc
	v_add_co_u32_e32 v72, vcc, s22, v4
	s_mov_b32 s22, 0xfefff000
	s_nop 0
	v_addc_co_u32_e32 v73, vcc, -1, v5, vcc
	v_add_co_u32_e32 v80, vcc, s22, v4
	global_load_dwordx4 v[6:9], v[14:15], off offset:-3072
	global_load_dwordx4 v[10:13], v[14:15], off offset:-2048
	s_nop 0
	global_load_dwordx4 v[14:17], v[14:15], off offset:-1024
	s_nop 0
	global_load_dwordx4 v[18:21], v[34:35], off offset:-4096
	global_load_dwordx4 v[22:25], v[34:35], off offset:-3072
	global_load_dwordx4 v[26:29], v[34:35], off offset:-2048
	global_load_dwordx4 v[30:33], v[34:35], off offset:-1024
	s_nop 0
	global_load_dwordx4 v[34:37], v[34:35], off
	s_nop 0
	global_load_dwordx4 v[44:47], v[52:53], off offset:-3072
	global_load_dwordx4 v[48:51], v[52:53], off offset:-2048
	s_nop 0
	global_load_dwordx4 v[52:55], v[52:53], off offset:-1024
	v_addc_co_u32_e32 v81, vcc, -1, v5, vcc
	s_mov_b32 s22, 0xff000000
	global_load_dwordx4 v[56:59], v[72:73], off offset:-4096
	global_load_dwordx4 v[60:63], v[72:73], off offset:-3072
	global_load_dwordx4 v[64:67], v[72:73], off offset:-2048
	global_load_dwordx4 v[68:71], v[72:73], off offset:-1024
	s_nop 0
	global_load_dwordx4 v[72:75], v[72:73], off
	s_nop 0
	global_load_dwordx4 v[76:79], v[80:81], off offset:-3072
	global_load_dwordx4 v[84:87], v[80:81], off offset:-2048
	global_load_dwordx4 v[88:91], v[80:81], off offset:-1024
	v_add_co_u32_e32 v80, vcc, s22, v4
	s_mov_b32 s22, 0xff1ff000
	s_nop 0
	v_addc_co_u32_e32 v81, vcc, -1, v5, vcc
	global_load_dwordx4 v[92:95], v[80:81], off offset:-4096
	global_load_dwordx4 v[96:99], v[80:81], off offset:-3072
	global_load_dwordx4 v[100:103], v[80:81], off offset:-2048
	global_load_dwordx4 v[104:107], v[80:81], off offset:-1024
	global_load_dwordx4 v[108:111], v[80:81], off
	s_ashr_i32 s15, s14, 31
	s_lshl_b64 s[16:17], s[14:15], 11
	s_lshl_b64 s[18:19], s[14:15], 13
	s_add_u32 s20, s12, s18
	s_addc_u32 s21, s13, s19
	v_lshl_add_u64 v[2:3], v[2:3], 0, v[42:43]
	s_waitcnt vmcnt(15)
	v_pk_add_f32 v[8:9], v[8:9], v[46:47]
	v_pk_add_f32 v[6:7], v[6:7], v[44:45]
	s_waitcnt vmcnt(13)
	v_pk_add_f32 v[14:15], v[14:15], v[52:53]
	v_pk_add_f32 v[12:13], v[12:13], v[50:51]
	v_pk_add_f32 v[10:11], v[10:11], v[48:49]
	v_pk_add_f32 v[16:17], v[16:17], v[54:55]
	s_waitcnt vmcnt(8)
	v_pk_add_f32 v[34:35], v[34:35], v[72:73]
	s_waitcnt vmcnt(5)
	v_pk_add_f32 v[88:89], v[14:15], v[88:89]
	v_add_co_u32_e32 v14, vcc, s22, v4
	s_mov_b32 s22, 0xff200000
	s_nop 0
	v_addc_co_u32_e32 v15, vcc, -1, v5, vcc
	s_waitcnt vmcnt(0)
	v_pk_add_f32 v[108:109], v[34:35], v[108:109]
	v_add_co_u32_e32 v34, vcc, s22, v4
	s_mov_b32 s22, 0xff3ff000
	s_nop 0
	v_addc_co_u32_e32 v35, vcc, -1, v5, vcc
	v_add_co_u32_e32 v52, vcc, s22, v4
	v_pk_add_f32 v[20:21], v[20:21], v[58:59]
	v_pk_add_f32 v[18:19], v[18:19], v[56:57]
	v_pk_add_f32 v[24:25], v[24:25], v[62:63]
	v_pk_add_f32 v[22:23], v[22:23], v[60:61]
	v_pk_add_f32 v[28:29], v[28:29], v[66:67]
	v_pk_add_f32 v[26:27], v[26:27], v[64:65]
	v_pk_add_f32 v[32:33], v[32:33], v[70:71]
	v_pk_add_f32 v[30:31], v[30:31], v[68:69]
	v_pk_add_f32 v[36:37], v[36:37], v[74:75]
	v_pk_add_f32 v[78:79], v[8:9], v[78:79]
	v_pk_add_f32 v[76:77], v[6:7], v[76:77]
	v_pk_add_f32 v[80:81], v[12:13], v[86:87]
	v_pk_add_f32 v[84:85], v[10:11], v[84:85]
	v_pk_add_f32 v[86:87], v[16:17], v[90:91]
	global_load_dwordx4 v[6:9], v[14:15], off offset:-3072
	global_load_dwordx4 v[10:13], v[14:15], off offset:-2048
	s_nop 0
	global_load_dwordx4 v[14:17], v[14:15], off offset:-1024
	v_addc_co_u32_e32 v53, vcc, -1, v5, vcc
	s_mov_b32 s22, 0xff400000
	v_pk_add_f32 v[90:91], v[20:21], v[94:95]
	v_pk_add_f32 v[92:93], v[18:19], v[92:93]
	v_pk_add_f32 v[94:95], v[24:25], v[98:99]
	v_pk_add_f32 v[96:97], v[22:23], v[96:97]
	v_pk_add_f32 v[98:99], v[28:29], v[102:103]
	v_pk_add_f32 v[100:101], v[26:27], v[100:101]
	v_pk_add_f32 v[102:103], v[32:33], v[106:107]
	v_pk_add_f32 v[104:105], v[30:31], v[104:105]
	v_pk_add_f32 v[106:107], v[36:37], v[110:111]
	global_load_dwordx4 v[18:21], v[34:35], off offset:-4096
	global_load_dwordx4 v[22:25], v[34:35], off offset:-3072
	global_load_dwordx4 v[26:29], v[34:35], off offset:-2048
	global_load_dwordx4 v[30:33], v[34:35], off offset:-1024
	s_nop 0
	global_load_dwordx4 v[34:37], v[34:35], off
	s_nop 0
	global_load_dwordx4 v[44:47], v[52:53], off offset:-3072
	global_load_dwordx4 v[48:51], v[52:53], off offset:-2048
	s_nop 0
	global_load_dwordx4 v[52:55], v[52:53], off offset:-1024
	v_add_co_u32_e32 v72, vcc, s22, v4
	s_mov_b32 s22, 0xff5ff000
	s_nop 0
	v_addc_co_u32_e32 v73, vcc, -1, v5, vcc
	global_load_dwordx4 v[56:59], v[72:73], off offset:-4096
	global_load_dwordx4 v[60:63], v[72:73], off offset:-3072
	global_load_dwordx4 v[64:67], v[72:73], off offset:-2048
	global_load_dwordx4 v[68:71], v[72:73], off offset:-1024
	s_nop 0
	global_load_dwordx4 v[72:75], v[72:73], off
	s_waitcnt vmcnt(15)
	v_pk_add_f32 v[8:9], v[78:79], v[8:9]
	s_waitcnt vmcnt(14)
	v_pk_add_f32 v[12:13], v[80:81], v[12:13]
	s_waitcnt vmcnt(13)
	v_pk_add_f32 v[16:17], v[86:87], v[16:17]
	v_pk_add_f32 v[80:81], v[88:89], v[14:15]
	v_pk_add_f32 v[78:79], v[84:85], v[10:11]
	v_pk_add_f32 v[76:77], v[76:77], v[6:7]
	s_waitcnt vmcnt(12)
	v_pk_add_f32 v[84:85], v[92:93], v[18:19]
	v_pk_add_f32 v[20:21], v[90:91], v[20:21]
	s_waitcnt vmcnt(11)
	v_pk_add_f32 v[24:25], v[94:95], v[24:25]
	s_waitcnt vmcnt(7)
	v_pk_add_f32 v[6:7], v[8:9], v[46:47]
	v_pk_add_f32 v[36:37], v[106:107], v[36:37]
	s_waitcnt vmcnt(5)
	v_pk_add_f32 v[14:15], v[16:17], v[54:55]
	v_pk_add_f32 v[16:17], v[80:81], v[52:53]
	v_add_co_u32_e32 v52, vcc, s22, v4
	v_pk_add_f32 v[92:93], v[108:109], v[34:35]
	s_nop 0
	v_addc_co_u32_e32 v53, vcc, -1, v5, vcc
	s_mov_b32 s22, 0xff600000
	s_waitcnt vmcnt(0)
	v_pk_add_f32 v[34:35], v[36:37], v[74:75]
	v_pk_add_f32 v[36:37], v[92:93], v[72:73]
	v_add_co_u32_e32 v72, vcc, s22, v4
	v_pk_add_f32 v[8:9], v[76:77], v[44:45]
	v_pk_add_f32 v[10:11], v[12:13], v[50:51]
	v_pk_add_f32 v[12:13], v[78:79], v[48:49]
	global_load_dwordx4 v[44:47], v[52:53], off offset:-3072
	global_load_dwordx4 v[48:51], v[52:53], off offset:-2048
	s_nop 0
	global_load_dwordx4 v[52:55], v[52:53], off offset:-1024
	v_addc_co_u32_e32 v73, vcc, -1, v5, vcc
	s_mov_b32 s22, 0xff7ff000
	v_pk_add_f32 v[86:87], v[96:97], v[22:23]
	v_pk_add_f32 v[28:29], v[98:99], v[28:29]
	v_pk_add_f32 v[88:89], v[100:101], v[26:27]
	v_pk_add_f32 v[32:33], v[102:103], v[32:33]
	v_pk_add_f32 v[90:91], v[104:105], v[30:31]
	v_add_co_u32_e32 v80, vcc, s22, v4
	v_pk_add_f32 v[18:19], v[20:21], v[58:59]
	v_pk_add_f32 v[20:21], v[84:85], v[56:57]
	v_pk_add_f32 v[22:23], v[24:25], v[62:63]
	v_pk_add_f32 v[24:25], v[86:87], v[60:61]
	v_pk_add_f32 v[26:27], v[28:29], v[66:67]
	v_pk_add_f32 v[28:29], v[88:89], v[64:65]
	v_pk_add_f32 v[30:31], v[32:33], v[70:71]
	v_pk_add_f32 v[32:33], v[90:91], v[68:69]
	global_load_dwordx4 v[56:59], v[72:73], off offset:-4096
	global_load_dwordx4 v[60:63], v[72:73], off offset:-3072
	global_load_dwordx4 v[64:67], v[72:73], off offset:-2048
	global_load_dwordx4 v[68:71], v[72:73], off offset:-1024
	s_nop 0
	global_load_dwordx4 v[72:75], v[72:73], off
	v_addc_co_u32_e32 v81, vcc, -1, v5, vcc
	s_mov_b32 s22, 0xff800000
	global_load_dwordx4 v[76:79], v[80:81], off offset:-3072
	global_load_dwordx4 v[84:87], v[80:81], off offset:-2048
	global_load_dwordx4 v[88:91], v[80:81], off offset:-1024
	v_add_co_u32_e32 v80, vcc, s22, v4
	s_mov_b32 s22, 0xff9ff000
	s_nop 0
	v_addc_co_u32_e32 v81, vcc, -1, v5, vcc
	global_load_dwordx4 v[92:95], v[80:81], off offset:-4096
	global_load_dwordx4 v[96:99], v[80:81], off offset:-3072
	global_load_dwordx4 v[100:103], v[80:81], off offset:-2048
	global_load_dwordx4 v[104:107], v[80:81], off offset:-1024
	global_load_dwordx4 v[108:111], v[80:81], off
	s_waitcnt vmcnt(15)
	v_pk_add_f32 v[6:7], v[6:7], v[46:47]
	v_pk_add_f32 v[8:9], v[8:9], v[44:45]
	s_waitcnt vmcnt(13)
	v_pk_add_f32 v[16:17], v[16:17], v[52:53]
	v_add_co_u32_e32 v52, vcc, s22, v4
	s_mov_b32 s22, 0xffa00000
	s_nop 0
	v_addc_co_u32_e32 v53, vcc, -1, v5, vcc
	v_pk_add_f32 v[10:11], v[10:11], v[50:51]
	v_pk_add_f32 v[12:13], v[12:13], v[48:49]
	v_pk_add_f32 v[14:15], v[14:15], v[54:55]
	s_waitcnt vmcnt(12)
	v_pk_add_f32 v[18:19], v[18:19], v[58:59]
	v_pk_add_f32 v[20:21], v[20:21], v[56:57]
	s_waitcnt vmcnt(11)
	v_pk_add_f32 v[22:23], v[22:23], v[62:63]
	v_pk_add_f32 v[24:25], v[24:25], v[60:61]
	s_waitcnt vmcnt(8)
	v_pk_add_f32 v[46:47], v[36:37], v[72:73]
	v_add_co_u32_e32 v72, vcc, s22, v4
	s_mov_b32 s22, 0xffbff000
	s_nop 0
	v_addc_co_u32_e32 v73, vcc, -1, v5, vcc
	v_pk_add_f32 v[26:27], v[26:27], v[66:67]
	v_pk_add_f32 v[28:29], v[28:29], v[64:65]
	v_pk_add_f32 v[30:31], v[30:31], v[70:71]
	v_pk_add_f32 v[32:33], v[32:33], v[68:69]
	v_pk_add_f32 v[44:45], v[34:35], v[74:75]
	v_add_co_u32_e32 v80, vcc, s22, v4
	s_waitcnt vmcnt(7)
	v_pk_add_f32 v[34:35], v[6:7], v[78:79]
	v_pk_add_f32 v[36:37], v[8:9], v[76:77]
	s_waitcnt vmcnt(6)
	v_pk_add_f32 v[6:7], v[10:11], v[86:87]
	v_pk_add_f32 v[8:9], v[12:13], v[84:85]
	s_waitcnt vmcnt(5)
	v_pk_add_f32 v[10:11], v[14:15], v[90:91]
	v_pk_add_f32 v[12:13], v[16:17], v[88:89]
	s_waitcnt vmcnt(4)
	v_pk_add_f32 v[14:15], v[18:19], v[94:95]
	v_pk_add_f32 v[16:17], v[20:21], v[92:93]
	s_waitcnt vmcnt(3)
	v_pk_add_f32 v[18:19], v[22:23], v[98:99]
	v_pk_add_f32 v[20:21], v[24:25], v[96:97]
	s_waitcnt vmcnt(2)
	v_pk_add_f32 v[22:23], v[26:27], v[102:103]
	v_pk_add_f32 v[24:25], v[28:29], v[100:101]
	s_waitcnt vmcnt(1)
	v_pk_add_f32 v[26:27], v[30:31], v[106:107]
	v_pk_add_f32 v[28:29], v[32:33], v[104:105]
	s_waitcnt vmcnt(0)
	v_pk_add_f32 v[30:31], v[44:45], v[110:111]
	v_pk_add_f32 v[32:33], v[46:47], v[108:109]
	global_load_dwordx4 v[44:47], v[52:53], off offset:-3072
	global_load_dwordx4 v[48:51], v[52:53], off offset:-2048
	s_nop 0
	global_load_dwordx4 v[52:55], v[52:53], off offset:-1024
	v_addc_co_u32_e32 v81, vcc, -1, v5, vcc
	global_load_dwordx4 v[56:59], v[72:73], off offset:-4096
	global_load_dwordx4 v[60:63], v[72:73], off offset:-3072
	global_load_dwordx4 v[64:67], v[72:73], off offset:-2048
	global_load_dwordx4 v[68:71], v[72:73], off offset:-1024
	s_nop 0
	global_load_dwordx4 v[72:75], v[72:73], off
	s_nop 0
	global_load_dwordx4 v[76:79], v[80:81], off offset:-3072
	global_load_dwordx4 v[84:87], v[80:81], off offset:-2048
	global_load_dwordx4 v[88:91], v[80:81], off offset:-1024
	s_mov_b32 s22, 0xffc00000
	v_add_co_u32_e32 v80, vcc, s22, v4
	s_mov_b32 s22, 0xffdff000
	s_nop 0
	v_addc_co_u32_e32 v81, vcc, -1, v5, vcc
	global_load_dwordx4 v[92:95], v[80:81], off offset:-4096
	global_load_dwordx4 v[96:99], v[80:81], off offset:-3072
	global_load_dwordx4 v[100:103], v[80:81], off offset:-2048
	global_load_dwordx4 v[104:107], v[80:81], off offset:-1024
	global_load_dwordx4 v[108:111], v[80:81], off
	s_waitcnt vmcnt(15)
	v_pk_add_f32 v[34:35], v[34:35], v[46:47]
	s_waitcnt vmcnt(14)
	v_pk_add_f32 v[6:7], v[6:7], v[50:51]
	s_waitcnt vmcnt(13)
	v_pk_add_f32 v[10:11], v[10:11], v[54:55]
	s_waitcnt vmcnt(12)
	v_pk_add_f32 v[14:15], v[14:15], v[58:59]
	s_waitcnt vmcnt(7)
	v_pk_add_f32 v[78:79], v[34:35], v[78:79]
	s_waitcnt vmcnt(6)
	v_pk_add_f32 v[80:81], v[6:7], v[86:87]
	s_waitcnt vmcnt(5)
	v_pk_add_f32 v[86:87], v[10:11], v[90:91]
	v_pk_add_f32 v[36:37], v[36:37], v[44:45]
	v_pk_add_f32 v[8:9], v[8:9], v[48:49]
	s_waitcnt vmcnt(4)
	v_pk_add_f32 v[90:91], v[14:15], v[94:95]
	v_add_co_u32_e32 v14, vcc, s22, v4
	s_mov_b32 s22, 0xffe00000
	s_nop 0
	v_addc_co_u32_e32 v15, vcc, -1, v5, vcc
	v_add_co_u32_e32 v34, vcc, s22, v4
	v_pk_add_f32 v[12:13], v[12:13], v[52:53]
	s_nop 0
	v_addc_co_u32_e32 v35, vcc, -1, v5, vcc
	v_pk_add_f32 v[16:17], v[16:17], v[56:57]
	v_pk_add_f32 v[18:19], v[18:19], v[62:63]
	v_pk_add_f32 v[20:21], v[20:21], v[60:61]
	v_pk_add_f32 v[22:23], v[22:23], v[66:67]
	v_pk_add_f32 v[24:25], v[24:25], v[64:65]
	v_pk_add_f32 v[26:27], v[26:27], v[70:71]
	v_pk_add_f32 v[28:29], v[28:29], v[68:69]
	v_pk_add_f32 v[30:31], v[30:31], v[74:75]
	v_pk_add_f32 v[32:33], v[32:33], v[72:73]
	v_add_co_u32_e32 v52, vcc, s31, v4
	v_pk_add_f32 v[76:77], v[36:37], v[76:77]
	v_pk_add_f32 v[84:85], v[8:9], v[84:85]
	v_pk_add_f32 v[88:89], v[12:13], v[88:89]
	v_pk_add_f32 v[92:93], v[16:17], v[92:93]
	s_waitcnt vmcnt(3)
	v_pk_add_f32 v[94:95], v[18:19], v[98:99]
	v_pk_add_f32 v[96:97], v[20:21], v[96:97]
	s_waitcnt vmcnt(2)
	v_pk_add_f32 v[98:99], v[22:23], v[102:103]
	v_pk_add_f32 v[100:101], v[24:25], v[100:101]
	s_waitcnt vmcnt(1)
	v_pk_add_f32 v[102:103], v[26:27], v[106:107]
	v_pk_add_f32 v[104:105], v[28:29], v[104:105]
	s_waitcnt vmcnt(0)
	v_pk_add_f32 v[106:107], v[30:31], v[110:111]
	v_pk_add_f32 v[108:109], v[32:33], v[108:109]
	global_load_dwordx4 v[6:9], v[14:15], off offset:-3072
	global_load_dwordx4 v[10:13], v[14:15], off offset:-2048
	s_nop 0
	global_load_dwordx4 v[14:17], v[14:15], off offset:-1024
	s_nop 0
	global_load_dwordx4 v[18:21], v[34:35], off offset:-4096
	global_load_dwordx4 v[22:25], v[34:35], off offset:-3072
	global_load_dwordx4 v[26:29], v[34:35], off offset:-2048
	global_load_dwordx4 v[30:33], v[34:35], off offset:-1024
	s_nop 0
	global_load_dwordx4 v[34:37], v[34:35], off
	v_addc_co_u32_e32 v53, vcc, -1, v5, vcc
	global_load_dwordx4 v[44:47], v[52:53], off offset:-3072
	global_load_dwordx4 v[48:51], v[52:53], off offset:-2048
	s_nop 0
	global_load_dwordx4 v[52:55], v[52:53], off offset:-1024
	s_nop 0
	global_load_dwordx4 v[56:59], v[4:5], off offset:-4096
	global_load_dwordx4 v[60:63], v[4:5], off offset:-3072
	global_load_dwordx4 v[64:67], v[4:5], off offset:-2048
	global_load_dwordx4 v[68:71], v[4:5], off offset:-1024
	global_load_dwordx4 v[72:75], v[4:5], off
	s_waitcnt vmcnt(15)
	v_pk_add_f32 v[4:5], v[78:79], v[8:9]
	s_waitcnt vmcnt(14)
	v_pk_add_f32 v[10:11], v[84:85], v[10:11]
	v_pk_add_f32 v[6:7], v[76:77], v[6:7]
	v_pk_add_f32 v[8:9], v[80:81], v[12:13]
	s_waitcnt vmcnt(13)
	v_pk_add_f32 v[12:13], v[86:87], v[16:17]
	s_waitcnt vmcnt(8)
	v_pk_add_f32 v[36:37], v[106:107], v[36:37]
	s_waitcnt vmcnt(6)
	v_pk_add_f32 v[16:17], v[10:11], v[48:49]
	v_lshl_add_u64 v[10:11], s[20:21], 0, v[42:43]
	s_mov_b64 s[20:21], 0x21b1e000
	v_pk_add_f32 v[76:77], v[88:89], v[14:15]
	v_pk_add_f32 v[80:81], v[92:93], v[18:19]
	v_pk_add_f32 v[86:87], v[96:97], v[22:23]
	v_pk_add_f32 v[96:97], v[6:7], v[44:45]
	v_pk_add_f32 v[14:15], v[8:9], v[50:51]
	s_waitcnt vmcnt(0)
	v_pk_add_f32 v[44:45], v[36:37], v[74:75]
	v_lshl_add_u64 v[36:37], v[10:11], 0, s[20:21]
	v_add_co_u32_e32 v50, vcc, s70, v10
	s_mov_b64 s[20:21], 0xa000
	v_pk_add_f32 v[84:85], v[94:95], v[24:25]
	v_pk_add_f32 v[24:25], v[80:81], v[56:57]
	v_addc_co_u32_e32 v51, vcc, 0, v11, vcc
	v_lshl_add_u64 v[56:57], v[2:3], 0, s[20:21]
	s_mov_b32 s20, 0xb000
	v_add_co_u32_e32 v48, vcc, s20, v2
	v_pk_add_f32 v[32:33], v[102:103], v[32:33]
	v_pk_add_f32 v[34:35], v[108:109], v[34:35]
	v_addc_co_u32_e32 v49, vcc, 0, v3, vcc
	v_pk_add_f32 v[94:95], v[4:5], v[46:47]
	v_pk_add_f32 v[18:19], v[12:13], v[54:55]
	v_pk_add_f32 v[4:5], v[32:33], v[70:71]
	v_pk_add_f32 v[46:47], v[34:35], v[72:73]
	global_load_dwordx4 v[32:35], v[50:51], off offset:-4096
	global_load_dwordx4 v[10:13], v[48:49], off offset:-4096
	v_pk_add_f32 v[78:79], v[90:91], v[20:21]
	v_pk_add_f32 v[20:21], v[76:77], v[52:53]
	v_pk_add_f32 v[22:23], v[78:79], v[58:59]
	v_pk_add_f32 v[88:89], v[98:99], v[28:29]
	v_pk_add_f32 v[90:91], v[100:101], v[26:27]
	v_pk_add_f32 v[26:27], v[84:85], v[62:63]
	v_pk_add_f32 v[28:29], v[86:87], v[60:61]
	v_pk_add_f32 v[8:9], v[88:89], v[66:67]
	v_pk_add_f32 v[92:93], v[104:105], v[30:31]
	v_pk_add_f32 v[30:31], v[90:91], v[64:65]
	v_pk_add_f32 v[6:7], v[92:93], v[68:69]
	s_waitcnt vmcnt(0)
	v_pk_add_f32 v[2:3], v[12:13], 1.0 op_sel_hi:[1,0]
	v_pk_add_f32 v[10:11], v[10:11], 1.0 op_sel_hi:[1,0]
	v_pk_mul_f32 v[2:3], v[94:95], v[2:3]
	v_pk_mul_f32 v[12:13], v[96:97], v[10:11]
	v_pk_fma_f32 v[10:11], v[34:35], s[92:93], v[2:3] op_sel_hi:[1,0,1]
	v_pk_fma_f32 v[12:13], v[32:33], s[92:93], v[12:13] op_sel_hi:[1,0,1]
	global_load_dwordx4 v[32:35], v[36:37], off offset:1024
	global_load_dwordx4 v[52:55], v[56:57], off offset:1024
	s_waitcnt vmcnt(0)
	v_pk_add_f32 v[2:3], v[54:55], 1.0 op_sel_hi:[1,0]
	v_pk_add_f32 v[52:53], v[52:53], 1.0 op_sel_hi:[1,0]
	v_pk_mul_f32 v[2:3], v[14:15], v[2:3]
	v_pk_mul_f32 v[16:17], v[16:17], v[52:53]
	v_pk_fma_f32 v[14:15], v[34:35], s[92:93], v[2:3] op_sel_hi:[1,0,1]
	v_pk_fma_f32 v[16:17], v[32:33], s[92:93], v[16:17] op_sel_hi:[1,0,1]
	global_load_dwordx4 v[32:35], v[36:37], off offset:2048
	global_load_dwordx4 v[52:55], v[56:57], off offset:2048
	s_waitcnt vmcnt(0)
	v_pk_add_f32 v[2:3], v[54:55], 1.0 op_sel_hi:[1,0]
	v_pk_add_f32 v[52:53], v[52:53], 1.0 op_sel_hi:[1,0]
	v_pk_mul_f32 v[2:3], v[18:19], v[2:3]
	v_pk_mul_f32 v[20:21], v[20:21], v[52:53]
	v_pk_fma_f32 v[18:19], v[34:35], s[92:93], v[2:3] op_sel_hi:[1,0,1]
	v_pk_fma_f32 v[20:21], v[32:33], s[92:93], v[20:21] op_sel_hi:[1,0,1]
	global_load_dwordx4 v[32:35], v[36:37], off offset:3072
	global_load_dwordx4 v[52:55], v[56:57], off offset:3072
	s_waitcnt vmcnt(0)
	v_pk_add_f32 v[2:3], v[54:55], 1.0 op_sel_hi:[1,0]
	v_pk_add_f32 v[36:37], v[52:53], 1.0 op_sel_hi:[1,0]
	v_pk_mul_f32 v[2:3], v[22:23], v[2:3]
	v_pk_mul_f32 v[24:25], v[24:25], v[36:37]
	v_pk_fma_f32 v[22:23], v[34:35], s[92:93], v[2:3] op_sel_hi:[1,0,1]
	v_pk_fma_f32 v[24:25], v[32:33], s[92:93], v[24:25] op_sel_hi:[1,0,1]
	global_load_dwordx4 v[32:35], v[50:51], off
	global_load_dwordx4 v[52:55], v[48:49], off
	s_waitcnt vmcnt(0)
	v_pk_add_f32 v[2:3], v[54:55], 1.0 op_sel_hi:[1,0]
	v_pk_add_f32 v[36:37], v[52:53], 1.0 op_sel_hi:[1,0]
	v_pk_mul_f32 v[2:3], v[26:27], v[2:3]
	v_pk_mul_f32 v[28:29], v[28:29], v[36:37]
	v_pk_fma_f32 v[26:27], v[34:35], s[92:93], v[2:3] op_sel_hi:[1,0,1]
	v_pk_fma_f32 v[28:29], v[32:33], s[92:93], v[28:29] op_sel_hi:[1,0,1]
	global_load_dwordx4 v[32:35], v[50:51], off offset:1024
	global_load_dwordx4 v[52:55], v[48:49], off offset:1024
	s_waitcnt vmcnt(0)
	v_pk_add_f32 v[2:3], v[54:55], 1.0 op_sel_hi:[1,0]
	v_pk_add_f32 v[36:37], v[52:53], 1.0 op_sel_hi:[1,0]
	v_pk_mul_f32 v[2:3], v[8:9], v[2:3]
	v_pk_mul_f32 v[8:9], v[30:31], v[36:37]
	v_pk_fma_f32 v[30:31], v[34:35], s[92:93], v[2:3] op_sel_hi:[1,0,1]
	global_load_dwordx4 v[52:55], v[50:51], off offset:2048
	global_load_dwordx4 v[34:37], v[48:49], off offset:2048
	v_pk_fma_f32 v[32:33], v[32:33], s[92:93], v[8:9] op_sel_hi:[1,0,1]
	s_waitcnt vmcnt(0)
	v_pk_add_f32 v[2:3], v[36:37], 1.0 op_sel_hi:[1,0]
	v_pk_add_f32 v[8:9], v[34:35], 1.0 op_sel_hi:[1,0]
	v_pk_mul_f32 v[2:3], v[4:5], v[2:3]
	v_pk_mul_f32 v[4:5], v[6:7], v[8:9]
	v_pk_fma_f32 v[34:35], v[54:55], s[92:93], v[2:3] op_sel_hi:[1,0,1]
	v_pk_fma_f32 v[36:37], v[52:53], s[92:93], v[4:5] op_sel_hi:[1,0,1]
	global_load_dwordx4 v[2:5], v[50:51], off offset:3072
	global_load_dwordx4 v[6:9], v[48:49], off offset:3072
	v_add_f32_e32 v48, v22, v23
	v_mov_b32_e32 v49, v27
	s_load_dwordx4 s[36:39], s[8:9], 0xb0
	s_waitcnt lgkmcnt(0)
	s_add_u32 s22, s36, s40
	s_addc_u32 s23, s37, s41
	s_add_u32 s24, s38, s40
	s_addc_u32 s25, s39, s41
	s_add_u32 s18, s30, s18
	s_addc_u32 s19, s27, s19
	s_and_b64 s[20:21], s[34:35], exec
	s_cselect_b32 s17, s17, 0
	s_cselect_b32 s16, s16, 0
	s_lshl_b64 s[16:17], s[16:17], 1
	s_add_u32 s20, s29, s16
	s_addc_u32 s21, s26, s17
	s_load_dwordx2 s[16:17], s[8:9], 0x68
	s_waitcnt vmcnt(0)
	v_pk_add_f32 v[8:9], v[8:9], 1.0 op_sel_hi:[1,0]
	v_pk_add_f32 v[6:7], v[6:7], 1.0 op_sel_hi:[1,0]
	v_pk_mul_f32 v[8:9], v[44:45], v[8:9]
	v_pk_mul_f32 v[6:7], v[46:47], v[6:7]
	v_pk_fma_f32 v[44:45], v[4:5], s[92:93], v[8:9] op_sel_hi:[1,0,1]
	v_pk_fma_f32 v[8:9], v[2:3], s[92:93], v[6:7] op_sel_hi:[1,0,1]
	v_mov_b32_e32 v2, v12
	v_mov_b32_e32 v3, v16
	v_mov_b32_e32 v4, v13
	v_mov_b32_e32 v5, v17
	v_pk_add_f32 v[2:3], v[2:3], v[4:5]
	v_mov_b32_e32 v4, v10
	v_mov_b32_e32 v5, v14
	v_mov_b32_e32 v46, v11
	v_mov_b32_e32 v47, v15
	v_pk_add_f32 v[4:5], v[4:5], v[46:47]
	v_mov_b32_e32 v46, v20
	v_pk_add_f32 v[2:3], v[2:3], v[4:5]
	v_pk_mov_b32 v[4:5], v[20:21], v[18:19] op_sel:[1,0]
	v_mov_b32_e32 v47, v19
	v_pk_add_f32 v[4:5], v[4:5], v[46:47]
	v_add_f32_e32 v2, 0, v2
	v_pk_add_f32 v[4:5], v[4:5], v[4:5] op_sel:[0,1] op_sel_hi:[1,0]
	v_add_f32_e32 v2, v2, v3
	v_add_f32_e32 v46, v24, v25
	v_mov_b32_e32 v3, v28
	v_mov_b32_e32 v5, v29
	v_mov_b32_e32 v47, v26
	v_pk_add_f32 v[2:3], v[2:3], v[4:5]
	v_pk_add_f32 v[4:5], v[46:47], v[48:49]
	v_mov_b32_e32 v46, v32
	v_pk_add_f32 v[2:3], v[2:3], v[4:5]
	v_pk_mov_b32 v[4:5], v[32:33], v[30:31] op_sel:[1,0]
	v_mov_b32_e32 v47, v31
	v_pk_add_f32 v[4:5], v[4:5], v[46:47]
	v_pk_add_f32 v[2:3], v[2:3], v[2:3] op_sel:[0,1] op_sel_hi:[1,0]
	v_pk_add_f32 v[4:5], v[4:5], v[4:5] op_sel:[0,1] op_sel_hi:[1,0]
	v_add_f32_e32 v46, v36, v37
	v_add_f32_e32 v48, v34, v35
	v_mov_b32_e32 v3, v8
	v_mov_b32_e32 v5, v9
	v_mov_b32_e32 v47, v44
	v_mov_b32_e32 v49, v45
	v_pk_add_f32 v[2:3], v[2:3], v[4:5]
	v_pk_add_f32 v[4:5], v[46:47], v[48:49]
	v_lshl_add_u64 v[6:7], v[38:39], 0, s[6:7]
	v_pk_add_f32 v[2:3], v[2:3], v[4:5]
	v_xor_b32_e32 v4, 1, v249
	v_add_f32_e32 v2, v2, v3
	v_and_b32_e32 v3, 64, v249
	v_add_u32_e32 v3, 64, v3
	v_cmp_lt_i32_e32 vcc, v4, v3
	s_nop 1
	v_cndmask_b32_e32 v4, v249, v4, vcc
	v_lshlrev_b32_e32 v58, 2, v4
	ds_bpermute_b32 v4, v58, v2
	s_waitcnt lgkmcnt(0)
	v_add_f32_e32 v2, v2, v4
	v_xor_b32_e32 v4, 2, v249
	v_cmp_lt_i32_e32 vcc, v4, v3
	s_nop 1
	v_cndmask_b32_e32 v4, v249, v4, vcc
	v_lshlrev_b32_e32 v59, 2, v4
	ds_bpermute_b32 v4, v59, v2
	s_waitcnt lgkmcnt(0)
	v_add_f32_e32 v2, v2, v4
	v_xor_b32_e32 v4, 4, v249
	v_cmp_lt_i32_e32 vcc, v4, v3
	s_nop 1
	v_cndmask_b32_e32 v4, v249, v4, vcc
	v_lshlrev_b32_e32 v60, 2, v4
	ds_bpermute_b32 v4, v60, v2
	s_waitcnt lgkmcnt(0)
	v_add_f32_e32 v2, v2, v4
	v_xor_b32_e32 v4, 8, v249
	v_cmp_lt_i32_e32 vcc, v4, v3
	s_nop 1
	v_cndmask_b32_e32 v4, v249, v4, vcc
	v_lshlrev_b32_e32 v61, 2, v4
	ds_bpermute_b32 v4, v61, v2
	s_waitcnt lgkmcnt(0)
	v_add_f32_e32 v2, v2, v4
	v_xor_b32_e32 v4, 16, v249
	v_cmp_lt_i32_e32 vcc, v4, v3
	s_nop 1
	v_cndmask_b32_e32 v4, v249, v4, vcc
	v_lshlrev_b32_e32 v62, 2, v4
	ds_bpermute_b32 v4, v62, v2
	s_waitcnt lgkmcnt(0)
	v_add_f32_e32 v2, v2, v4
	v_xor_b32_e32 v4, 32, v249
	v_cmp_lt_i32_e32 vcc, v4, v3
	s_nop 1
	v_cndmask_b32_e32 v3, v249, v4, vcc
	v_lshlrev_b32_e32 v63, 2, v3
	ds_bpermute_b32 v3, v63, v2
	s_waitcnt lgkmcnt(0)
	v_add_f32_e32 v50, v2, v3
	v_fmamk_f32 v13, v50, 0xba000000, v13
	v_fmamk_f32 v17, v50, 0xba000000, v17
	v_fmamk_f32 v11, v50, 0xba000000, v11
	v_fmac_f32_e32 v12, 0xba000000, v50
	v_fmamk_f32 v15, v50, 0xba000000, v15
	v_fmac_f32_e32 v16, 0xba000000, v50
	v_mov_b32_e32 v4, v13
	v_mov_b32_e32 v5, v17
	v_fmac_f32_e32 v10, 0xba000000, v50
	v_fmac_f32_e32 v14, 0xba000000, v50
	v_mov_b32_e32 v2, v12
	v_mov_b32_e32 v3, v16
	v_pk_mul_f32 v[4:5], v[4:5], v[4:5]
	v_mov_b32_e32 v46, v11
	v_mov_b32_e32 v47, v15
	v_pk_fma_f32 v[2:3], v[2:3], v[2:3], v[4:5]
	v_mov_b32_e32 v4, v10
	v_mov_b32_e32 v5, v14
	v_pk_mul_f32 v[46:47], v[46:47], v[46:47]
	v_fmamk_f32 v21, v50, 0xba000000, v21
	v_pk_fma_f32 v[4:5], v[4:5], v[4:5], v[46:47]
	v_fmac_f32_e32 v20, 0xba000000, v50
	v_pk_add_f32 v[2:3], v[2:3], v[4:5]
	v_fmamk_f32 v19, v50, 0xba000000, v19
	v_fmac_f32_e32 v18, 0xba000000, v50
	v_pk_add_f32 v[2:3], v[2:3], v[2:3] op_sel_hi:[0,1]
	v_pk_mul_f32 v[4:5], v[18:19], v[18:19]
	v_pk_mul_f32 v[46:47], v[20:21], v[20:21]
	v_fmac_f32_e32 v24, 0xba000000, v50
	v_pk_mov_b32 v[48:49], v[46:47], v[4:5] op_sel:[1,0]
	v_mov_b32_e32 v47, v5
	v_fmamk_f32 v25, v50, 0xba000000, v25
	v_fmac_f32_e32 v22, 0xba000000, v50
	v_mul_f32_e32 v2, v24, v24
	v_pk_add_f32 v[4:5], v[48:49], v[46:47]
	v_fmamk_f32 v23, v50, 0xba000000, v23
	v_pk_fma_f32 v[46:47], v[24:25], v[24:25], v[2:3] op_sel_hi:[1,1,0]
	v_mul_f32_e32 v2, v22, v22
	v_pk_add_f32 v[4:5], v[4:5], v[4:5] op_sel_hi:[0,1]
	v_pk_fma_f32 v[48:49], v[22:23], v[22:23], v[2:3] op_sel_hi:[1,1,0]
	v_fmamk_f32 v27, v50, 0xba000000, v27
	v_fmac_f32_e32 v26, 0xba000000, v50
	v_fmamk_f32 v29, v50, 0xba000000, v29
	v_fmac_f32_e32 v28, 0xba000000, v50
	v_mul_f32_e32 v46, v28, v28
	v_mul_f32_e32 v48, v29, v29
	v_mul_f32_e32 v4, v26, v26
	v_mul_f32_e32 v2, v27, v27
	v_pk_add_f32 v[46:47], v[46:47], v[48:49]
	v_pk_add_f32 v[2:3], v[4:5], v[2:3]
	v_fmamk_f32 v33, v50, 0xba000000, v33
	v_pk_add_f32 v[2:3], v[46:47], v[2:3]
	v_fmac_f32_e32 v32, 0xba000000, v50
	v_fmamk_f32 v31, v50, 0xba000000, v31
	v_fmac_f32_e32 v30, 0xba000000, v50
	v_pk_add_f32 v[2:3], v[2:3], v[2:3] op_sel_hi:[0,1]
	v_pk_mul_f32 v[4:5], v[30:31], v[30:31]
	v_pk_mul_f32 v[46:47], v[32:33], v[32:33]
	v_fmac_f32_e32 v36, 0xba000000, v50
	v_pk_mov_b32 v[48:49], v[46:47], v[4:5] op_sel:[1,0]
	v_mov_b32_e32 v47, v5
	v_fmamk_f32 v37, v50, 0xba000000, v37
	v_fmac_f32_e32 v34, 0xba000000, v50
	v_mul_f32_e32 v2, v36, v36
	v_pk_add_f32 v[4:5], v[48:49], v[46:47]
	v_fmamk_f32 v35, v50, 0xba000000, v35
	v_pk_fma_f32 v[46:47], v[36:37], v[36:37], v[2:3] op_sel_hi:[1,1,0]
	v_mul_f32_e32 v2, v34, v34
	v_pk_add_f32 v[4:5], v[4:5], v[4:5] op_sel_hi:[0,1]
	v_pk_fma_f32 v[48:49], v[34:35], v[34:35], v[2:3] op_sel_hi:[1,1,0]
	v_fmamk_f32 v45, v50, 0xba000000, v45
	v_fmac_f32_e32 v44, 0xba000000, v50
	v_fmamk_f32 v9, v50, 0xba000000, v9
	v_fmac_f32_e32 v8, 0xba000000, v50
	v_mul_f32_e32 v46, v8, v8
	v_mul_f32_e32 v48, v9, v9
	v_mul_f32_e32 v4, v44, v44
	v_mul_f32_e32 v2, v45, v45
	v_pk_add_f32 v[46:47], v[46:47], v[48:49]
	v_pk_add_f32 v[2:3], v[4:5], v[2:3]
	v_lshl_add_u64 v[50:51], s[22:23], 0, v[42:43]
	v_pk_add_f32 v[2:3], v[46:47], v[2:3]
	v_lshl_add_u64 v[48:49], s[24:25], 0, v[42:43]
	v_add_f32_e32 v2, v2, v3
	ds_bpermute_b32 v3, v58, v2
	global_load_dwordx4 v[52:55], v[48:49], off
	s_waitcnt lgkmcnt(0)
	v_add_f32_e32 v2, v2, v3
	ds_bpermute_b32 v3, v59, v2
	s_waitcnt lgkmcnt(0)
	v_add_f32_e32 v2, v2, v3
	ds_bpermute_b32 v3, v60, v2
	s_waitcnt lgkmcnt(0)
	v_add_f32_e32 v2, v2, v3
	ds_bpermute_b32 v3, v61, v2
	s_waitcnt lgkmcnt(0)
	v_add_f32_e32 v2, v2, v3
	ds_bpermute_b32 v3, v62, v2
	s_waitcnt lgkmcnt(0)
	v_add_f32_e32 v2, v2, v3
	ds_bpermute_b32 v3, v63, v2
	s_waitcnt lgkmcnt(0)
	v_add_f32_e32 v2, v2, v3
	v_fmamk_f32 v2, v2, 0x3a000000, v250
	v_cmp_gt_f32_e32 vcc, s96, v2
	v_mul_f32_e32 v3, 0x4f800000, v2
	s_nop 0
	v_cndmask_b32_e32 v2, v2, v3, vcc
	v_sqrt_f32_e32 v3, v2
	s_nop 0
	v_add_u32_e32 v4, -1, v3
	v_fma_f32 v5, -v4, v3, v2
	v_cmp_ge_f32_e64 s[8:9], 0, v5
	v_add_u32_e32 v5, 1, v3
	s_nop 0
	v_cndmask_b32_e64 v4, v3, v4, s[8:9]
	v_fma_f32 v3, -v5, v3, v2
	v_cmp_lt_f32_e64 s[8:9], 0, v3
	s_nop 1
	v_cndmask_b32_e64 v3, v4, v5, s[8:9]
	v_mul_f32_e32 v4, 0x37800000, v3
	v_cndmask_b32_e32 v3, v3, v4, vcc
	v_cmp_class_f32_e32 vcc, v2, v251
	s_nop 1
	v_cndmask_b32_e32 v2, v3, v2, vcc
	v_div_scale_f32 v3, s[8:9], v2, v2, 1.0
	v_rcp_f32_e32 v4, v3
	s_nop 0
	v_fma_f32 v5, -v3, v4, 1.0
	v_fmac_f32_e32 v4, v5, v4
	v_div_scale_f32 v5, vcc, 1.0, v2, 1.0
	v_mul_f32_e32 v46, v5, v4
	v_fma_f32 v47, -v3, v46, v5
	v_fmac_f32_e32 v46, v47, v4
	v_fma_f32 v3, -v3, v46, v5
	v_div_fmas_f32 v3, v3, v4, v46
	v_div_fixup_f32 v46, v3, v2, 1.0
	global_load_dwordx4 v[2:5], v[50:51], off
	v_pk_mul_f32 v[56:57], v[12:13], v[46:47] op_sel_hi:[1,0]
	v_pk_mul_f32 v[64:65], v[10:11], v[46:47] op_sel_hi:[1,0]
	v_cndmask_b32_e64 v47, 0, 1, s[34:35]
	v_cmp_ne_u32_e64 s[8:9], 1, v47
	s_andn2_b64 vcc, exec, s[34:35]
	s_waitcnt vmcnt(0)
	v_pk_fma_f32 v[4:5], v[4:5], v[64:65], v[54:55]
	v_pk_fma_f32 v[2:3], v[2:3], v[56:57], v[52:53]
	v_lshl_add_u64 v[54:55], s[18:19], 0, v[42:43]
	v_lshl_add_u64 v[52:53], v[40:41], 1, s[20:21]
	global_store_dwordx4 v[54:55], v[2:5], off
	s_cbranch_vccnz .LBB0_1760
	v_lshl_add_u64 v[10:11], v[6:7], 0, v[42:43]
	global_load_dwordx4 v[10:13], v[10:11], off
	v_lshl_add_u64 v[42:43], v[38:39], 0, v[42:43]
	global_load_dwordx4 v[64:67], v[42:43], off
	s_waitcnt vmcnt(1)
	v_pk_add_f32 v[12:13], v[12:13], 1.0 op_sel_hi:[1,0]
	v_pk_add_f32 v[42:43], v[10:11], 1.0 op_sel_hi:[1,0]
	s_waitcnt vmcnt(0)
	v_pk_fma_f32 v[10:11], v[4:5], v[12:13], v[66:67]
	v_pk_fma_f32 v[12:13], v[2:3], v[42:43], v[64:65]
	v_cvt_pk_bf16_f32 v2, v12, v13
	v_cvt_pk_bf16_f32 v3, v10, v11
	global_store_dwordx2 v[52:53], v[2:3], off
.LBB0_1760:
	global_load_dwordx4 v[2:5], v[50:51], off offset:1024
	s_nop 0
	global_load_dwordx4 v[64:67], v[48:49], off offset:1024
	v_mov_b32_e32 v47, v46
	v_mov_b32_e32 v42, v46
	v_mov_b32_e32 v43, v46
	v_pk_mul_f32 v[42:43], v[42:43], v[14:15]
	v_pk_mul_f32 v[56:57], v[46:47], v[16:17]
	s_and_b64 vcc, exec, s[8:9]
	s_waitcnt vmcnt(0)
	v_pk_fma_f32 v[4:5], v[4:5], v[42:43], v[66:67]
	v_pk_fma_f32 v[2:3], v[2:3], v[56:57], v[64:65]
	v_lshl_add_u64 v[42:43], v[40:41], 2, v[38:39]
	global_store_dwordx4 v[54:55], v[2:5], off offset:1024
	s_cbranch_vccnz .LBB0_1762
	v_lshl_add_u64 v[14:15], v[40:41], 2, v[6:7]
	global_load_dwordx4 v[14:17], v[14:15], off offset:1024
	s_nop 0
	global_load_dwordx4 v[64:67], v[42:43], off offset:1024
	s_waitcnt vmcnt(1)
	v_pk_add_f32 v[16:17], v[16:17], 1.0 op_sel_hi:[1,0]
	v_pk_add_f32 v[56:57], v[14:15], 1.0 op_sel_hi:[1,0]
	s_waitcnt vmcnt(0)
	v_pk_fma_f32 v[14:15], v[4:5], v[16:17], v[66:67]
	v_pk_fma_f32 v[16:17], v[2:3], v[56:57], v[64:65]
	v_cvt_pk_bf16_f32 v2, v16, v17
	v_cvt_pk_bf16_f32 v3, v14, v15
	global_store_dwordx2 v[52:53], v[2:3], off offset:512
.LBB0_1762:
	global_load_dwordx4 v[2:5], v[50:51], off offset:2048
	s_nop 0
	global_load_dwordx4 v[64:67], v[48:49], off offset:2048
	v_mov_b32_e32 v56, v46
	v_mov_b32_e32 v57, v46
	v_pk_mul_f32 v[68:69], v[46:47], v[20:21]
	v_pk_mul_f32 v[70:71], v[56:57], v[18:19]
	s_and_b64 vcc, exec, s[8:9]
	s_waitcnt vmcnt(0)
	v_pk_fma_f32 v[4:5], v[4:5], v[70:71], v[66:67]
	v_pk_fma_f32 v[2:3], v[2:3], v[68:69], v[64:65]
	global_store_dwordx4 v[54:55], v[2:5], off offset:2048
	s_cbranch_vccnz .LBB0_1764
	v_lshl_add_u64 v[18:19], v[40:41], 2, v[6:7]
	global_load_dwordx4 v[18:21], v[18:19], off offset:2048
	s_nop 0
	global_load_dwordx4 v[64:67], v[42:43], off offset:2048
	s_waitcnt vmcnt(1)
	v_pk_add_f32 v[20:21], v[20:21], 1.0 op_sel_hi:[1,0]
	v_pk_add_f32 v[68:69], v[18:19], 1.0 op_sel_hi:[1,0]
	s_waitcnt vmcnt(0)
	v_pk_fma_f32 v[18:19], v[4:5], v[20:21], v[66:67]
	v_pk_fma_f32 v[20:21], v[2:3], v[68:69], v[64:65]
	v_cvt_pk_bf16_f32 v2, v20, v21
	v_cvt_pk_bf16_f32 v3, v18, v19
	global_store_dwordx2 v[52:53], v[2:3], off offset:1024
.LBB0_1764:
	global_load_dwordx4 v[2:5], v[50:51], off offset:3072
	s_nop 0
	global_load_dwordx4 v[64:67], v[48:49], off offset:3072
	v_pk_mul_f32 v[56:57], v[56:57], v[22:23]
	v_pk_mul_f32 v[68:69], v[46:47], v[24:25]
	s_and_b64 vcc, exec, s[8:9]
	s_waitcnt vmcnt(0)
	v_pk_fma_f32 v[4:5], v[4:5], v[56:57], v[66:67]
	v_pk_fma_f32 v[2:3], v[2:3], v[68:69], v[64:65]
	global_store_dwordx4 v[54:55], v[2:5], off offset:3072
	s_cbranch_vccnz .LBB0_1766
	v_lshl_add_u64 v[22:23], v[40:41], 2, v[6:7]
	global_load_dwordx4 v[22:25], v[22:23], off offset:3072
	s_nop 0
	global_load_dwordx4 v[64:67], v[42:43], off offset:3072
	s_waitcnt vmcnt(1)
	v_pk_add_f32 v[24:25], v[24:25], 1.0 op_sel_hi:[1,0]
	v_pk_add_f32 v[42:43], v[22:23], 1.0 op_sel_hi:[1,0]
	s_waitcnt vmcnt(0)
	v_pk_fma_f32 v[22:23], v[4:5], v[24:25], v[66:67]
	v_pk_fma_f32 v[24:25], v[2:3], v[42:43], v[64:65]
	v_cvt_pk_bf16_f32 v2, v24, v25
	v_cvt_pk_bf16_f32 v3, v22, v23
	global_store_dwordx2 v[52:53], v[2:3], off offset:1536
.LBB0_1766:
	s_nop 0
	v_add_co_u32_e32 v2, vcc, 0x1000, v50
	v_pk_mul_f32 v[68:69], v[46:47], v[28:29]
	s_nop 0
	v_addc_co_u32_e32 v3, vcc, 0, v51, vcc
	v_add_co_u32_e32 v42, vcc, 0x1000, v48
	global_load_dwordx4 v[2:5], v[2:3], off
	s_nop 0
	v_addc_co_u32_e32 v43, vcc, 0, v49, vcc
	global_load_dwordx4 v[64:67], v[42:43], off
	v_mov_b32_e32 v42, v46
	v_mov_b32_e32 v43, v46
	v_pk_mul_f32 v[56:57], v[42:43], v[26:27]
	s_waitcnt vmcnt(0)
	v_pk_fma_f32 v[2:3], v[2:3], v[68:69], v[64:65]
	v_pk_fma_f32 v[4:5], v[4:5], v[56:57], v[66:67]
	v_add_co_u32_e32 v56, vcc, 0x1000, v54
	s_nop 1
	v_addc_co_u32_e32 v57, vcc, 0, v55, vcc
	s_and_b64 vcc, exec, s[8:9]
	global_store_dwordx4 v[56:57], v[2:5], off
	s_cbranch_vccnz .LBB0_1768
	v_mov_b64_e32 v[26:27], 0x1000
	v_lshl_add_u64 v[56:57], v[40:41], 2, v[26:27]
	v_lshl_add_u64 v[26:27], v[6:7], 0, v[56:57]
	global_load_dwordx4 v[26:29], v[26:27], off
	v_lshl_add_u64 v[56:57], v[38:39], 0, v[56:57]
	global_load_dwordx4 v[64:67], v[56:57], off
	s_waitcnt vmcnt(1)
	v_pk_add_f32 v[28:29], v[28:29], 1.0 op_sel_hi:[1,0]
	v_pk_add_f32 v[56:57], v[26:27], 1.0 op_sel_hi:[1,0]
	s_waitcnt vmcnt(0)
	v_pk_fma_f32 v[26:27], v[4:5], v[28:29], v[66:67]
	v_pk_fma_f32 v[28:29], v[2:3], v[56:57], v[64:65]
	v_cvt_pk_bf16_f32 v2, v28, v29
	v_cvt_pk_bf16_f32 v3, v26, v27
	global_store_dwordx2 v[52:53], v[2:3], off offset:2048
.LBB0_1768:
	s_nop 0
	v_add_co_u32_e32 v2, vcc, 0x1000, v50
	v_pk_mul_f32 v[42:43], v[42:43], v[30:31]
	s_nop 0
	v_addc_co_u32_e32 v3, vcc, 0, v51, vcc
	v_add_co_u32_e32 v56, vcc, 0x1000, v48
	global_load_dwordx4 v[2:5], v[2:3], off offset:1024
	s_nop 0
	v_addc_co_u32_e32 v57, vcc, 0, v49, vcc
	global_load_dwordx4 v[64:67], v[56:57], off offset:1024
	v_pk_mul_f32 v[56:57], v[46:47], v[32:33]
	s_waitcnt vmcnt(0)
	v_pk_fma_f32 v[4:5], v[4:5], v[42:43], v[66:67]
	v_add_co_u32_e32 v42, vcc, 0x1000, v54
	v_pk_fma_f32 v[2:3], v[2:3], v[56:57], v[64:65]
	s_nop 0
	v_addc_co_u32_e32 v43, vcc, 0, v55, vcc
	s_and_b64 vcc, exec, s[8:9]
	global_store_dwordx4 v[42:43], v[2:5], off offset:1024
	s_cbranch_vccnz .LBB0_1770
	v_mov_b64_e32 v[30:31], 0x1400
	v_lshl_add_u64 v[42:43], v[40:41], 2, v[30:31]
	v_lshl_add_u64 v[30:31], v[6:7], 0, v[42:43]
	global_load_dwordx4 v[30:33], v[30:31], off
	v_lshl_add_u64 v[42:43], v[38:39], 0, v[42:43]
	global_load_dwordx4 v[64:67], v[42:43], off
	s_waitcnt vmcnt(1)
	v_pk_add_f32 v[32:33], v[32:33], 1.0 op_sel_hi:[1,0]
	v_pk_add_f32 v[42:43], v[30:31], 1.0 op_sel_hi:[1,0]
	s_waitcnt vmcnt(0)
	v_pk_fma_f32 v[30:31], v[4:5], v[32:33], v[66:67]
	v_pk_fma_f32 v[32:33], v[2:3], v[42:43], v[64:65]
	v_cvt_pk_bf16_f32 v2, v32, v33
	v_cvt_pk_bf16_f32 v3, v30, v31
	global_store_dwordx2 v[52:53], v[2:3], off offset:2560
.LBB0_1770:
	s_nop 0
	v_add_co_u32_e32 v2, vcc, 0x1000, v50
	v_pk_mul_f32 v[68:69], v[46:47], v[36:37]
	s_nop 0
	v_addc_co_u32_e32 v3, vcc, 0, v51, vcc
	v_add_co_u32_e32 v42, vcc, 0x1000, v48
	global_load_dwordx4 v[2:5], v[2:3], off offset:2048
	s_nop 0
	v_addc_co_u32_e32 v43, vcc, 0, v49, vcc
	global_load_dwordx4 v[64:67], v[42:43], off offset:2048
	v_mov_b32_e32 v42, v46
	v_mov_b32_e32 v43, v46
	v_pk_mul_f32 v[56:57], v[42:43], v[34:35]
	s_waitcnt vmcnt(0)
	v_pk_fma_f32 v[2:3], v[2:3], v[68:69], v[64:65]
	v_pk_fma_f32 v[4:5], v[4:5], v[56:57], v[66:67]
	v_add_co_u32_e32 v56, vcc, 0x1000, v54
	s_nop 1
	v_addc_co_u32_e32 v57, vcc, 0, v55, vcc
	s_and_b64 vcc, exec, s[8:9]
	global_store_dwordx4 v[56:57], v[2:5], off offset:2048
	s_cbranch_vccnz .LBB0_1772
	v_mov_b64_e32 v[34:35], 0x1800
	v_lshl_add_u64 v[56:57], v[40:41], 2, v[34:35]
	v_lshl_add_u64 v[34:35], v[6:7], 0, v[56:57]
	global_load_dwordx4 v[34:37], v[34:35], off
	v_lshl_add_u64 v[56:57], v[38:39], 0, v[56:57]
	global_load_dwordx4 v[64:67], v[56:57], off
	s_waitcnt vmcnt(1)
	v_pk_add_f32 v[36:37], v[36:37], 1.0 op_sel_hi:[1,0]
	v_pk_add_f32 v[56:57], v[34:35], 1.0 op_sel_hi:[1,0]
	s_waitcnt vmcnt(0)
	v_pk_fma_f32 v[34:35], v[4:5], v[36:37], v[66:67]
	v_pk_fma_f32 v[36:37], v[2:3], v[56:57], v[64:65]
	v_cvt_pk_bf16_f32 v2, v36, v37
	v_cvt_pk_bf16_f32 v3, v34, v35
	global_store_dwordx2 v[52:53], v[2:3], off offset:3072
